# removed redundant s_setprio 0/1 flip between the two MFMA blocks of each super-phase (78 sites), on top of v017
# speedup vs baseline: 1.1113x; 1.1113x over previous
.LBB0_183:
	s_ashr_i32 s13, s12, 31
	s_lshl_b64 s[24:25], s[12:13], 19
	s_add_u32 s24, s80, s24
	s_addc_u32 s25, s81, s25
	s_and_b64 s[30:31], s[4:5], exec
	s_cselect_b32 s13, s25, s45
	s_cselect_b32 s66, s24, s44
	s_ashr_i32 s11, s10, 31
	s_lshl_b64 s[30:31], s[10:11], 19
	s_add_u32 s30, s52, s30
	s_addc_u32 s31, s53, s31
	s_and_b64 s[48:49], s[4:5], exec
	s_cselect_b32 s11, s31, s47
	s_cselect_b32 s67, s30, s46
	s_add_u32 s44, s44, 0x40080
	s_addc_u32 s45, s45, 0
	s_add_u32 s68, s46, 0x100
	s_addc_u32 s69, s47, 0
	s_mov_b32 s70, -2
	ds_read_b128 v[140:143], v147
	ds_read_b128 v[150:153], v147 offset:1024
	ds_read_b128 v[154:157], v147 offset:2048
	ds_read_b128 v[158:161], v147 offset:3072
	ds_read_b128 v[162:165], v148
	ds_read_b128 v[166:169], v148 offset:1024
	ds_read_b128 v[170:173], v148 offset:2048
	ds_read_b128 v[174:177], v148 offset:3072
	s_add_u32 s18, s44, 0xfffc0080
	s_addc_u32 s19, s45, -1
	s_cmp_eq_u32 s70, 12
	s_cselect_b32 s49, s13, s19
	s_cselect_b32 s48, s66, s18
	s_cselect_b32 s47, s11, s69
	s_cselect_b32 s46, s67, s68
	v_lshl_add_u64 v[178:179], s[44:45], 0, v[132:133]
	s_add_i32 m0, s37, 0xc000
	ds_read_b128 v[184:187], v149
	ds_read_b128 v[188:191], v149 offset:1024
	ds_read_b128 v[192:195], v149 offset:2048
	ds_read_b128 v[196:199], v149 offset:3072
	ds_read_b128 v[200:203], v149 offset:4096
	ds_read_b128 v[204:207], v149 offset:5120
	ds_read_b128 v[208:211], v149 offset:6144
	ds_read_b128 v[212:215], v149 offset:7168
	global_load_lds_dwordx4 v[178:179], off
	v_lshl_add_u64 v[178:179], s[44:45], 0, v[134:135]
	s_add_i32 m0, s37, 0xe000
	s_nop 0
	global_load_lds_dwordx4 v[178:179], off
	s_waitcnt vmcnt(8)
	s_waitcnt lgkmcnt(0)
	s_barrier
	s_setprio 1
	s_waitcnt lgkmcnt(0)
	v_mfma_f32_16x16x32_bf16 v[124:127], v[140:143], v[184:187], 0
	v_mfma_f32_16x16x32_bf16 v[124:127], v[150:153], v[188:191], v[124:127]
	v_mfma_f32_16x16x32_bf16 v[120:123], v[154:157], v[184:187], 0
	v_mfma_f32_16x16x32_bf16 v[120:123], v[158:161], v[188:191], v[120:123]
	v_mfma_f32_16x16x32_bf16 v[108:111], v[140:143], v[192:195], 0
	v_mfma_f32_16x16x32_bf16 v[108:111], v[150:153], v[196:199], v[108:111]
	v_mfma_f32_16x16x32_bf16 v[104:107], v[154:157], v[192:195], 0
	v_mfma_f32_16x16x32_bf16 v[104:107], v[158:161], v[196:199], v[104:107]
	v_mfma_f32_16x16x32_bf16 v[92:95], v[140:143], v[200:203], 0
	v_mfma_f32_16x16x32_bf16 v[92:95], v[150:153], v[204:207], v[92:95]
	v_mfma_f32_16x16x32_bf16 v[88:91], v[154:157], v[200:203], 0
	v_mfma_f32_16x16x32_bf16 v[88:91], v[158:161], v[204:207], v[88:91]
	v_mfma_f32_16x16x32_bf16 v[76:79], v[140:143], v[208:211], 0
	v_mfma_f32_16x16x32_bf16 v[76:79], v[150:153], v[212:215], v[76:79]
	v_mfma_f32_16x16x32_bf16 v[72:75], v[154:157], v[208:211], 0
	v_mfma_f32_16x16x32_bf16 v[72:75], v[158:161], v[212:215], v[72:75]
	v_mfma_f32_16x16x32_bf16 v[116:119], v[162:165], v[184:187], 0
	v_mfma_f32_16x16x32_bf16 v[116:119], v[166:169], v[188:191], v[116:119]
	v_mfma_f32_16x16x32_bf16 v[112:115], v[170:173], v[184:187], 0
	v_mfma_f32_16x16x32_bf16 v[112:115], v[174:177], v[188:191], v[112:115]
	v_mfma_f32_16x16x32_bf16 v[100:103], v[162:165], v[192:195], 0
	v_mfma_f32_16x16x32_bf16 v[100:103], v[166:169], v[196:199], v[100:103]
	v_mfma_f32_16x16x32_bf16 v[96:99], v[170:173], v[192:195], 0
	v_mfma_f32_16x16x32_bf16 v[96:99], v[174:177], v[196:199], v[96:99]
	v_mfma_f32_16x16x32_bf16 v[84:87], v[162:165], v[200:203], 0
	v_mfma_f32_16x16x32_bf16 v[84:87], v[166:169], v[204:207], v[84:87]
	v_mfma_f32_16x16x32_bf16 v[80:83], v[170:173], v[200:203], 0
	v_mfma_f32_16x16x32_bf16 v[80:83], v[174:177], v[204:207], v[80:83]
	v_mfma_f32_16x16x32_bf16 v[68:71], v[162:165], v[208:211], 0
	v_mfma_f32_16x16x32_bf16 v[68:71], v[166:169], v[212:215], v[68:71]
	v_mfma_f32_16x16x32_bf16 v[64:67], v[170:173], v[208:211], 0
	v_mfma_f32_16x16x32_bf16 v[64:67], v[174:177], v[212:215], v[64:67]
	s_setprio 0
	s_barrier
	s_add_i32 s18, s62, s54
	v_lshl_add_u64 v[178:179], s[46:47], 0, v[130:131]
	s_mov_b32 m0, s18
	ds_read_b128 v[184:187], v149 offset:16384
	ds_read_b128 v[188:191], v149 offset:17408
	ds_read_b128 v[192:195], v149 offset:18432
	ds_read_b128 v[196:199], v149 offset:19456
	ds_read_b128 v[200:203], v149 offset:20480
	ds_read_b128 v[204:207], v149 offset:21504
	ds_read_b128 v[208:211], v149 offset:22528
	ds_read_b128 v[212:215], v149 offset:23552
	global_load_lds_dwordx4 v[178:179], off
	s_add_i32 m0, s18, 0x2000
	s_add_u32 s72, s46, 0x40000
	v_lshl_add_u64 v[216:217], s[46:47], 0, v[128:129]
	s_addc_u32 s73, s47, 0
	s_add_i32 s18, s63, s54
	global_load_lds_dwordx4 v[216:217], off
	v_lshl_add_u64 v[218:219], s[72:73], 0, v[130:131]
	s_mov_b32 m0, s18
	v_lshl_add_u64 v[220:221], s[48:49], 0, v[128:129]
	global_load_lds_dwordx4 v[218:219], off
	v_lshl_add_u64 v[218:219], s[72:73], 0, v[128:129]
	s_add_i32 m0, s18, 0x2000
	s_nop 0
	global_load_lds_dwordx4 v[218:219], off
	v_lshl_add_u64 v[218:219], s[48:49], 0, v[130:131]
	s_mov_b32 m0, s37
	s_nop 0
	global_load_lds_dwordx4 v[218:219], off
	s_mov_b32 m0, s56
	s_nop 0
	global_load_lds_dwordx4 v[220:221], off
	s_waitcnt vmcnt(8)
	s_waitcnt lgkmcnt(0)
	s_barrier
	s_setprio 1
	s_waitcnt lgkmcnt(0)
	v_mfma_f32_16x16x32_bf16 v[60:63], v[140:143], v[184:187], 0
	v_mfma_f32_16x16x32_bf16 v[60:63], v[150:153], v[188:191], v[60:63]
	v_mfma_f32_16x16x32_bf16 v[56:59], v[154:157], v[184:187], 0
	v_mfma_f32_16x16x32_bf16 v[56:59], v[158:161], v[188:191], v[56:59]
	v_mfma_f32_16x16x32_bf16 v[44:47], v[140:143], v[192:195], 0
	v_mfma_f32_16x16x32_bf16 v[44:47], v[150:153], v[196:199], v[44:47]
	v_mfma_f32_16x16x32_bf16 v[40:43], v[154:157], v[192:195], 0
	v_mfma_f32_16x16x32_bf16 v[40:43], v[158:161], v[196:199], v[40:43]
	v_mfma_f32_16x16x32_bf16 v[28:31], v[140:143], v[200:203], 0
	v_mfma_f32_16x16x32_bf16 v[28:31], v[150:153], v[204:207], v[28:31]
	v_mfma_f32_16x16x32_bf16 v[24:27], v[154:157], v[200:203], 0
	v_mfma_f32_16x16x32_bf16 v[24:27], v[158:161], v[204:207], v[24:27]
	v_mfma_f32_16x16x32_bf16 v[12:15], v[140:143], v[208:211], 0
	v_mfma_f32_16x16x32_bf16 v[12:15], v[150:153], v[212:215], v[12:15]
	v_mfma_f32_16x16x32_bf16 v[8:11], v[154:157], v[208:211], 0
	v_mfma_f32_16x16x32_bf16 v[8:11], v[158:161], v[212:215], v[8:11]
	v_mfma_f32_16x16x32_bf16 v[52:55], v[162:165], v[184:187], 0
	v_mfma_f32_16x16x32_bf16 v[52:55], v[166:169], v[188:191], v[52:55]
	v_mfma_f32_16x16x32_bf16 v[48:51], v[170:173], v[184:187], 0
	v_mfma_f32_16x16x32_bf16 v[48:51], v[174:177], v[188:191], v[48:51]
	v_mfma_f32_16x16x32_bf16 v[36:39], v[162:165], v[192:195], 0
	v_mfma_f32_16x16x32_bf16 v[36:39], v[166:169], v[196:199], v[36:39]
	v_mfma_f32_16x16x32_bf16 v[32:35], v[170:173], v[192:195], 0
	v_mfma_f32_16x16x32_bf16 v[32:35], v[174:177], v[196:199], v[32:35]
	v_mfma_f32_16x16x32_bf16 v[20:23], v[162:165], v[200:203], 0
	v_mfma_f32_16x16x32_bf16 v[20:23], v[166:169], v[204:207], v[20:23]
	v_mfma_f32_16x16x32_bf16 v[16:19], v[170:173], v[200:203], 0
	v_mfma_f32_16x16x32_bf16 v[16:19], v[174:177], v[204:207], v[16:19]
	v_mfma_f32_16x16x32_bf16 v[4:7], v[162:165], v[208:211], 0
	v_mfma_f32_16x16x32_bf16 v[4:7], v[166:169], v[212:215], v[4:7]
	v_mfma_f32_16x16x32_bf16 v[0:3], v[170:173], v[208:211], 0
	v_mfma_f32_16x16x32_bf16 v[0:3], v[174:177], v[212:215], v[0:3]
	s_setprio 0
	s_barrier
	s_branch .Lmid_gemm0
.LBB0_184:
	ds_read_b128 v[140:143], v147
	ds_read_b128 v[150:153], v147 offset:1024
	ds_read_b128 v[154:157], v147 offset:2048
	ds_read_b128 v[158:161], v147 offset:3072
	ds_read_b128 v[162:165], v148
	ds_read_b128 v[166:169], v148 offset:1024
	ds_read_b128 v[170:173], v148 offset:2048
	ds_read_b128 v[174:177], v148 offset:3072
	s_add_u32 s18, s44, 0xfffc0080
	s_addc_u32 s19, s45, -1
	s_cmp_eq_u32 s70, 12
	s_cselect_b32 s49, s13, s19
	s_cselect_b32 s48, s66, s18
	s_cselect_b32 s47, s11, s69
	s_cselect_b32 s46, s67, s68
	v_lshl_add_u64 v[178:179], s[44:45], 0, v[132:133]
	s_add_i32 m0, s37, 0xc000
	ds_read_b128 v[184:187], v149
	ds_read_b128 v[188:191], v149 offset:1024
	ds_read_b128 v[192:195], v149 offset:2048
	ds_read_b128 v[196:199], v149 offset:3072
	ds_read_b128 v[200:203], v149 offset:4096
	ds_read_b128 v[204:207], v149 offset:5120
	ds_read_b128 v[208:211], v149 offset:6144
	ds_read_b128 v[212:215], v149 offset:7168
	global_load_lds_dwordx4 v[178:179], off
	v_lshl_add_u64 v[178:179], s[44:45], 0, v[134:135]
	s_add_i32 m0, s37, 0xe000
	s_nop 0
	global_load_lds_dwordx4 v[178:179], off
	s_waitcnt vmcnt(8)
	s_waitcnt lgkmcnt(0)
	s_barrier
	s_setprio 1
	s_waitcnt lgkmcnt(0)
	v_mfma_f32_16x16x32_bf16 v[124:127], v[140:143], v[184:187], v[124:127]
	v_mfma_f32_16x16x32_bf16 v[124:127], v[150:153], v[188:191], v[124:127]
	v_mfma_f32_16x16x32_bf16 v[120:123], v[154:157], v[184:187], v[120:123]
	v_mfma_f32_16x16x32_bf16 v[120:123], v[158:161], v[188:191], v[120:123]
	v_mfma_f32_16x16x32_bf16 v[108:111], v[140:143], v[192:195], v[108:111]
	v_mfma_f32_16x16x32_bf16 v[108:111], v[150:153], v[196:199], v[108:111]
	v_mfma_f32_16x16x32_bf16 v[104:107], v[154:157], v[192:195], v[104:107]
	v_mfma_f32_16x16x32_bf16 v[104:107], v[158:161], v[196:199], v[104:107]
	v_mfma_f32_16x16x32_bf16 v[92:95], v[140:143], v[200:203], v[92:95]
	v_mfma_f32_16x16x32_bf16 v[92:95], v[150:153], v[204:207], v[92:95]
	v_mfma_f32_16x16x32_bf16 v[88:91], v[154:157], v[200:203], v[88:91]
	v_mfma_f32_16x16x32_bf16 v[88:91], v[158:161], v[204:207], v[88:91]
	v_mfma_f32_16x16x32_bf16 v[76:79], v[140:143], v[208:211], v[76:79]
	v_mfma_f32_16x16x32_bf16 v[76:79], v[150:153], v[212:215], v[76:79]
	v_mfma_f32_16x16x32_bf16 v[72:75], v[154:157], v[208:211], v[72:75]
	v_mfma_f32_16x16x32_bf16 v[72:75], v[158:161], v[212:215], v[72:75]
	v_mfma_f32_16x16x32_bf16 v[116:119], v[162:165], v[184:187], v[116:119]
	v_mfma_f32_16x16x32_bf16 v[116:119], v[166:169], v[188:191], v[116:119]
	v_mfma_f32_16x16x32_bf16 v[112:115], v[170:173], v[184:187], v[112:115]
	v_mfma_f32_16x16x32_bf16 v[112:115], v[174:177], v[188:191], v[112:115]
	v_mfma_f32_16x16x32_bf16 v[100:103], v[162:165], v[192:195], v[100:103]
	v_mfma_f32_16x16x32_bf16 v[100:103], v[166:169], v[196:199], v[100:103]
	v_mfma_f32_16x16x32_bf16 v[96:99], v[170:173], v[192:195], v[96:99]
	v_mfma_f32_16x16x32_bf16 v[96:99], v[174:177], v[196:199], v[96:99]
	v_mfma_f32_16x16x32_bf16 v[84:87], v[162:165], v[200:203], v[84:87]
	v_mfma_f32_16x16x32_bf16 v[84:87], v[166:169], v[204:207], v[84:87]
	v_mfma_f32_16x16x32_bf16 v[80:83], v[170:173], v[200:203], v[80:83]
	v_mfma_f32_16x16x32_bf16 v[80:83], v[174:177], v[204:207], v[80:83]
	v_mfma_f32_16x16x32_bf16 v[68:71], v[162:165], v[208:211], v[68:71]
	v_mfma_f32_16x16x32_bf16 v[68:71], v[166:169], v[212:215], v[68:71]
	v_mfma_f32_16x16x32_bf16 v[64:67], v[170:173], v[208:211], v[64:67]
	v_mfma_f32_16x16x32_bf16 v[64:67], v[174:177], v[212:215], v[64:67]
	s_setprio 0
	s_barrier
	s_add_i32 s18, s62, s54
	v_lshl_add_u64 v[178:179], s[46:47], 0, v[130:131]
	s_mov_b32 m0, s18
	ds_read_b128 v[184:187], v149 offset:16384
	ds_read_b128 v[188:191], v149 offset:17408
	ds_read_b128 v[192:195], v149 offset:18432
	ds_read_b128 v[196:199], v149 offset:19456
	ds_read_b128 v[200:203], v149 offset:20480
	ds_read_b128 v[204:207], v149 offset:21504
	ds_read_b128 v[208:211], v149 offset:22528
	ds_read_b128 v[212:215], v149 offset:23552
	global_load_lds_dwordx4 v[178:179], off
	s_add_i32 m0, s18, 0x2000
	s_add_u32 s72, s46, 0x40000
	v_lshl_add_u64 v[216:217], s[46:47], 0, v[128:129]
	s_addc_u32 s73, s47, 0
	s_add_i32 s18, s63, s54
	global_load_lds_dwordx4 v[216:217], off
	v_lshl_add_u64 v[218:219], s[72:73], 0, v[130:131]
	s_mov_b32 m0, s18
	v_lshl_add_u64 v[220:221], s[48:49], 0, v[128:129]
	global_load_lds_dwordx4 v[218:219], off
	v_lshl_add_u64 v[218:219], s[72:73], 0, v[128:129]
	s_add_i32 m0, s18, 0x2000
	s_nop 0
	global_load_lds_dwordx4 v[218:219], off
	v_lshl_add_u64 v[218:219], s[48:49], 0, v[130:131]
	s_mov_b32 m0, s37
	s_nop 0
	global_load_lds_dwordx4 v[218:219], off
	s_mov_b32 m0, s56
	s_nop 0
	global_load_lds_dwordx4 v[220:221], off
	s_waitcnt vmcnt(8)
	s_waitcnt lgkmcnt(0)
	s_barrier
	s_setprio 1
	s_waitcnt lgkmcnt(0)
	v_mfma_f32_16x16x32_bf16 v[60:63], v[140:143], v[184:187], v[60:63]
	v_mfma_f32_16x16x32_bf16 v[60:63], v[150:153], v[188:191], v[60:63]
	v_mfma_f32_16x16x32_bf16 v[56:59], v[154:157], v[184:187], v[56:59]
	v_mfma_f32_16x16x32_bf16 v[56:59], v[158:161], v[188:191], v[56:59]
	v_mfma_f32_16x16x32_bf16 v[44:47], v[140:143], v[192:195], v[44:47]
	v_mfma_f32_16x16x32_bf16 v[44:47], v[150:153], v[196:199], v[44:47]
	v_mfma_f32_16x16x32_bf16 v[40:43], v[154:157], v[192:195], v[40:43]
	v_mfma_f32_16x16x32_bf16 v[40:43], v[158:161], v[196:199], v[40:43]
	v_mfma_f32_16x16x32_bf16 v[28:31], v[140:143], v[200:203], v[28:31]
	v_mfma_f32_16x16x32_bf16 v[28:31], v[150:153], v[204:207], v[28:31]
	v_mfma_f32_16x16x32_bf16 v[24:27], v[154:157], v[200:203], v[24:27]
	v_mfma_f32_16x16x32_bf16 v[24:27], v[158:161], v[204:207], v[24:27]
	v_mfma_f32_16x16x32_bf16 v[12:15], v[140:143], v[208:211], v[12:15]
	v_mfma_f32_16x16x32_bf16 v[12:15], v[150:153], v[212:215], v[12:15]
	v_mfma_f32_16x16x32_bf16 v[8:11], v[154:157], v[208:211], v[8:11]
	v_mfma_f32_16x16x32_bf16 v[8:11], v[158:161], v[212:215], v[8:11]
	v_mfma_f32_16x16x32_bf16 v[52:55], v[162:165], v[184:187], v[52:55]
	v_mfma_f32_16x16x32_bf16 v[52:55], v[166:169], v[188:191], v[52:55]
	v_mfma_f32_16x16x32_bf16 v[48:51], v[170:173], v[184:187], v[48:51]
	v_mfma_f32_16x16x32_bf16 v[48:51], v[174:177], v[188:191], v[48:51]
	v_mfma_f32_16x16x32_bf16 v[36:39], v[162:165], v[192:195], v[36:39]
	v_mfma_f32_16x16x32_bf16 v[36:39], v[166:169], v[196:199], v[36:39]
	v_mfma_f32_16x16x32_bf16 v[32:35], v[170:173], v[192:195], v[32:35]
	v_mfma_f32_16x16x32_bf16 v[32:35], v[174:177], v[196:199], v[32:35]
	v_mfma_f32_16x16x32_bf16 v[20:23], v[162:165], v[200:203], v[20:23]
	v_mfma_f32_16x16x32_bf16 v[20:23], v[166:169], v[204:207], v[20:23]
	v_mfma_f32_16x16x32_bf16 v[16:19], v[170:173], v[200:203], v[16:19]
	v_mfma_f32_16x16x32_bf16 v[16:19], v[174:177], v[204:207], v[16:19]
	v_mfma_f32_16x16x32_bf16 v[4:7], v[162:165], v[208:211], v[4:7]
	v_mfma_f32_16x16x32_bf16 v[4:7], v[166:169], v[212:215], v[4:7]
	v_mfma_f32_16x16x32_bf16 v[0:3], v[170:173], v[208:211], v[0:3]
	v_mfma_f32_16x16x32_bf16 v[0:3], v[174:177], v[212:215], v[0:3]
	s_setprio 0
	s_barrier
.Lmid_gemm0:
	s_add_i32 s18, 0, 0x18000
	s_add_i32 s19, 0, 0x1c000
	v_add_u32_e32 v158, s18, v145
	v_add_u32_e32 v174, s19, v145
	ds_read_b128 v[140:143], v158
	ds_read_b128 v[150:153], v158 offset:1024
	ds_read_b128 v[154:157], v158 offset:2048
	ds_read_b128 v[158:161], v158 offset:3072
	ds_read_b128 v[162:165], v174
	ds_read_b128 v[166:169], v174 offset:1024
	ds_read_b128 v[170:173], v174 offset:2048
	ds_read_b128 v[174:177], v174 offset:3072
	s_add_u32 s48, s48, 0x40000
	s_addc_u32 s49, s49, 0
	s_mov_b32 m0, s57
	v_lshl_add_u64 v[222:223], s[48:49], 0, v[130:131]
	ds_read_b128 v[184:187], v149 offset:32768
	ds_read_b128 v[188:191], v149 offset:33792
	ds_read_b128 v[192:195], v149 offset:34816
	ds_read_b128 v[196:199], v149 offset:35840
	ds_read_b128 v[200:203], v149 offset:36864
	ds_read_b128 v[204:207], v149 offset:37888
	ds_read_b128 v[208:211], v149 offset:38912
	ds_read_b128 v[212:215], v149 offset:39936
	global_load_lds_dwordx4 v[222:223], off
	v_lshl_add_u64 v[222:223], s[48:49], 0, v[128:129]
	s_mov_b32 m0, s58
	s_nop 0
	global_load_lds_dwordx4 v[222:223], off
	s_waitcnt vmcnt(8)
	s_waitcnt lgkmcnt(0)
	s_barrier
	s_setprio 1
	s_waitcnt lgkmcnt(0)
	v_mfma_f32_16x16x32_bf16 v[124:127], v[140:143], v[184:187], v[124:127]
	v_mfma_f32_16x16x32_bf16 v[124:127], v[150:153], v[188:191], v[124:127]
	v_mfma_f32_16x16x32_bf16 v[120:123], v[154:157], v[184:187], v[120:123]
	v_mfma_f32_16x16x32_bf16 v[120:123], v[158:161], v[188:191], v[120:123]
	v_mfma_f32_16x16x32_bf16 v[108:111], v[140:143], v[192:195], v[108:111]
	v_mfma_f32_16x16x32_bf16 v[108:111], v[150:153], v[196:199], v[108:111]
	v_mfma_f32_16x16x32_bf16 v[104:107], v[154:157], v[192:195], v[104:107]
	v_mfma_f32_16x16x32_bf16 v[104:107], v[158:161], v[196:199], v[104:107]
	v_mfma_f32_16x16x32_bf16 v[92:95], v[140:143], v[200:203], v[92:95]
	v_mfma_f32_16x16x32_bf16 v[92:95], v[150:153], v[204:207], v[92:95]
	v_mfma_f32_16x16x32_bf16 v[88:91], v[154:157], v[200:203], v[88:91]
	v_mfma_f32_16x16x32_bf16 v[88:91], v[158:161], v[204:207], v[88:91]
	v_mfma_f32_16x16x32_bf16 v[76:79], v[140:143], v[208:211], v[76:79]
	v_mfma_f32_16x16x32_bf16 v[76:79], v[150:153], v[212:215], v[76:79]
	v_mfma_f32_16x16x32_bf16 v[72:75], v[154:157], v[208:211], v[72:75]
	v_mfma_f32_16x16x32_bf16 v[72:75], v[158:161], v[212:215], v[72:75]
	v_mfma_f32_16x16x32_bf16 v[116:119], v[162:165], v[184:187], v[116:119]
	v_mfma_f32_16x16x32_bf16 v[116:119], v[166:169], v[188:191], v[116:119]
	v_mfma_f32_16x16x32_bf16 v[112:115], v[170:173], v[184:187], v[112:115]
	v_mfma_f32_16x16x32_bf16 v[112:115], v[174:177], v[188:191], v[112:115]
	v_mfma_f32_16x16x32_bf16 v[100:103], v[162:165], v[192:195], v[100:103]
	v_mfma_f32_16x16x32_bf16 v[100:103], v[166:169], v[196:199], v[100:103]
	v_mfma_f32_16x16x32_bf16 v[96:99], v[170:173], v[192:195], v[96:99]
	v_mfma_f32_16x16x32_bf16 v[96:99], v[174:177], v[196:199], v[96:99]
	v_mfma_f32_16x16x32_bf16 v[84:87], v[162:165], v[200:203], v[84:87]
	v_mfma_f32_16x16x32_bf16 v[84:87], v[166:169], v[204:207], v[84:87]
	v_mfma_f32_16x16x32_bf16 v[80:83], v[170:173], v[200:203], v[80:83]
	v_mfma_f32_16x16x32_bf16 v[80:83], v[174:177], v[204:207], v[80:83]
	v_mfma_f32_16x16x32_bf16 v[68:71], v[162:165], v[208:211], v[68:71]
	v_mfma_f32_16x16x32_bf16 v[68:71], v[166:169], v[212:215], v[68:71]
	v_mfma_f32_16x16x32_bf16 v[64:67], v[170:173], v[208:211], v[64:67]
	v_mfma_f32_16x16x32_bf16 v[64:67], v[174:177], v[212:215], v[64:67]
	s_setprio 0
	s_barrier
	s_add_i32 s18, s18, s54
	v_lshl_add_u64 v[178:179], v[178:179], 0, s[6:7]
	s_mov_b32 m0, s18
	ds_read_b128 v[184:187], v149 offset:49152
	ds_read_b128 v[188:191], v149 offset:50176
	ds_read_b128 v[192:195], v149 offset:51200
	ds_read_b128 v[196:199], v149 offset:52224
	ds_read_b128 v[200:203], v149 offset:53248
	ds_read_b128 v[204:207], v149 offset:54272
	ds_read_b128 v[208:211], v149 offset:55296
	ds_read_b128 v[212:215], v149 offset:56320
	global_load_lds_dwordx4 v[178:179], off
	s_add_i32 m0, s18, 0x2000
	s_add_u32 s46, s46, 0x40080
	v_lshl_add_u64 v[178:179], v[216:217], 0, s[6:7]
	s_addc_u32 s47, s47, 0
	s_add_i32 s18, s19, s54
	global_load_lds_dwordx4 v[178:179], off
	v_lshl_add_u64 v[178:179], s[46:47], 0, v[130:131]
	s_mov_b32 m0, s18
	s_nop 0
	global_load_lds_dwordx4 v[178:179], off
	v_lshl_add_u64 v[178:179], s[46:47], 0, v[128:129]
	s_add_i32 m0, s18, 0x2000
	s_nop 0
	global_load_lds_dwordx4 v[178:179], off
	v_lshl_add_u64 v[178:179], v[218:219], 0, s[6:7]
	s_mov_b32 m0, s60
	s_nop 0
	global_load_lds_dwordx4 v[178:179], off
	v_lshl_add_u64 v[178:179], v[220:221], 0, s[6:7]
	s_mov_b32 m0, s61
	s_nop 0
	global_load_lds_dwordx4 v[178:179], off
	s_waitcnt vmcnt(8)
	s_waitcnt lgkmcnt(0)
	s_barrier
	s_setprio 1
	s_waitcnt lgkmcnt(0)
	v_mfma_f32_16x16x32_bf16 v[60:63], v[140:143], v[184:187], v[60:63]
	v_mfma_f32_16x16x32_bf16 v[60:63], v[150:153], v[188:191], v[60:63]
	v_mfma_f32_16x16x32_bf16 v[56:59], v[154:157], v[184:187], v[56:59]
	v_mfma_f32_16x16x32_bf16 v[56:59], v[158:161], v[188:191], v[56:59]
	v_mfma_f32_16x16x32_bf16 v[44:47], v[140:143], v[192:195], v[44:47]
	v_mfma_f32_16x16x32_bf16 v[44:47], v[150:153], v[196:199], v[44:47]
	v_mfma_f32_16x16x32_bf16 v[40:43], v[154:157], v[192:195], v[40:43]
	v_mfma_f32_16x16x32_bf16 v[40:43], v[158:161], v[196:199], v[40:43]
	v_mfma_f32_16x16x32_bf16 v[28:31], v[140:143], v[200:203], v[28:31]
	v_mfma_f32_16x16x32_bf16 v[28:31], v[150:153], v[204:207], v[28:31]
	v_mfma_f32_16x16x32_bf16 v[24:27], v[154:157], v[200:203], v[24:27]
	v_mfma_f32_16x16x32_bf16 v[24:27], v[158:161], v[204:207], v[24:27]
	v_mfma_f32_16x16x32_bf16 v[12:15], v[140:143], v[208:211], v[12:15]
	v_mfma_f32_16x16x32_bf16 v[12:15], v[150:153], v[212:215], v[12:15]
	v_mfma_f32_16x16x32_bf16 v[8:11], v[154:157], v[208:211], v[8:11]
	v_mfma_f32_16x16x32_bf16 v[8:11], v[158:161], v[212:215], v[8:11]
	v_mfma_f32_16x16x32_bf16 v[52:55], v[162:165], v[184:187], v[52:55]
	v_mfma_f32_16x16x32_bf16 v[52:55], v[166:169], v[188:191], v[52:55]
	v_mfma_f32_16x16x32_bf16 v[48:51], v[170:173], v[184:187], v[48:51]
	v_mfma_f32_16x16x32_bf16 v[48:51], v[174:177], v[188:191], v[48:51]
	v_mfma_f32_16x16x32_bf16 v[36:39], v[162:165], v[192:195], v[36:39]
	v_mfma_f32_16x16x32_bf16 v[36:39], v[166:169], v[196:199], v[36:39]
	v_mfma_f32_16x16x32_bf16 v[32:35], v[170:173], v[192:195], v[32:35]
	v_mfma_f32_16x16x32_bf16 v[32:35], v[174:177], v[196:199], v[32:35]
	v_mfma_f32_16x16x32_bf16 v[20:23], v[162:165], v[200:203], v[20:23]
	v_mfma_f32_16x16x32_bf16 v[20:23], v[166:169], v[204:207], v[20:23]
	v_mfma_f32_16x16x32_bf16 v[16:19], v[170:173], v[200:203], v[16:19]
	v_mfma_f32_16x16x32_bf16 v[16:19], v[174:177], v[204:207], v[16:19]
	v_mfma_f32_16x16x32_bf16 v[4:7], v[162:165], v[208:211], v[4:7]
	v_mfma_f32_16x16x32_bf16 v[4:7], v[166:169], v[212:215], v[4:7]
	v_mfma_f32_16x16x32_bf16 v[0:3], v[170:173], v[208:211], v[0:3]
	v_mfma_f32_16x16x32_bf16 v[0:3], v[174:177], v[212:215], v[0:3]
	s_setprio 0
	s_barrier
	s_add_i32 s70, s70, 2
	s_add_u32 s44, s44, 0x100
	s_addc_u32 s45, s45, 0
	s_add_u32 s68, s68, 0x100
	s_addc_u32 s69, s69, 0
	s_cmp_gt_u32 s70, 13
	s_cbranch_scc0 .LBB0_184
	s_and_b64 vcc, exec, s[8:9]
	s_cbranch_vccz .LBB0_187
	s_barrier

.LBB0_263:
	s_add_u32 s84, s54, 0x100
	s_addc_u32 s85, s55, 0
	s_mov_b32 s86, -2
	ds_read_b128 v[152:155], v149
	ds_read_b128 v[156:159], v149 offset:1024
	ds_read_b128 v[160:163], v149 offset:2048
	ds_read_b128 v[164:167], v149 offset:3072
	ds_read_b128 v[168:171], v150
	ds_read_b128 v[172:175], v150 offset:1024
	ds_read_b128 v[176:179], v150 offset:2048
	ds_read_b128 v[184:187], v150 offset:3072
	s_add_u32 s54, s52, 0x100
	s_addc_u32 s55, s53, 0
	s_cmp_eq_u32 s86, 40
	s_cselect_b32 s59, s7, s55
	s_cselect_b32 s58, s6, s54
	s_cselect_b32 s57, s49, s85
	s_cselect_b32 s56, s48, s84
	v_lshl_add_u64 v[144:145], s[52:53], 0, v[136:137]
	s_add_i32 m0, s63, 0xc000
	ds_read_b128 v[188:191], v151
	ds_read_b128 v[192:195], v151 offset:1024
	ds_read_b128 v[196:199], v151 offset:2048
	ds_read_b128 v[200:203], v151 offset:3072
	ds_read_b128 v[204:207], v151 offset:4096
	ds_read_b128 v[208:211], v151 offset:5120
	ds_read_b128 v[212:215], v151 offset:6144
	ds_read_b128 v[216:219], v151 offset:7168
	global_load_lds_dwordx4 v[144:145], off
	v_lshl_add_u64 v[144:145], s[52:53], 0, v[138:139]
	s_add_i32 m0, s63, 0xe000
	s_nop 0
	global_load_lds_dwordx4 v[144:145], off
	s_waitcnt vmcnt(8)
	s_waitcnt lgkmcnt(0)
	s_barrier
	s_setprio 1
	s_waitcnt lgkmcnt(0)
	v_mfma_f32_16x16x32_bf16 v[124:127], v[152:155], v[188:191], 0
	v_mfma_f32_16x16x32_bf16 v[124:127], v[156:159], v[192:195], v[124:127]
	v_mfma_f32_16x16x32_bf16 v[120:123], v[160:163], v[188:191], 0
	v_mfma_f32_16x16x32_bf16 v[120:123], v[164:167], v[192:195], v[120:123]
	v_mfma_f32_16x16x32_bf16 v[116:119], v[152:155], v[196:199], 0
	v_mfma_f32_16x16x32_bf16 v[116:119], v[156:159], v[200:203], v[116:119]
	v_mfma_f32_16x16x32_bf16 v[108:111], v[160:163], v[196:199], 0
	v_mfma_f32_16x16x32_bf16 v[108:111], v[164:167], v[200:203], v[108:111]
	v_mfma_f32_16x16x32_bf16 v[100:103], v[152:155], v[204:207], 0
	v_mfma_f32_16x16x32_bf16 v[100:103], v[156:159], v[208:211], v[100:103]
	v_mfma_f32_16x16x32_bf16 v[92:95], v[160:163], v[204:207], 0
	v_mfma_f32_16x16x32_bf16 v[92:95], v[164:167], v[208:211], v[92:95]
	v_mfma_f32_16x16x32_bf16 v[84:87], v[152:155], v[212:215], 0
	v_mfma_f32_16x16x32_bf16 v[84:87], v[156:159], v[216:219], v[84:87]
	v_mfma_f32_16x16x32_bf16 v[76:79], v[160:163], v[212:215], 0
	v_mfma_f32_16x16x32_bf16 v[76:79], v[164:167], v[216:219], v[76:79]
	v_mfma_f32_16x16x32_bf16 v[112:115], v[168:171], v[188:191], 0
	v_mfma_f32_16x16x32_bf16 v[112:115], v[172:175], v[192:195], v[112:115]
	v_mfma_f32_16x16x32_bf16 v[104:107], v[176:179], v[188:191], 0
	v_mfma_f32_16x16x32_bf16 v[104:107], v[184:187], v[192:195], v[104:107]
	v_mfma_f32_16x16x32_bf16 v[96:99], v[168:171], v[196:199], 0
	v_mfma_f32_16x16x32_bf16 v[96:99], v[172:175], v[200:203], v[96:99]
	v_mfma_f32_16x16x32_bf16 v[88:91], v[176:179], v[196:199], 0
	v_mfma_f32_16x16x32_bf16 v[88:91], v[184:187], v[200:203], v[88:91]
	v_mfma_f32_16x16x32_bf16 v[80:83], v[168:171], v[204:207], 0
	v_mfma_f32_16x16x32_bf16 v[80:83], v[172:175], v[208:211], v[80:83]
	v_mfma_f32_16x16x32_bf16 v[72:75], v[176:179], v[204:207], 0
	v_mfma_f32_16x16x32_bf16 v[72:75], v[184:187], v[208:211], v[72:75]
	v_mfma_f32_16x16x32_bf16 v[68:71], v[168:171], v[212:215], 0
	v_mfma_f32_16x16x32_bf16 v[68:71], v[172:175], v[216:219], v[68:71]
	v_mfma_f32_16x16x32_bf16 v[64:67], v[176:179], v[212:215], 0
	v_mfma_f32_16x16x32_bf16 v[64:67], v[184:187], v[216:219], v[64:67]
	s_setprio 0
	s_barrier
	s_add_i32 s18, s70, s62
	v_lshl_add_u64 v[144:145], s[56:57], 0, v[130:131]
	s_mov_b32 m0, s18
	ds_read_b128 v[188:191], v151 offset:16384
	ds_read_b128 v[192:195], v151 offset:17408
	ds_read_b128 v[196:199], v151 offset:18432
	ds_read_b128 v[200:203], v151 offset:19456
	ds_read_b128 v[204:207], v151 offset:20480
	ds_read_b128 v[208:211], v151 offset:21504
	ds_read_b128 v[212:215], v151 offset:22528
	ds_read_b128 v[216:219], v151 offset:23552
	global_load_lds_dwordx4 v[144:145], off
	s_add_i32 m0, s18, 0x2000
	s_add_u32 s52, s56, 0xb0000
	v_lshl_add_u64 v[220:221], s[56:57], 0, v[134:135]
	s_addc_u32 s53, s57, 0
	s_add_i32 s18, s71, s62
	global_load_lds_dwordx4 v[220:221], off
	v_lshl_add_u64 v[222:223], s[52:53], 0, v[130:131]
	s_mov_b32 m0, s18
	v_lshl_add_u64 v[224:225], s[58:59], 0, v[132:133]
	global_load_lds_dwordx4 v[222:223], off
	v_lshl_add_u64 v[222:223], s[52:53], 0, v[134:135]
	s_add_i32 m0, s18, 0x2000
	s_nop 0
	global_load_lds_dwordx4 v[222:223], off
	v_lshl_add_u64 v[222:223], s[58:59], 0, v[128:129]
	s_mov_b32 m0, s63
	s_nop 0
	global_load_lds_dwordx4 v[222:223], off
	s_mov_b32 m0, s64
	s_nop 0
	global_load_lds_dwordx4 v[224:225], off
	s_waitcnt vmcnt(8)
	s_waitcnt lgkmcnt(0)
	s_barrier
	s_setprio 1
	s_waitcnt lgkmcnt(0)
	v_mfma_f32_16x16x32_bf16 v[60:63], v[152:155], v[188:191], 0
	v_mfma_f32_16x16x32_bf16 v[60:63], v[156:159], v[192:195], v[60:63]
	v_mfma_f32_16x16x32_bf16 v[56:59], v[160:163], v[188:191], 0
	v_mfma_f32_16x16x32_bf16 v[56:59], v[164:167], v[192:195], v[56:59]
	v_mfma_f32_16x16x32_bf16 v[52:55], v[152:155], v[196:199], 0
	v_mfma_f32_16x16x32_bf16 v[52:55], v[156:159], v[200:203], v[52:55]
	v_mfma_f32_16x16x32_bf16 v[44:47], v[160:163], v[196:199], 0
	v_mfma_f32_16x16x32_bf16 v[44:47], v[164:167], v[200:203], v[44:47]
	v_mfma_f32_16x16x32_bf16 v[36:39], v[152:155], v[204:207], 0
	v_mfma_f32_16x16x32_bf16 v[36:39], v[156:159], v[208:211], v[36:39]
	v_mfma_f32_16x16x32_bf16 v[28:31], v[160:163], v[204:207], 0
	v_mfma_f32_16x16x32_bf16 v[28:31], v[164:167], v[208:211], v[28:31]
	v_mfma_f32_16x16x32_bf16 v[20:23], v[152:155], v[212:215], 0
	v_mfma_f32_16x16x32_bf16 v[20:23], v[156:159], v[216:219], v[20:23]
	v_mfma_f32_16x16x32_bf16 v[12:15], v[160:163], v[212:215], 0
	v_mfma_f32_16x16x32_bf16 v[12:15], v[164:167], v[216:219], v[12:15]
	v_mfma_f32_16x16x32_bf16 v[48:51], v[168:171], v[188:191], 0
	v_mfma_f32_16x16x32_bf16 v[48:51], v[172:175], v[192:195], v[48:51]
	v_mfma_f32_16x16x32_bf16 v[40:43], v[176:179], v[188:191], 0
	v_mfma_f32_16x16x32_bf16 v[40:43], v[184:187], v[192:195], v[40:43]
	v_mfma_f32_16x16x32_bf16 v[32:35], v[168:171], v[196:199], 0
	v_mfma_f32_16x16x32_bf16 v[32:35], v[172:175], v[200:203], v[32:35]
	v_mfma_f32_16x16x32_bf16 v[24:27], v[176:179], v[196:199], 0
	v_mfma_f32_16x16x32_bf16 v[24:27], v[184:187], v[200:203], v[24:27]
	v_mfma_f32_16x16x32_bf16 v[16:19], v[168:171], v[204:207], 0
	v_mfma_f32_16x16x32_bf16 v[16:19], v[172:175], v[208:211], v[16:19]
	v_mfma_f32_16x16x32_bf16 v[8:11], v[176:179], v[204:207], 0
	v_mfma_f32_16x16x32_bf16 v[8:11], v[184:187], v[208:211], v[8:11]
	v_mfma_f32_16x16x32_bf16 v[4:7], v[168:171], v[212:215], 0
	v_mfma_f32_16x16x32_bf16 v[4:7], v[172:175], v[216:219], v[4:7]
	v_mfma_f32_16x16x32_bf16 v[0:3], v[176:179], v[212:215], 0
	v_mfma_f32_16x16x32_bf16 v[0:3], v[184:187], v[216:219], v[0:3]
	s_setprio 0
	s_barrier
	s_branch .Lmid_gemm1
.LBB0_264:
	ds_read_b128 v[152:155], v149
	ds_read_b128 v[156:159], v149 offset:1024
	ds_read_b128 v[160:163], v149 offset:2048
	ds_read_b128 v[164:167], v149 offset:3072
	ds_read_b128 v[168:171], v150
	ds_read_b128 v[172:175], v150 offset:1024
	ds_read_b128 v[176:179], v150 offset:2048
	ds_read_b128 v[184:187], v150 offset:3072
	s_add_u32 s54, s52, 0x100
	s_addc_u32 s55, s53, 0
	s_cmp_eq_u32 s86, 40
	s_cselect_b32 s59, s7, s55
	s_cselect_b32 s58, s6, s54
	s_cselect_b32 s57, s49, s85
	s_cselect_b32 s56, s48, s84
	v_lshl_add_u64 v[144:145], s[52:53], 0, v[136:137]
	s_add_i32 m0, s63, 0xc000
	ds_read_b128 v[188:191], v151
	ds_read_b128 v[192:195], v151 offset:1024
	ds_read_b128 v[196:199], v151 offset:2048
	ds_read_b128 v[200:203], v151 offset:3072
	ds_read_b128 v[204:207], v151 offset:4096
	ds_read_b128 v[208:211], v151 offset:5120
	ds_read_b128 v[212:215], v151 offset:6144
	ds_read_b128 v[216:219], v151 offset:7168
	global_load_lds_dwordx4 v[144:145], off
	v_lshl_add_u64 v[144:145], s[52:53], 0, v[138:139]
	s_add_i32 m0, s63, 0xe000
	s_nop 0
	global_load_lds_dwordx4 v[144:145], off
	s_waitcnt vmcnt(8)
	s_waitcnt lgkmcnt(0)
	s_barrier
	s_setprio 1
	s_waitcnt lgkmcnt(0)
	v_mfma_f32_16x16x32_bf16 v[124:127], v[152:155], v[188:191], v[124:127]
	v_mfma_f32_16x16x32_bf16 v[124:127], v[156:159], v[192:195], v[124:127]
	v_mfma_f32_16x16x32_bf16 v[120:123], v[160:163], v[188:191], v[120:123]
	v_mfma_f32_16x16x32_bf16 v[120:123], v[164:167], v[192:195], v[120:123]
	v_mfma_f32_16x16x32_bf16 v[116:119], v[152:155], v[196:199], v[116:119]
	v_mfma_f32_16x16x32_bf16 v[116:119], v[156:159], v[200:203], v[116:119]
	v_mfma_f32_16x16x32_bf16 v[108:111], v[160:163], v[196:199], v[108:111]
	v_mfma_f32_16x16x32_bf16 v[108:111], v[164:167], v[200:203], v[108:111]
	v_mfma_f32_16x16x32_bf16 v[100:103], v[152:155], v[204:207], v[100:103]
	v_mfma_f32_16x16x32_bf16 v[100:103], v[156:159], v[208:211], v[100:103]
	v_mfma_f32_16x16x32_bf16 v[92:95], v[160:163], v[204:207], v[92:95]
	v_mfma_f32_16x16x32_bf16 v[92:95], v[164:167], v[208:211], v[92:95]
	v_mfma_f32_16x16x32_bf16 v[84:87], v[152:155], v[212:215], v[84:87]
	v_mfma_f32_16x16x32_bf16 v[84:87], v[156:159], v[216:219], v[84:87]
	v_mfma_f32_16x16x32_bf16 v[76:79], v[160:163], v[212:215], v[76:79]
	v_mfma_f32_16x16x32_bf16 v[76:79], v[164:167], v[216:219], v[76:79]
	v_mfma_f32_16x16x32_bf16 v[112:115], v[168:171], v[188:191], v[112:115]
	v_mfma_f32_16x16x32_bf16 v[112:115], v[172:175], v[192:195], v[112:115]
	v_mfma_f32_16x16x32_bf16 v[104:107], v[176:179], v[188:191], v[104:107]
	v_mfma_f32_16x16x32_bf16 v[104:107], v[184:187], v[192:195], v[104:107]
	v_mfma_f32_16x16x32_bf16 v[96:99], v[168:171], v[196:199], v[96:99]
	v_mfma_f32_16x16x32_bf16 v[96:99], v[172:175], v[200:203], v[96:99]
	v_mfma_f32_16x16x32_bf16 v[88:91], v[176:179], v[196:199], v[88:91]
	v_mfma_f32_16x16x32_bf16 v[88:91], v[184:187], v[200:203], v[88:91]
	v_mfma_f32_16x16x32_bf16 v[80:83], v[168:171], v[204:207], v[80:83]
	v_mfma_f32_16x16x32_bf16 v[80:83], v[172:175], v[208:211], v[80:83]
	v_mfma_f32_16x16x32_bf16 v[72:75], v[176:179], v[204:207], v[72:75]
	v_mfma_f32_16x16x32_bf16 v[72:75], v[184:187], v[208:211], v[72:75]
	v_mfma_f32_16x16x32_bf16 v[68:71], v[168:171], v[212:215], v[68:71]
	v_mfma_f32_16x16x32_bf16 v[68:71], v[172:175], v[216:219], v[68:71]
	v_mfma_f32_16x16x32_bf16 v[64:67], v[176:179], v[212:215], v[64:67]
	v_mfma_f32_16x16x32_bf16 v[64:67], v[184:187], v[216:219], v[64:67]
	s_setprio 0
	s_barrier
	s_add_i32 s18, s70, s62
	v_lshl_add_u64 v[144:145], s[56:57], 0, v[130:131]
	s_mov_b32 m0, s18
	ds_read_b128 v[188:191], v151 offset:16384
	ds_read_b128 v[192:195], v151 offset:17408
	ds_read_b128 v[196:199], v151 offset:18432
	ds_read_b128 v[200:203], v151 offset:19456
	ds_read_b128 v[204:207], v151 offset:20480
	ds_read_b128 v[208:211], v151 offset:21504
	ds_read_b128 v[212:215], v151 offset:22528
	ds_read_b128 v[216:219], v151 offset:23552
	global_load_lds_dwordx4 v[144:145], off
	s_add_i32 m0, s18, 0x2000
	s_add_u32 s52, s56, 0xb0000
	v_lshl_add_u64 v[220:221], s[56:57], 0, v[134:135]
	s_addc_u32 s53, s57, 0
	s_add_i32 s18, s71, s62
	global_load_lds_dwordx4 v[220:221], off
	v_lshl_add_u64 v[222:223], s[52:53], 0, v[130:131]
	s_mov_b32 m0, s18
	v_lshl_add_u64 v[224:225], s[58:59], 0, v[132:133]
	global_load_lds_dwordx4 v[222:223], off
	v_lshl_add_u64 v[222:223], s[52:53], 0, v[134:135]
	s_add_i32 m0, s18, 0x2000
	s_nop 0
	global_load_lds_dwordx4 v[222:223], off
	v_lshl_add_u64 v[222:223], s[58:59], 0, v[128:129]
	s_mov_b32 m0, s63
	s_nop 0
	global_load_lds_dwordx4 v[222:223], off
	s_mov_b32 m0, s64
	s_nop 0
	global_load_lds_dwordx4 v[224:225], off
	s_waitcnt vmcnt(8)
	s_waitcnt lgkmcnt(0)
	s_barrier
	s_setprio 1
	s_waitcnt lgkmcnt(0)
	v_mfma_f32_16x16x32_bf16 v[60:63], v[152:155], v[188:191], v[60:63]
	v_mfma_f32_16x16x32_bf16 v[60:63], v[156:159], v[192:195], v[60:63]
	v_mfma_f32_16x16x32_bf16 v[56:59], v[160:163], v[188:191], v[56:59]
	v_mfma_f32_16x16x32_bf16 v[56:59], v[164:167], v[192:195], v[56:59]
	v_mfma_f32_16x16x32_bf16 v[52:55], v[152:155], v[196:199], v[52:55]
	v_mfma_f32_16x16x32_bf16 v[52:55], v[156:159], v[200:203], v[52:55]
	v_mfma_f32_16x16x32_bf16 v[44:47], v[160:163], v[196:199], v[44:47]
	v_mfma_f32_16x16x32_bf16 v[44:47], v[164:167], v[200:203], v[44:47]
	v_mfma_f32_16x16x32_bf16 v[36:39], v[152:155], v[204:207], v[36:39]
	v_mfma_f32_16x16x32_bf16 v[36:39], v[156:159], v[208:211], v[36:39]
	v_mfma_f32_16x16x32_bf16 v[28:31], v[160:163], v[204:207], v[28:31]
	v_mfma_f32_16x16x32_bf16 v[28:31], v[164:167], v[208:211], v[28:31]
	v_mfma_f32_16x16x32_bf16 v[20:23], v[152:155], v[212:215], v[20:23]
	v_mfma_f32_16x16x32_bf16 v[20:23], v[156:159], v[216:219], v[20:23]
	v_mfma_f32_16x16x32_bf16 v[12:15], v[160:163], v[212:215], v[12:15]
	v_mfma_f32_16x16x32_bf16 v[12:15], v[164:167], v[216:219], v[12:15]
	v_mfma_f32_16x16x32_bf16 v[48:51], v[168:171], v[188:191], v[48:51]
	v_mfma_f32_16x16x32_bf16 v[48:51], v[172:175], v[192:195], v[48:51]
	v_mfma_f32_16x16x32_bf16 v[40:43], v[176:179], v[188:191], v[40:43]
	v_mfma_f32_16x16x32_bf16 v[40:43], v[184:187], v[192:195], v[40:43]
	v_mfma_f32_16x16x32_bf16 v[32:35], v[168:171], v[196:199], v[32:35]
	v_mfma_f32_16x16x32_bf16 v[32:35], v[172:175], v[200:203], v[32:35]
	v_mfma_f32_16x16x32_bf16 v[24:27], v[176:179], v[196:199], v[24:27]
	v_mfma_f32_16x16x32_bf16 v[24:27], v[184:187], v[200:203], v[24:27]
	v_mfma_f32_16x16x32_bf16 v[16:19], v[168:171], v[204:207], v[16:19]
	v_mfma_f32_16x16x32_bf16 v[16:19], v[172:175], v[208:211], v[16:19]
	v_mfma_f32_16x16x32_bf16 v[8:11], v[176:179], v[204:207], v[8:11]
	v_mfma_f32_16x16x32_bf16 v[8:11], v[184:187], v[208:211], v[8:11]
	v_mfma_f32_16x16x32_bf16 v[4:7], v[168:171], v[212:215], v[4:7]
	v_mfma_f32_16x16x32_bf16 v[4:7], v[172:175], v[216:219], v[4:7]
	v_mfma_f32_16x16x32_bf16 v[0:3], v[176:179], v[212:215], v[0:3]
	v_mfma_f32_16x16x32_bf16 v[0:3], v[184:187], v[216:219], v[0:3]
	s_setprio 0
	s_barrier
.Lmid_gemm1:
	s_add_i32 s18, 0, 0x18000
	s_add_i32 s19, 0, 0x1c000
	v_add_u32_e32 v164, s18, v147
	v_add_u32_e32 v181, s19, v147
	ds_read_b128 v[152:155], v164
	ds_read_b128 v[156:159], v164 offset:1024
	ds_read_b128 v[160:163], v164 offset:2048
	ds_read_b128 v[164:167], v164 offset:3072
	ds_read_b128 v[168:171], v181
	ds_read_b128 v[172:175], v181 offset:1024
	ds_read_b128 v[176:179], v181 offset:2048
	ds_read_b128 v[184:187], v181 offset:3072
	s_add_u32 s52, s58, 0xb0000
	s_addc_u32 s53, s59, 0
	s_mov_b32 m0, s65
	v_lshl_add_u64 v[226:227], s[52:53], 0, v[128:129]
	ds_read_b128 v[188:191], v151 offset:32768
	ds_read_b128 v[192:195], v151 offset:33792
	ds_read_b128 v[196:199], v151 offset:34816
	ds_read_b128 v[200:203], v151 offset:35840
	ds_read_b128 v[204:207], v151 offset:36864
	ds_read_b128 v[208:211], v151 offset:37888
	ds_read_b128 v[212:215], v151 offset:38912
	ds_read_b128 v[216:219], v151 offset:39936
	global_load_lds_dwordx4 v[226:227], off
	v_lshl_add_u64 v[226:227], s[52:53], 0, v[132:133]
	s_mov_b32 m0, s66
	s_nop 0
	global_load_lds_dwordx4 v[226:227], off
	s_waitcnt vmcnt(8)
	s_waitcnt lgkmcnt(0)
	s_barrier
	s_setprio 1
	s_waitcnt lgkmcnt(0)
	v_mfma_f32_16x16x32_bf16 v[124:127], v[152:155], v[188:191], v[124:127]
	v_mfma_f32_16x16x32_bf16 v[124:127], v[156:159], v[192:195], v[124:127]
	v_mfma_f32_16x16x32_bf16 v[120:123], v[160:163], v[188:191], v[120:123]
	v_mfma_f32_16x16x32_bf16 v[120:123], v[164:167], v[192:195], v[120:123]
	v_mfma_f32_16x16x32_bf16 v[116:119], v[152:155], v[196:199], v[116:119]
	v_mfma_f32_16x16x32_bf16 v[116:119], v[156:159], v[200:203], v[116:119]
	v_mfma_f32_16x16x32_bf16 v[108:111], v[160:163], v[196:199], v[108:111]
	v_mfma_f32_16x16x32_bf16 v[108:111], v[164:167], v[200:203], v[108:111]
	v_mfma_f32_16x16x32_bf16 v[100:103], v[152:155], v[204:207], v[100:103]
	v_mfma_f32_16x16x32_bf16 v[100:103], v[156:159], v[208:211], v[100:103]
	v_mfma_f32_16x16x32_bf16 v[92:95], v[160:163], v[204:207], v[92:95]
	v_mfma_f32_16x16x32_bf16 v[92:95], v[164:167], v[208:211], v[92:95]
	v_mfma_f32_16x16x32_bf16 v[84:87], v[152:155], v[212:215], v[84:87]
	v_mfma_f32_16x16x32_bf16 v[84:87], v[156:159], v[216:219], v[84:87]
	v_mfma_f32_16x16x32_bf16 v[76:79], v[160:163], v[212:215], v[76:79]
	v_mfma_f32_16x16x32_bf16 v[76:79], v[164:167], v[216:219], v[76:79]
	v_mfma_f32_16x16x32_bf16 v[112:115], v[168:171], v[188:191], v[112:115]
	v_mfma_f32_16x16x32_bf16 v[112:115], v[172:175], v[192:195], v[112:115]
	v_mfma_f32_16x16x32_bf16 v[104:107], v[176:179], v[188:191], v[104:107]
	v_mfma_f32_16x16x32_bf16 v[104:107], v[184:187], v[192:195], v[104:107]
	v_mfma_f32_16x16x32_bf16 v[96:99], v[168:171], v[196:199], v[96:99]
	v_mfma_f32_16x16x32_bf16 v[96:99], v[172:175], v[200:203], v[96:99]
	v_mfma_f32_16x16x32_bf16 v[88:91], v[176:179], v[196:199], v[88:91]
	v_mfma_f32_16x16x32_bf16 v[88:91], v[184:187], v[200:203], v[88:91]
	v_mfma_f32_16x16x32_bf16 v[80:83], v[168:171], v[204:207], v[80:83]
	v_mfma_f32_16x16x32_bf16 v[80:83], v[172:175], v[208:211], v[80:83]
	v_mfma_f32_16x16x32_bf16 v[72:75], v[176:179], v[204:207], v[72:75]
	v_mfma_f32_16x16x32_bf16 v[72:75], v[184:187], v[208:211], v[72:75]
	v_mfma_f32_16x16x32_bf16 v[68:71], v[168:171], v[212:215], v[68:71]
	v_mfma_f32_16x16x32_bf16 v[68:71], v[172:175], v[216:219], v[68:71]
	v_mfma_f32_16x16x32_bf16 v[64:67], v[176:179], v[212:215], v[64:67]
	v_mfma_f32_16x16x32_bf16 v[64:67], v[184:187], v[216:219], v[64:67]
	s_setprio 0
	s_barrier
	s_add_i32 s18, s18, s62
	v_lshl_add_u64 v[144:145], v[144:145], 0, s[8:9]
	s_mov_b32 m0, s18
	ds_read_b128 v[188:191], v151 offset:49152
	ds_read_b128 v[192:195], v151 offset:50176
	ds_read_b128 v[196:199], v151 offset:51200
	ds_read_b128 v[200:203], v151 offset:52224
	ds_read_b128 v[204:207], v151 offset:53248
	ds_read_b128 v[208:211], v151 offset:54272
	ds_read_b128 v[212:215], v151 offset:55296
	ds_read_b128 v[216:219], v151 offset:56320
	global_load_lds_dwordx4 v[144:145], off
	s_add_i32 m0, s18, 0x2000
	s_add_u32 s52, s56, 0xb0080
	v_lshl_add_u64 v[144:145], v[220:221], 0, s[8:9]
	s_addc_u32 s53, s57, 0
	s_add_i32 s18, s19, s62
	global_load_lds_dwordx4 v[144:145], off
	v_lshl_add_u64 v[144:145], s[52:53], 0, v[130:131]
	s_mov_b32 m0, s18
	s_nop 0
	global_load_lds_dwordx4 v[144:145], off
	v_lshl_add_u64 v[144:145], s[52:53], 0, v[134:135]
	s_add_i32 m0, s18, 0x2000
	s_nop 0
	global_load_lds_dwordx4 v[144:145], off
	v_lshl_add_u64 v[144:145], v[222:223], 0, s[8:9]
	s_mov_b32 m0, s68
	s_nop 0
	global_load_lds_dwordx4 v[144:145], off
	v_lshl_add_u64 v[144:145], v[224:225], 0, s[8:9]
	s_mov_b32 m0, s69
	s_nop 0
	global_load_lds_dwordx4 v[144:145], off
	s_waitcnt vmcnt(8)
	s_waitcnt lgkmcnt(0)
	s_barrier
	s_setprio 1
	s_waitcnt lgkmcnt(0)
	v_mfma_f32_16x16x32_bf16 v[60:63], v[152:155], v[188:191], v[60:63]
	v_mfma_f32_16x16x32_bf16 v[60:63], v[156:159], v[192:195], v[60:63]
	v_mfma_f32_16x16x32_bf16 v[56:59], v[160:163], v[188:191], v[56:59]
	v_mfma_f32_16x16x32_bf16 v[56:59], v[164:167], v[192:195], v[56:59]
	v_mfma_f32_16x16x32_bf16 v[52:55], v[152:155], v[196:199], v[52:55]
	v_mfma_f32_16x16x32_bf16 v[52:55], v[156:159], v[200:203], v[52:55]
	v_mfma_f32_16x16x32_bf16 v[44:47], v[160:163], v[196:199], v[44:47]
	v_mfma_f32_16x16x32_bf16 v[44:47], v[164:167], v[200:203], v[44:47]
	v_mfma_f32_16x16x32_bf16 v[36:39], v[152:155], v[204:207], v[36:39]
	v_mfma_f32_16x16x32_bf16 v[36:39], v[156:159], v[208:211], v[36:39]
	v_mfma_f32_16x16x32_bf16 v[28:31], v[160:163], v[204:207], v[28:31]
	v_mfma_f32_16x16x32_bf16 v[28:31], v[164:167], v[208:211], v[28:31]
	v_mfma_f32_16x16x32_bf16 v[20:23], v[152:155], v[212:215], v[20:23]
	v_mfma_f32_16x16x32_bf16 v[20:23], v[156:159], v[216:219], v[20:23]
	v_mfma_f32_16x16x32_bf16 v[12:15], v[160:163], v[212:215], v[12:15]
	v_mfma_f32_16x16x32_bf16 v[12:15], v[164:167], v[216:219], v[12:15]
	v_mfma_f32_16x16x32_bf16 v[48:51], v[168:171], v[188:191], v[48:51]
	v_mfma_f32_16x16x32_bf16 v[48:51], v[172:175], v[192:195], v[48:51]
	v_mfma_f32_16x16x32_bf16 v[40:43], v[176:179], v[188:191], v[40:43]
	v_mfma_f32_16x16x32_bf16 v[40:43], v[184:187], v[192:195], v[40:43]
	v_mfma_f32_16x16x32_bf16 v[32:35], v[168:171], v[196:199], v[32:35]
	v_mfma_f32_16x16x32_bf16 v[32:35], v[172:175], v[200:203], v[32:35]
	v_mfma_f32_16x16x32_bf16 v[24:27], v[176:179], v[196:199], v[24:27]
	v_mfma_f32_16x16x32_bf16 v[24:27], v[184:187], v[200:203], v[24:27]
	v_mfma_f32_16x16x32_bf16 v[16:19], v[168:171], v[204:207], v[16:19]
	v_mfma_f32_16x16x32_bf16 v[16:19], v[172:175], v[208:211], v[16:19]
	v_mfma_f32_16x16x32_bf16 v[8:11], v[176:179], v[204:207], v[8:11]
	v_mfma_f32_16x16x32_bf16 v[8:11], v[184:187], v[208:211], v[8:11]
	v_mfma_f32_16x16x32_bf16 v[4:7], v[168:171], v[212:215], v[4:7]
	v_mfma_f32_16x16x32_bf16 v[4:7], v[172:175], v[216:219], v[4:7]
	v_mfma_f32_16x16x32_bf16 v[0:3], v[176:179], v[212:215], v[0:3]
	v_mfma_f32_16x16x32_bf16 v[0:3], v[184:187], v[216:219], v[0:3]
	s_setprio 0
	s_barrier
	s_add_i32 s86, s86, 2
	s_add_u32 s84, s84, 0x100
	s_addc_u32 s85, s85, 0
	s_cmp_gt_u32 s86, 41
	s_mov_b64 s[52:53], s[54:55]
	s_cbranch_scc0 .LBB0_264
	s_and_b64 vcc, exec, s[10:11]
	s_cbranch_vccz .LBB0_267
	s_barrier

.LBB0_386:
	s_ashr_i32 s49, s48, 31
	s_lshl_b64 s[52:53], s[48:49], 19
	s_add_u32 s52, s80, s52
	s_addc_u32 s53, s81, s53
	s_and_b64 s[54:55], s[4:5], exec
	s_cselect_b32 s49, s53, s59
	s_cselect_b32 s82, s52, s58
	s_ashr_i32 s47, s46, 31
	s_lshl_b64 s[54:55], s[46:47], 19
	s_add_u32 s54, s64, s54
	s_addc_u32 s55, s65, s55
	s_and_b64 s[62:63], s[4:5], exec
	s_cselect_b32 s47, s55, s61
	s_cselect_b32 s83, s54, s60
	s_add_u32 s58, s58, 0x40080
	s_addc_u32 s59, s59, 0
	s_add_u32 s84, s60, 0x100
	s_addc_u32 s85, s61, 0
	s_mov_b32 s86, -2
	ds_read_b128 v[152:155], v148
	ds_read_b128 v[156:159], v148 offset:1024
	ds_read_b128 v[160:163], v148 offset:2048
	ds_read_b128 v[164:167], v148 offset:3072
	ds_read_b128 v[168:171], v149
	ds_read_b128 v[172:175], v149 offset:1024
	ds_read_b128 v[176:179], v149 offset:2048
	ds_read_b128 v[184:187], v149 offset:3072
	s_add_u32 s18, s58, 0xfffc0080
	s_addc_u32 s19, s59, -1
	s_cmp_eq_u32 s86, 12
	s_cselect_b32 s63, s49, s19
	s_cselect_b32 s62, s82, s18
	s_cselect_b32 s61, s47, s85
	s_cselect_b32 s60, s83, s84
	v_lshl_add_u64 v[220:221], s[58:59], 0, v[138:139]
	s_add_i32 m0, s68, 0xc000
	ds_read_b128 v[188:191], v150
	ds_read_b128 v[192:195], v150 offset:1024
	ds_read_b128 v[196:199], v150 offset:2048
	ds_read_b128 v[200:203], v150 offset:3072
	ds_read_b128 v[204:207], v150 offset:4096
	ds_read_b128 v[208:211], v150 offset:5120
	ds_read_b128 v[212:215], v150 offset:6144
	ds_read_b128 v[216:219], v150 offset:7168
	global_load_lds_dwordx4 v[220:221], off
	v_lshl_add_u64 v[220:221], s[58:59], 0, v[140:141]
	s_add_i32 m0, s68, 0xe000
	s_nop 0
	global_load_lds_dwordx4 v[220:221], off
	s_waitcnt vmcnt(8)
	s_waitcnt lgkmcnt(0)
	s_barrier
	s_setprio 1
	s_waitcnt lgkmcnt(0)
	v_mfma_f32_16x16x32_bf16 v[124:127], v[152:155], v[188:191], 0
	v_mfma_f32_16x16x32_bf16 v[124:127], v[156:159], v[192:195], v[124:127]
	v_mfma_f32_16x16x32_bf16 v[120:123], v[160:163], v[188:191], 0
	v_mfma_f32_16x16x32_bf16 v[120:123], v[164:167], v[192:195], v[120:123]
	v_mfma_f32_16x16x32_bf16 v[116:119], v[152:155], v[196:199], 0
	v_mfma_f32_16x16x32_bf16 v[116:119], v[156:159], v[200:203], v[116:119]
	v_mfma_f32_16x16x32_bf16 v[112:115], v[160:163], v[196:199], 0
	v_mfma_f32_16x16x32_bf16 v[112:115], v[164:167], v[200:203], v[112:115]
	v_mfma_f32_16x16x32_bf16 v[108:111], v[152:155], v[204:207], 0
	v_mfma_f32_16x16x32_bf16 v[108:111], v[156:159], v[208:211], v[108:111]
	v_mfma_f32_16x16x32_bf16 v[104:107], v[160:163], v[204:207], 0
	v_mfma_f32_16x16x32_bf16 v[104:107], v[164:167], v[208:211], v[104:107]
	v_mfma_f32_16x16x32_bf16 v[100:103], v[152:155], v[212:215], 0
	v_mfma_f32_16x16x32_bf16 v[100:103], v[156:159], v[216:219], v[100:103]
	v_mfma_f32_16x16x32_bf16 v[96:99], v[160:163], v[212:215], 0
	v_mfma_f32_16x16x32_bf16 v[96:99], v[164:167], v[216:219], v[96:99]
	v_mfma_f32_16x16x32_bf16 v[68:71], v[168:171], v[188:191], 0
	v_mfma_f32_16x16x32_bf16 v[68:71], v[172:175], v[192:195], v[68:71]
	v_mfma_f32_16x16x32_bf16 v[64:67], v[176:179], v[188:191], 0
	v_mfma_f32_16x16x32_bf16 v[64:67], v[184:187], v[192:195], v[64:67]
	v_mfma_f32_16x16x32_bf16 v[52:55], v[168:171], v[196:199], 0
	v_mfma_f32_16x16x32_bf16 v[52:55], v[172:175], v[200:203], v[52:55]
	v_mfma_f32_16x16x32_bf16 v[48:51], v[176:179], v[196:199], 0
	v_mfma_f32_16x16x32_bf16 v[48:51], v[184:187], v[200:203], v[48:51]
	v_mfma_f32_16x16x32_bf16 v[44:47], v[168:171], v[204:207], 0
	v_mfma_f32_16x16x32_bf16 v[44:47], v[172:175], v[208:211], v[44:47]
	v_mfma_f32_16x16x32_bf16 v[40:43], v[176:179], v[204:207], 0
	v_mfma_f32_16x16x32_bf16 v[40:43], v[184:187], v[208:211], v[40:43]
	v_mfma_f32_16x16x32_bf16 v[36:39], v[168:171], v[212:215], 0
	v_mfma_f32_16x16x32_bf16 v[36:39], v[172:175], v[216:219], v[36:39]
	v_mfma_f32_16x16x32_bf16 v[32:35], v[176:179], v[212:215], 0
	v_mfma_f32_16x16x32_bf16 v[32:35], v[184:187], v[216:219], v[32:35]
	s_setprio 0
	s_barrier
	s_add_i32 s18, s76, s66
	v_lshl_add_u64 v[220:221], s[60:61], 0, v[132:133]
	s_mov_b32 m0, s18
	ds_read_b128 v[188:191], v150 offset:16384
	ds_read_b128 v[192:195], v150 offset:17408
	ds_read_b128 v[196:199], v150 offset:18432
	ds_read_b128 v[200:203], v150 offset:19456
	ds_read_b128 v[204:207], v150 offset:20480
	ds_read_b128 v[208:211], v150 offset:21504
	ds_read_b128 v[212:215], v150 offset:22528
	ds_read_b128 v[216:219], v150 offset:23552
	global_load_lds_dwordx4 v[220:221], off
	s_add_i32 m0, s18, 0x2000
	s_add_u32 s88, s60, 0x40000
	v_lshl_add_u64 v[222:223], s[60:61], 0, v[128:129]
	s_addc_u32 s89, s61, 0
	s_add_i32 s18, s77, s66
	global_load_lds_dwordx4 v[222:223], off
	v_lshl_add_u64 v[224:225], s[88:89], 0, v[132:133]
	s_mov_b32 m0, s18
	v_lshl_add_u64 v[226:227], s[62:63], 0, v[130:131]
	global_load_lds_dwordx4 v[224:225], off
	v_lshl_add_u64 v[224:225], s[88:89], 0, v[128:129]
	s_add_i32 m0, s18, 0x2000
	s_nop 0
	global_load_lds_dwordx4 v[224:225], off
	v_lshl_add_u64 v[224:225], s[62:63], 0, v[134:135]
	s_mov_b32 m0, s68
	s_nop 0
	global_load_lds_dwordx4 v[224:225], off
	s_mov_b32 m0, s69
	s_nop 0
	global_load_lds_dwordx4 v[226:227], off
	s_waitcnt vmcnt(8)
	s_waitcnt lgkmcnt(0)
	s_barrier
	s_setprio 1
	s_waitcnt lgkmcnt(0)
	v_mfma_f32_16x16x32_bf16 v[92:95], v[152:155], v[188:191], 0
	v_mfma_f32_16x16x32_bf16 v[92:95], v[156:159], v[192:195], v[92:95]
	v_mfma_f32_16x16x32_bf16 v[88:91], v[160:163], v[188:191], 0
	v_mfma_f32_16x16x32_bf16 v[88:91], v[164:167], v[192:195], v[88:91]
	v_mfma_f32_16x16x32_bf16 v[84:87], v[152:155], v[196:199], 0
	v_mfma_f32_16x16x32_bf16 v[84:87], v[156:159], v[200:203], v[84:87]
	v_mfma_f32_16x16x32_bf16 v[80:83], v[160:163], v[196:199], 0
	v_mfma_f32_16x16x32_bf16 v[80:83], v[164:167], v[200:203], v[80:83]
	v_mfma_f32_16x16x32_bf16 v[76:79], v[152:155], v[204:207], 0
	v_mfma_f32_16x16x32_bf16 v[76:79], v[156:159], v[208:211], v[76:79]
	v_mfma_f32_16x16x32_bf16 v[72:75], v[160:163], v[204:207], 0
	v_mfma_f32_16x16x32_bf16 v[72:75], v[164:167], v[208:211], v[72:75]
	v_mfma_f32_16x16x32_bf16 v[60:63], v[152:155], v[212:215], 0
	v_mfma_f32_16x16x32_bf16 v[60:63], v[156:159], v[216:219], v[60:63]
	v_mfma_f32_16x16x32_bf16 v[56:59], v[160:163], v[212:215], 0
	v_mfma_f32_16x16x32_bf16 v[56:59], v[164:167], v[216:219], v[56:59]
	v_mfma_f32_16x16x32_bf16 v[28:31], v[168:171], v[188:191], 0
	v_mfma_f32_16x16x32_bf16 v[28:31], v[172:175], v[192:195], v[28:31]
	v_mfma_f32_16x16x32_bf16 v[24:27], v[176:179], v[188:191], 0
	v_mfma_f32_16x16x32_bf16 v[24:27], v[184:187], v[192:195], v[24:27]
	v_mfma_f32_16x16x32_bf16 v[20:23], v[168:171], v[196:199], 0
	v_mfma_f32_16x16x32_bf16 v[20:23], v[172:175], v[200:203], v[20:23]
	v_mfma_f32_16x16x32_bf16 v[16:19], v[176:179], v[196:199], 0
	v_mfma_f32_16x16x32_bf16 v[16:19], v[184:187], v[200:203], v[16:19]
	v_mfma_f32_16x16x32_bf16 v[12:15], v[168:171], v[204:207], 0
	v_mfma_f32_16x16x32_bf16 v[12:15], v[172:175], v[208:211], v[12:15]
	v_mfma_f32_16x16x32_bf16 v[8:11], v[176:179], v[204:207], 0
	v_mfma_f32_16x16x32_bf16 v[8:11], v[184:187], v[208:211], v[8:11]
	v_mfma_f32_16x16x32_bf16 v[4:7], v[168:171], v[212:215], 0
	v_mfma_f32_16x16x32_bf16 v[4:7], v[172:175], v[216:219], v[4:7]
	v_mfma_f32_16x16x32_bf16 v[0:3], v[176:179], v[212:215], 0
	v_mfma_f32_16x16x32_bf16 v[0:3], v[184:187], v[216:219], v[0:3]
	s_setprio 0
	s_barrier
	s_branch .Lmid_gemm2
.LBB0_387:
	ds_read_b128 v[152:155], v148
	ds_read_b128 v[156:159], v148 offset:1024
	ds_read_b128 v[160:163], v148 offset:2048
	ds_read_b128 v[164:167], v148 offset:3072
	ds_read_b128 v[168:171], v149
	ds_read_b128 v[172:175], v149 offset:1024
	ds_read_b128 v[176:179], v149 offset:2048
	ds_read_b128 v[184:187], v149 offset:3072
	s_add_u32 s18, s58, 0xfffc0080
	s_addc_u32 s19, s59, -1
	s_cmp_eq_u32 s86, 12
	s_cselect_b32 s63, s49, s19
	s_cselect_b32 s62, s82, s18
	s_cselect_b32 s61, s47, s85
	s_cselect_b32 s60, s83, s84
	v_lshl_add_u64 v[220:221], s[58:59], 0, v[138:139]
	s_add_i32 m0, s68, 0xc000
	ds_read_b128 v[188:191], v150
	ds_read_b128 v[192:195], v150 offset:1024
	ds_read_b128 v[196:199], v150 offset:2048
	ds_read_b128 v[200:203], v150 offset:3072
	ds_read_b128 v[204:207], v150 offset:4096
	ds_read_b128 v[208:211], v150 offset:5120
	ds_read_b128 v[212:215], v150 offset:6144
	ds_read_b128 v[216:219], v150 offset:7168
	global_load_lds_dwordx4 v[220:221], off
	v_lshl_add_u64 v[220:221], s[58:59], 0, v[140:141]
	s_add_i32 m0, s68, 0xe000
	s_nop 0
	global_load_lds_dwordx4 v[220:221], off
	s_waitcnt vmcnt(8)
	s_waitcnt lgkmcnt(0)
	s_barrier
	s_setprio 1
	s_waitcnt lgkmcnt(0)
	v_mfma_f32_16x16x32_bf16 v[124:127], v[152:155], v[188:191], v[124:127]
	v_mfma_f32_16x16x32_bf16 v[124:127], v[156:159], v[192:195], v[124:127]
	v_mfma_f32_16x16x32_bf16 v[120:123], v[160:163], v[188:191], v[120:123]
	v_mfma_f32_16x16x32_bf16 v[120:123], v[164:167], v[192:195], v[120:123]
	v_mfma_f32_16x16x32_bf16 v[116:119], v[152:155], v[196:199], v[116:119]
	v_mfma_f32_16x16x32_bf16 v[116:119], v[156:159], v[200:203], v[116:119]
	v_mfma_f32_16x16x32_bf16 v[112:115], v[160:163], v[196:199], v[112:115]
	v_mfma_f32_16x16x32_bf16 v[112:115], v[164:167], v[200:203], v[112:115]
	v_mfma_f32_16x16x32_bf16 v[108:111], v[152:155], v[204:207], v[108:111]
	v_mfma_f32_16x16x32_bf16 v[108:111], v[156:159], v[208:211], v[108:111]
	v_mfma_f32_16x16x32_bf16 v[104:107], v[160:163], v[204:207], v[104:107]
	v_mfma_f32_16x16x32_bf16 v[104:107], v[164:167], v[208:211], v[104:107]
	v_mfma_f32_16x16x32_bf16 v[100:103], v[152:155], v[212:215], v[100:103]
	v_mfma_f32_16x16x32_bf16 v[100:103], v[156:159], v[216:219], v[100:103]
	v_mfma_f32_16x16x32_bf16 v[96:99], v[160:163], v[212:215], v[96:99]
	v_mfma_f32_16x16x32_bf16 v[96:99], v[164:167], v[216:219], v[96:99]
	v_mfma_f32_16x16x32_bf16 v[68:71], v[168:171], v[188:191], v[68:71]
	v_mfma_f32_16x16x32_bf16 v[68:71], v[172:175], v[192:195], v[68:71]
	v_mfma_f32_16x16x32_bf16 v[64:67], v[176:179], v[188:191], v[64:67]
	v_mfma_f32_16x16x32_bf16 v[64:67], v[184:187], v[192:195], v[64:67]
	v_mfma_f32_16x16x32_bf16 v[52:55], v[168:171], v[196:199], v[52:55]
	v_mfma_f32_16x16x32_bf16 v[52:55], v[172:175], v[200:203], v[52:55]
	v_mfma_f32_16x16x32_bf16 v[48:51], v[176:179], v[196:199], v[48:51]
	v_mfma_f32_16x16x32_bf16 v[48:51], v[184:187], v[200:203], v[48:51]
	v_mfma_f32_16x16x32_bf16 v[44:47], v[168:171], v[204:207], v[44:47]
	v_mfma_f32_16x16x32_bf16 v[44:47], v[172:175], v[208:211], v[44:47]
	v_mfma_f32_16x16x32_bf16 v[40:43], v[176:179], v[204:207], v[40:43]
	v_mfma_f32_16x16x32_bf16 v[40:43], v[184:187], v[208:211], v[40:43]
	v_mfma_f32_16x16x32_bf16 v[36:39], v[168:171], v[212:215], v[36:39]
	v_mfma_f32_16x16x32_bf16 v[36:39], v[172:175], v[216:219], v[36:39]
	v_mfma_f32_16x16x32_bf16 v[32:35], v[176:179], v[212:215], v[32:35]
	v_mfma_f32_16x16x32_bf16 v[32:35], v[184:187], v[216:219], v[32:35]
	s_setprio 0
	s_barrier
	s_add_i32 s18, s76, s66
	v_lshl_add_u64 v[220:221], s[60:61], 0, v[132:133]
	s_mov_b32 m0, s18
	ds_read_b128 v[188:191], v150 offset:16384
	ds_read_b128 v[192:195], v150 offset:17408
	ds_read_b128 v[196:199], v150 offset:18432
	ds_read_b128 v[200:203], v150 offset:19456
	ds_read_b128 v[204:207], v150 offset:20480
	ds_read_b128 v[208:211], v150 offset:21504
	ds_read_b128 v[212:215], v150 offset:22528
	ds_read_b128 v[216:219], v150 offset:23552
	global_load_lds_dwordx4 v[220:221], off
	s_add_i32 m0, s18, 0x2000
	s_add_u32 s88, s60, 0x40000
	v_lshl_add_u64 v[222:223], s[60:61], 0, v[128:129]
	s_addc_u32 s89, s61, 0
	s_add_i32 s18, s77, s66
	global_load_lds_dwordx4 v[222:223], off
	v_lshl_add_u64 v[224:225], s[88:89], 0, v[132:133]
	s_mov_b32 m0, s18
	v_lshl_add_u64 v[226:227], s[62:63], 0, v[130:131]
	global_load_lds_dwordx4 v[224:225], off
	v_lshl_add_u64 v[224:225], s[88:89], 0, v[128:129]
	s_add_i32 m0, s18, 0x2000
	s_nop 0
	global_load_lds_dwordx4 v[224:225], off
	v_lshl_add_u64 v[224:225], s[62:63], 0, v[134:135]
	s_mov_b32 m0, s68
	s_nop 0
	global_load_lds_dwordx4 v[224:225], off
	s_mov_b32 m0, s69
	s_nop 0
	global_load_lds_dwordx4 v[226:227], off
	s_waitcnt vmcnt(8)
	s_waitcnt lgkmcnt(0)
	s_barrier
	s_setprio 1
	s_waitcnt lgkmcnt(0)
	v_mfma_f32_16x16x32_bf16 v[92:95], v[152:155], v[188:191], v[92:95]
	v_mfma_f32_16x16x32_bf16 v[92:95], v[156:159], v[192:195], v[92:95]
	v_mfma_f32_16x16x32_bf16 v[88:91], v[160:163], v[188:191], v[88:91]
	v_mfma_f32_16x16x32_bf16 v[88:91], v[164:167], v[192:195], v[88:91]
	v_mfma_f32_16x16x32_bf16 v[84:87], v[152:155], v[196:199], v[84:87]
	v_mfma_f32_16x16x32_bf16 v[84:87], v[156:159], v[200:203], v[84:87]
	v_mfma_f32_16x16x32_bf16 v[80:83], v[160:163], v[196:199], v[80:83]
	v_mfma_f32_16x16x32_bf16 v[80:83], v[164:167], v[200:203], v[80:83]
	v_mfma_f32_16x16x32_bf16 v[76:79], v[152:155], v[204:207], v[76:79]
	v_mfma_f32_16x16x32_bf16 v[76:79], v[156:159], v[208:211], v[76:79]
	v_mfma_f32_16x16x32_bf16 v[72:75], v[160:163], v[204:207], v[72:75]
	v_mfma_f32_16x16x32_bf16 v[72:75], v[164:167], v[208:211], v[72:75]
	v_mfma_f32_16x16x32_bf16 v[60:63], v[152:155], v[212:215], v[60:63]
	v_mfma_f32_16x16x32_bf16 v[60:63], v[156:159], v[216:219], v[60:63]
	v_mfma_f32_16x16x32_bf16 v[56:59], v[160:163], v[212:215], v[56:59]
	v_mfma_f32_16x16x32_bf16 v[56:59], v[164:167], v[216:219], v[56:59]
	v_mfma_f32_16x16x32_bf16 v[28:31], v[168:171], v[188:191], v[28:31]
	v_mfma_f32_16x16x32_bf16 v[28:31], v[172:175], v[192:195], v[28:31]
	v_mfma_f32_16x16x32_bf16 v[24:27], v[176:179], v[188:191], v[24:27]
	v_mfma_f32_16x16x32_bf16 v[24:27], v[184:187], v[192:195], v[24:27]
	v_mfma_f32_16x16x32_bf16 v[20:23], v[168:171], v[196:199], v[20:23]
	v_mfma_f32_16x16x32_bf16 v[20:23], v[172:175], v[200:203], v[20:23]
	v_mfma_f32_16x16x32_bf16 v[16:19], v[176:179], v[196:199], v[16:19]
	v_mfma_f32_16x16x32_bf16 v[16:19], v[184:187], v[200:203], v[16:19]
	v_mfma_f32_16x16x32_bf16 v[12:15], v[168:171], v[204:207], v[12:15]
	v_mfma_f32_16x16x32_bf16 v[12:15], v[172:175], v[208:211], v[12:15]
	v_mfma_f32_16x16x32_bf16 v[8:11], v[176:179], v[204:207], v[8:11]
	v_mfma_f32_16x16x32_bf16 v[8:11], v[184:187], v[208:211], v[8:11]
	v_mfma_f32_16x16x32_bf16 v[4:7], v[168:171], v[212:215], v[4:7]
	v_mfma_f32_16x16x32_bf16 v[4:7], v[172:175], v[216:219], v[4:7]
	v_mfma_f32_16x16x32_bf16 v[0:3], v[176:179], v[212:215], v[0:3]
	v_mfma_f32_16x16x32_bf16 v[0:3], v[184:187], v[216:219], v[0:3]
	s_setprio 0
	s_barrier
.Lmid_gemm2:
	s_add_i32 s18, 0, 0x18000
	s_add_i32 s19, 0, 0x1c000
	v_add_u32_e32 v164, s18, v147
	v_add_u32_e32 v181, s19, v147
	ds_read_b128 v[152:155], v164
	ds_read_b128 v[156:159], v164 offset:1024
	ds_read_b128 v[160:163], v164 offset:2048
	ds_read_b128 v[164:167], v164 offset:3072
	ds_read_b128 v[168:171], v181
	ds_read_b128 v[172:175], v181 offset:1024
	ds_read_b128 v[176:179], v181 offset:2048
	ds_read_b128 v[184:187], v181 offset:3072
	s_add_u32 s62, s62, 0x40000
	s_addc_u32 s63, s63, 0
	s_mov_b32 m0, s70
	v_lshl_add_u64 v[228:229], s[62:63], 0, v[134:135]
	ds_read_b128 v[188:191], v150 offset:32768
	ds_read_b128 v[192:195], v150 offset:33792
	ds_read_b128 v[196:199], v150 offset:34816
	ds_read_b128 v[200:203], v150 offset:35840
	ds_read_b128 v[204:207], v150 offset:36864
	ds_read_b128 v[208:211], v150 offset:37888
	ds_read_b128 v[212:215], v150 offset:38912
	ds_read_b128 v[216:219], v150 offset:39936
	global_load_lds_dwordx4 v[228:229], off
	v_lshl_add_u64 v[228:229], s[62:63], 0, v[130:131]
	s_mov_b32 m0, s71
	s_nop 0
	global_load_lds_dwordx4 v[228:229], off
	s_waitcnt vmcnt(8)
	s_waitcnt lgkmcnt(0)
	s_barrier
	s_setprio 1
	s_waitcnt lgkmcnt(0)
	v_mfma_f32_16x16x32_bf16 v[124:127], v[152:155], v[188:191], v[124:127]
	v_mfma_f32_16x16x32_bf16 v[124:127], v[156:159], v[192:195], v[124:127]
	v_mfma_f32_16x16x32_bf16 v[120:123], v[160:163], v[188:191], v[120:123]
	v_mfma_f32_16x16x32_bf16 v[120:123], v[164:167], v[192:195], v[120:123]
	v_mfma_f32_16x16x32_bf16 v[116:119], v[152:155], v[196:199], v[116:119]
	v_mfma_f32_16x16x32_bf16 v[116:119], v[156:159], v[200:203], v[116:119]
	v_mfma_f32_16x16x32_bf16 v[112:115], v[160:163], v[196:199], v[112:115]
	v_mfma_f32_16x16x32_bf16 v[112:115], v[164:167], v[200:203], v[112:115]
	v_mfma_f32_16x16x32_bf16 v[108:111], v[152:155], v[204:207], v[108:111]
	v_mfma_f32_16x16x32_bf16 v[108:111], v[156:159], v[208:211], v[108:111]
	v_mfma_f32_16x16x32_bf16 v[104:107], v[160:163], v[204:207], v[104:107]
	v_mfma_f32_16x16x32_bf16 v[104:107], v[164:167], v[208:211], v[104:107]
	v_mfma_f32_16x16x32_bf16 v[100:103], v[152:155], v[212:215], v[100:103]
	v_mfma_f32_16x16x32_bf16 v[100:103], v[156:159], v[216:219], v[100:103]
	v_mfma_f32_16x16x32_bf16 v[96:99], v[160:163], v[212:215], v[96:99]
	v_mfma_f32_16x16x32_bf16 v[96:99], v[164:167], v[216:219], v[96:99]
	v_mfma_f32_16x16x32_bf16 v[68:71], v[168:171], v[188:191], v[68:71]
	v_mfma_f32_16x16x32_bf16 v[68:71], v[172:175], v[192:195], v[68:71]
	v_mfma_f32_16x16x32_bf16 v[64:67], v[176:179], v[188:191], v[64:67]
	v_mfma_f32_16x16x32_bf16 v[64:67], v[184:187], v[192:195], v[64:67]
	v_mfma_f32_16x16x32_bf16 v[52:55], v[168:171], v[196:199], v[52:55]
	v_mfma_f32_16x16x32_bf16 v[52:55], v[172:175], v[200:203], v[52:55]
	v_mfma_f32_16x16x32_bf16 v[48:51], v[176:179], v[196:199], v[48:51]
	v_mfma_f32_16x16x32_bf16 v[48:51], v[184:187], v[200:203], v[48:51]
	v_mfma_f32_16x16x32_bf16 v[44:47], v[168:171], v[204:207], v[44:47]
	v_mfma_f32_16x16x32_bf16 v[44:47], v[172:175], v[208:211], v[44:47]
	v_mfma_f32_16x16x32_bf16 v[40:43], v[176:179], v[204:207], v[40:43]
	v_mfma_f32_16x16x32_bf16 v[40:43], v[184:187], v[208:211], v[40:43]
	v_mfma_f32_16x16x32_bf16 v[36:39], v[168:171], v[212:215], v[36:39]
	v_mfma_f32_16x16x32_bf16 v[36:39], v[172:175], v[216:219], v[36:39]
	v_mfma_f32_16x16x32_bf16 v[32:35], v[176:179], v[212:215], v[32:35]
	v_mfma_f32_16x16x32_bf16 v[32:35], v[184:187], v[216:219], v[32:35]
	s_setprio 0
	s_barrier
	s_add_i32 s18, s18, s66
	v_lshl_add_u64 v[220:221], v[220:221], 0, s[6:7]
	s_mov_b32 m0, s18
	ds_read_b128 v[188:191], v150 offset:49152
	ds_read_b128 v[192:195], v150 offset:50176
	ds_read_b128 v[196:199], v150 offset:51200
	ds_read_b128 v[200:203], v150 offset:52224
	ds_read_b128 v[204:207], v150 offset:53248
	ds_read_b128 v[208:211], v150 offset:54272
	ds_read_b128 v[212:215], v150 offset:55296
	ds_read_b128 v[216:219], v150 offset:56320
	global_load_lds_dwordx4 v[220:221], off
	s_add_i32 m0, s18, 0x2000
	s_add_u32 s60, s60, 0x40080
	v_lshl_add_u64 v[220:221], v[222:223], 0, s[6:7]
	s_addc_u32 s61, s61, 0
	s_add_i32 s18, s19, s66
	global_load_lds_dwordx4 v[220:221], off
	v_lshl_add_u64 v[220:221], s[60:61], 0, v[132:133]
	s_mov_b32 m0, s18
	s_nop 0
	global_load_lds_dwordx4 v[220:221], off
	v_lshl_add_u64 v[220:221], s[60:61], 0, v[128:129]
	s_add_i32 m0, s18, 0x2000
	s_nop 0
	global_load_lds_dwordx4 v[220:221], off
	v_lshl_add_u64 v[220:221], v[224:225], 0, s[6:7]
	s_mov_b32 m0, s74
	s_nop 0
	global_load_lds_dwordx4 v[220:221], off
	v_lshl_add_u64 v[220:221], v[226:227], 0, s[6:7]
	s_mov_b32 m0, s75
	s_nop 0
	global_load_lds_dwordx4 v[220:221], off
	s_waitcnt vmcnt(8)
	s_waitcnt lgkmcnt(0)
	s_barrier
	s_setprio 1
	s_waitcnt lgkmcnt(0)
	v_mfma_f32_16x16x32_bf16 v[92:95], v[152:155], v[188:191], v[92:95]
	v_mfma_f32_16x16x32_bf16 v[92:95], v[156:159], v[192:195], v[92:95]
	v_mfma_f32_16x16x32_bf16 v[88:91], v[160:163], v[188:191], v[88:91]
	v_mfma_f32_16x16x32_bf16 v[88:91], v[164:167], v[192:195], v[88:91]
	v_mfma_f32_16x16x32_bf16 v[84:87], v[152:155], v[196:199], v[84:87]
	v_mfma_f32_16x16x32_bf16 v[84:87], v[156:159], v[200:203], v[84:87]
	v_mfma_f32_16x16x32_bf16 v[80:83], v[160:163], v[196:199], v[80:83]
	v_mfma_f32_16x16x32_bf16 v[80:83], v[164:167], v[200:203], v[80:83]
	v_mfma_f32_16x16x32_bf16 v[76:79], v[152:155], v[204:207], v[76:79]
	v_mfma_f32_16x16x32_bf16 v[76:79], v[156:159], v[208:211], v[76:79]
	v_mfma_f32_16x16x32_bf16 v[72:75], v[160:163], v[204:207], v[72:75]
	v_mfma_f32_16x16x32_bf16 v[72:75], v[164:167], v[208:211], v[72:75]
	v_mfma_f32_16x16x32_bf16 v[60:63], v[152:155], v[212:215], v[60:63]
	v_mfma_f32_16x16x32_bf16 v[60:63], v[156:159], v[216:219], v[60:63]
	v_mfma_f32_16x16x32_bf16 v[56:59], v[160:163], v[212:215], v[56:59]
	v_mfma_f32_16x16x32_bf16 v[56:59], v[164:167], v[216:219], v[56:59]
	v_mfma_f32_16x16x32_bf16 v[28:31], v[168:171], v[188:191], v[28:31]
	v_mfma_f32_16x16x32_bf16 v[28:31], v[172:175], v[192:195], v[28:31]
	v_mfma_f32_16x16x32_bf16 v[24:27], v[176:179], v[188:191], v[24:27]
	v_mfma_f32_16x16x32_bf16 v[24:27], v[184:187], v[192:195], v[24:27]
	v_mfma_f32_16x16x32_bf16 v[20:23], v[168:171], v[196:199], v[20:23]
	v_mfma_f32_16x16x32_bf16 v[20:23], v[172:175], v[200:203], v[20:23]
	v_mfma_f32_16x16x32_bf16 v[16:19], v[176:179], v[196:199], v[16:19]
	v_mfma_f32_16x16x32_bf16 v[16:19], v[184:187], v[200:203], v[16:19]
	v_mfma_f32_16x16x32_bf16 v[12:15], v[168:171], v[204:207], v[12:15]
	v_mfma_f32_16x16x32_bf16 v[12:15], v[172:175], v[208:211], v[12:15]
	v_mfma_f32_16x16x32_bf16 v[8:11], v[176:179], v[204:207], v[8:11]
	v_mfma_f32_16x16x32_bf16 v[8:11], v[184:187], v[208:211], v[8:11]
	v_mfma_f32_16x16x32_bf16 v[4:7], v[168:171], v[212:215], v[4:7]
	v_mfma_f32_16x16x32_bf16 v[4:7], v[172:175], v[216:219], v[4:7]
	v_mfma_f32_16x16x32_bf16 v[0:3], v[176:179], v[212:215], v[0:3]
	v_mfma_f32_16x16x32_bf16 v[0:3], v[184:187], v[216:219], v[0:3]
	s_setprio 0
	s_barrier
	s_add_i32 s86, s86, 2
	s_add_u32 s58, s58, 0x100
	s_addc_u32 s59, s59, 0
	s_add_u32 s84, s84, 0x100
	s_addc_u32 s85, s85, 0
	s_cmp_gt_u32 s86, 13
	s_cbranch_scc0 .LBB0_387
	s_and_b64 vcc, exec, s[8:9]
	s_cbranch_vccz .LBB0_390
	s_barrier

.LBB0_600:
	s_ashr_i32 s49, s48, 31
	s_lshl_b64 s[18:19], s[48:49], 19
	s_add_u32 s52, s38, s18
	s_addc_u32 s53, s39, s19
	s_and_b64 s[18:19], s[4:5], exec
	s_cselect_b32 s49, s53, s59
	s_cselect_b32 s84, s52, s58
	s_ashr_i32 s47, s46, 31
	s_lshl_b64 s[18:19], s[46:47], 19
	s_add_u32 s54, s64, s18
	s_addc_u32 s55, s65, s19
	s_and_b64 s[18:19], s[4:5], exec
	s_cselect_b32 s47, s55, s61
	s_cselect_b32 s85, s54, s60
	s_add_u32 s58, s58, 0x40080
	s_addc_u32 s59, s59, 0
	s_add_u32 s86, s60, 0x100
	s_addc_u32 s87, s61, 0
	s_mov_b32 s88, -2
	ds_read_b128 v[152:155], v149
	ds_read_b128 v[156:159], v149 offset:1024
	ds_read_b128 v[160:163], v149 offset:2048
	ds_read_b128 v[164:167], v149 offset:3072
	ds_read_b128 v[168:171], v150
	ds_read_b128 v[172:175], v150 offset:1024
	ds_read_b128 v[176:179], v150 offset:2048
	ds_read_b128 v[184:187], v150 offset:3072
	s_add_u32 s18, s58, 0xfffc0080
	s_addc_u32 s19, s59, -1
	s_cmp_eq_u32 s88, 12
	s_cselect_b32 s63, s49, s19
	s_cselect_b32 s62, s84, s18
	s_cselect_b32 s61, s47, s87
	s_cselect_b32 s60, s85, s86
	v_lshl_add_u64 v[144:145], s[58:59], 0, v[136:137]
	s_add_i32 m0, s57, 0xc000
	ds_read_b128 v[188:191], v151
	ds_read_b128 v[192:195], v151 offset:1024
	ds_read_b128 v[196:199], v151 offset:2048
	ds_read_b128 v[200:203], v151 offset:3072
	ds_read_b128 v[204:207], v151 offset:4096
	ds_read_b128 v[208:211], v151 offset:5120
	ds_read_b128 v[212:215], v151 offset:6144
	ds_read_b128 v[216:219], v151 offset:7168
	global_load_lds_dwordx4 v[144:145], off
	v_lshl_add_u64 v[144:145], s[58:59], 0, v[138:139]
	s_add_i32 m0, s57, 0xe000
	s_nop 0
	global_load_lds_dwordx4 v[144:145], off
	s_waitcnt vmcnt(8)
	s_waitcnt lgkmcnt(0)
	s_barrier
	s_setprio 1
	s_waitcnt lgkmcnt(0)
	v_mfma_f32_16x16x32_bf16 v[124:127], v[152:155], v[188:191], 0
	v_mfma_f32_16x16x32_bf16 v[124:127], v[156:159], v[192:195], v[124:127]
	v_mfma_f32_16x16x32_bf16 v[120:123], v[160:163], v[188:191], 0
	v_mfma_f32_16x16x32_bf16 v[120:123], v[164:167], v[192:195], v[120:123]
	v_mfma_f32_16x16x32_bf16 v[116:119], v[152:155], v[196:199], 0
	v_mfma_f32_16x16x32_bf16 v[116:119], v[156:159], v[200:203], v[116:119]
	v_mfma_f32_16x16x32_bf16 v[108:111], v[160:163], v[196:199], 0
	v_mfma_f32_16x16x32_bf16 v[108:111], v[164:167], v[200:203], v[108:111]
	v_mfma_f32_16x16x32_bf16 v[100:103], v[152:155], v[204:207], 0
	v_mfma_f32_16x16x32_bf16 v[100:103], v[156:159], v[208:211], v[100:103]
	v_mfma_f32_16x16x32_bf16 v[92:95], v[160:163], v[204:207], 0
	v_mfma_f32_16x16x32_bf16 v[92:95], v[164:167], v[208:211], v[92:95]
	v_mfma_f32_16x16x32_bf16 v[84:87], v[152:155], v[212:215], 0
	v_mfma_f32_16x16x32_bf16 v[84:87], v[156:159], v[216:219], v[84:87]
	v_mfma_f32_16x16x32_bf16 v[76:79], v[160:163], v[212:215], 0
	v_mfma_f32_16x16x32_bf16 v[76:79], v[164:167], v[216:219], v[76:79]
	v_mfma_f32_16x16x32_bf16 v[112:115], v[168:171], v[188:191], 0
	v_mfma_f32_16x16x32_bf16 v[112:115], v[172:175], v[192:195], v[112:115]
	v_mfma_f32_16x16x32_bf16 v[104:107], v[176:179], v[188:191], 0
	v_mfma_f32_16x16x32_bf16 v[104:107], v[184:187], v[192:195], v[104:107]
	v_mfma_f32_16x16x32_bf16 v[96:99], v[168:171], v[196:199], 0
	v_mfma_f32_16x16x32_bf16 v[96:99], v[172:175], v[200:203], v[96:99]
	v_mfma_f32_16x16x32_bf16 v[88:91], v[176:179], v[196:199], 0
	v_mfma_f32_16x16x32_bf16 v[88:91], v[184:187], v[200:203], v[88:91]
	v_mfma_f32_16x16x32_bf16 v[80:83], v[168:171], v[204:207], 0
	v_mfma_f32_16x16x32_bf16 v[80:83], v[172:175], v[208:211], v[80:83]
	v_mfma_f32_16x16x32_bf16 v[72:75], v[176:179], v[204:207], 0
	v_mfma_f32_16x16x32_bf16 v[72:75], v[184:187], v[208:211], v[72:75]
	v_mfma_f32_16x16x32_bf16 v[68:71], v[168:171], v[212:215], 0
	v_mfma_f32_16x16x32_bf16 v[68:71], v[172:175], v[216:219], v[68:71]
	v_mfma_f32_16x16x32_bf16 v[64:67], v[176:179], v[212:215], 0
	v_mfma_f32_16x16x32_bf16 v[64:67], v[184:187], v[216:219], v[64:67]
	s_setprio 0
	s_barrier
	s_add_i32 s18, s73, s66
	v_lshl_add_u64 v[144:145], s[60:61], 0, v[130:131]
	s_mov_b32 m0, s18
	ds_read_b128 v[188:191], v151 offset:16384
	ds_read_b128 v[192:195], v151 offset:17408
	ds_read_b128 v[196:199], v151 offset:18432
	ds_read_b128 v[200:203], v151 offset:19456
	ds_read_b128 v[204:207], v151 offset:20480
	ds_read_b128 v[208:211], v151 offset:21504
	ds_read_b128 v[212:215], v151 offset:22528
	ds_read_b128 v[216:219], v151 offset:23552
	global_load_lds_dwordx4 v[144:145], off
	s_add_i32 m0, s18, 0x2000
	s_add_u32 s18, s60, 0x40000
	v_lshl_add_u64 v[220:221], s[60:61], 0, v[134:135]
	s_addc_u32 s19, s61, 0
	s_add_i32 s79, s74, s66
	global_load_lds_dwordx4 v[220:221], off
	v_lshl_add_u64 v[222:223], s[18:19], 0, v[130:131]
	s_mov_b32 m0, s79
	v_lshl_add_u64 v[224:225], s[62:63], 0, v[132:133]
	global_load_lds_dwordx4 v[222:223], off
	v_lshl_add_u64 v[222:223], s[18:19], 0, v[134:135]
	s_add_i32 m0, s79, 0x2000
	s_nop 0
	global_load_lds_dwordx4 v[222:223], off
	v_lshl_add_u64 v[222:223], s[62:63], 0, v[128:129]
	s_mov_b32 m0, s57
	s_nop 0
	global_load_lds_dwordx4 v[222:223], off
	s_mov_b32 m0, s67
	s_nop 0
	global_load_lds_dwordx4 v[224:225], off
	s_waitcnt vmcnt(8)
	s_waitcnt lgkmcnt(0)
	s_barrier
	s_setprio 1
	s_waitcnt lgkmcnt(0)
	v_mfma_f32_16x16x32_bf16 v[60:63], v[152:155], v[188:191], 0
	v_mfma_f32_16x16x32_bf16 v[60:63], v[156:159], v[192:195], v[60:63]
	v_mfma_f32_16x16x32_bf16 v[56:59], v[160:163], v[188:191], 0
	v_mfma_f32_16x16x32_bf16 v[56:59], v[164:167], v[192:195], v[56:59]
	v_mfma_f32_16x16x32_bf16 v[52:55], v[152:155], v[196:199], 0
	v_mfma_f32_16x16x32_bf16 v[52:55], v[156:159], v[200:203], v[52:55]
	v_mfma_f32_16x16x32_bf16 v[44:47], v[160:163], v[196:199], 0
	v_mfma_f32_16x16x32_bf16 v[44:47], v[164:167], v[200:203], v[44:47]
	v_mfma_f32_16x16x32_bf16 v[36:39], v[152:155], v[204:207], 0
	v_mfma_f32_16x16x32_bf16 v[36:39], v[156:159], v[208:211], v[36:39]
	v_mfma_f32_16x16x32_bf16 v[28:31], v[160:163], v[204:207], 0
	v_mfma_f32_16x16x32_bf16 v[28:31], v[164:167], v[208:211], v[28:31]
	v_mfma_f32_16x16x32_bf16 v[20:23], v[152:155], v[212:215], 0
	v_mfma_f32_16x16x32_bf16 v[20:23], v[156:159], v[216:219], v[20:23]
	v_mfma_f32_16x16x32_bf16 v[12:15], v[160:163], v[212:215], 0
	v_mfma_f32_16x16x32_bf16 v[12:15], v[164:167], v[216:219], v[12:15]
	v_mfma_f32_16x16x32_bf16 v[48:51], v[168:171], v[188:191], 0
	v_mfma_f32_16x16x32_bf16 v[48:51], v[172:175], v[192:195], v[48:51]
	v_mfma_f32_16x16x32_bf16 v[40:43], v[176:179], v[188:191], 0
	v_mfma_f32_16x16x32_bf16 v[40:43], v[184:187], v[192:195], v[40:43]
	v_mfma_f32_16x16x32_bf16 v[32:35], v[168:171], v[196:199], 0
	v_mfma_f32_16x16x32_bf16 v[32:35], v[172:175], v[200:203], v[32:35]
	v_mfma_f32_16x16x32_bf16 v[24:27], v[176:179], v[196:199], 0
	v_mfma_f32_16x16x32_bf16 v[24:27], v[184:187], v[200:203], v[24:27]
	v_mfma_f32_16x16x32_bf16 v[16:19], v[168:171], v[204:207], 0
	v_mfma_f32_16x16x32_bf16 v[16:19], v[172:175], v[208:211], v[16:19]
	v_mfma_f32_16x16x32_bf16 v[8:11], v[176:179], v[204:207], 0
	v_mfma_f32_16x16x32_bf16 v[8:11], v[184:187], v[208:211], v[8:11]
	v_mfma_f32_16x16x32_bf16 v[4:7], v[168:171], v[212:215], 0
	v_mfma_f32_16x16x32_bf16 v[4:7], v[172:175], v[216:219], v[4:7]
	v_mfma_f32_16x16x32_bf16 v[0:3], v[176:179], v[212:215], 0
	v_mfma_f32_16x16x32_bf16 v[0:3], v[184:187], v[216:219], v[0:3]
	s_setprio 0
	s_barrier
	s_branch .Lmid_gemm3
.LBB0_601:
	ds_read_b128 v[152:155], v149
	ds_read_b128 v[156:159], v149 offset:1024
	ds_read_b128 v[160:163], v149 offset:2048
	ds_read_b128 v[164:167], v149 offset:3072
	ds_read_b128 v[168:171], v150
	ds_read_b128 v[172:175], v150 offset:1024
	ds_read_b128 v[176:179], v150 offset:2048
	ds_read_b128 v[184:187], v150 offset:3072
	s_add_u32 s18, s58, 0xfffc0080
	s_addc_u32 s19, s59, -1
	s_cmp_eq_u32 s88, 12
	s_cselect_b32 s63, s49, s19
	s_cselect_b32 s62, s84, s18
	s_cselect_b32 s61, s47, s87
	s_cselect_b32 s60, s85, s86
	v_lshl_add_u64 v[144:145], s[58:59], 0, v[136:137]
	s_add_i32 m0, s57, 0xc000
	ds_read_b128 v[188:191], v151
	ds_read_b128 v[192:195], v151 offset:1024
	ds_read_b128 v[196:199], v151 offset:2048
	ds_read_b128 v[200:203], v151 offset:3072
	ds_read_b128 v[204:207], v151 offset:4096
	ds_read_b128 v[208:211], v151 offset:5120
	ds_read_b128 v[212:215], v151 offset:6144
	ds_read_b128 v[216:219], v151 offset:7168
	global_load_lds_dwordx4 v[144:145], off
	v_lshl_add_u64 v[144:145], s[58:59], 0, v[138:139]
	s_add_i32 m0, s57, 0xe000
	s_nop 0
	global_load_lds_dwordx4 v[144:145], off
	s_waitcnt vmcnt(8)
	s_waitcnt lgkmcnt(0)
	s_barrier
	s_setprio 1
	s_waitcnt lgkmcnt(0)
	v_mfma_f32_16x16x32_bf16 v[124:127], v[152:155], v[188:191], v[124:127]
	v_mfma_f32_16x16x32_bf16 v[124:127], v[156:159], v[192:195], v[124:127]
	v_mfma_f32_16x16x32_bf16 v[120:123], v[160:163], v[188:191], v[120:123]
	v_mfma_f32_16x16x32_bf16 v[120:123], v[164:167], v[192:195], v[120:123]
	v_mfma_f32_16x16x32_bf16 v[116:119], v[152:155], v[196:199], v[116:119]
	v_mfma_f32_16x16x32_bf16 v[116:119], v[156:159], v[200:203], v[116:119]
	v_mfma_f32_16x16x32_bf16 v[108:111], v[160:163], v[196:199], v[108:111]
	v_mfma_f32_16x16x32_bf16 v[108:111], v[164:167], v[200:203], v[108:111]
	v_mfma_f32_16x16x32_bf16 v[100:103], v[152:155], v[204:207], v[100:103]
	v_mfma_f32_16x16x32_bf16 v[100:103], v[156:159], v[208:211], v[100:103]
	v_mfma_f32_16x16x32_bf16 v[92:95], v[160:163], v[204:207], v[92:95]
	v_mfma_f32_16x16x32_bf16 v[92:95], v[164:167], v[208:211], v[92:95]
	v_mfma_f32_16x16x32_bf16 v[84:87], v[152:155], v[212:215], v[84:87]
	v_mfma_f32_16x16x32_bf16 v[84:87], v[156:159], v[216:219], v[84:87]
	v_mfma_f32_16x16x32_bf16 v[76:79], v[160:163], v[212:215], v[76:79]
	v_mfma_f32_16x16x32_bf16 v[76:79], v[164:167], v[216:219], v[76:79]
	v_mfma_f32_16x16x32_bf16 v[112:115], v[168:171], v[188:191], v[112:115]
	v_mfma_f32_16x16x32_bf16 v[112:115], v[172:175], v[192:195], v[112:115]
	v_mfma_f32_16x16x32_bf16 v[104:107], v[176:179], v[188:191], v[104:107]
	v_mfma_f32_16x16x32_bf16 v[104:107], v[184:187], v[192:195], v[104:107]
	v_mfma_f32_16x16x32_bf16 v[96:99], v[168:171], v[196:199], v[96:99]
	v_mfma_f32_16x16x32_bf16 v[96:99], v[172:175], v[200:203], v[96:99]
	v_mfma_f32_16x16x32_bf16 v[88:91], v[176:179], v[196:199], v[88:91]
	v_mfma_f32_16x16x32_bf16 v[88:91], v[184:187], v[200:203], v[88:91]
	v_mfma_f32_16x16x32_bf16 v[80:83], v[168:171], v[204:207], v[80:83]
	v_mfma_f32_16x16x32_bf16 v[80:83], v[172:175], v[208:211], v[80:83]
	v_mfma_f32_16x16x32_bf16 v[72:75], v[176:179], v[204:207], v[72:75]
	v_mfma_f32_16x16x32_bf16 v[72:75], v[184:187], v[208:211], v[72:75]
	v_mfma_f32_16x16x32_bf16 v[68:71], v[168:171], v[212:215], v[68:71]
	v_mfma_f32_16x16x32_bf16 v[68:71], v[172:175], v[216:219], v[68:71]
	v_mfma_f32_16x16x32_bf16 v[64:67], v[176:179], v[212:215], v[64:67]
	v_mfma_f32_16x16x32_bf16 v[64:67], v[184:187], v[216:219], v[64:67]
	s_setprio 0
	s_barrier
	s_add_i32 s18, s73, s66
	v_lshl_add_u64 v[144:145], s[60:61], 0, v[130:131]
	s_mov_b32 m0, s18
	ds_read_b128 v[188:191], v151 offset:16384
	ds_read_b128 v[192:195], v151 offset:17408
	ds_read_b128 v[196:199], v151 offset:18432
	ds_read_b128 v[200:203], v151 offset:19456
	ds_read_b128 v[204:207], v151 offset:20480
	ds_read_b128 v[208:211], v151 offset:21504
	ds_read_b128 v[212:215], v151 offset:22528
	ds_read_b128 v[216:219], v151 offset:23552
	global_load_lds_dwordx4 v[144:145], off
	s_add_i32 m0, s18, 0x2000
	s_add_u32 s18, s60, 0x40000
	v_lshl_add_u64 v[220:221], s[60:61], 0, v[134:135]
	s_addc_u32 s19, s61, 0
	s_add_i32 s79, s74, s66
	global_load_lds_dwordx4 v[220:221], off
	v_lshl_add_u64 v[222:223], s[18:19], 0, v[130:131]
	s_mov_b32 m0, s79
	v_lshl_add_u64 v[224:225], s[62:63], 0, v[132:133]
	global_load_lds_dwordx4 v[222:223], off
	v_lshl_add_u64 v[222:223], s[18:19], 0, v[134:135]
	s_add_i32 m0, s79, 0x2000
	s_nop 0
	global_load_lds_dwordx4 v[222:223], off
	v_lshl_add_u64 v[222:223], s[62:63], 0, v[128:129]
	s_mov_b32 m0, s57
	s_nop 0
	global_load_lds_dwordx4 v[222:223], off
	s_mov_b32 m0, s67
	s_nop 0
	global_load_lds_dwordx4 v[224:225], off
	s_waitcnt vmcnt(8)
	s_waitcnt lgkmcnt(0)
	s_barrier
	s_setprio 1
	s_waitcnt lgkmcnt(0)
	v_mfma_f32_16x16x32_bf16 v[60:63], v[152:155], v[188:191], v[60:63]
	v_mfma_f32_16x16x32_bf16 v[60:63], v[156:159], v[192:195], v[60:63]
	v_mfma_f32_16x16x32_bf16 v[56:59], v[160:163], v[188:191], v[56:59]
	v_mfma_f32_16x16x32_bf16 v[56:59], v[164:167], v[192:195], v[56:59]
	v_mfma_f32_16x16x32_bf16 v[52:55], v[152:155], v[196:199], v[52:55]
	v_mfma_f32_16x16x32_bf16 v[52:55], v[156:159], v[200:203], v[52:55]
	v_mfma_f32_16x16x32_bf16 v[44:47], v[160:163], v[196:199], v[44:47]
	v_mfma_f32_16x16x32_bf16 v[44:47], v[164:167], v[200:203], v[44:47]
	v_mfma_f32_16x16x32_bf16 v[36:39], v[152:155], v[204:207], v[36:39]
	v_mfma_f32_16x16x32_bf16 v[36:39], v[156:159], v[208:211], v[36:39]
	v_mfma_f32_16x16x32_bf16 v[28:31], v[160:163], v[204:207], v[28:31]
	v_mfma_f32_16x16x32_bf16 v[28:31], v[164:167], v[208:211], v[28:31]
	v_mfma_f32_16x16x32_bf16 v[20:23], v[152:155], v[212:215], v[20:23]
	v_mfma_f32_16x16x32_bf16 v[20:23], v[156:159], v[216:219], v[20:23]
	v_mfma_f32_16x16x32_bf16 v[12:15], v[160:163], v[212:215], v[12:15]
	v_mfma_f32_16x16x32_bf16 v[12:15], v[164:167], v[216:219], v[12:15]
	v_mfma_f32_16x16x32_bf16 v[48:51], v[168:171], v[188:191], v[48:51]
	v_mfma_f32_16x16x32_bf16 v[48:51], v[172:175], v[192:195], v[48:51]
	v_mfma_f32_16x16x32_bf16 v[40:43], v[176:179], v[188:191], v[40:43]
	v_mfma_f32_16x16x32_bf16 v[40:43], v[184:187], v[192:195], v[40:43]
	v_mfma_f32_16x16x32_bf16 v[32:35], v[168:171], v[196:199], v[32:35]
	v_mfma_f32_16x16x32_bf16 v[32:35], v[172:175], v[200:203], v[32:35]
	v_mfma_f32_16x16x32_bf16 v[24:27], v[176:179], v[196:199], v[24:27]
	v_mfma_f32_16x16x32_bf16 v[24:27], v[184:187], v[200:203], v[24:27]
	v_mfma_f32_16x16x32_bf16 v[16:19], v[168:171], v[204:207], v[16:19]
	v_mfma_f32_16x16x32_bf16 v[16:19], v[172:175], v[208:211], v[16:19]
	v_mfma_f32_16x16x32_bf16 v[8:11], v[176:179], v[204:207], v[8:11]
	v_mfma_f32_16x16x32_bf16 v[8:11], v[184:187], v[208:211], v[8:11]
	v_mfma_f32_16x16x32_bf16 v[4:7], v[168:171], v[212:215], v[4:7]
	v_mfma_f32_16x16x32_bf16 v[4:7], v[172:175], v[216:219], v[4:7]
	v_mfma_f32_16x16x32_bf16 v[0:3], v[176:179], v[212:215], v[0:3]
	v_mfma_f32_16x16x32_bf16 v[0:3], v[184:187], v[216:219], v[0:3]
	s_setprio 0
	s_barrier
.Lmid_gemm3:
	s_add_i32 s79, 0, 0x18000
	s_add_i32 s89, 0, 0x1c000
	v_add_u32_e32 v164, s79, v147
	v_add_u32_e32 v181, s89, v147
	ds_read_b128 v[152:155], v164
	ds_read_b128 v[156:159], v164 offset:1024
	ds_read_b128 v[160:163], v164 offset:2048
	ds_read_b128 v[164:167], v164 offset:3072
	ds_read_b128 v[168:171], v181
	ds_read_b128 v[172:175], v181 offset:1024
	ds_read_b128 v[176:179], v181 offset:2048
	ds_read_b128 v[184:187], v181 offset:3072
	s_add_u32 s18, s62, 0x40000
	s_addc_u32 s19, s63, 0
	s_mov_b32 m0, s68
	v_lshl_add_u64 v[226:227], s[18:19], 0, v[128:129]
	ds_read_b128 v[188:191], v151 offset:32768
	ds_read_b128 v[192:195], v151 offset:33792
	ds_read_b128 v[196:199], v151 offset:34816
	ds_read_b128 v[200:203], v151 offset:35840
	ds_read_b128 v[204:207], v151 offset:36864
	ds_read_b128 v[208:211], v151 offset:37888
	ds_read_b128 v[212:215], v151 offset:38912
	ds_read_b128 v[216:219], v151 offset:39936
	global_load_lds_dwordx4 v[226:227], off
	v_lshl_add_u64 v[226:227], s[18:19], 0, v[132:133]
	s_mov_b32 m0, s69
	s_nop 0
	global_load_lds_dwordx4 v[226:227], off
	s_waitcnt vmcnt(8)
	s_waitcnt lgkmcnt(0)
	s_barrier
	s_setprio 1
	s_waitcnt lgkmcnt(0)
	v_mfma_f32_16x16x32_bf16 v[124:127], v[152:155], v[188:191], v[124:127]
	v_mfma_f32_16x16x32_bf16 v[124:127], v[156:159], v[192:195], v[124:127]
	v_mfma_f32_16x16x32_bf16 v[120:123], v[160:163], v[188:191], v[120:123]
	v_mfma_f32_16x16x32_bf16 v[120:123], v[164:167], v[192:195], v[120:123]
	v_mfma_f32_16x16x32_bf16 v[116:119], v[152:155], v[196:199], v[116:119]
	v_mfma_f32_16x16x32_bf16 v[116:119], v[156:159], v[200:203], v[116:119]
	v_mfma_f32_16x16x32_bf16 v[108:111], v[160:163], v[196:199], v[108:111]
	v_mfma_f32_16x16x32_bf16 v[108:111], v[164:167], v[200:203], v[108:111]
	v_mfma_f32_16x16x32_bf16 v[100:103], v[152:155], v[204:207], v[100:103]
	v_mfma_f32_16x16x32_bf16 v[100:103], v[156:159], v[208:211], v[100:103]
	v_mfma_f32_16x16x32_bf16 v[92:95], v[160:163], v[204:207], v[92:95]
	v_mfma_f32_16x16x32_bf16 v[92:95], v[164:167], v[208:211], v[92:95]
	v_mfma_f32_16x16x32_bf16 v[84:87], v[152:155], v[212:215], v[84:87]
	v_mfma_f32_16x16x32_bf16 v[84:87], v[156:159], v[216:219], v[84:87]
	v_mfma_f32_16x16x32_bf16 v[76:79], v[160:163], v[212:215], v[76:79]
	v_mfma_f32_16x16x32_bf16 v[76:79], v[164:167], v[216:219], v[76:79]
	v_mfma_f32_16x16x32_bf16 v[112:115], v[168:171], v[188:191], v[112:115]
	v_mfma_f32_16x16x32_bf16 v[112:115], v[172:175], v[192:195], v[112:115]
	v_mfma_f32_16x16x32_bf16 v[104:107], v[176:179], v[188:191], v[104:107]
	v_mfma_f32_16x16x32_bf16 v[104:107], v[184:187], v[192:195], v[104:107]
	v_mfma_f32_16x16x32_bf16 v[96:99], v[168:171], v[196:199], v[96:99]
	v_mfma_f32_16x16x32_bf16 v[96:99], v[172:175], v[200:203], v[96:99]
	v_mfma_f32_16x16x32_bf16 v[88:91], v[176:179], v[196:199], v[88:91]
	v_mfma_f32_16x16x32_bf16 v[88:91], v[184:187], v[200:203], v[88:91]
	v_mfma_f32_16x16x32_bf16 v[80:83], v[168:171], v[204:207], v[80:83]
	v_mfma_f32_16x16x32_bf16 v[80:83], v[172:175], v[208:211], v[80:83]
	v_mfma_f32_16x16x32_bf16 v[72:75], v[176:179], v[204:207], v[72:75]
	v_mfma_f32_16x16x32_bf16 v[72:75], v[184:187], v[208:211], v[72:75]
	v_mfma_f32_16x16x32_bf16 v[68:71], v[168:171], v[212:215], v[68:71]
	v_mfma_f32_16x16x32_bf16 v[68:71], v[172:175], v[216:219], v[68:71]
	v_mfma_f32_16x16x32_bf16 v[64:67], v[176:179], v[212:215], v[64:67]
	v_mfma_f32_16x16x32_bf16 v[64:67], v[184:187], v[216:219], v[64:67]
	s_setprio 0
	s_barrier
	s_add_i32 s18, s79, s66
	v_lshl_add_u64 v[144:145], v[144:145], 0, s[10:11]
	s_mov_b32 m0, s18
	ds_read_b128 v[188:191], v151 offset:49152
	ds_read_b128 v[192:195], v151 offset:50176
	ds_read_b128 v[196:199], v151 offset:51200
	ds_read_b128 v[200:203], v151 offset:52224
	ds_read_b128 v[204:207], v151 offset:53248
	ds_read_b128 v[208:211], v151 offset:54272
	ds_read_b128 v[212:215], v151 offset:55296
	ds_read_b128 v[216:219], v151 offset:56320
	global_load_lds_dwordx4 v[144:145], off
	s_add_i32 m0, s18, 0x2000
	s_add_u32 s18, s60, 0x40080
	v_lshl_add_u64 v[144:145], v[220:221], 0, s[10:11]
	s_addc_u32 s19, s61, 0
	s_add_i32 s60, s89, s66
	global_load_lds_dwordx4 v[144:145], off
	v_lshl_add_u64 v[144:145], s[18:19], 0, v[130:131]
	s_mov_b32 m0, s60
	s_nop 0
	global_load_lds_dwordx4 v[144:145], off
	v_lshl_add_u64 v[144:145], s[18:19], 0, v[134:135]
	s_add_i32 m0, s60, 0x2000
	s_nop 0
	global_load_lds_dwordx4 v[144:145], off
	v_lshl_add_u64 v[144:145], v[222:223], 0, s[10:11]
	s_mov_b32 m0, s71
	s_nop 0
	global_load_lds_dwordx4 v[144:145], off
	v_lshl_add_u64 v[144:145], v[224:225], 0, s[10:11]
	s_mov_b32 m0, s72
	s_nop 0
	global_load_lds_dwordx4 v[144:145], off
	s_waitcnt vmcnt(8)
	s_waitcnt lgkmcnt(0)
	s_barrier
	s_setprio 1
	s_waitcnt lgkmcnt(0)
	v_mfma_f32_16x16x32_bf16 v[60:63], v[152:155], v[188:191], v[60:63]
	v_mfma_f32_16x16x32_bf16 v[60:63], v[156:159], v[192:195], v[60:63]
	v_mfma_f32_16x16x32_bf16 v[56:59], v[160:163], v[188:191], v[56:59]
	v_mfma_f32_16x16x32_bf16 v[56:59], v[164:167], v[192:195], v[56:59]
	v_mfma_f32_16x16x32_bf16 v[52:55], v[152:155], v[196:199], v[52:55]
	v_mfma_f32_16x16x32_bf16 v[52:55], v[156:159], v[200:203], v[52:55]
	v_mfma_f32_16x16x32_bf16 v[44:47], v[160:163], v[196:199], v[44:47]
	v_mfma_f32_16x16x32_bf16 v[44:47], v[164:167], v[200:203], v[44:47]
	v_mfma_f32_16x16x32_bf16 v[36:39], v[152:155], v[204:207], v[36:39]
	v_mfma_f32_16x16x32_bf16 v[36:39], v[156:159], v[208:211], v[36:39]
	v_mfma_f32_16x16x32_bf16 v[28:31], v[160:163], v[204:207], v[28:31]
	v_mfma_f32_16x16x32_bf16 v[28:31], v[164:167], v[208:211], v[28:31]
	v_mfma_f32_16x16x32_bf16 v[20:23], v[152:155], v[212:215], v[20:23]
	v_mfma_f32_16x16x32_bf16 v[20:23], v[156:159], v[216:219], v[20:23]
	v_mfma_f32_16x16x32_bf16 v[12:15], v[160:163], v[212:215], v[12:15]
	v_mfma_f32_16x16x32_bf16 v[12:15], v[164:167], v[216:219], v[12:15]
	v_mfma_f32_16x16x32_bf16 v[48:51], v[168:171], v[188:191], v[48:51]
	v_mfma_f32_16x16x32_bf16 v[48:51], v[172:175], v[192:195], v[48:51]
	v_mfma_f32_16x16x32_bf16 v[40:43], v[176:179], v[188:191], v[40:43]
	v_mfma_f32_16x16x32_bf16 v[40:43], v[184:187], v[192:195], v[40:43]
	v_mfma_f32_16x16x32_bf16 v[32:35], v[168:171], v[196:199], v[32:35]
	v_mfma_f32_16x16x32_bf16 v[32:35], v[172:175], v[200:203], v[32:35]
	v_mfma_f32_16x16x32_bf16 v[24:27], v[176:179], v[196:199], v[24:27]
	v_mfma_f32_16x16x32_bf16 v[24:27], v[184:187], v[200:203], v[24:27]
	v_mfma_f32_16x16x32_bf16 v[16:19], v[168:171], v[204:207], v[16:19]
	v_mfma_f32_16x16x32_bf16 v[16:19], v[172:175], v[208:211], v[16:19]
	v_mfma_f32_16x16x32_bf16 v[8:11], v[176:179], v[204:207], v[8:11]
	v_mfma_f32_16x16x32_bf16 v[8:11], v[184:187], v[208:211], v[8:11]
	v_mfma_f32_16x16x32_bf16 v[4:7], v[168:171], v[212:215], v[4:7]
	v_mfma_f32_16x16x32_bf16 v[4:7], v[172:175], v[216:219], v[4:7]
	v_mfma_f32_16x16x32_bf16 v[0:3], v[176:179], v[212:215], v[0:3]
	v_mfma_f32_16x16x32_bf16 v[0:3], v[184:187], v[216:219], v[0:3]
	s_setprio 0
	s_barrier
	s_add_i32 s88, s88, 2
	s_add_u32 s58, s58, 0x100
	s_addc_u32 s59, s59, 0
	s_add_u32 s86, s86, 0x100
	s_addc_u32 s87, s87, 0
	s_cmp_gt_u32 s88, 13
	s_cbranch_scc0 .LBB0_601
	s_and_b64 vcc, exec, s[12:13]
	s_cbranch_vccz .LBB0_604
	s_barrier

.LBB0_723:
	s_ashr_i32 s31, s30, 31
	s_lshl_b64 s[36:37], s[30:31], 19
	s_add_u32 s36, s80, s36
	s_addc_u32 s37, s81, s37
	s_and_b64 s[44:45], s[10:11], exec
	s_cselect_b32 s31, s37, s49
	s_cselect_b32 s70, s36, s48
	s_ashr_i32 s19, s18, 31
	s_lshl_b64 s[44:45], s[18:19], 19
	s_add_u32 s44, s56, s44
	s_addc_u32 s45, s57, s45
	s_and_b64 s[54:55], s[10:11], exec
	s_cselect_b32 s19, s45, s53
	s_cselect_b32 s71, s44, s52
	s_add_u32 s48, s48, 0x40080
	s_addc_u32 s49, s49, 0
	s_add_u32 s72, s52, 0x100
	s_addc_u32 s73, s53, 0
	s_mov_b32 s74, -2
	ds_read_b128 v[140:143], v147
	ds_read_b128 v[150:153], v147 offset:1024
	ds_read_b128 v[154:157], v147 offset:2048
	ds_read_b128 v[158:161], v147 offset:3072
	ds_read_b128 v[162:165], v148
	ds_read_b128 v[166:169], v148 offset:1024
	ds_read_b128 v[170:173], v148 offset:2048
	ds_read_b128 v[174:177], v148 offset:3072
	s_add_u32 s52, s48, 0xfffc0080
	s_addc_u32 s53, s49, -1
	s_cmp_eq_u32 s74, 12
	s_cselect_b32 s55, s31, s53
	s_cselect_b32 s54, s70, s52
	s_cselect_b32 s53, s19, s73
	s_cselect_b32 s52, s71, s72
	v_lshl_add_u64 v[178:179], s[48:49], 0, v[132:133]
	s_add_i32 m0, s47, 0xc000
	ds_read_b128 v[184:187], v149
	ds_read_b128 v[188:191], v149 offset:1024
	ds_read_b128 v[192:195], v149 offset:2048
	ds_read_b128 v[196:199], v149 offset:3072
	ds_read_b128 v[200:203], v149 offset:4096
	ds_read_b128 v[204:207], v149 offset:5120
	ds_read_b128 v[208:211], v149 offset:6144
	ds_read_b128 v[212:215], v149 offset:7168
	global_load_lds_dwordx4 v[178:179], off
	v_lshl_add_u64 v[178:179], s[48:49], 0, v[134:135]
	s_add_i32 m0, s47, 0xe000
	s_nop 0
	global_load_lds_dwordx4 v[178:179], off
	s_waitcnt vmcnt(8)
	s_waitcnt lgkmcnt(0)
	s_barrier
	s_setprio 1
	s_waitcnt lgkmcnt(0)
	v_mfma_f32_16x16x32_bf16 v[124:127], v[140:143], v[184:187], 0
	v_mfma_f32_16x16x32_bf16 v[124:127], v[150:153], v[188:191], v[124:127]
	v_mfma_f32_16x16x32_bf16 v[120:123], v[154:157], v[184:187], 0
	v_mfma_f32_16x16x32_bf16 v[120:123], v[158:161], v[188:191], v[120:123]
	v_mfma_f32_16x16x32_bf16 v[108:111], v[140:143], v[192:195], 0
	v_mfma_f32_16x16x32_bf16 v[108:111], v[150:153], v[196:199], v[108:111]
	v_mfma_f32_16x16x32_bf16 v[104:107], v[154:157], v[192:195], 0
	v_mfma_f32_16x16x32_bf16 v[104:107], v[158:161], v[196:199], v[104:107]
	v_mfma_f32_16x16x32_bf16 v[92:95], v[140:143], v[200:203], 0
	v_mfma_f32_16x16x32_bf16 v[92:95], v[150:153], v[204:207], v[92:95]
	v_mfma_f32_16x16x32_bf16 v[88:91], v[154:157], v[200:203], 0
	v_mfma_f32_16x16x32_bf16 v[88:91], v[158:161], v[204:207], v[88:91]
	v_mfma_f32_16x16x32_bf16 v[76:79], v[140:143], v[208:211], 0
	v_mfma_f32_16x16x32_bf16 v[76:79], v[150:153], v[212:215], v[76:79]
	v_mfma_f32_16x16x32_bf16 v[72:75], v[154:157], v[208:211], 0
	v_mfma_f32_16x16x32_bf16 v[72:75], v[158:161], v[212:215], v[72:75]
	v_mfma_f32_16x16x32_bf16 v[116:119], v[162:165], v[184:187], 0
	v_mfma_f32_16x16x32_bf16 v[116:119], v[166:169], v[188:191], v[116:119]
	v_mfma_f32_16x16x32_bf16 v[112:115], v[170:173], v[184:187], 0
	v_mfma_f32_16x16x32_bf16 v[112:115], v[174:177], v[188:191], v[112:115]
	v_mfma_f32_16x16x32_bf16 v[100:103], v[162:165], v[192:195], 0
	v_mfma_f32_16x16x32_bf16 v[100:103], v[166:169], v[196:199], v[100:103]
	v_mfma_f32_16x16x32_bf16 v[96:99], v[170:173], v[192:195], 0
	v_mfma_f32_16x16x32_bf16 v[96:99], v[174:177], v[196:199], v[96:99]
	v_mfma_f32_16x16x32_bf16 v[84:87], v[162:165], v[200:203], 0
	v_mfma_f32_16x16x32_bf16 v[84:87], v[166:169], v[204:207], v[84:87]
	v_mfma_f32_16x16x32_bf16 v[80:83], v[170:173], v[200:203], 0
	v_mfma_f32_16x16x32_bf16 v[80:83], v[174:177], v[204:207], v[80:83]
	v_mfma_f32_16x16x32_bf16 v[68:71], v[162:165], v[208:211], 0
	v_mfma_f32_16x16x32_bf16 v[68:71], v[166:169], v[212:215], v[68:71]
	v_mfma_f32_16x16x32_bf16 v[64:67], v[170:173], v[208:211], 0
	v_mfma_f32_16x16x32_bf16 v[64:67], v[174:177], v[212:215], v[64:67]
	s_setprio 0
	s_barrier
	s_add_i32 s75, s66, s58
	v_lshl_add_u64 v[178:179], s[52:53], 0, v[130:131]
	s_mov_b32 m0, s75
	ds_read_b128 v[184:187], v149 offset:16384
	ds_read_b128 v[188:191], v149 offset:17408
	ds_read_b128 v[192:195], v149 offset:18432
	ds_read_b128 v[196:199], v149 offset:19456
	ds_read_b128 v[200:203], v149 offset:20480
	ds_read_b128 v[204:207], v149 offset:21504
	ds_read_b128 v[208:211], v149 offset:22528
	ds_read_b128 v[212:215], v149 offset:23552
	global_load_lds_dwordx4 v[178:179], off
	s_add_i32 m0, s75, 0x2000
	s_add_u32 s76, s52, 0x40000
	v_lshl_add_u64 v[216:217], s[52:53], 0, v[128:129]
	s_addc_u32 s77, s53, 0
	s_add_i32 s75, s67, s58
	global_load_lds_dwordx4 v[216:217], off
	v_lshl_add_u64 v[218:219], s[76:77], 0, v[130:131]
	s_mov_b32 m0, s75
	v_lshl_add_u64 v[220:221], s[54:55], 0, v[128:129]
	global_load_lds_dwordx4 v[218:219], off
	v_lshl_add_u64 v[218:219], s[76:77], 0, v[128:129]
	s_add_i32 m0, s75, 0x2000
	s_nop 0
	global_load_lds_dwordx4 v[218:219], off
	v_lshl_add_u64 v[218:219], s[54:55], 0, v[130:131]
	s_mov_b32 m0, s47
	s_nop 0
	global_load_lds_dwordx4 v[218:219], off
	s_mov_b32 m0, s60
	s_nop 0
	global_load_lds_dwordx4 v[220:221], off
	s_waitcnt vmcnt(8)
	s_waitcnt lgkmcnt(0)
	s_barrier
	s_setprio 1
	s_waitcnt lgkmcnt(0)
	v_mfma_f32_16x16x32_bf16 v[60:63], v[140:143], v[184:187], 0
	v_mfma_f32_16x16x32_bf16 v[60:63], v[150:153], v[188:191], v[60:63]
	v_mfma_f32_16x16x32_bf16 v[56:59], v[154:157], v[184:187], 0
	v_mfma_f32_16x16x32_bf16 v[56:59], v[158:161], v[188:191], v[56:59]
	v_mfma_f32_16x16x32_bf16 v[44:47], v[140:143], v[192:195], 0
	v_mfma_f32_16x16x32_bf16 v[44:47], v[150:153], v[196:199], v[44:47]
	v_mfma_f32_16x16x32_bf16 v[40:43], v[154:157], v[192:195], 0
	v_mfma_f32_16x16x32_bf16 v[40:43], v[158:161], v[196:199], v[40:43]
	v_mfma_f32_16x16x32_bf16 v[28:31], v[140:143], v[200:203], 0
	v_mfma_f32_16x16x32_bf16 v[28:31], v[150:153], v[204:207], v[28:31]
	v_mfma_f32_16x16x32_bf16 v[24:27], v[154:157], v[200:203], 0
	v_mfma_f32_16x16x32_bf16 v[24:27], v[158:161], v[204:207], v[24:27]
	v_mfma_f32_16x16x32_bf16 v[12:15], v[140:143], v[208:211], 0
	v_mfma_f32_16x16x32_bf16 v[12:15], v[150:153], v[212:215], v[12:15]
	v_mfma_f32_16x16x32_bf16 v[8:11], v[154:157], v[208:211], 0
	v_mfma_f32_16x16x32_bf16 v[8:11], v[158:161], v[212:215], v[8:11]
	v_mfma_f32_16x16x32_bf16 v[52:55], v[162:165], v[184:187], 0
	v_mfma_f32_16x16x32_bf16 v[52:55], v[166:169], v[188:191], v[52:55]
	v_mfma_f32_16x16x32_bf16 v[48:51], v[170:173], v[184:187], 0
	v_mfma_f32_16x16x32_bf16 v[48:51], v[174:177], v[188:191], v[48:51]
	v_mfma_f32_16x16x32_bf16 v[36:39], v[162:165], v[192:195], 0
	v_mfma_f32_16x16x32_bf16 v[36:39], v[166:169], v[196:199], v[36:39]
	v_mfma_f32_16x16x32_bf16 v[32:35], v[170:173], v[192:195], 0
	v_mfma_f32_16x16x32_bf16 v[32:35], v[174:177], v[196:199], v[32:35]
	v_mfma_f32_16x16x32_bf16 v[20:23], v[162:165], v[200:203], 0
	v_mfma_f32_16x16x32_bf16 v[20:23], v[166:169], v[204:207], v[20:23]
	v_mfma_f32_16x16x32_bf16 v[16:19], v[170:173], v[200:203], 0
	v_mfma_f32_16x16x32_bf16 v[16:19], v[174:177], v[204:207], v[16:19]
	v_mfma_f32_16x16x32_bf16 v[4:7], v[162:165], v[208:211], 0
	v_mfma_f32_16x16x32_bf16 v[4:7], v[166:169], v[212:215], v[4:7]
	v_mfma_f32_16x16x32_bf16 v[0:3], v[170:173], v[208:211], 0
	v_mfma_f32_16x16x32_bf16 v[0:3], v[174:177], v[212:215], v[0:3]
	s_setprio 0
	s_barrier
	s_branch .Lmid_gemm4
.LBB0_724:
	ds_read_b128 v[140:143], v147
	ds_read_b128 v[150:153], v147 offset:1024
	ds_read_b128 v[154:157], v147 offset:2048
	ds_read_b128 v[158:161], v147 offset:3072
	ds_read_b128 v[162:165], v148
	ds_read_b128 v[166:169], v148 offset:1024
	ds_read_b128 v[170:173], v148 offset:2048
	ds_read_b128 v[174:177], v148 offset:3072
	s_add_u32 s52, s48, 0xfffc0080
	s_addc_u32 s53, s49, -1
	s_cmp_eq_u32 s74, 12
	s_cselect_b32 s55, s31, s53
	s_cselect_b32 s54, s70, s52
	s_cselect_b32 s53, s19, s73
	s_cselect_b32 s52, s71, s72
	v_lshl_add_u64 v[178:179], s[48:49], 0, v[132:133]
	s_add_i32 m0, s47, 0xc000
	ds_read_b128 v[184:187], v149
	ds_read_b128 v[188:191], v149 offset:1024
	ds_read_b128 v[192:195], v149 offset:2048
	ds_read_b128 v[196:199], v149 offset:3072
	ds_read_b128 v[200:203], v149 offset:4096
	ds_read_b128 v[204:207], v149 offset:5120
	ds_read_b128 v[208:211], v149 offset:6144
	ds_read_b128 v[212:215], v149 offset:7168
	global_load_lds_dwordx4 v[178:179], off
	v_lshl_add_u64 v[178:179], s[48:49], 0, v[134:135]
	s_add_i32 m0, s47, 0xe000
	s_nop 0
	global_load_lds_dwordx4 v[178:179], off
	s_waitcnt vmcnt(8)
	s_waitcnt lgkmcnt(0)
	s_barrier
	s_setprio 1
	s_waitcnt lgkmcnt(0)
	v_mfma_f32_16x16x32_bf16 v[124:127], v[140:143], v[184:187], v[124:127]
	v_mfma_f32_16x16x32_bf16 v[124:127], v[150:153], v[188:191], v[124:127]
	v_mfma_f32_16x16x32_bf16 v[120:123], v[154:157], v[184:187], v[120:123]
	v_mfma_f32_16x16x32_bf16 v[120:123], v[158:161], v[188:191], v[120:123]
	v_mfma_f32_16x16x32_bf16 v[108:111], v[140:143], v[192:195], v[108:111]
	v_mfma_f32_16x16x32_bf16 v[108:111], v[150:153], v[196:199], v[108:111]
	v_mfma_f32_16x16x32_bf16 v[104:107], v[154:157], v[192:195], v[104:107]
	v_mfma_f32_16x16x32_bf16 v[104:107], v[158:161], v[196:199], v[104:107]
	v_mfma_f32_16x16x32_bf16 v[92:95], v[140:143], v[200:203], v[92:95]
	v_mfma_f32_16x16x32_bf16 v[92:95], v[150:153], v[204:207], v[92:95]
	v_mfma_f32_16x16x32_bf16 v[88:91], v[154:157], v[200:203], v[88:91]
	v_mfma_f32_16x16x32_bf16 v[88:91], v[158:161], v[204:207], v[88:91]
	v_mfma_f32_16x16x32_bf16 v[76:79], v[140:143], v[208:211], v[76:79]
	v_mfma_f32_16x16x32_bf16 v[76:79], v[150:153], v[212:215], v[76:79]
	v_mfma_f32_16x16x32_bf16 v[72:75], v[154:157], v[208:211], v[72:75]
	v_mfma_f32_16x16x32_bf16 v[72:75], v[158:161], v[212:215], v[72:75]
	v_mfma_f32_16x16x32_bf16 v[116:119], v[162:165], v[184:187], v[116:119]
	v_mfma_f32_16x16x32_bf16 v[116:119], v[166:169], v[188:191], v[116:119]
	v_mfma_f32_16x16x32_bf16 v[112:115], v[170:173], v[184:187], v[112:115]
	v_mfma_f32_16x16x32_bf16 v[112:115], v[174:177], v[188:191], v[112:115]
	v_mfma_f32_16x16x32_bf16 v[100:103], v[162:165], v[192:195], v[100:103]
	v_mfma_f32_16x16x32_bf16 v[100:103], v[166:169], v[196:199], v[100:103]
	v_mfma_f32_16x16x32_bf16 v[96:99], v[170:173], v[192:195], v[96:99]
	v_mfma_f32_16x16x32_bf16 v[96:99], v[174:177], v[196:199], v[96:99]
	v_mfma_f32_16x16x32_bf16 v[84:87], v[162:165], v[200:203], v[84:87]
	v_mfma_f32_16x16x32_bf16 v[84:87], v[166:169], v[204:207], v[84:87]
	v_mfma_f32_16x16x32_bf16 v[80:83], v[170:173], v[200:203], v[80:83]
	v_mfma_f32_16x16x32_bf16 v[80:83], v[174:177], v[204:207], v[80:83]
	v_mfma_f32_16x16x32_bf16 v[68:71], v[162:165], v[208:211], v[68:71]
	v_mfma_f32_16x16x32_bf16 v[68:71], v[166:169], v[212:215], v[68:71]
	v_mfma_f32_16x16x32_bf16 v[64:67], v[170:173], v[208:211], v[64:67]
	v_mfma_f32_16x16x32_bf16 v[64:67], v[174:177], v[212:215], v[64:67]
	s_setprio 0
	s_barrier
	s_add_i32 s75, s66, s58
	v_lshl_add_u64 v[178:179], s[52:53], 0, v[130:131]
	s_mov_b32 m0, s75
	ds_read_b128 v[184:187], v149 offset:16384
	ds_read_b128 v[188:191], v149 offset:17408
	ds_read_b128 v[192:195], v149 offset:18432
	ds_read_b128 v[196:199], v149 offset:19456
	ds_read_b128 v[200:203], v149 offset:20480
	ds_read_b128 v[204:207], v149 offset:21504
	ds_read_b128 v[208:211], v149 offset:22528
	ds_read_b128 v[212:215], v149 offset:23552
	global_load_lds_dwordx4 v[178:179], off
	s_add_i32 m0, s75, 0x2000
	s_add_u32 s76, s52, 0x40000
	v_lshl_add_u64 v[216:217], s[52:53], 0, v[128:129]
	s_addc_u32 s77, s53, 0
	s_add_i32 s75, s67, s58
	global_load_lds_dwordx4 v[216:217], off
	v_lshl_add_u64 v[218:219], s[76:77], 0, v[130:131]
	s_mov_b32 m0, s75
	v_lshl_add_u64 v[220:221], s[54:55], 0, v[128:129]
	global_load_lds_dwordx4 v[218:219], off
	v_lshl_add_u64 v[218:219], s[76:77], 0, v[128:129]
	s_add_i32 m0, s75, 0x2000
	s_nop 0
	global_load_lds_dwordx4 v[218:219], off
	v_lshl_add_u64 v[218:219], s[54:55], 0, v[130:131]
	s_mov_b32 m0, s47
	s_nop 0
	global_load_lds_dwordx4 v[218:219], off
	s_mov_b32 m0, s60
	s_nop 0
	global_load_lds_dwordx4 v[220:221], off
	s_waitcnt vmcnt(8)
	s_waitcnt lgkmcnt(0)
	s_barrier
	s_setprio 1
	s_waitcnt lgkmcnt(0)
	v_mfma_f32_16x16x32_bf16 v[60:63], v[140:143], v[184:187], v[60:63]
	v_mfma_f32_16x16x32_bf16 v[60:63], v[150:153], v[188:191], v[60:63]
	v_mfma_f32_16x16x32_bf16 v[56:59], v[154:157], v[184:187], v[56:59]
	v_mfma_f32_16x16x32_bf16 v[56:59], v[158:161], v[188:191], v[56:59]
	v_mfma_f32_16x16x32_bf16 v[44:47], v[140:143], v[192:195], v[44:47]
	v_mfma_f32_16x16x32_bf16 v[44:47], v[150:153], v[196:199], v[44:47]
	v_mfma_f32_16x16x32_bf16 v[40:43], v[154:157], v[192:195], v[40:43]
	v_mfma_f32_16x16x32_bf16 v[40:43], v[158:161], v[196:199], v[40:43]
	v_mfma_f32_16x16x32_bf16 v[28:31], v[140:143], v[200:203], v[28:31]
	v_mfma_f32_16x16x32_bf16 v[28:31], v[150:153], v[204:207], v[28:31]
	v_mfma_f32_16x16x32_bf16 v[24:27], v[154:157], v[200:203], v[24:27]
	v_mfma_f32_16x16x32_bf16 v[24:27], v[158:161], v[204:207], v[24:27]
	v_mfma_f32_16x16x32_bf16 v[12:15], v[140:143], v[208:211], v[12:15]
	v_mfma_f32_16x16x32_bf16 v[12:15], v[150:153], v[212:215], v[12:15]
	v_mfma_f32_16x16x32_bf16 v[8:11], v[154:157], v[208:211], v[8:11]
	v_mfma_f32_16x16x32_bf16 v[8:11], v[158:161], v[212:215], v[8:11]
	v_mfma_f32_16x16x32_bf16 v[52:55], v[162:165], v[184:187], v[52:55]
	v_mfma_f32_16x16x32_bf16 v[52:55], v[166:169], v[188:191], v[52:55]
	v_mfma_f32_16x16x32_bf16 v[48:51], v[170:173], v[184:187], v[48:51]
	v_mfma_f32_16x16x32_bf16 v[48:51], v[174:177], v[188:191], v[48:51]
	v_mfma_f32_16x16x32_bf16 v[36:39], v[162:165], v[192:195], v[36:39]
	v_mfma_f32_16x16x32_bf16 v[36:39], v[166:169], v[196:199], v[36:39]
	v_mfma_f32_16x16x32_bf16 v[32:35], v[170:173], v[192:195], v[32:35]
	v_mfma_f32_16x16x32_bf16 v[32:35], v[174:177], v[196:199], v[32:35]
	v_mfma_f32_16x16x32_bf16 v[20:23], v[162:165], v[200:203], v[20:23]
	v_mfma_f32_16x16x32_bf16 v[20:23], v[166:169], v[204:207], v[20:23]
	v_mfma_f32_16x16x32_bf16 v[16:19], v[170:173], v[200:203], v[16:19]
	v_mfma_f32_16x16x32_bf16 v[16:19], v[174:177], v[204:207], v[16:19]
	v_mfma_f32_16x16x32_bf16 v[4:7], v[162:165], v[208:211], v[4:7]
	v_mfma_f32_16x16x32_bf16 v[4:7], v[166:169], v[212:215], v[4:7]
	v_mfma_f32_16x16x32_bf16 v[0:3], v[170:173], v[208:211], v[0:3]
	v_mfma_f32_16x16x32_bf16 v[0:3], v[174:177], v[212:215], v[0:3]
	s_setprio 0
	s_barrier
.Lmid_gemm4:
	s_add_i32 s75, 0, 0x18000
	s_add_i32 s76, 0, 0x1c000
	v_add_u32_e32 v158, s75, v145
	v_add_u32_e32 v174, s76, v145
	ds_read_b128 v[140:143], v158
	ds_read_b128 v[150:153], v158 offset:1024
	ds_read_b128 v[154:157], v158 offset:2048
	ds_read_b128 v[158:161], v158 offset:3072
	ds_read_b128 v[162:165], v174
	ds_read_b128 v[166:169], v174 offset:1024
	ds_read_b128 v[170:173], v174 offset:2048
	ds_read_b128 v[174:177], v174 offset:3072
	s_add_u32 s54, s54, 0x40000
	s_addc_u32 s55, s55, 0
	s_mov_b32 m0, s61
	v_lshl_add_u64 v[222:223], s[54:55], 0, v[130:131]
	ds_read_b128 v[184:187], v149 offset:32768
	ds_read_b128 v[188:191], v149 offset:33792
	ds_read_b128 v[192:195], v149 offset:34816
	ds_read_b128 v[196:199], v149 offset:35840
	ds_read_b128 v[200:203], v149 offset:36864
	ds_read_b128 v[204:207], v149 offset:37888
	ds_read_b128 v[208:211], v149 offset:38912
	ds_read_b128 v[212:215], v149 offset:39936
	global_load_lds_dwordx4 v[222:223], off
	v_lshl_add_u64 v[222:223], s[54:55], 0, v[128:129]
	s_mov_b32 m0, s62
	s_nop 0
	global_load_lds_dwordx4 v[222:223], off
	s_waitcnt vmcnt(8)
	s_waitcnt lgkmcnt(0)
	s_barrier
	s_setprio 1
	s_waitcnt lgkmcnt(0)
	v_mfma_f32_16x16x32_bf16 v[124:127], v[140:143], v[184:187], v[124:127]
	v_mfma_f32_16x16x32_bf16 v[124:127], v[150:153], v[188:191], v[124:127]
	v_mfma_f32_16x16x32_bf16 v[120:123], v[154:157], v[184:187], v[120:123]
	v_mfma_f32_16x16x32_bf16 v[120:123], v[158:161], v[188:191], v[120:123]
	v_mfma_f32_16x16x32_bf16 v[108:111], v[140:143], v[192:195], v[108:111]
	v_mfma_f32_16x16x32_bf16 v[108:111], v[150:153], v[196:199], v[108:111]
	v_mfma_f32_16x16x32_bf16 v[104:107], v[154:157], v[192:195], v[104:107]
	v_mfma_f32_16x16x32_bf16 v[104:107], v[158:161], v[196:199], v[104:107]
	v_mfma_f32_16x16x32_bf16 v[92:95], v[140:143], v[200:203], v[92:95]
	v_mfma_f32_16x16x32_bf16 v[92:95], v[150:153], v[204:207], v[92:95]
	v_mfma_f32_16x16x32_bf16 v[88:91], v[154:157], v[200:203], v[88:91]
	v_mfma_f32_16x16x32_bf16 v[88:91], v[158:161], v[204:207], v[88:91]
	v_mfma_f32_16x16x32_bf16 v[76:79], v[140:143], v[208:211], v[76:79]
	v_mfma_f32_16x16x32_bf16 v[76:79], v[150:153], v[212:215], v[76:79]
	v_mfma_f32_16x16x32_bf16 v[72:75], v[154:157], v[208:211], v[72:75]
	v_mfma_f32_16x16x32_bf16 v[72:75], v[158:161], v[212:215], v[72:75]
	v_mfma_f32_16x16x32_bf16 v[116:119], v[162:165], v[184:187], v[116:119]
	v_mfma_f32_16x16x32_bf16 v[116:119], v[166:169], v[188:191], v[116:119]
	v_mfma_f32_16x16x32_bf16 v[112:115], v[170:173], v[184:187], v[112:115]
	v_mfma_f32_16x16x32_bf16 v[112:115], v[174:177], v[188:191], v[112:115]
	v_mfma_f32_16x16x32_bf16 v[100:103], v[162:165], v[192:195], v[100:103]
	v_mfma_f32_16x16x32_bf16 v[100:103], v[166:169], v[196:199], v[100:103]
	v_mfma_f32_16x16x32_bf16 v[96:99], v[170:173], v[192:195], v[96:99]
	v_mfma_f32_16x16x32_bf16 v[96:99], v[174:177], v[196:199], v[96:99]
	v_mfma_f32_16x16x32_bf16 v[84:87], v[162:165], v[200:203], v[84:87]
	v_mfma_f32_16x16x32_bf16 v[84:87], v[166:169], v[204:207], v[84:87]
	v_mfma_f32_16x16x32_bf16 v[80:83], v[170:173], v[200:203], v[80:83]
	v_mfma_f32_16x16x32_bf16 v[80:83], v[174:177], v[204:207], v[80:83]
	v_mfma_f32_16x16x32_bf16 v[68:71], v[162:165], v[208:211], v[68:71]
	v_mfma_f32_16x16x32_bf16 v[68:71], v[166:169], v[212:215], v[68:71]
	v_mfma_f32_16x16x32_bf16 v[64:67], v[170:173], v[208:211], v[64:67]
	v_mfma_f32_16x16x32_bf16 v[64:67], v[174:177], v[212:215], v[64:67]
	s_setprio 0
	s_barrier
	s_add_i32 s54, s75, s58
	v_lshl_add_u64 v[178:179], v[178:179], 0, s[12:13]
	s_mov_b32 m0, s54
	ds_read_b128 v[184:187], v149 offset:49152
	ds_read_b128 v[188:191], v149 offset:50176
	ds_read_b128 v[192:195], v149 offset:51200
	ds_read_b128 v[196:199], v149 offset:52224
	ds_read_b128 v[200:203], v149 offset:53248
	ds_read_b128 v[204:207], v149 offset:54272
	ds_read_b128 v[208:211], v149 offset:55296
	ds_read_b128 v[212:215], v149 offset:56320
	global_load_lds_dwordx4 v[178:179], off
	s_add_i32 m0, s54, 0x2000
	s_add_u32 s52, s52, 0x40080
	v_lshl_add_u64 v[178:179], v[216:217], 0, s[12:13]
	s_addc_u32 s53, s53, 0
	s_add_i32 s54, s76, s58
	global_load_lds_dwordx4 v[178:179], off
	v_lshl_add_u64 v[178:179], s[52:53], 0, v[130:131]
	s_mov_b32 m0, s54
	s_nop 0
	global_load_lds_dwordx4 v[178:179], off
	v_lshl_add_u64 v[178:179], s[52:53], 0, v[128:129]
	s_add_i32 m0, s54, 0x2000
	s_nop 0
	global_load_lds_dwordx4 v[178:179], off
	v_lshl_add_u64 v[178:179], v[218:219], 0, s[12:13]
	s_mov_b32 m0, s64
	s_nop 0
	global_load_lds_dwordx4 v[178:179], off
	v_lshl_add_u64 v[178:179], v[220:221], 0, s[12:13]
	s_mov_b32 m0, s65
	s_nop 0
	global_load_lds_dwordx4 v[178:179], off
	s_waitcnt vmcnt(8)
	s_waitcnt lgkmcnt(0)
	s_barrier
	s_setprio 1
	s_waitcnt lgkmcnt(0)
	v_mfma_f32_16x16x32_bf16 v[60:63], v[140:143], v[184:187], v[60:63]
	v_mfma_f32_16x16x32_bf16 v[60:63], v[150:153], v[188:191], v[60:63]
	v_mfma_f32_16x16x32_bf16 v[56:59], v[154:157], v[184:187], v[56:59]
	v_mfma_f32_16x16x32_bf16 v[56:59], v[158:161], v[188:191], v[56:59]
	v_mfma_f32_16x16x32_bf16 v[44:47], v[140:143], v[192:195], v[44:47]
	v_mfma_f32_16x16x32_bf16 v[44:47], v[150:153], v[196:199], v[44:47]
	v_mfma_f32_16x16x32_bf16 v[40:43], v[154:157], v[192:195], v[40:43]
	v_mfma_f32_16x16x32_bf16 v[40:43], v[158:161], v[196:199], v[40:43]
	v_mfma_f32_16x16x32_bf16 v[28:31], v[140:143], v[200:203], v[28:31]
	v_mfma_f32_16x16x32_bf16 v[28:31], v[150:153], v[204:207], v[28:31]
	v_mfma_f32_16x16x32_bf16 v[24:27], v[154:157], v[200:203], v[24:27]
	v_mfma_f32_16x16x32_bf16 v[24:27], v[158:161], v[204:207], v[24:27]
	v_mfma_f32_16x16x32_bf16 v[12:15], v[140:143], v[208:211], v[12:15]
	v_mfma_f32_16x16x32_bf16 v[12:15], v[150:153], v[212:215], v[12:15]
	v_mfma_f32_16x16x32_bf16 v[8:11], v[154:157], v[208:211], v[8:11]
	v_mfma_f32_16x16x32_bf16 v[8:11], v[158:161], v[212:215], v[8:11]
	v_mfma_f32_16x16x32_bf16 v[52:55], v[162:165], v[184:187], v[52:55]
	v_mfma_f32_16x16x32_bf16 v[52:55], v[166:169], v[188:191], v[52:55]
	v_mfma_f32_16x16x32_bf16 v[48:51], v[170:173], v[184:187], v[48:51]
	v_mfma_f32_16x16x32_bf16 v[48:51], v[174:177], v[188:191], v[48:51]
	v_mfma_f32_16x16x32_bf16 v[36:39], v[162:165], v[192:195], v[36:39]
	v_mfma_f32_16x16x32_bf16 v[36:39], v[166:169], v[196:199], v[36:39]
	v_mfma_f32_16x16x32_bf16 v[32:35], v[170:173], v[192:195], v[32:35]
	v_mfma_f32_16x16x32_bf16 v[32:35], v[174:177], v[196:199], v[32:35]
	v_mfma_f32_16x16x32_bf16 v[20:23], v[162:165], v[200:203], v[20:23]
	v_mfma_f32_16x16x32_bf16 v[20:23], v[166:169], v[204:207], v[20:23]
	v_mfma_f32_16x16x32_bf16 v[16:19], v[170:173], v[200:203], v[16:19]
	v_mfma_f32_16x16x32_bf16 v[16:19], v[174:177], v[204:207], v[16:19]
	v_mfma_f32_16x16x32_bf16 v[4:7], v[162:165], v[208:211], v[4:7]
	v_mfma_f32_16x16x32_bf16 v[4:7], v[166:169], v[212:215], v[4:7]
	v_mfma_f32_16x16x32_bf16 v[0:3], v[170:173], v[208:211], v[0:3]
	v_mfma_f32_16x16x32_bf16 v[0:3], v[174:177], v[212:215], v[0:3]
	s_setprio 0
	s_barrier
	s_add_i32 s74, s74, 2
	s_add_u32 s48, s48, 0x100
	s_addc_u32 s49, s49, 0
	s_add_u32 s72, s72, 0x100
	s_addc_u32 s73, s73, 0
	s_cmp_gt_u32 s74, 13
	s_cbranch_scc0 .LBB0_724
	s_and_b64 vcc, exec, s[16:17]
	s_cbranch_vccz .LBB0_727
	s_barrier

.LBB0_803:
	s_add_u32 s84, s54, 0x100
	s_addc_u32 s85, s55, 0
	s_mov_b32 s86, -2
	ds_read_b128 v[152:155], v149
	ds_read_b128 v[156:159], v149 offset:1024
	ds_read_b128 v[160:163], v149 offset:2048
	ds_read_b128 v[164:167], v149 offset:3072
	ds_read_b128 v[168:171], v150
	ds_read_b128 v[172:175], v150 offset:1024
	ds_read_b128 v[176:179], v150 offset:2048
	ds_read_b128 v[184:187], v150 offset:3072
	s_add_u32 s54, s52, 0x100
	s_addc_u32 s55, s53, 0
	s_cmp_eq_u32 s86, 40
	s_cselect_b32 s59, s13, s55
	s_cselect_b32 s58, s12, s54
	s_cselect_b32 s57, s49, s85
	s_cselect_b32 s56, s48, s84
	v_lshl_add_u64 v[144:145], s[52:53], 0, v[136:137]
	s_add_i32 m0, s63, 0xc000
	ds_read_b128 v[188:191], v151
	ds_read_b128 v[192:195], v151 offset:1024
	ds_read_b128 v[196:199], v151 offset:2048
	ds_read_b128 v[200:203], v151 offset:3072
	ds_read_b128 v[204:207], v151 offset:4096
	ds_read_b128 v[208:211], v151 offset:5120
	ds_read_b128 v[212:215], v151 offset:6144
	ds_read_b128 v[216:219], v151 offset:7168
	global_load_lds_dwordx4 v[144:145], off
	v_lshl_add_u64 v[144:145], s[52:53], 0, v[138:139]
	s_add_i32 m0, s63, 0xe000
	s_nop 0
	global_load_lds_dwordx4 v[144:145], off
	s_waitcnt vmcnt(8)
	s_waitcnt lgkmcnt(0)
	s_barrier
	s_setprio 1
	s_waitcnt lgkmcnt(0)
	v_mfma_f32_16x16x32_bf16 v[124:127], v[152:155], v[188:191], 0
	v_mfma_f32_16x16x32_bf16 v[124:127], v[156:159], v[192:195], v[124:127]
	v_mfma_f32_16x16x32_bf16 v[120:123], v[160:163], v[188:191], 0
	v_mfma_f32_16x16x32_bf16 v[120:123], v[164:167], v[192:195], v[120:123]
	v_mfma_f32_16x16x32_bf16 v[116:119], v[152:155], v[196:199], 0
	v_mfma_f32_16x16x32_bf16 v[116:119], v[156:159], v[200:203], v[116:119]
	v_mfma_f32_16x16x32_bf16 v[108:111], v[160:163], v[196:199], 0
	v_mfma_f32_16x16x32_bf16 v[108:111], v[164:167], v[200:203], v[108:111]
	v_mfma_f32_16x16x32_bf16 v[100:103], v[152:155], v[204:207], 0
	v_mfma_f32_16x16x32_bf16 v[100:103], v[156:159], v[208:211], v[100:103]
	v_mfma_f32_16x16x32_bf16 v[92:95], v[160:163], v[204:207], 0
	v_mfma_f32_16x16x32_bf16 v[92:95], v[164:167], v[208:211], v[92:95]
	v_mfma_f32_16x16x32_bf16 v[84:87], v[152:155], v[212:215], 0
	v_mfma_f32_16x16x32_bf16 v[84:87], v[156:159], v[216:219], v[84:87]
	v_mfma_f32_16x16x32_bf16 v[76:79], v[160:163], v[212:215], 0
	v_mfma_f32_16x16x32_bf16 v[76:79], v[164:167], v[216:219], v[76:79]
	v_mfma_f32_16x16x32_bf16 v[112:115], v[168:171], v[188:191], 0
	v_mfma_f32_16x16x32_bf16 v[112:115], v[172:175], v[192:195], v[112:115]
	v_mfma_f32_16x16x32_bf16 v[104:107], v[176:179], v[188:191], 0
	v_mfma_f32_16x16x32_bf16 v[104:107], v[184:187], v[192:195], v[104:107]
	v_mfma_f32_16x16x32_bf16 v[96:99], v[168:171], v[196:199], 0
	v_mfma_f32_16x16x32_bf16 v[96:99], v[172:175], v[200:203], v[96:99]
	v_mfma_f32_16x16x32_bf16 v[88:91], v[176:179], v[196:199], 0
	v_mfma_f32_16x16x32_bf16 v[88:91], v[184:187], v[200:203], v[88:91]
	v_mfma_f32_16x16x32_bf16 v[80:83], v[168:171], v[204:207], 0
	v_mfma_f32_16x16x32_bf16 v[80:83], v[172:175], v[208:211], v[80:83]
	v_mfma_f32_16x16x32_bf16 v[72:75], v[176:179], v[204:207], 0
	v_mfma_f32_16x16x32_bf16 v[72:75], v[184:187], v[208:211], v[72:75]
	v_mfma_f32_16x16x32_bf16 v[68:71], v[168:171], v[212:215], 0
	v_mfma_f32_16x16x32_bf16 v[68:71], v[172:175], v[216:219], v[68:71]
	v_mfma_f32_16x16x32_bf16 v[64:67], v[176:179], v[212:215], 0
	v_mfma_f32_16x16x32_bf16 v[64:67], v[184:187], v[216:219], v[64:67]
	s_setprio 0
	s_barrier
	s_add_i32 s52, s70, s62
	v_lshl_add_u64 v[144:145], s[56:57], 0, v[130:131]
	s_mov_b32 m0, s52
	ds_read_b128 v[188:191], v151 offset:16384
	ds_read_b128 v[192:195], v151 offset:17408
	ds_read_b128 v[196:199], v151 offset:18432
	ds_read_b128 v[200:203], v151 offset:19456
	ds_read_b128 v[204:207], v151 offset:20480
	ds_read_b128 v[208:211], v151 offset:21504
	ds_read_b128 v[212:215], v151 offset:22528
	ds_read_b128 v[216:219], v151 offset:23552
	global_load_lds_dwordx4 v[144:145], off
	s_add_i32 m0, s52, 0x2000
	s_add_u32 s52, s56, 0xb0000
	v_lshl_add_u64 v[220:221], s[56:57], 0, v[134:135]
	s_addc_u32 s53, s57, 0
	s_add_i32 s79, s71, s62
	global_load_lds_dwordx4 v[220:221], off
	v_lshl_add_u64 v[222:223], s[52:53], 0, v[130:131]
	s_mov_b32 m0, s79
	v_lshl_add_u64 v[224:225], s[58:59], 0, v[132:133]
	global_load_lds_dwordx4 v[222:223], off
	v_lshl_add_u64 v[222:223], s[52:53], 0, v[134:135]
	s_add_i32 m0, s79, 0x2000
	s_nop 0
	global_load_lds_dwordx4 v[222:223], off
	v_lshl_add_u64 v[222:223], s[58:59], 0, v[128:129]
	s_mov_b32 m0, s63
	s_nop 0
	global_load_lds_dwordx4 v[222:223], off
	s_mov_b32 m0, s64
	s_nop 0
	global_load_lds_dwordx4 v[224:225], off
	s_waitcnt vmcnt(8)
	s_waitcnt lgkmcnt(0)
	s_barrier
	s_setprio 1
	s_waitcnt lgkmcnt(0)
	v_mfma_f32_16x16x32_bf16 v[60:63], v[152:155], v[188:191], 0
	v_mfma_f32_16x16x32_bf16 v[60:63], v[156:159], v[192:195], v[60:63]
	v_mfma_f32_16x16x32_bf16 v[56:59], v[160:163], v[188:191], 0
	v_mfma_f32_16x16x32_bf16 v[56:59], v[164:167], v[192:195], v[56:59]
	v_mfma_f32_16x16x32_bf16 v[52:55], v[152:155], v[196:199], 0
	v_mfma_f32_16x16x32_bf16 v[52:55], v[156:159], v[200:203], v[52:55]
	v_mfma_f32_16x16x32_bf16 v[44:47], v[160:163], v[196:199], 0
	v_mfma_f32_16x16x32_bf16 v[44:47], v[164:167], v[200:203], v[44:47]
	v_mfma_f32_16x16x32_bf16 v[36:39], v[152:155], v[204:207], 0
	v_mfma_f32_16x16x32_bf16 v[36:39], v[156:159], v[208:211], v[36:39]
	v_mfma_f32_16x16x32_bf16 v[28:31], v[160:163], v[204:207], 0
	v_mfma_f32_16x16x32_bf16 v[28:31], v[164:167], v[208:211], v[28:31]
	v_mfma_f32_16x16x32_bf16 v[20:23], v[152:155], v[212:215], 0
	v_mfma_f32_16x16x32_bf16 v[20:23], v[156:159], v[216:219], v[20:23]
	v_mfma_f32_16x16x32_bf16 v[12:15], v[160:163], v[212:215], 0
	v_mfma_f32_16x16x32_bf16 v[12:15], v[164:167], v[216:219], v[12:15]
	v_mfma_f32_16x16x32_bf16 v[48:51], v[168:171], v[188:191], 0
	v_mfma_f32_16x16x32_bf16 v[48:51], v[172:175], v[192:195], v[48:51]
	v_mfma_f32_16x16x32_bf16 v[40:43], v[176:179], v[188:191], 0
	v_mfma_f32_16x16x32_bf16 v[40:43], v[184:187], v[192:195], v[40:43]
	v_mfma_f32_16x16x32_bf16 v[32:35], v[168:171], v[196:199], 0
	v_mfma_f32_16x16x32_bf16 v[32:35], v[172:175], v[200:203], v[32:35]
	v_mfma_f32_16x16x32_bf16 v[24:27], v[176:179], v[196:199], 0
	v_mfma_f32_16x16x32_bf16 v[24:27], v[184:187], v[200:203], v[24:27]
	v_mfma_f32_16x16x32_bf16 v[16:19], v[168:171], v[204:207], 0
	v_mfma_f32_16x16x32_bf16 v[16:19], v[172:175], v[208:211], v[16:19]
	v_mfma_f32_16x16x32_bf16 v[8:11], v[176:179], v[204:207], 0
	v_mfma_f32_16x16x32_bf16 v[8:11], v[184:187], v[208:211], v[8:11]
	v_mfma_f32_16x16x32_bf16 v[4:7], v[168:171], v[212:215], 0
	v_mfma_f32_16x16x32_bf16 v[4:7], v[172:175], v[216:219], v[4:7]
	v_mfma_f32_16x16x32_bf16 v[0:3], v[176:179], v[212:215], 0
	v_mfma_f32_16x16x32_bf16 v[0:3], v[184:187], v[216:219], v[0:3]
	s_setprio 0
	s_barrier
	s_branch .Lmid_gemm5
.LBB0_804:
	ds_read_b128 v[152:155], v149
	ds_read_b128 v[156:159], v149 offset:1024
	ds_read_b128 v[160:163], v149 offset:2048
	ds_read_b128 v[164:167], v149 offset:3072
	ds_read_b128 v[168:171], v150
	ds_read_b128 v[172:175], v150 offset:1024
	ds_read_b128 v[176:179], v150 offset:2048
	ds_read_b128 v[184:187], v150 offset:3072
	s_add_u32 s54, s52, 0x100
	s_addc_u32 s55, s53, 0
	s_cmp_eq_u32 s86, 40
	s_cselect_b32 s59, s13, s55
	s_cselect_b32 s58, s12, s54
	s_cselect_b32 s57, s49, s85
	s_cselect_b32 s56, s48, s84
	v_lshl_add_u64 v[144:145], s[52:53], 0, v[136:137]
	s_add_i32 m0, s63, 0xc000
	ds_read_b128 v[188:191], v151
	ds_read_b128 v[192:195], v151 offset:1024
	ds_read_b128 v[196:199], v151 offset:2048
	ds_read_b128 v[200:203], v151 offset:3072
	ds_read_b128 v[204:207], v151 offset:4096
	ds_read_b128 v[208:211], v151 offset:5120
	ds_read_b128 v[212:215], v151 offset:6144
	ds_read_b128 v[216:219], v151 offset:7168
	global_load_lds_dwordx4 v[144:145], off
	v_lshl_add_u64 v[144:145], s[52:53], 0, v[138:139]
	s_add_i32 m0, s63, 0xe000
	s_nop 0
	global_load_lds_dwordx4 v[144:145], off
	s_waitcnt vmcnt(8)
	s_waitcnt lgkmcnt(0)
	s_barrier
	s_setprio 1
	s_waitcnt lgkmcnt(0)
	v_mfma_f32_16x16x32_bf16 v[124:127], v[152:155], v[188:191], v[124:127]
	v_mfma_f32_16x16x32_bf16 v[124:127], v[156:159], v[192:195], v[124:127]
	v_mfma_f32_16x16x32_bf16 v[120:123], v[160:163], v[188:191], v[120:123]
	v_mfma_f32_16x16x32_bf16 v[120:123], v[164:167], v[192:195], v[120:123]
	v_mfma_f32_16x16x32_bf16 v[116:119], v[152:155], v[196:199], v[116:119]
	v_mfma_f32_16x16x32_bf16 v[116:119], v[156:159], v[200:203], v[116:119]
	v_mfma_f32_16x16x32_bf16 v[108:111], v[160:163], v[196:199], v[108:111]
	v_mfma_f32_16x16x32_bf16 v[108:111], v[164:167], v[200:203], v[108:111]
	v_mfma_f32_16x16x32_bf16 v[100:103], v[152:155], v[204:207], v[100:103]
	v_mfma_f32_16x16x32_bf16 v[100:103], v[156:159], v[208:211], v[100:103]
	v_mfma_f32_16x16x32_bf16 v[92:95], v[160:163], v[204:207], v[92:95]
	v_mfma_f32_16x16x32_bf16 v[92:95], v[164:167], v[208:211], v[92:95]
	v_mfma_f32_16x16x32_bf16 v[84:87], v[152:155], v[212:215], v[84:87]
	v_mfma_f32_16x16x32_bf16 v[84:87], v[156:159], v[216:219], v[84:87]
	v_mfma_f32_16x16x32_bf16 v[76:79], v[160:163], v[212:215], v[76:79]
	v_mfma_f32_16x16x32_bf16 v[76:79], v[164:167], v[216:219], v[76:79]
	v_mfma_f32_16x16x32_bf16 v[112:115], v[168:171], v[188:191], v[112:115]
	v_mfma_f32_16x16x32_bf16 v[112:115], v[172:175], v[192:195], v[112:115]
	v_mfma_f32_16x16x32_bf16 v[104:107], v[176:179], v[188:191], v[104:107]
	v_mfma_f32_16x16x32_bf16 v[104:107], v[184:187], v[192:195], v[104:107]
	v_mfma_f32_16x16x32_bf16 v[96:99], v[168:171], v[196:199], v[96:99]
	v_mfma_f32_16x16x32_bf16 v[96:99], v[172:175], v[200:203], v[96:99]
	v_mfma_f32_16x16x32_bf16 v[88:91], v[176:179], v[196:199], v[88:91]
	v_mfma_f32_16x16x32_bf16 v[88:91], v[184:187], v[200:203], v[88:91]
	v_mfma_f32_16x16x32_bf16 v[80:83], v[168:171], v[204:207], v[80:83]
	v_mfma_f32_16x16x32_bf16 v[80:83], v[172:175], v[208:211], v[80:83]
	v_mfma_f32_16x16x32_bf16 v[72:75], v[176:179], v[204:207], v[72:75]
	v_mfma_f32_16x16x32_bf16 v[72:75], v[184:187], v[208:211], v[72:75]
	v_mfma_f32_16x16x32_bf16 v[68:71], v[168:171], v[212:215], v[68:71]
	v_mfma_f32_16x16x32_bf16 v[68:71], v[172:175], v[216:219], v[68:71]
	v_mfma_f32_16x16x32_bf16 v[64:67], v[176:179], v[212:215], v[64:67]
	v_mfma_f32_16x16x32_bf16 v[64:67], v[184:187], v[216:219], v[64:67]
	s_setprio 0
	s_barrier
	s_add_i32 s52, s70, s62
	v_lshl_add_u64 v[144:145], s[56:57], 0, v[130:131]
	s_mov_b32 m0, s52
	ds_read_b128 v[188:191], v151 offset:16384
	ds_read_b128 v[192:195], v151 offset:17408
	ds_read_b128 v[196:199], v151 offset:18432
	ds_read_b128 v[200:203], v151 offset:19456
	ds_read_b128 v[204:207], v151 offset:20480
	ds_read_b128 v[208:211], v151 offset:21504
	ds_read_b128 v[212:215], v151 offset:22528
	ds_read_b128 v[216:219], v151 offset:23552
	global_load_lds_dwordx4 v[144:145], off
	s_add_i32 m0, s52, 0x2000
	s_add_u32 s52, s56, 0xb0000
	v_lshl_add_u64 v[220:221], s[56:57], 0, v[134:135]
	s_addc_u32 s53, s57, 0
	s_add_i32 s79, s71, s62
	global_load_lds_dwordx4 v[220:221], off
	v_lshl_add_u64 v[222:223], s[52:53], 0, v[130:131]
	s_mov_b32 m0, s79
	v_lshl_add_u64 v[224:225], s[58:59], 0, v[132:133]
	global_load_lds_dwordx4 v[222:223], off
	v_lshl_add_u64 v[222:223], s[52:53], 0, v[134:135]
	s_add_i32 m0, s79, 0x2000
	s_nop 0
	global_load_lds_dwordx4 v[222:223], off
	v_lshl_add_u64 v[222:223], s[58:59], 0, v[128:129]
	s_mov_b32 m0, s63
	s_nop 0
	global_load_lds_dwordx4 v[222:223], off
	s_mov_b32 m0, s64
	s_nop 0
	global_load_lds_dwordx4 v[224:225], off
	s_waitcnt vmcnt(8)
	s_waitcnt lgkmcnt(0)
	s_barrier
	s_setprio 1
	s_waitcnt lgkmcnt(0)
	v_mfma_f32_16x16x32_bf16 v[60:63], v[152:155], v[188:191], v[60:63]
	v_mfma_f32_16x16x32_bf16 v[60:63], v[156:159], v[192:195], v[60:63]
	v_mfma_f32_16x16x32_bf16 v[56:59], v[160:163], v[188:191], v[56:59]
	v_mfma_f32_16x16x32_bf16 v[56:59], v[164:167], v[192:195], v[56:59]
	v_mfma_f32_16x16x32_bf16 v[52:55], v[152:155], v[196:199], v[52:55]
	v_mfma_f32_16x16x32_bf16 v[52:55], v[156:159], v[200:203], v[52:55]
	v_mfma_f32_16x16x32_bf16 v[44:47], v[160:163], v[196:199], v[44:47]
	v_mfma_f32_16x16x32_bf16 v[44:47], v[164:167], v[200:203], v[44:47]
	v_mfma_f32_16x16x32_bf16 v[36:39], v[152:155], v[204:207], v[36:39]
	v_mfma_f32_16x16x32_bf16 v[36:39], v[156:159], v[208:211], v[36:39]
	v_mfma_f32_16x16x32_bf16 v[28:31], v[160:163], v[204:207], v[28:31]
	v_mfma_f32_16x16x32_bf16 v[28:31], v[164:167], v[208:211], v[28:31]
	v_mfma_f32_16x16x32_bf16 v[20:23], v[152:155], v[212:215], v[20:23]
	v_mfma_f32_16x16x32_bf16 v[20:23], v[156:159], v[216:219], v[20:23]
	v_mfma_f32_16x16x32_bf16 v[12:15], v[160:163], v[212:215], v[12:15]
	v_mfma_f32_16x16x32_bf16 v[12:15], v[164:167], v[216:219], v[12:15]
	v_mfma_f32_16x16x32_bf16 v[48:51], v[168:171], v[188:191], v[48:51]
	v_mfma_f32_16x16x32_bf16 v[48:51], v[172:175], v[192:195], v[48:51]
	v_mfma_f32_16x16x32_bf16 v[40:43], v[176:179], v[188:191], v[40:43]
	v_mfma_f32_16x16x32_bf16 v[40:43], v[184:187], v[192:195], v[40:43]
	v_mfma_f32_16x16x32_bf16 v[32:35], v[168:171], v[196:199], v[32:35]
	v_mfma_f32_16x16x32_bf16 v[32:35], v[172:175], v[200:203], v[32:35]
	v_mfma_f32_16x16x32_bf16 v[24:27], v[176:179], v[196:199], v[24:27]
	v_mfma_f32_16x16x32_bf16 v[24:27], v[184:187], v[200:203], v[24:27]
	v_mfma_f32_16x16x32_bf16 v[16:19], v[168:171], v[204:207], v[16:19]
	v_mfma_f32_16x16x32_bf16 v[16:19], v[172:175], v[208:211], v[16:19]
	v_mfma_f32_16x16x32_bf16 v[8:11], v[176:179], v[204:207], v[8:11]
	v_mfma_f32_16x16x32_bf16 v[8:11], v[184:187], v[208:211], v[8:11]
	v_mfma_f32_16x16x32_bf16 v[4:7], v[168:171], v[212:215], v[4:7]
	v_mfma_f32_16x16x32_bf16 v[4:7], v[172:175], v[216:219], v[4:7]
	v_mfma_f32_16x16x32_bf16 v[0:3], v[176:179], v[212:215], v[0:3]
	v_mfma_f32_16x16x32_bf16 v[0:3], v[184:187], v[216:219], v[0:3]
	s_setprio 0
	s_barrier
.Lmid_gemm5:
	s_add_i32 s79, 0, 0x18000
	s_add_i32 s87, 0, 0x1c000
	v_add_u32_e32 v164, s79, v147
	v_add_u32_e32 v181, s87, v147
	ds_read_b128 v[152:155], v164
	ds_read_b128 v[156:159], v164 offset:1024
	ds_read_b128 v[160:163], v164 offset:2048
	ds_read_b128 v[164:167], v164 offset:3072
	ds_read_b128 v[168:171], v181
	ds_read_b128 v[172:175], v181 offset:1024
	ds_read_b128 v[176:179], v181 offset:2048
	ds_read_b128 v[184:187], v181 offset:3072
	s_add_u32 s52, s58, 0xb0000
	s_addc_u32 s53, s59, 0
	s_mov_b32 m0, s65
	v_lshl_add_u64 v[226:227], s[52:53], 0, v[128:129]
	ds_read_b128 v[188:191], v151 offset:32768
	ds_read_b128 v[192:195], v151 offset:33792
	ds_read_b128 v[196:199], v151 offset:34816
	ds_read_b128 v[200:203], v151 offset:35840
	ds_read_b128 v[204:207], v151 offset:36864
	ds_read_b128 v[208:211], v151 offset:37888
	ds_read_b128 v[212:215], v151 offset:38912
	ds_read_b128 v[216:219], v151 offset:39936
	global_load_lds_dwordx4 v[226:227], off
	v_lshl_add_u64 v[226:227], s[52:53], 0, v[132:133]
	s_mov_b32 m0, s66
	s_nop 0
	global_load_lds_dwordx4 v[226:227], off
	s_waitcnt vmcnt(8)
	s_waitcnt lgkmcnt(0)
	s_barrier
	s_setprio 1
	s_waitcnt lgkmcnt(0)
	v_mfma_f32_16x16x32_bf16 v[124:127], v[152:155], v[188:191], v[124:127]
	v_mfma_f32_16x16x32_bf16 v[124:127], v[156:159], v[192:195], v[124:127]
	v_mfma_f32_16x16x32_bf16 v[120:123], v[160:163], v[188:191], v[120:123]
	v_mfma_f32_16x16x32_bf16 v[120:123], v[164:167], v[192:195], v[120:123]
	v_mfma_f32_16x16x32_bf16 v[116:119], v[152:155], v[196:199], v[116:119]
	v_mfma_f32_16x16x32_bf16 v[116:119], v[156:159], v[200:203], v[116:119]
	v_mfma_f32_16x16x32_bf16 v[108:111], v[160:163], v[196:199], v[108:111]
	v_mfma_f32_16x16x32_bf16 v[108:111], v[164:167], v[200:203], v[108:111]
	v_mfma_f32_16x16x32_bf16 v[100:103], v[152:155], v[204:207], v[100:103]
	v_mfma_f32_16x16x32_bf16 v[100:103], v[156:159], v[208:211], v[100:103]
	v_mfma_f32_16x16x32_bf16 v[92:95], v[160:163], v[204:207], v[92:95]
	v_mfma_f32_16x16x32_bf16 v[92:95], v[164:167], v[208:211], v[92:95]
	v_mfma_f32_16x16x32_bf16 v[84:87], v[152:155], v[212:215], v[84:87]
	v_mfma_f32_16x16x32_bf16 v[84:87], v[156:159], v[216:219], v[84:87]
	v_mfma_f32_16x16x32_bf16 v[76:79], v[160:163], v[212:215], v[76:79]
	v_mfma_f32_16x16x32_bf16 v[76:79], v[164:167], v[216:219], v[76:79]
	v_mfma_f32_16x16x32_bf16 v[112:115], v[168:171], v[188:191], v[112:115]
	v_mfma_f32_16x16x32_bf16 v[112:115], v[172:175], v[192:195], v[112:115]
	v_mfma_f32_16x16x32_bf16 v[104:107], v[176:179], v[188:191], v[104:107]
	v_mfma_f32_16x16x32_bf16 v[104:107], v[184:187], v[192:195], v[104:107]
	v_mfma_f32_16x16x32_bf16 v[96:99], v[168:171], v[196:199], v[96:99]
	v_mfma_f32_16x16x32_bf16 v[96:99], v[172:175], v[200:203], v[96:99]
	v_mfma_f32_16x16x32_bf16 v[88:91], v[176:179], v[196:199], v[88:91]
	v_mfma_f32_16x16x32_bf16 v[88:91], v[184:187], v[200:203], v[88:91]
	v_mfma_f32_16x16x32_bf16 v[80:83], v[168:171], v[204:207], v[80:83]
	v_mfma_f32_16x16x32_bf16 v[80:83], v[172:175], v[208:211], v[80:83]
	v_mfma_f32_16x16x32_bf16 v[72:75], v[176:179], v[204:207], v[72:75]
	v_mfma_f32_16x16x32_bf16 v[72:75], v[184:187], v[208:211], v[72:75]
	v_mfma_f32_16x16x32_bf16 v[68:71], v[168:171], v[212:215], v[68:71]
	v_mfma_f32_16x16x32_bf16 v[68:71], v[172:175], v[216:219], v[68:71]
	v_mfma_f32_16x16x32_bf16 v[64:67], v[176:179], v[212:215], v[64:67]
	v_mfma_f32_16x16x32_bf16 v[64:67], v[184:187], v[216:219], v[64:67]
	s_setprio 0
	s_barrier
	s_add_i32 s52, s79, s62
	v_lshl_add_u64 v[144:145], v[144:145], 0, s[16:17]
	s_mov_b32 m0, s52
	ds_read_b128 v[188:191], v151 offset:49152
	ds_read_b128 v[192:195], v151 offset:50176
	ds_read_b128 v[196:199], v151 offset:51200
	ds_read_b128 v[200:203], v151 offset:52224
	ds_read_b128 v[204:207], v151 offset:53248
	ds_read_b128 v[208:211], v151 offset:54272
	ds_read_b128 v[212:215], v151 offset:55296
	ds_read_b128 v[216:219], v151 offset:56320
	global_load_lds_dwordx4 v[144:145], off
	s_add_i32 m0, s52, 0x2000
	s_add_u32 s52, s56, 0xb0080
	v_lshl_add_u64 v[144:145], v[220:221], 0, s[16:17]
	s_addc_u32 s53, s57, 0
	s_add_i32 s56, s87, s62
	global_load_lds_dwordx4 v[144:145], off
	v_lshl_add_u64 v[144:145], s[52:53], 0, v[130:131]
	s_mov_b32 m0, s56
	s_nop 0
	global_load_lds_dwordx4 v[144:145], off
	v_lshl_add_u64 v[144:145], s[52:53], 0, v[134:135]
	s_add_i32 m0, s56, 0x2000
	s_nop 0
	global_load_lds_dwordx4 v[144:145], off
	v_lshl_add_u64 v[144:145], v[222:223], 0, s[16:17]
	s_mov_b32 m0, s68
	s_nop 0
	global_load_lds_dwordx4 v[144:145], off
	v_lshl_add_u64 v[144:145], v[224:225], 0, s[16:17]
	s_mov_b32 m0, s69
	s_nop 0
	global_load_lds_dwordx4 v[144:145], off
	s_waitcnt vmcnt(8)
	s_waitcnt lgkmcnt(0)
	s_barrier
	s_setprio 1
	s_waitcnt lgkmcnt(0)
	v_mfma_f32_16x16x32_bf16 v[60:63], v[152:155], v[188:191], v[60:63]
	v_mfma_f32_16x16x32_bf16 v[60:63], v[156:159], v[192:195], v[60:63]
	v_mfma_f32_16x16x32_bf16 v[56:59], v[160:163], v[188:191], v[56:59]
	v_mfma_f32_16x16x32_bf16 v[56:59], v[164:167], v[192:195], v[56:59]
	v_mfma_f32_16x16x32_bf16 v[52:55], v[152:155], v[196:199], v[52:55]
	v_mfma_f32_16x16x32_bf16 v[52:55], v[156:159], v[200:203], v[52:55]
	v_mfma_f32_16x16x32_bf16 v[44:47], v[160:163], v[196:199], v[44:47]
	v_mfma_f32_16x16x32_bf16 v[44:47], v[164:167], v[200:203], v[44:47]
	v_mfma_f32_16x16x32_bf16 v[36:39], v[152:155], v[204:207], v[36:39]
	v_mfma_f32_16x16x32_bf16 v[36:39], v[156:159], v[208:211], v[36:39]
	v_mfma_f32_16x16x32_bf16 v[28:31], v[160:163], v[204:207], v[28:31]
	v_mfma_f32_16x16x32_bf16 v[28:31], v[164:167], v[208:211], v[28:31]
	v_mfma_f32_16x16x32_bf16 v[20:23], v[152:155], v[212:215], v[20:23]
	v_mfma_f32_16x16x32_bf16 v[20:23], v[156:159], v[216:219], v[20:23]
	v_mfma_f32_16x16x32_bf16 v[12:15], v[160:163], v[212:215], v[12:15]
	v_mfma_f32_16x16x32_bf16 v[12:15], v[164:167], v[216:219], v[12:15]
	v_mfma_f32_16x16x32_bf16 v[48:51], v[168:171], v[188:191], v[48:51]
	v_mfma_f32_16x16x32_bf16 v[48:51], v[172:175], v[192:195], v[48:51]
	v_mfma_f32_16x16x32_bf16 v[40:43], v[176:179], v[188:191], v[40:43]
	v_mfma_f32_16x16x32_bf16 v[40:43], v[184:187], v[192:195], v[40:43]
	v_mfma_f32_16x16x32_bf16 v[32:35], v[168:171], v[196:199], v[32:35]
	v_mfma_f32_16x16x32_bf16 v[32:35], v[172:175], v[200:203], v[32:35]
	v_mfma_f32_16x16x32_bf16 v[24:27], v[176:179], v[196:199], v[24:27]
	v_mfma_f32_16x16x32_bf16 v[24:27], v[184:187], v[200:203], v[24:27]
	v_mfma_f32_16x16x32_bf16 v[16:19], v[168:171], v[204:207], v[16:19]
	v_mfma_f32_16x16x32_bf16 v[16:19], v[172:175], v[208:211], v[16:19]
	v_mfma_f32_16x16x32_bf16 v[8:11], v[176:179], v[204:207], v[8:11]
	v_mfma_f32_16x16x32_bf16 v[8:11], v[184:187], v[208:211], v[8:11]
	v_mfma_f32_16x16x32_bf16 v[4:7], v[168:171], v[212:215], v[4:7]
	v_mfma_f32_16x16x32_bf16 v[4:7], v[172:175], v[216:219], v[4:7]
	v_mfma_f32_16x16x32_bf16 v[0:3], v[176:179], v[212:215], v[0:3]
	v_mfma_f32_16x16x32_bf16 v[0:3], v[184:187], v[216:219], v[0:3]
	s_setprio 0
	s_barrier
	s_add_i32 s86, s86, 2
	s_add_u32 s84, s84, 0x100
	s_addc_u32 s85, s85, 0
	s_cmp_gt_u32 s86, 41
	s_mov_b64 s[52:53], s[54:55]
	s_cbranch_scc0 .LBB0_804
	s_and_b64 vcc, exec, s[18:19]
	s_cbranch_vccz .LBB0_807
	s_barrier

.LBB0_934:
	s_ashr_i32 s53, s52, 31
	s_lshl_b64 s[54:55], s[52:53], 19
	s_add_u32 s54, s80, s54
	s_addc_u32 s55, s81, s55
	s_and_b64 s[56:57], s[10:11], exec
	s_cselect_b32 s53, s55, s61
	s_cselect_b32 s83, s54, s60
	s_ashr_i32 s49, s48, 31
	s_lshl_b64 s[56:57], s[48:49], 19
	s_add_u32 s56, s66, s56
	s_addc_u32 s57, s67, s57
	s_and_b64 s[64:65], s[10:11], exec
	s_cselect_b32 s49, s57, s63
	s_cselect_b32 s84, s56, s62
	s_add_u32 s60, s60, 0x40080
	s_addc_u32 s61, s61, 0
	s_add_u32 s85, s62, 0x100
	s_addc_u32 s86, s63, 0
	s_mov_b32 s87, -2
	ds_read_b128 v[152:155], v148
	ds_read_b128 v[156:159], v148 offset:1024
	ds_read_b128 v[160:163], v148 offset:2048
	ds_read_b128 v[164:167], v148 offset:3072
	ds_read_b128 v[168:171], v149
	ds_read_b128 v[172:175], v149 offset:1024
	ds_read_b128 v[176:179], v149 offset:2048
	ds_read_b128 v[184:187], v149 offset:3072
	s_add_u32 s62, s60, 0xfffc0080
	s_addc_u32 s63, s61, -1
	s_cmp_eq_u32 s87, 12
	s_cselect_b32 s65, s53, s63
	s_cselect_b32 s64, s83, s62
	s_cselect_b32 s63, s49, s86
	s_cselect_b32 s62, s84, s85
	v_lshl_add_u64 v[220:221], s[60:61], 0, v[138:139]
	s_add_i32 m0, s69, 0xc000
	ds_read_b128 v[188:191], v150
	ds_read_b128 v[192:195], v150 offset:1024
	ds_read_b128 v[196:199], v150 offset:2048
	ds_read_b128 v[200:203], v150 offset:3072
	ds_read_b128 v[204:207], v150 offset:4096
	ds_read_b128 v[208:211], v150 offset:5120
	ds_read_b128 v[212:215], v150 offset:6144
	ds_read_b128 v[216:219], v150 offset:7168
	global_load_lds_dwordx4 v[220:221], off
	v_lshl_add_u64 v[220:221], s[60:61], 0, v[140:141]
	s_add_i32 m0, s69, 0xe000
	s_nop 0
	global_load_lds_dwordx4 v[220:221], off
	s_waitcnt vmcnt(8)
	s_waitcnt lgkmcnt(0)
	s_barrier
	s_setprio 1
	s_waitcnt lgkmcnt(0)
	v_mfma_f32_16x16x32_bf16 v[124:127], v[152:155], v[188:191], 0
	v_mfma_f32_16x16x32_bf16 v[124:127], v[156:159], v[192:195], v[124:127]
	v_mfma_f32_16x16x32_bf16 v[120:123], v[160:163], v[188:191], 0
	v_mfma_f32_16x16x32_bf16 v[120:123], v[164:167], v[192:195], v[120:123]
	v_mfma_f32_16x16x32_bf16 v[116:119], v[152:155], v[196:199], 0
	v_mfma_f32_16x16x32_bf16 v[116:119], v[156:159], v[200:203], v[116:119]
	v_mfma_f32_16x16x32_bf16 v[112:115], v[160:163], v[196:199], 0
	v_mfma_f32_16x16x32_bf16 v[112:115], v[164:167], v[200:203], v[112:115]
	v_mfma_f32_16x16x32_bf16 v[108:111], v[152:155], v[204:207], 0
	v_mfma_f32_16x16x32_bf16 v[108:111], v[156:159], v[208:211], v[108:111]
	v_mfma_f32_16x16x32_bf16 v[104:107], v[160:163], v[204:207], 0
	v_mfma_f32_16x16x32_bf16 v[104:107], v[164:167], v[208:211], v[104:107]
	v_mfma_f32_16x16x32_bf16 v[100:103], v[152:155], v[212:215], 0
	v_mfma_f32_16x16x32_bf16 v[100:103], v[156:159], v[216:219], v[100:103]
	v_mfma_f32_16x16x32_bf16 v[96:99], v[160:163], v[212:215], 0
	v_mfma_f32_16x16x32_bf16 v[96:99], v[164:167], v[216:219], v[96:99]
	v_mfma_f32_16x16x32_bf16 v[76:79], v[168:171], v[188:191], 0
	v_mfma_f32_16x16x32_bf16 v[76:79], v[172:175], v[192:195], v[76:79]
	v_mfma_f32_16x16x32_bf16 v[68:71], v[176:179], v[188:191], 0
	v_mfma_f32_16x16x32_bf16 v[68:71], v[184:187], v[192:195], v[68:71]
	v_mfma_f32_16x16x32_bf16 v[60:63], v[168:171], v[196:199], 0
	v_mfma_f32_16x16x32_bf16 v[60:63], v[172:175], v[200:203], v[60:63]
	v_mfma_f32_16x16x32_bf16 v[52:55], v[176:179], v[196:199], 0
	v_mfma_f32_16x16x32_bf16 v[52:55], v[184:187], v[200:203], v[52:55]
	v_mfma_f32_16x16x32_bf16 v[44:47], v[168:171], v[204:207], 0
	v_mfma_f32_16x16x32_bf16 v[44:47], v[172:175], v[208:211], v[44:47]
	v_mfma_f32_16x16x32_bf16 v[40:43], v[176:179], v[204:207], 0
	v_mfma_f32_16x16x32_bf16 v[40:43], v[184:187], v[208:211], v[40:43]
	v_mfma_f32_16x16x32_bf16 v[36:39], v[168:171], v[212:215], 0
	v_mfma_f32_16x16x32_bf16 v[36:39], v[172:175], v[216:219], v[36:39]
	v_mfma_f32_16x16x32_bf16 v[32:35], v[176:179], v[212:215], 0
	v_mfma_f32_16x16x32_bf16 v[32:35], v[184:187], v[216:219], v[32:35]
	s_setprio 0
	s_barrier
	s_add_i32 s79, s77, s68
	v_lshl_add_u64 v[220:221], s[62:63], 0, v[130:131]
	s_mov_b32 m0, s79
	ds_read_b128 v[188:191], v150 offset:16384
	ds_read_b128 v[192:195], v150 offset:17408
	ds_read_b128 v[196:199], v150 offset:18432
	ds_read_b128 v[200:203], v150 offset:19456
	ds_read_b128 v[204:207], v150 offset:20480
	ds_read_b128 v[208:211], v150 offset:21504
	ds_read_b128 v[212:215], v150 offset:22528
	ds_read_b128 v[216:219], v150 offset:23552
	global_load_lds_dwordx4 v[220:221], off
	s_add_i32 m0, s79, 0x2000
	s_add_u32 s88, s62, 0x40000
	v_lshl_add_u64 v[222:223], s[62:63], 0, v[134:135]
	s_addc_u32 s89, s63, 0
	s_add_i32 s79, s82, s68
	global_load_lds_dwordx4 v[222:223], off
	v_lshl_add_u64 v[224:225], s[88:89], 0, v[130:131]
	s_mov_b32 m0, s79
	v_lshl_add_u64 v[226:227], s[64:65], 0, v[132:133]
	global_load_lds_dwordx4 v[224:225], off
	v_lshl_add_u64 v[224:225], s[88:89], 0, v[134:135]
	s_add_i32 m0, s79, 0x2000
	s_nop 0
	global_load_lds_dwordx4 v[224:225], off
	v_lshl_add_u64 v[224:225], s[64:65], 0, v[128:129]
	s_mov_b32 m0, s69
	s_nop 0
	global_load_lds_dwordx4 v[224:225], off
	s_mov_b32 m0, s70
	s_nop 0
	global_load_lds_dwordx4 v[226:227], off
	s_waitcnt vmcnt(8)
	s_waitcnt lgkmcnt(0)
	s_barrier
	s_setprio 1
	s_waitcnt lgkmcnt(0)
	v_mfma_f32_16x16x32_bf16 v[92:95], v[152:155], v[188:191], 0
	v_mfma_f32_16x16x32_bf16 v[92:95], v[156:159], v[192:195], v[92:95]
	v_mfma_f32_16x16x32_bf16 v[88:91], v[160:163], v[188:191], 0
	v_mfma_f32_16x16x32_bf16 v[88:91], v[164:167], v[192:195], v[88:91]
	v_mfma_f32_16x16x32_bf16 v[84:87], v[152:155], v[196:199], 0
	v_mfma_f32_16x16x32_bf16 v[84:87], v[156:159], v[200:203], v[84:87]
	v_mfma_f32_16x16x32_bf16 v[80:83], v[160:163], v[196:199], 0
	v_mfma_f32_16x16x32_bf16 v[80:83], v[164:167], v[200:203], v[80:83]
	v_mfma_f32_16x16x32_bf16 v[72:75], v[152:155], v[204:207], 0
	v_mfma_f32_16x16x32_bf16 v[72:75], v[156:159], v[208:211], v[72:75]
	v_mfma_f32_16x16x32_bf16 v[64:67], v[160:163], v[204:207], 0
	v_mfma_f32_16x16x32_bf16 v[64:67], v[164:167], v[208:211], v[64:67]
	v_mfma_f32_16x16x32_bf16 v[56:59], v[152:155], v[212:215], 0
	v_mfma_f32_16x16x32_bf16 v[56:59], v[156:159], v[216:219], v[56:59]
	v_mfma_f32_16x16x32_bf16 v[48:51], v[160:163], v[212:215], 0
	v_mfma_f32_16x16x32_bf16 v[48:51], v[164:167], v[216:219], v[48:51]
	v_mfma_f32_16x16x32_bf16 v[28:31], v[168:171], v[188:191], 0
	v_mfma_f32_16x16x32_bf16 v[28:31], v[172:175], v[192:195], v[28:31]
	v_mfma_f32_16x16x32_bf16 v[24:27], v[176:179], v[188:191], 0
	v_mfma_f32_16x16x32_bf16 v[24:27], v[184:187], v[192:195], v[24:27]
	v_mfma_f32_16x16x32_bf16 v[20:23], v[168:171], v[196:199], 0
	v_mfma_f32_16x16x32_bf16 v[20:23], v[172:175], v[200:203], v[20:23]
	v_mfma_f32_16x16x32_bf16 v[16:19], v[176:179], v[196:199], 0
	v_mfma_f32_16x16x32_bf16 v[16:19], v[184:187], v[200:203], v[16:19]
	v_mfma_f32_16x16x32_bf16 v[12:15], v[168:171], v[204:207], 0
	v_mfma_f32_16x16x32_bf16 v[12:15], v[172:175], v[208:211], v[12:15]
	v_mfma_f32_16x16x32_bf16 v[8:11], v[176:179], v[204:207], 0
	v_mfma_f32_16x16x32_bf16 v[8:11], v[184:187], v[208:211], v[8:11]
	v_mfma_f32_16x16x32_bf16 v[4:7], v[168:171], v[212:215], 0
	v_mfma_f32_16x16x32_bf16 v[4:7], v[172:175], v[216:219], v[4:7]
	v_mfma_f32_16x16x32_bf16 v[0:3], v[176:179], v[212:215], 0
	v_mfma_f32_16x16x32_bf16 v[0:3], v[184:187], v[216:219], v[0:3]
	s_setprio 0
	s_barrier
	s_branch .Lmid_gemm6
.LBB0_935:
	ds_read_b128 v[152:155], v148
	ds_read_b128 v[156:159], v148 offset:1024
	ds_read_b128 v[160:163], v148 offset:2048
	ds_read_b128 v[164:167], v148 offset:3072
	ds_read_b128 v[168:171], v149
	ds_read_b128 v[172:175], v149 offset:1024
	ds_read_b128 v[176:179], v149 offset:2048
	ds_read_b128 v[184:187], v149 offset:3072
	s_add_u32 s62, s60, 0xfffc0080
	s_addc_u32 s63, s61, -1
	s_cmp_eq_u32 s87, 12
	s_cselect_b32 s65, s53, s63
	s_cselect_b32 s64, s83, s62
	s_cselect_b32 s63, s49, s86
	s_cselect_b32 s62, s84, s85
	v_lshl_add_u64 v[220:221], s[60:61], 0, v[138:139]
	s_add_i32 m0, s69, 0xc000
	ds_read_b128 v[188:191], v150
	ds_read_b128 v[192:195], v150 offset:1024
	ds_read_b128 v[196:199], v150 offset:2048
	ds_read_b128 v[200:203], v150 offset:3072
	ds_read_b128 v[204:207], v150 offset:4096
	ds_read_b128 v[208:211], v150 offset:5120
	ds_read_b128 v[212:215], v150 offset:6144
	ds_read_b128 v[216:219], v150 offset:7168
	global_load_lds_dwordx4 v[220:221], off
	v_lshl_add_u64 v[220:221], s[60:61], 0, v[140:141]
	s_add_i32 m0, s69, 0xe000
	s_nop 0
	global_load_lds_dwordx4 v[220:221], off
	s_waitcnt vmcnt(8)
	s_waitcnt lgkmcnt(0)
	s_barrier
	s_setprio 1
	s_waitcnt lgkmcnt(0)
	v_mfma_f32_16x16x32_bf16 v[124:127], v[152:155], v[188:191], v[124:127]
	v_mfma_f32_16x16x32_bf16 v[124:127], v[156:159], v[192:195], v[124:127]
	v_mfma_f32_16x16x32_bf16 v[120:123], v[160:163], v[188:191], v[120:123]
	v_mfma_f32_16x16x32_bf16 v[120:123], v[164:167], v[192:195], v[120:123]
	v_mfma_f32_16x16x32_bf16 v[116:119], v[152:155], v[196:199], v[116:119]
	v_mfma_f32_16x16x32_bf16 v[116:119], v[156:159], v[200:203], v[116:119]
	v_mfma_f32_16x16x32_bf16 v[112:115], v[160:163], v[196:199], v[112:115]
	v_mfma_f32_16x16x32_bf16 v[112:115], v[164:167], v[200:203], v[112:115]
	v_mfma_f32_16x16x32_bf16 v[108:111], v[152:155], v[204:207], v[108:111]
	v_mfma_f32_16x16x32_bf16 v[108:111], v[156:159], v[208:211], v[108:111]
	v_mfma_f32_16x16x32_bf16 v[104:107], v[160:163], v[204:207], v[104:107]
	v_mfma_f32_16x16x32_bf16 v[104:107], v[164:167], v[208:211], v[104:107]
	v_mfma_f32_16x16x32_bf16 v[100:103], v[152:155], v[212:215], v[100:103]
	v_mfma_f32_16x16x32_bf16 v[100:103], v[156:159], v[216:219], v[100:103]
	v_mfma_f32_16x16x32_bf16 v[96:99], v[160:163], v[212:215], v[96:99]
	v_mfma_f32_16x16x32_bf16 v[96:99], v[164:167], v[216:219], v[96:99]
	v_mfma_f32_16x16x32_bf16 v[76:79], v[168:171], v[188:191], v[76:79]
	v_mfma_f32_16x16x32_bf16 v[76:79], v[172:175], v[192:195], v[76:79]
	v_mfma_f32_16x16x32_bf16 v[68:71], v[176:179], v[188:191], v[68:71]
	v_mfma_f32_16x16x32_bf16 v[68:71], v[184:187], v[192:195], v[68:71]
	v_mfma_f32_16x16x32_bf16 v[60:63], v[168:171], v[196:199], v[60:63]
	v_mfma_f32_16x16x32_bf16 v[60:63], v[172:175], v[200:203], v[60:63]
	v_mfma_f32_16x16x32_bf16 v[52:55], v[176:179], v[196:199], v[52:55]
	v_mfma_f32_16x16x32_bf16 v[52:55], v[184:187], v[200:203], v[52:55]
	v_mfma_f32_16x16x32_bf16 v[44:47], v[168:171], v[204:207], v[44:47]
	v_mfma_f32_16x16x32_bf16 v[44:47], v[172:175], v[208:211], v[44:47]
	v_mfma_f32_16x16x32_bf16 v[40:43], v[176:179], v[204:207], v[40:43]
	v_mfma_f32_16x16x32_bf16 v[40:43], v[184:187], v[208:211], v[40:43]
	v_mfma_f32_16x16x32_bf16 v[36:39], v[168:171], v[212:215], v[36:39]
	v_mfma_f32_16x16x32_bf16 v[36:39], v[172:175], v[216:219], v[36:39]
	v_mfma_f32_16x16x32_bf16 v[32:35], v[176:179], v[212:215], v[32:35]
	v_mfma_f32_16x16x32_bf16 v[32:35], v[184:187], v[216:219], v[32:35]
	s_setprio 0
	s_barrier
	s_add_i32 s79, s77, s68
	v_lshl_add_u64 v[220:221], s[62:63], 0, v[130:131]
	s_mov_b32 m0, s79
	ds_read_b128 v[188:191], v150 offset:16384
	ds_read_b128 v[192:195], v150 offset:17408
	ds_read_b128 v[196:199], v150 offset:18432
	ds_read_b128 v[200:203], v150 offset:19456
	ds_read_b128 v[204:207], v150 offset:20480
	ds_read_b128 v[208:211], v150 offset:21504
	ds_read_b128 v[212:215], v150 offset:22528
	ds_read_b128 v[216:219], v150 offset:23552
	global_load_lds_dwordx4 v[220:221], off
	s_add_i32 m0, s79, 0x2000
	s_add_u32 s88, s62, 0x40000
	v_lshl_add_u64 v[222:223], s[62:63], 0, v[134:135]
	s_addc_u32 s89, s63, 0
	s_add_i32 s79, s82, s68
	global_load_lds_dwordx4 v[222:223], off
	v_lshl_add_u64 v[224:225], s[88:89], 0, v[130:131]
	s_mov_b32 m0, s79
	v_lshl_add_u64 v[226:227], s[64:65], 0, v[132:133]
	global_load_lds_dwordx4 v[224:225], off
	v_lshl_add_u64 v[224:225], s[88:89], 0, v[134:135]
	s_add_i32 m0, s79, 0x2000
	s_nop 0
	global_load_lds_dwordx4 v[224:225], off
	v_lshl_add_u64 v[224:225], s[64:65], 0, v[128:129]
	s_mov_b32 m0, s69
	s_nop 0
	global_load_lds_dwordx4 v[224:225], off
	s_mov_b32 m0, s70
	s_nop 0
	global_load_lds_dwordx4 v[226:227], off
	s_waitcnt vmcnt(8)
	s_waitcnt lgkmcnt(0)
	s_barrier
	s_setprio 1
	s_waitcnt lgkmcnt(0)
	v_mfma_f32_16x16x32_bf16 v[92:95], v[152:155], v[188:191], v[92:95]
	v_mfma_f32_16x16x32_bf16 v[92:95], v[156:159], v[192:195], v[92:95]
	v_mfma_f32_16x16x32_bf16 v[88:91], v[160:163], v[188:191], v[88:91]
	v_mfma_f32_16x16x32_bf16 v[88:91], v[164:167], v[192:195], v[88:91]
	v_mfma_f32_16x16x32_bf16 v[84:87], v[152:155], v[196:199], v[84:87]
	v_mfma_f32_16x16x32_bf16 v[84:87], v[156:159], v[200:203], v[84:87]
	v_mfma_f32_16x16x32_bf16 v[80:83], v[160:163], v[196:199], v[80:83]
	v_mfma_f32_16x16x32_bf16 v[80:83], v[164:167], v[200:203], v[80:83]
	v_mfma_f32_16x16x32_bf16 v[72:75], v[152:155], v[204:207], v[72:75]
	v_mfma_f32_16x16x32_bf16 v[72:75], v[156:159], v[208:211], v[72:75]
	v_mfma_f32_16x16x32_bf16 v[64:67], v[160:163], v[204:207], v[64:67]
	v_mfma_f32_16x16x32_bf16 v[64:67], v[164:167], v[208:211], v[64:67]
	v_mfma_f32_16x16x32_bf16 v[56:59], v[152:155], v[212:215], v[56:59]
	v_mfma_f32_16x16x32_bf16 v[56:59], v[156:159], v[216:219], v[56:59]
	v_mfma_f32_16x16x32_bf16 v[48:51], v[160:163], v[212:215], v[48:51]
	v_mfma_f32_16x16x32_bf16 v[48:51], v[164:167], v[216:219], v[48:51]
	v_mfma_f32_16x16x32_bf16 v[28:31], v[168:171], v[188:191], v[28:31]
	v_mfma_f32_16x16x32_bf16 v[28:31], v[172:175], v[192:195], v[28:31]
	v_mfma_f32_16x16x32_bf16 v[24:27], v[176:179], v[188:191], v[24:27]
	v_mfma_f32_16x16x32_bf16 v[24:27], v[184:187], v[192:195], v[24:27]
	v_mfma_f32_16x16x32_bf16 v[20:23], v[168:171], v[196:199], v[20:23]
	v_mfma_f32_16x16x32_bf16 v[20:23], v[172:175], v[200:203], v[20:23]
	v_mfma_f32_16x16x32_bf16 v[16:19], v[176:179], v[196:199], v[16:19]
	v_mfma_f32_16x16x32_bf16 v[16:19], v[184:187], v[200:203], v[16:19]
	v_mfma_f32_16x16x32_bf16 v[12:15], v[168:171], v[204:207], v[12:15]
	v_mfma_f32_16x16x32_bf16 v[12:15], v[172:175], v[208:211], v[12:15]
	v_mfma_f32_16x16x32_bf16 v[8:11], v[176:179], v[204:207], v[8:11]
	v_mfma_f32_16x16x32_bf16 v[8:11], v[184:187], v[208:211], v[8:11]
	v_mfma_f32_16x16x32_bf16 v[4:7], v[168:171], v[212:215], v[4:7]
	v_mfma_f32_16x16x32_bf16 v[4:7], v[172:175], v[216:219], v[4:7]
	v_mfma_f32_16x16x32_bf16 v[0:3], v[176:179], v[212:215], v[0:3]
	v_mfma_f32_16x16x32_bf16 v[0:3], v[184:187], v[216:219], v[0:3]
	s_setprio 0
	s_barrier
.Lmid_gemm6:
	s_add_i32 s79, 0, 0x18000
	v_add_u32_e32 v151, s79, v147
	s_add_i32 s88, 0, 0x1c000
	ds_read_b128 v[152:155], v151
	ds_read_b128 v[156:159], v151 offset:1024
	ds_read_b128 v[160:163], v151 offset:2048
	ds_read_b128 v[164:167], v151 offset:3072
	v_add_u32_e32 v151, s88, v147
	ds_read_b128 v[168:171], v151
	ds_read_b128 v[172:175], v151 offset:1024
	ds_read_b128 v[176:179], v151 offset:2048
	ds_read_b128 v[184:187], v151 offset:3072
	s_add_u32 s64, s64, 0x40000
	s_addc_u32 s65, s65, 0
	s_mov_b32 m0, s71
	v_lshl_add_u64 v[228:229], s[64:65], 0, v[128:129]
	ds_read_b128 v[188:191], v150 offset:32768
	ds_read_b128 v[192:195], v150 offset:33792
	ds_read_b128 v[196:199], v150 offset:34816
	ds_read_b128 v[200:203], v150 offset:35840
	ds_read_b128 v[204:207], v150 offset:36864
	ds_read_b128 v[208:211], v150 offset:37888
	ds_read_b128 v[212:215], v150 offset:38912
	ds_read_b128 v[216:219], v150 offset:39936
	global_load_lds_dwordx4 v[228:229], off
	v_lshl_add_u64 v[228:229], s[64:65], 0, v[132:133]
	s_mov_b32 m0, s72
	s_nop 0
	global_load_lds_dwordx4 v[228:229], off
	s_waitcnt vmcnt(8)
	s_waitcnt lgkmcnt(0)
	s_barrier
	s_setprio 1
	s_waitcnt lgkmcnt(0)
	v_mfma_f32_16x16x32_bf16 v[124:127], v[152:155], v[188:191], v[124:127]
	v_mfma_f32_16x16x32_bf16 v[124:127], v[156:159], v[192:195], v[124:127]
	v_mfma_f32_16x16x32_bf16 v[120:123], v[160:163], v[188:191], v[120:123]
	v_mfma_f32_16x16x32_bf16 v[120:123], v[164:167], v[192:195], v[120:123]
	v_mfma_f32_16x16x32_bf16 v[116:119], v[152:155], v[196:199], v[116:119]
	v_mfma_f32_16x16x32_bf16 v[116:119], v[156:159], v[200:203], v[116:119]
	v_mfma_f32_16x16x32_bf16 v[112:115], v[160:163], v[196:199], v[112:115]
	v_mfma_f32_16x16x32_bf16 v[112:115], v[164:167], v[200:203], v[112:115]
	v_mfma_f32_16x16x32_bf16 v[108:111], v[152:155], v[204:207], v[108:111]
	v_mfma_f32_16x16x32_bf16 v[108:111], v[156:159], v[208:211], v[108:111]
	v_mfma_f32_16x16x32_bf16 v[104:107], v[160:163], v[204:207], v[104:107]
	v_mfma_f32_16x16x32_bf16 v[104:107], v[164:167], v[208:211], v[104:107]
	v_mfma_f32_16x16x32_bf16 v[100:103], v[152:155], v[212:215], v[100:103]
	v_mfma_f32_16x16x32_bf16 v[100:103], v[156:159], v[216:219], v[100:103]
	v_mfma_f32_16x16x32_bf16 v[96:99], v[160:163], v[212:215], v[96:99]
	v_mfma_f32_16x16x32_bf16 v[96:99], v[164:167], v[216:219], v[96:99]
	v_mfma_f32_16x16x32_bf16 v[76:79], v[168:171], v[188:191], v[76:79]
	v_mfma_f32_16x16x32_bf16 v[76:79], v[172:175], v[192:195], v[76:79]
	v_mfma_f32_16x16x32_bf16 v[68:71], v[176:179], v[188:191], v[68:71]
	v_mfma_f32_16x16x32_bf16 v[68:71], v[184:187], v[192:195], v[68:71]
	v_mfma_f32_16x16x32_bf16 v[60:63], v[168:171], v[196:199], v[60:63]
	v_mfma_f32_16x16x32_bf16 v[60:63], v[172:175], v[200:203], v[60:63]
	v_mfma_f32_16x16x32_bf16 v[52:55], v[176:179], v[196:199], v[52:55]
	v_mfma_f32_16x16x32_bf16 v[52:55], v[184:187], v[200:203], v[52:55]
	v_mfma_f32_16x16x32_bf16 v[44:47], v[168:171], v[204:207], v[44:47]
	v_mfma_f32_16x16x32_bf16 v[44:47], v[172:175], v[208:211], v[44:47]
	v_mfma_f32_16x16x32_bf16 v[40:43], v[176:179], v[204:207], v[40:43]
	v_mfma_f32_16x16x32_bf16 v[40:43], v[184:187], v[208:211], v[40:43]
	v_mfma_f32_16x16x32_bf16 v[36:39], v[168:171], v[212:215], v[36:39]
	v_mfma_f32_16x16x32_bf16 v[36:39], v[172:175], v[216:219], v[36:39]
	v_mfma_f32_16x16x32_bf16 v[32:35], v[176:179], v[212:215], v[32:35]
	v_mfma_f32_16x16x32_bf16 v[32:35], v[184:187], v[216:219], v[32:35]
	s_setprio 0
	s_barrier
	s_add_i32 s64, s79, s68
	v_lshl_add_u64 v[220:221], v[220:221], 0, s[12:13]
	s_mov_b32 m0, s64
	ds_read_b128 v[188:191], v150 offset:49152
	ds_read_b128 v[192:195], v150 offset:50176
	ds_read_b128 v[196:199], v150 offset:51200
	ds_read_b128 v[200:203], v150 offset:52224
	ds_read_b128 v[204:207], v150 offset:53248
	ds_read_b128 v[208:211], v150 offset:54272
	ds_read_b128 v[212:215], v150 offset:55296
	ds_read_b128 v[216:219], v150 offset:56320
	global_load_lds_dwordx4 v[220:221], off
	s_add_i32 m0, s64, 0x2000
	s_add_u32 s62, s62, 0x40080
	v_lshl_add_u64 v[220:221], v[222:223], 0, s[12:13]
	s_addc_u32 s63, s63, 0
	s_add_i32 s64, s88, s68
	global_load_lds_dwordx4 v[220:221], off
	v_lshl_add_u64 v[220:221], s[62:63], 0, v[130:131]
	s_mov_b32 m0, s64
	s_nop 0
	global_load_lds_dwordx4 v[220:221], off
	v_lshl_add_u64 v[220:221], s[62:63], 0, v[134:135]
	s_add_i32 m0, s64, 0x2000
	s_nop 0
	global_load_lds_dwordx4 v[220:221], off
	v_lshl_add_u64 v[220:221], v[224:225], 0, s[12:13]
	s_mov_b32 m0, s75
	s_nop 0
	global_load_lds_dwordx4 v[220:221], off
	v_lshl_add_u64 v[220:221], v[226:227], 0, s[12:13]
	s_mov_b32 m0, s76
	s_nop 0
	global_load_lds_dwordx4 v[220:221], off
	s_waitcnt vmcnt(8)
	s_waitcnt lgkmcnt(0)
	s_barrier
	s_setprio 1
	s_waitcnt lgkmcnt(0)
	v_mfma_f32_16x16x32_bf16 v[92:95], v[152:155], v[188:191], v[92:95]
	v_mfma_f32_16x16x32_bf16 v[92:95], v[156:159], v[192:195], v[92:95]
	v_mfma_f32_16x16x32_bf16 v[88:91], v[160:163], v[188:191], v[88:91]
	v_mfma_f32_16x16x32_bf16 v[88:91], v[164:167], v[192:195], v[88:91]
	v_mfma_f32_16x16x32_bf16 v[84:87], v[152:155], v[196:199], v[84:87]
	v_mfma_f32_16x16x32_bf16 v[84:87], v[156:159], v[200:203], v[84:87]
	v_mfma_f32_16x16x32_bf16 v[80:83], v[160:163], v[196:199], v[80:83]
	v_mfma_f32_16x16x32_bf16 v[80:83], v[164:167], v[200:203], v[80:83]
	v_mfma_f32_16x16x32_bf16 v[72:75], v[152:155], v[204:207], v[72:75]
	v_mfma_f32_16x16x32_bf16 v[72:75], v[156:159], v[208:211], v[72:75]
	v_mfma_f32_16x16x32_bf16 v[64:67], v[160:163], v[204:207], v[64:67]
	v_mfma_f32_16x16x32_bf16 v[64:67], v[164:167], v[208:211], v[64:67]
	v_mfma_f32_16x16x32_bf16 v[56:59], v[152:155], v[212:215], v[56:59]
	v_mfma_f32_16x16x32_bf16 v[56:59], v[156:159], v[216:219], v[56:59]
	v_mfma_f32_16x16x32_bf16 v[48:51], v[160:163], v[212:215], v[48:51]
	v_mfma_f32_16x16x32_bf16 v[48:51], v[164:167], v[216:219], v[48:51]
	v_mfma_f32_16x16x32_bf16 v[28:31], v[168:171], v[188:191], v[28:31]
	v_mfma_f32_16x16x32_bf16 v[28:31], v[172:175], v[192:195], v[28:31]
	v_mfma_f32_16x16x32_bf16 v[24:27], v[176:179], v[188:191], v[24:27]
	v_mfma_f32_16x16x32_bf16 v[24:27], v[184:187], v[192:195], v[24:27]
	v_mfma_f32_16x16x32_bf16 v[20:23], v[168:171], v[196:199], v[20:23]
	v_mfma_f32_16x16x32_bf16 v[20:23], v[172:175], v[200:203], v[20:23]
	v_mfma_f32_16x16x32_bf16 v[16:19], v[176:179], v[196:199], v[16:19]
	v_mfma_f32_16x16x32_bf16 v[16:19], v[184:187], v[200:203], v[16:19]
	v_mfma_f32_16x16x32_bf16 v[12:15], v[168:171], v[204:207], v[12:15]
	v_mfma_f32_16x16x32_bf16 v[12:15], v[172:175], v[208:211], v[12:15]
	v_mfma_f32_16x16x32_bf16 v[8:11], v[176:179], v[204:207], v[8:11]
	v_mfma_f32_16x16x32_bf16 v[8:11], v[184:187], v[208:211], v[8:11]
	v_mfma_f32_16x16x32_bf16 v[4:7], v[168:171], v[212:215], v[4:7]
	v_mfma_f32_16x16x32_bf16 v[4:7], v[172:175], v[216:219], v[4:7]
	v_mfma_f32_16x16x32_bf16 v[0:3], v[176:179], v[212:215], v[0:3]
	v_mfma_f32_16x16x32_bf16 v[0:3], v[184:187], v[216:219], v[0:3]
	s_setprio 0
	s_barrier
	s_add_i32 s87, s87, 2
	s_add_u32 s60, s60, 0x100
	s_addc_u32 s61, s61, 0
	s_add_u32 s85, s85, 0x100
	s_addc_u32 s86, s86, 0
	s_cmp_gt_u32 s87, 13
	s_cbranch_scc0 .LBB0_935
	s_and_b64 vcc, exec, s[16:17]
	s_cbranch_vccz .LBB0_938
	s_barrier

.LBB0_950:
	s_ashr_i32 s37, s36, 31
	s_lshl_b64 s[44:45], s[36:37], 19
	s_add_u32 s44, s80, s44
	s_addc_u32 s45, s81, s45
	s_and_b64 s[46:47], s[10:11], exec
	s_cselect_b32 s37, s45, s53
	s_cselect_b32 s72, s44, s52
	s_ashr_i32 s19, s18, 31
	s_lshl_b64 s[46:47], s[18:19], 19
	s_add_u32 s46, s58, s46
	s_addc_u32 s47, s59, s47
	s_and_b64 s[56:57], s[10:11], exec
	s_cselect_b32 s19, s47, s55
	s_cselect_b32 s73, s46, s54
	s_add_u32 s52, s52, 0x40080
	s_addc_u32 s53, s53, 0
	s_add_u32 s74, s54, 0x100
	s_addc_u32 s75, s55, 0
	s_mov_b32 s76, -2
	ds_read_b128 v[140:143], v147
	ds_read_b128 v[150:153], v147 offset:1024
	ds_read_b128 v[154:157], v147 offset:2048
	ds_read_b128 v[158:161], v147 offset:3072
	ds_read_b128 v[162:165], v148
	ds_read_b128 v[166:169], v148 offset:1024
	ds_read_b128 v[170:173], v148 offset:2048
	ds_read_b128 v[174:177], v148 offset:3072
	s_add_u32 s54, s52, 0xfffc0080
	s_addc_u32 s55, s53, -1
	s_cmp_eq_u32 s76, 12
	s_cselect_b32 s57, s37, s55
	s_cselect_b32 s56, s72, s54
	s_cselect_b32 s55, s19, s75
	s_cselect_b32 s54, s73, s74
	v_lshl_add_u64 v[178:179], s[52:53], 0, v[132:133]
	s_add_i32 m0, s49, 0xc000
	ds_read_b128 v[184:187], v149
	ds_read_b128 v[188:191], v149 offset:1024
	ds_read_b128 v[192:195], v149 offset:2048
	ds_read_b128 v[196:199], v149 offset:3072
	ds_read_b128 v[200:203], v149 offset:4096
	ds_read_b128 v[204:207], v149 offset:5120
	ds_read_b128 v[208:211], v149 offset:6144
	ds_read_b128 v[212:215], v149 offset:7168
	global_load_lds_dwordx4 v[178:179], off
	v_lshl_add_u64 v[178:179], s[52:53], 0, v[134:135]
	s_add_i32 m0, s49, 0xe000
	s_nop 0
	global_load_lds_dwordx4 v[178:179], off
	s_waitcnt vmcnt(8)
	s_waitcnt lgkmcnt(0)
	s_barrier
	s_setprio 1
	s_waitcnt lgkmcnt(0)
	v_mfma_f32_16x16x32_bf16 v[124:127], v[140:143], v[184:187], 0
	v_mfma_f32_16x16x32_bf16 v[124:127], v[150:153], v[188:191], v[124:127]
	v_mfma_f32_16x16x32_bf16 v[120:123], v[154:157], v[184:187], 0
	v_mfma_f32_16x16x32_bf16 v[120:123], v[158:161], v[188:191], v[120:123]
	v_mfma_f32_16x16x32_bf16 v[108:111], v[140:143], v[192:195], 0
	v_mfma_f32_16x16x32_bf16 v[108:111], v[150:153], v[196:199], v[108:111]
	v_mfma_f32_16x16x32_bf16 v[104:107], v[154:157], v[192:195], 0
	v_mfma_f32_16x16x32_bf16 v[104:107], v[158:161], v[196:199], v[104:107]
	v_mfma_f32_16x16x32_bf16 v[92:95], v[140:143], v[200:203], 0
	v_mfma_f32_16x16x32_bf16 v[92:95], v[150:153], v[204:207], v[92:95]
	v_mfma_f32_16x16x32_bf16 v[88:91], v[154:157], v[200:203], 0
	v_mfma_f32_16x16x32_bf16 v[88:91], v[158:161], v[204:207], v[88:91]
	v_mfma_f32_16x16x32_bf16 v[76:79], v[140:143], v[208:211], 0
	v_mfma_f32_16x16x32_bf16 v[76:79], v[150:153], v[212:215], v[76:79]
	v_mfma_f32_16x16x32_bf16 v[72:75], v[154:157], v[208:211], 0
	v_mfma_f32_16x16x32_bf16 v[72:75], v[158:161], v[212:215], v[72:75]
	v_mfma_f32_16x16x32_bf16 v[116:119], v[162:165], v[184:187], 0
	v_mfma_f32_16x16x32_bf16 v[116:119], v[166:169], v[188:191], v[116:119]
	v_mfma_f32_16x16x32_bf16 v[112:115], v[170:173], v[184:187], 0
	v_mfma_f32_16x16x32_bf16 v[112:115], v[174:177], v[188:191], v[112:115]
	v_mfma_f32_16x16x32_bf16 v[100:103], v[162:165], v[192:195], 0
	v_mfma_f32_16x16x32_bf16 v[100:103], v[166:169], v[196:199], v[100:103]
	v_mfma_f32_16x16x32_bf16 v[96:99], v[170:173], v[192:195], 0
	v_mfma_f32_16x16x32_bf16 v[96:99], v[174:177], v[196:199], v[96:99]
	v_mfma_f32_16x16x32_bf16 v[84:87], v[162:165], v[200:203], 0
	v_mfma_f32_16x16x32_bf16 v[84:87], v[166:169], v[204:207], v[84:87]
	v_mfma_f32_16x16x32_bf16 v[80:83], v[170:173], v[200:203], 0
	v_mfma_f32_16x16x32_bf16 v[80:83], v[174:177], v[204:207], v[80:83]
	v_mfma_f32_16x16x32_bf16 v[68:71], v[162:165], v[208:211], 0
	v_mfma_f32_16x16x32_bf16 v[68:71], v[166:169], v[212:215], v[68:71]
	v_mfma_f32_16x16x32_bf16 v[64:67], v[170:173], v[208:211], 0
	v_mfma_f32_16x16x32_bf16 v[64:67], v[174:177], v[212:215], v[64:67]
	s_setprio 0
	s_barrier
	s_add_i32 s77, s68, s60
	v_lshl_add_u64 v[178:179], s[54:55], 0, v[130:131]
	s_mov_b32 m0, s77
	ds_read_b128 v[184:187], v149 offset:16384
	ds_read_b128 v[188:191], v149 offset:17408
	ds_read_b128 v[192:195], v149 offset:18432
	ds_read_b128 v[196:199], v149 offset:19456
	ds_read_b128 v[200:203], v149 offset:20480
	ds_read_b128 v[204:207], v149 offset:21504
	ds_read_b128 v[208:211], v149 offset:22528
	ds_read_b128 v[212:215], v149 offset:23552
	global_load_lds_dwordx4 v[178:179], off
	s_add_i32 m0, s77, 0x2000
	s_add_u32 s82, s54, 0x40000
	v_lshl_add_u64 v[216:217], s[54:55], 0, v[128:129]
	s_addc_u32 s83, s55, 0
	s_add_i32 s77, s69, s60
	global_load_lds_dwordx4 v[216:217], off
	v_lshl_add_u64 v[218:219], s[82:83], 0, v[130:131]
	s_mov_b32 m0, s77
	v_lshl_add_u64 v[220:221], s[56:57], 0, v[128:129]
	global_load_lds_dwordx4 v[218:219], off
	v_lshl_add_u64 v[218:219], s[82:83], 0, v[128:129]
	s_add_i32 m0, s77, 0x2000
	s_nop 0
	global_load_lds_dwordx4 v[218:219], off
	v_lshl_add_u64 v[218:219], s[56:57], 0, v[130:131]
	s_mov_b32 m0, s49
	s_nop 0
	global_load_lds_dwordx4 v[218:219], off
	s_mov_b32 m0, s62
	s_nop 0
	global_load_lds_dwordx4 v[220:221], off
	s_waitcnt vmcnt(8)
	s_waitcnt lgkmcnt(0)
	s_barrier
	s_setprio 1
	s_waitcnt lgkmcnt(0)
	v_mfma_f32_16x16x32_bf16 v[60:63], v[140:143], v[184:187], 0
	v_mfma_f32_16x16x32_bf16 v[60:63], v[150:153], v[188:191], v[60:63]
	v_mfma_f32_16x16x32_bf16 v[56:59], v[154:157], v[184:187], 0
	v_mfma_f32_16x16x32_bf16 v[56:59], v[158:161], v[188:191], v[56:59]
	v_mfma_f32_16x16x32_bf16 v[44:47], v[140:143], v[192:195], 0
	v_mfma_f32_16x16x32_bf16 v[44:47], v[150:153], v[196:199], v[44:47]
	v_mfma_f32_16x16x32_bf16 v[40:43], v[154:157], v[192:195], 0
	v_mfma_f32_16x16x32_bf16 v[40:43], v[158:161], v[196:199], v[40:43]
	v_mfma_f32_16x16x32_bf16 v[28:31], v[140:143], v[200:203], 0
	v_mfma_f32_16x16x32_bf16 v[28:31], v[150:153], v[204:207], v[28:31]
	v_mfma_f32_16x16x32_bf16 v[24:27], v[154:157], v[200:203], 0
	v_mfma_f32_16x16x32_bf16 v[24:27], v[158:161], v[204:207], v[24:27]
	v_mfma_f32_16x16x32_bf16 v[12:15], v[140:143], v[208:211], 0
	v_mfma_f32_16x16x32_bf16 v[12:15], v[150:153], v[212:215], v[12:15]
	v_mfma_f32_16x16x32_bf16 v[8:11], v[154:157], v[208:211], 0
	v_mfma_f32_16x16x32_bf16 v[8:11], v[158:161], v[212:215], v[8:11]
	v_mfma_f32_16x16x32_bf16 v[52:55], v[162:165], v[184:187], 0
	v_mfma_f32_16x16x32_bf16 v[52:55], v[166:169], v[188:191], v[52:55]
	v_mfma_f32_16x16x32_bf16 v[48:51], v[170:173], v[184:187], 0
	v_mfma_f32_16x16x32_bf16 v[48:51], v[174:177], v[188:191], v[48:51]
	v_mfma_f32_16x16x32_bf16 v[36:39], v[162:165], v[192:195], 0
	v_mfma_f32_16x16x32_bf16 v[36:39], v[166:169], v[196:199], v[36:39]
	v_mfma_f32_16x16x32_bf16 v[32:35], v[170:173], v[192:195], 0
	v_mfma_f32_16x16x32_bf16 v[32:35], v[174:177], v[196:199], v[32:35]
	v_mfma_f32_16x16x32_bf16 v[20:23], v[162:165], v[200:203], 0
	v_mfma_f32_16x16x32_bf16 v[20:23], v[166:169], v[204:207], v[20:23]
	v_mfma_f32_16x16x32_bf16 v[16:19], v[170:173], v[200:203], 0
	v_mfma_f32_16x16x32_bf16 v[16:19], v[174:177], v[204:207], v[16:19]
	v_mfma_f32_16x16x32_bf16 v[4:7], v[162:165], v[208:211], 0
	v_mfma_f32_16x16x32_bf16 v[4:7], v[166:169], v[212:215], v[4:7]
	v_mfma_f32_16x16x32_bf16 v[0:3], v[170:173], v[208:211], 0
	v_mfma_f32_16x16x32_bf16 v[0:3], v[174:177], v[212:215], v[0:3]
	s_setprio 0
	s_barrier
	s_branch .Lmid_gemm7
.LBB0_951:
	ds_read_b128 v[140:143], v147
	ds_read_b128 v[150:153], v147 offset:1024
	ds_read_b128 v[154:157], v147 offset:2048
	ds_read_b128 v[158:161], v147 offset:3072
	ds_read_b128 v[162:165], v148
	ds_read_b128 v[166:169], v148 offset:1024
	ds_read_b128 v[170:173], v148 offset:2048
	ds_read_b128 v[174:177], v148 offset:3072
	s_add_u32 s54, s52, 0xfffc0080
	s_addc_u32 s55, s53, -1
	s_cmp_eq_u32 s76, 12
	s_cselect_b32 s57, s37, s55
	s_cselect_b32 s56, s72, s54
	s_cselect_b32 s55, s19, s75
	s_cselect_b32 s54, s73, s74
	v_lshl_add_u64 v[178:179], s[52:53], 0, v[132:133]
	s_add_i32 m0, s49, 0xc000
	ds_read_b128 v[184:187], v149
	ds_read_b128 v[188:191], v149 offset:1024
	ds_read_b128 v[192:195], v149 offset:2048
	ds_read_b128 v[196:199], v149 offset:3072
	ds_read_b128 v[200:203], v149 offset:4096
	ds_read_b128 v[204:207], v149 offset:5120
	ds_read_b128 v[208:211], v149 offset:6144
	ds_read_b128 v[212:215], v149 offset:7168
	global_load_lds_dwordx4 v[178:179], off
	v_lshl_add_u64 v[178:179], s[52:53], 0, v[134:135]
	s_add_i32 m0, s49, 0xe000
	s_nop 0
	global_load_lds_dwordx4 v[178:179], off
	s_waitcnt vmcnt(8)
	s_waitcnt lgkmcnt(0)
	s_barrier
	s_setprio 1
	s_waitcnt lgkmcnt(0)
	v_mfma_f32_16x16x32_bf16 v[124:127], v[140:143], v[184:187], v[124:127]
	v_mfma_f32_16x16x32_bf16 v[124:127], v[150:153], v[188:191], v[124:127]
	v_mfma_f32_16x16x32_bf16 v[120:123], v[154:157], v[184:187], v[120:123]
	v_mfma_f32_16x16x32_bf16 v[120:123], v[158:161], v[188:191], v[120:123]
	v_mfma_f32_16x16x32_bf16 v[108:111], v[140:143], v[192:195], v[108:111]
	v_mfma_f32_16x16x32_bf16 v[108:111], v[150:153], v[196:199], v[108:111]
	v_mfma_f32_16x16x32_bf16 v[104:107], v[154:157], v[192:195], v[104:107]
	v_mfma_f32_16x16x32_bf16 v[104:107], v[158:161], v[196:199], v[104:107]
	v_mfma_f32_16x16x32_bf16 v[92:95], v[140:143], v[200:203], v[92:95]
	v_mfma_f32_16x16x32_bf16 v[92:95], v[150:153], v[204:207], v[92:95]
	v_mfma_f32_16x16x32_bf16 v[88:91], v[154:157], v[200:203], v[88:91]
	v_mfma_f32_16x16x32_bf16 v[88:91], v[158:161], v[204:207], v[88:91]
	v_mfma_f32_16x16x32_bf16 v[76:79], v[140:143], v[208:211], v[76:79]
	v_mfma_f32_16x16x32_bf16 v[76:79], v[150:153], v[212:215], v[76:79]
	v_mfma_f32_16x16x32_bf16 v[72:75], v[154:157], v[208:211], v[72:75]
	v_mfma_f32_16x16x32_bf16 v[72:75], v[158:161], v[212:215], v[72:75]
	v_mfma_f32_16x16x32_bf16 v[116:119], v[162:165], v[184:187], v[116:119]
	v_mfma_f32_16x16x32_bf16 v[116:119], v[166:169], v[188:191], v[116:119]
	v_mfma_f32_16x16x32_bf16 v[112:115], v[170:173], v[184:187], v[112:115]
	v_mfma_f32_16x16x32_bf16 v[112:115], v[174:177], v[188:191], v[112:115]
	v_mfma_f32_16x16x32_bf16 v[100:103], v[162:165], v[192:195], v[100:103]
	v_mfma_f32_16x16x32_bf16 v[100:103], v[166:169], v[196:199], v[100:103]
	v_mfma_f32_16x16x32_bf16 v[96:99], v[170:173], v[192:195], v[96:99]
	v_mfma_f32_16x16x32_bf16 v[96:99], v[174:177], v[196:199], v[96:99]
	v_mfma_f32_16x16x32_bf16 v[84:87], v[162:165], v[200:203], v[84:87]
	v_mfma_f32_16x16x32_bf16 v[84:87], v[166:169], v[204:207], v[84:87]
	v_mfma_f32_16x16x32_bf16 v[80:83], v[170:173], v[200:203], v[80:83]
	v_mfma_f32_16x16x32_bf16 v[80:83], v[174:177], v[204:207], v[80:83]
	v_mfma_f32_16x16x32_bf16 v[68:71], v[162:165], v[208:211], v[68:71]
	v_mfma_f32_16x16x32_bf16 v[68:71], v[166:169], v[212:215], v[68:71]
	v_mfma_f32_16x16x32_bf16 v[64:67], v[170:173], v[208:211], v[64:67]
	v_mfma_f32_16x16x32_bf16 v[64:67], v[174:177], v[212:215], v[64:67]
	s_setprio 0
	s_barrier
	s_add_i32 s77, s68, s60
	v_lshl_add_u64 v[178:179], s[54:55], 0, v[130:131]
	s_mov_b32 m0, s77
	ds_read_b128 v[184:187], v149 offset:16384
	ds_read_b128 v[188:191], v149 offset:17408
	ds_read_b128 v[192:195], v149 offset:18432
	ds_read_b128 v[196:199], v149 offset:19456
	ds_read_b128 v[200:203], v149 offset:20480
	ds_read_b128 v[204:207], v149 offset:21504
	ds_read_b128 v[208:211], v149 offset:22528
	ds_read_b128 v[212:215], v149 offset:23552
	global_load_lds_dwordx4 v[178:179], off
	s_add_i32 m0, s77, 0x2000
	s_add_u32 s82, s54, 0x40000
	v_lshl_add_u64 v[216:217], s[54:55], 0, v[128:129]
	s_addc_u32 s83, s55, 0
	s_add_i32 s77, s69, s60
	global_load_lds_dwordx4 v[216:217], off
	v_lshl_add_u64 v[218:219], s[82:83], 0, v[130:131]
	s_mov_b32 m0, s77
	v_lshl_add_u64 v[220:221], s[56:57], 0, v[128:129]
	global_load_lds_dwordx4 v[218:219], off
	v_lshl_add_u64 v[218:219], s[82:83], 0, v[128:129]
	s_add_i32 m0, s77, 0x2000
	s_nop 0
	global_load_lds_dwordx4 v[218:219], off
	v_lshl_add_u64 v[218:219], s[56:57], 0, v[130:131]
	s_mov_b32 m0, s49
	s_nop 0
	global_load_lds_dwordx4 v[218:219], off
	s_mov_b32 m0, s62
	s_nop 0
	global_load_lds_dwordx4 v[220:221], off
	s_waitcnt vmcnt(8)
	s_waitcnt lgkmcnt(0)
	s_barrier
	s_setprio 1
	s_waitcnt lgkmcnt(0)
	v_mfma_f32_16x16x32_bf16 v[60:63], v[140:143], v[184:187], v[60:63]
	v_mfma_f32_16x16x32_bf16 v[60:63], v[150:153], v[188:191], v[60:63]
	v_mfma_f32_16x16x32_bf16 v[56:59], v[154:157], v[184:187], v[56:59]
	v_mfma_f32_16x16x32_bf16 v[56:59], v[158:161], v[188:191], v[56:59]
	v_mfma_f32_16x16x32_bf16 v[44:47], v[140:143], v[192:195], v[44:47]
	v_mfma_f32_16x16x32_bf16 v[44:47], v[150:153], v[196:199], v[44:47]
	v_mfma_f32_16x16x32_bf16 v[40:43], v[154:157], v[192:195], v[40:43]
	v_mfma_f32_16x16x32_bf16 v[40:43], v[158:161], v[196:199], v[40:43]
	v_mfma_f32_16x16x32_bf16 v[28:31], v[140:143], v[200:203], v[28:31]
	v_mfma_f32_16x16x32_bf16 v[28:31], v[150:153], v[204:207], v[28:31]
	v_mfma_f32_16x16x32_bf16 v[24:27], v[154:157], v[200:203], v[24:27]
	v_mfma_f32_16x16x32_bf16 v[24:27], v[158:161], v[204:207], v[24:27]
	v_mfma_f32_16x16x32_bf16 v[12:15], v[140:143], v[208:211], v[12:15]
	v_mfma_f32_16x16x32_bf16 v[12:15], v[150:153], v[212:215], v[12:15]
	v_mfma_f32_16x16x32_bf16 v[8:11], v[154:157], v[208:211], v[8:11]
	v_mfma_f32_16x16x32_bf16 v[8:11], v[158:161], v[212:215], v[8:11]
	v_mfma_f32_16x16x32_bf16 v[52:55], v[162:165], v[184:187], v[52:55]
	v_mfma_f32_16x16x32_bf16 v[52:55], v[166:169], v[188:191], v[52:55]
	v_mfma_f32_16x16x32_bf16 v[48:51], v[170:173], v[184:187], v[48:51]
	v_mfma_f32_16x16x32_bf16 v[48:51], v[174:177], v[188:191], v[48:51]
	v_mfma_f32_16x16x32_bf16 v[36:39], v[162:165], v[192:195], v[36:39]
	v_mfma_f32_16x16x32_bf16 v[36:39], v[166:169], v[196:199], v[36:39]
	v_mfma_f32_16x16x32_bf16 v[32:35], v[170:173], v[192:195], v[32:35]
	v_mfma_f32_16x16x32_bf16 v[32:35], v[174:177], v[196:199], v[32:35]
	v_mfma_f32_16x16x32_bf16 v[20:23], v[162:165], v[200:203], v[20:23]
	v_mfma_f32_16x16x32_bf16 v[20:23], v[166:169], v[204:207], v[20:23]
	v_mfma_f32_16x16x32_bf16 v[16:19], v[170:173], v[200:203], v[16:19]
	v_mfma_f32_16x16x32_bf16 v[16:19], v[174:177], v[204:207], v[16:19]
	v_mfma_f32_16x16x32_bf16 v[4:7], v[162:165], v[208:211], v[4:7]
	v_mfma_f32_16x16x32_bf16 v[4:7], v[166:169], v[212:215], v[4:7]
	v_mfma_f32_16x16x32_bf16 v[0:3], v[170:173], v[208:211], v[0:3]
	v_mfma_f32_16x16x32_bf16 v[0:3], v[174:177], v[212:215], v[0:3]
	s_setprio 0
	s_barrier
.Lmid_gemm7:
	s_add_i32 s77, 0, 0x18000
	s_add_i32 s79, 0, 0x1c000
	v_add_u32_e32 v158, s77, v145
	v_add_u32_e32 v174, s79, v145
	ds_read_b128 v[140:143], v158
	ds_read_b128 v[150:153], v158 offset:1024
	ds_read_b128 v[154:157], v158 offset:2048
	ds_read_b128 v[158:161], v158 offset:3072
	ds_read_b128 v[162:165], v174
	ds_read_b128 v[166:169], v174 offset:1024
	ds_read_b128 v[170:173], v174 offset:2048
	ds_read_b128 v[174:177], v174 offset:3072
	s_add_u32 s56, s56, 0x40000
	s_addc_u32 s57, s57, 0
	s_mov_b32 m0, s63
	v_lshl_add_u64 v[222:223], s[56:57], 0, v[130:131]
	ds_read_b128 v[184:187], v149 offset:32768
	ds_read_b128 v[188:191], v149 offset:33792
	ds_read_b128 v[192:195], v149 offset:34816
	ds_read_b128 v[196:199], v149 offset:35840
	ds_read_b128 v[200:203], v149 offset:36864
	ds_read_b128 v[204:207], v149 offset:37888
	ds_read_b128 v[208:211], v149 offset:38912
	ds_read_b128 v[212:215], v149 offset:39936
	global_load_lds_dwordx4 v[222:223], off
	v_lshl_add_u64 v[222:223], s[56:57], 0, v[128:129]
	s_mov_b32 m0, s64
	s_nop 0
	global_load_lds_dwordx4 v[222:223], off
	s_waitcnt vmcnt(8)
	s_waitcnt lgkmcnt(0)
	s_barrier
	s_setprio 1
	s_waitcnt lgkmcnt(0)
	v_mfma_f32_16x16x32_bf16 v[124:127], v[140:143], v[184:187], v[124:127]
	v_mfma_f32_16x16x32_bf16 v[124:127], v[150:153], v[188:191], v[124:127]
	v_mfma_f32_16x16x32_bf16 v[120:123], v[154:157], v[184:187], v[120:123]
	v_mfma_f32_16x16x32_bf16 v[120:123], v[158:161], v[188:191], v[120:123]
	v_mfma_f32_16x16x32_bf16 v[108:111], v[140:143], v[192:195], v[108:111]
	v_mfma_f32_16x16x32_bf16 v[108:111], v[150:153], v[196:199], v[108:111]
	v_mfma_f32_16x16x32_bf16 v[104:107], v[154:157], v[192:195], v[104:107]
	v_mfma_f32_16x16x32_bf16 v[104:107], v[158:161], v[196:199], v[104:107]
	v_mfma_f32_16x16x32_bf16 v[92:95], v[140:143], v[200:203], v[92:95]
	v_mfma_f32_16x16x32_bf16 v[92:95], v[150:153], v[204:207], v[92:95]
	v_mfma_f32_16x16x32_bf16 v[88:91], v[154:157], v[200:203], v[88:91]
	v_mfma_f32_16x16x32_bf16 v[88:91], v[158:161], v[204:207], v[88:91]
	v_mfma_f32_16x16x32_bf16 v[76:79], v[140:143], v[208:211], v[76:79]
	v_mfma_f32_16x16x32_bf16 v[76:79], v[150:153], v[212:215], v[76:79]
	v_mfma_f32_16x16x32_bf16 v[72:75], v[154:157], v[208:211], v[72:75]
	v_mfma_f32_16x16x32_bf16 v[72:75], v[158:161], v[212:215], v[72:75]
	v_mfma_f32_16x16x32_bf16 v[116:119], v[162:165], v[184:187], v[116:119]
	v_mfma_f32_16x16x32_bf16 v[116:119], v[166:169], v[188:191], v[116:119]
	v_mfma_f32_16x16x32_bf16 v[112:115], v[170:173], v[184:187], v[112:115]
	v_mfma_f32_16x16x32_bf16 v[112:115], v[174:177], v[188:191], v[112:115]
	v_mfma_f32_16x16x32_bf16 v[100:103], v[162:165], v[192:195], v[100:103]
	v_mfma_f32_16x16x32_bf16 v[100:103], v[166:169], v[196:199], v[100:103]
	v_mfma_f32_16x16x32_bf16 v[96:99], v[170:173], v[192:195], v[96:99]
	v_mfma_f32_16x16x32_bf16 v[96:99], v[174:177], v[196:199], v[96:99]
	v_mfma_f32_16x16x32_bf16 v[84:87], v[162:165], v[200:203], v[84:87]
	v_mfma_f32_16x16x32_bf16 v[84:87], v[166:169], v[204:207], v[84:87]
	v_mfma_f32_16x16x32_bf16 v[80:83], v[170:173], v[200:203], v[80:83]
	v_mfma_f32_16x16x32_bf16 v[80:83], v[174:177], v[204:207], v[80:83]
	v_mfma_f32_16x16x32_bf16 v[68:71], v[162:165], v[208:211], v[68:71]
	v_mfma_f32_16x16x32_bf16 v[68:71], v[166:169], v[212:215], v[68:71]
	v_mfma_f32_16x16x32_bf16 v[64:67], v[170:173], v[208:211], v[64:67]
	v_mfma_f32_16x16x32_bf16 v[64:67], v[174:177], v[212:215], v[64:67]
	s_setprio 0
	s_barrier
	s_add_i32 s56, s77, s60
	v_lshl_add_u64 v[178:179], v[178:179], 0, s[12:13]
	s_mov_b32 m0, s56
	ds_read_b128 v[184:187], v149 offset:49152
	ds_read_b128 v[188:191], v149 offset:50176
	ds_read_b128 v[192:195], v149 offset:51200
	ds_read_b128 v[196:199], v149 offset:52224
	ds_read_b128 v[200:203], v149 offset:53248
	ds_read_b128 v[204:207], v149 offset:54272
	ds_read_b128 v[208:211], v149 offset:55296
	ds_read_b128 v[212:215], v149 offset:56320
	global_load_lds_dwordx4 v[178:179], off
	s_add_i32 m0, s56, 0x2000
	s_add_u32 s54, s54, 0x40080
	v_lshl_add_u64 v[178:179], v[216:217], 0, s[12:13]
	s_addc_u32 s55, s55, 0
	s_add_i32 s56, s79, s60
	global_load_lds_dwordx4 v[178:179], off
	v_lshl_add_u64 v[178:179], s[54:55], 0, v[130:131]
	s_mov_b32 m0, s56
	s_nop 0
	global_load_lds_dwordx4 v[178:179], off
	v_lshl_add_u64 v[178:179], s[54:55], 0, v[128:129]
	s_add_i32 m0, s56, 0x2000
	s_nop 0
	global_load_lds_dwordx4 v[178:179], off
	v_lshl_add_u64 v[178:179], v[218:219], 0, s[12:13]
	s_mov_b32 m0, s66
	s_nop 0
	global_load_lds_dwordx4 v[178:179], off
	v_lshl_add_u64 v[178:179], v[220:221], 0, s[12:13]
	s_mov_b32 m0, s67
	s_nop 0
	global_load_lds_dwordx4 v[178:179], off
	s_waitcnt vmcnt(8)
	s_waitcnt lgkmcnt(0)
	s_barrier
	s_setprio 1
	s_waitcnt lgkmcnt(0)
	v_mfma_f32_16x16x32_bf16 v[60:63], v[140:143], v[184:187], v[60:63]
	v_mfma_f32_16x16x32_bf16 v[60:63], v[150:153], v[188:191], v[60:63]
	v_mfma_f32_16x16x32_bf16 v[56:59], v[154:157], v[184:187], v[56:59]
	v_mfma_f32_16x16x32_bf16 v[56:59], v[158:161], v[188:191], v[56:59]
	v_mfma_f32_16x16x32_bf16 v[44:47], v[140:143], v[192:195], v[44:47]
	v_mfma_f32_16x16x32_bf16 v[44:47], v[150:153], v[196:199], v[44:47]
	v_mfma_f32_16x16x32_bf16 v[40:43], v[154:157], v[192:195], v[40:43]
	v_mfma_f32_16x16x32_bf16 v[40:43], v[158:161], v[196:199], v[40:43]
	v_mfma_f32_16x16x32_bf16 v[28:31], v[140:143], v[200:203], v[28:31]
	v_mfma_f32_16x16x32_bf16 v[28:31], v[150:153], v[204:207], v[28:31]
	v_mfma_f32_16x16x32_bf16 v[24:27], v[154:157], v[200:203], v[24:27]
	v_mfma_f32_16x16x32_bf16 v[24:27], v[158:161], v[204:207], v[24:27]
	v_mfma_f32_16x16x32_bf16 v[12:15], v[140:143], v[208:211], v[12:15]
	v_mfma_f32_16x16x32_bf16 v[12:15], v[150:153], v[212:215], v[12:15]
	v_mfma_f32_16x16x32_bf16 v[8:11], v[154:157], v[208:211], v[8:11]
	v_mfma_f32_16x16x32_bf16 v[8:11], v[158:161], v[212:215], v[8:11]
	v_mfma_f32_16x16x32_bf16 v[52:55], v[162:165], v[184:187], v[52:55]
	v_mfma_f32_16x16x32_bf16 v[52:55], v[166:169], v[188:191], v[52:55]
	v_mfma_f32_16x16x32_bf16 v[48:51], v[170:173], v[184:187], v[48:51]
	v_mfma_f32_16x16x32_bf16 v[48:51], v[174:177], v[188:191], v[48:51]
	v_mfma_f32_16x16x32_bf16 v[36:39], v[162:165], v[192:195], v[36:39]
	v_mfma_f32_16x16x32_bf16 v[36:39], v[166:169], v[196:199], v[36:39]
	v_mfma_f32_16x16x32_bf16 v[32:35], v[170:173], v[192:195], v[32:35]
	v_mfma_f32_16x16x32_bf16 v[32:35], v[174:177], v[196:199], v[32:35]
	v_mfma_f32_16x16x32_bf16 v[20:23], v[162:165], v[200:203], v[20:23]
	v_mfma_f32_16x16x32_bf16 v[20:23], v[166:169], v[204:207], v[20:23]
	v_mfma_f32_16x16x32_bf16 v[16:19], v[170:173], v[200:203], v[16:19]
	v_mfma_f32_16x16x32_bf16 v[16:19], v[174:177], v[204:207], v[16:19]
	v_mfma_f32_16x16x32_bf16 v[4:7], v[162:165], v[208:211], v[4:7]
	v_mfma_f32_16x16x32_bf16 v[4:7], v[166:169], v[212:215], v[4:7]
	v_mfma_f32_16x16x32_bf16 v[0:3], v[170:173], v[208:211], v[0:3]
	v_mfma_f32_16x16x32_bf16 v[0:3], v[174:177], v[212:215], v[0:3]
	s_setprio 0
	s_barrier
	s_add_i32 s76, s76, 2
	s_add_u32 s52, s52, 0x100
	s_addc_u32 s53, s53, 0
	s_add_u32 s74, s74, 0x100
	s_addc_u32 s75, s75, 0
	s_cmp_gt_u32 s76, 13
	s_cbranch_scc0 .LBB0_951
	s_and_b64 vcc, exec, s[16:17]
	s_cbranch_vccz .LBB0_954
	s_barrier

.LBB0_1030:
	s_add_u32 s86, s56, 0x100
	s_addc_u32 s87, s57, 0
	s_mov_b32 s88, -2
	ds_read_b128 v[152:155], v149
	ds_read_b128 v[156:159], v149 offset:1024
	ds_read_b128 v[160:163], v149 offset:2048
	ds_read_b128 v[164:167], v149 offset:3072
	ds_read_b128 v[168:171], v150
	ds_read_b128 v[172:175], v150 offset:1024
	ds_read_b128 v[176:179], v150 offset:2048
	ds_read_b128 v[184:187], v150 offset:3072
	s_add_u32 s56, s54, 0x100
	s_addc_u32 s57, s55, 0
	s_cmp_eq_u32 s88, 40
	s_cselect_b32 s61, s13, s57
	s_cselect_b32 s60, s12, s56
	s_cselect_b32 s59, s53, s87
	s_cselect_b32 s58, s52, s86
	v_lshl_add_u64 v[144:145], s[54:55], 0, v[136:137]
	s_add_i32 m0, s65, 0xc000
	ds_read_b128 v[188:191], v151
	ds_read_b128 v[192:195], v151 offset:1024
	ds_read_b128 v[196:199], v151 offset:2048
	ds_read_b128 v[200:203], v151 offset:3072
	ds_read_b128 v[204:207], v151 offset:4096
	ds_read_b128 v[208:211], v151 offset:5120
	ds_read_b128 v[212:215], v151 offset:6144
	ds_read_b128 v[216:219], v151 offset:7168
	global_load_lds_dwordx4 v[144:145], off
	v_lshl_add_u64 v[144:145], s[54:55], 0, v[138:139]
	s_add_i32 m0, s65, 0xe000
	s_nop 0
	global_load_lds_dwordx4 v[144:145], off
	s_waitcnt vmcnt(8)
	s_waitcnt lgkmcnt(0)
	s_barrier
	s_setprio 1
	s_waitcnt lgkmcnt(0)
	v_mfma_f32_16x16x32_bf16 v[124:127], v[152:155], v[188:191], 0
	v_mfma_f32_16x16x32_bf16 v[124:127], v[156:159], v[192:195], v[124:127]
	v_mfma_f32_16x16x32_bf16 v[120:123], v[160:163], v[188:191], 0
	v_mfma_f32_16x16x32_bf16 v[120:123], v[164:167], v[192:195], v[120:123]
	v_mfma_f32_16x16x32_bf16 v[116:119], v[152:155], v[196:199], 0
	v_mfma_f32_16x16x32_bf16 v[116:119], v[156:159], v[200:203], v[116:119]
	v_mfma_f32_16x16x32_bf16 v[108:111], v[160:163], v[196:199], 0
	v_mfma_f32_16x16x32_bf16 v[108:111], v[164:167], v[200:203], v[108:111]
	v_mfma_f32_16x16x32_bf16 v[100:103], v[152:155], v[204:207], 0
	v_mfma_f32_16x16x32_bf16 v[100:103], v[156:159], v[208:211], v[100:103]
	v_mfma_f32_16x16x32_bf16 v[92:95], v[160:163], v[204:207], 0
	v_mfma_f32_16x16x32_bf16 v[92:95], v[164:167], v[208:211], v[92:95]
	v_mfma_f32_16x16x32_bf16 v[84:87], v[152:155], v[212:215], 0
	v_mfma_f32_16x16x32_bf16 v[84:87], v[156:159], v[216:219], v[84:87]
	v_mfma_f32_16x16x32_bf16 v[76:79], v[160:163], v[212:215], 0
	v_mfma_f32_16x16x32_bf16 v[76:79], v[164:167], v[216:219], v[76:79]
	v_mfma_f32_16x16x32_bf16 v[112:115], v[168:171], v[188:191], 0
	v_mfma_f32_16x16x32_bf16 v[112:115], v[172:175], v[192:195], v[112:115]
	v_mfma_f32_16x16x32_bf16 v[104:107], v[176:179], v[188:191], 0
	v_mfma_f32_16x16x32_bf16 v[104:107], v[184:187], v[192:195], v[104:107]
	v_mfma_f32_16x16x32_bf16 v[96:99], v[168:171], v[196:199], 0
	v_mfma_f32_16x16x32_bf16 v[96:99], v[172:175], v[200:203], v[96:99]
	v_mfma_f32_16x16x32_bf16 v[88:91], v[176:179], v[196:199], 0
	v_mfma_f32_16x16x32_bf16 v[88:91], v[184:187], v[200:203], v[88:91]
	v_mfma_f32_16x16x32_bf16 v[80:83], v[168:171], v[204:207], 0
	v_mfma_f32_16x16x32_bf16 v[80:83], v[172:175], v[208:211], v[80:83]
	v_mfma_f32_16x16x32_bf16 v[72:75], v[176:179], v[204:207], 0
	v_mfma_f32_16x16x32_bf16 v[72:75], v[184:187], v[208:211], v[72:75]
	v_mfma_f32_16x16x32_bf16 v[68:71], v[168:171], v[212:215], 0
	v_mfma_f32_16x16x32_bf16 v[68:71], v[172:175], v[216:219], v[68:71]
	v_mfma_f32_16x16x32_bf16 v[64:67], v[176:179], v[212:215], 0
	v_mfma_f32_16x16x32_bf16 v[64:67], v[184:187], v[216:219], v[64:67]
	s_setprio 0
	s_barrier
	s_add_i32 s54, s72, s64
	v_lshl_add_u64 v[144:145], s[58:59], 0, v[130:131]
	s_mov_b32 m0, s54
	ds_read_b128 v[188:191], v151 offset:16384
	ds_read_b128 v[192:195], v151 offset:17408
	ds_read_b128 v[196:199], v151 offset:18432
	ds_read_b128 v[200:203], v151 offset:19456
	ds_read_b128 v[204:207], v151 offset:20480
	ds_read_b128 v[208:211], v151 offset:21504
	ds_read_b128 v[212:215], v151 offset:22528
	ds_read_b128 v[216:219], v151 offset:23552
	global_load_lds_dwordx4 v[144:145], off
	s_add_i32 m0, s54, 0x2000
	s_add_u32 s54, s58, 0xb0000
	v_lshl_add_u64 v[220:221], s[58:59], 0, v[134:135]
	s_addc_u32 s55, s59, 0
	s_add_i32 s79, s73, s64
	global_load_lds_dwordx4 v[220:221], off
	v_lshl_add_u64 v[222:223], s[54:55], 0, v[130:131]
	s_mov_b32 m0, s79
	v_lshl_add_u64 v[224:225], s[60:61], 0, v[132:133]
	global_load_lds_dwordx4 v[222:223], off
	v_lshl_add_u64 v[222:223], s[54:55], 0, v[134:135]
	s_add_i32 m0, s79, 0x2000
	s_nop 0
	global_load_lds_dwordx4 v[222:223], off
	v_lshl_add_u64 v[222:223], s[60:61], 0, v[128:129]
	s_mov_b32 m0, s65
	s_nop 0
	global_load_lds_dwordx4 v[222:223], off
	s_mov_b32 m0, s66
	s_nop 0
	global_load_lds_dwordx4 v[224:225], off
	s_waitcnt vmcnt(8)
	s_waitcnt lgkmcnt(0)
	s_barrier
	s_setprio 1
	s_waitcnt lgkmcnt(0)
	v_mfma_f32_16x16x32_bf16 v[60:63], v[152:155], v[188:191], 0
	v_mfma_f32_16x16x32_bf16 v[60:63], v[156:159], v[192:195], v[60:63]
	v_mfma_f32_16x16x32_bf16 v[56:59], v[160:163], v[188:191], 0
	v_mfma_f32_16x16x32_bf16 v[56:59], v[164:167], v[192:195], v[56:59]
	v_mfma_f32_16x16x32_bf16 v[52:55], v[152:155], v[196:199], 0
	v_mfma_f32_16x16x32_bf16 v[52:55], v[156:159], v[200:203], v[52:55]
	v_mfma_f32_16x16x32_bf16 v[44:47], v[160:163], v[196:199], 0
	v_mfma_f32_16x16x32_bf16 v[44:47], v[164:167], v[200:203], v[44:47]
	v_mfma_f32_16x16x32_bf16 v[36:39], v[152:155], v[204:207], 0
	v_mfma_f32_16x16x32_bf16 v[36:39], v[156:159], v[208:211], v[36:39]
	v_mfma_f32_16x16x32_bf16 v[28:31], v[160:163], v[204:207], 0
	v_mfma_f32_16x16x32_bf16 v[28:31], v[164:167], v[208:211], v[28:31]
	v_mfma_f32_16x16x32_bf16 v[20:23], v[152:155], v[212:215], 0
	v_mfma_f32_16x16x32_bf16 v[20:23], v[156:159], v[216:219], v[20:23]
	v_mfma_f32_16x16x32_bf16 v[12:15], v[160:163], v[212:215], 0
	v_mfma_f32_16x16x32_bf16 v[12:15], v[164:167], v[216:219], v[12:15]
	v_mfma_f32_16x16x32_bf16 v[48:51], v[168:171], v[188:191], 0
	v_mfma_f32_16x16x32_bf16 v[48:51], v[172:175], v[192:195], v[48:51]
	v_mfma_f32_16x16x32_bf16 v[40:43], v[176:179], v[188:191], 0
	v_mfma_f32_16x16x32_bf16 v[40:43], v[184:187], v[192:195], v[40:43]
	v_mfma_f32_16x16x32_bf16 v[32:35], v[168:171], v[196:199], 0
	v_mfma_f32_16x16x32_bf16 v[32:35], v[172:175], v[200:203], v[32:35]
	v_mfma_f32_16x16x32_bf16 v[24:27], v[176:179], v[196:199], 0
	v_mfma_f32_16x16x32_bf16 v[24:27], v[184:187], v[200:203], v[24:27]
	v_mfma_f32_16x16x32_bf16 v[16:19], v[168:171], v[204:207], 0
	v_mfma_f32_16x16x32_bf16 v[16:19], v[172:175], v[208:211], v[16:19]
	v_mfma_f32_16x16x32_bf16 v[8:11], v[176:179], v[204:207], 0
	v_mfma_f32_16x16x32_bf16 v[8:11], v[184:187], v[208:211], v[8:11]
	v_mfma_f32_16x16x32_bf16 v[4:7], v[168:171], v[212:215], 0
	v_mfma_f32_16x16x32_bf16 v[4:7], v[172:175], v[216:219], v[4:7]
	v_mfma_f32_16x16x32_bf16 v[0:3], v[176:179], v[212:215], 0
	v_mfma_f32_16x16x32_bf16 v[0:3], v[184:187], v[216:219], v[0:3]
	s_setprio 0
	s_barrier
	s_branch .Lmid_gemm8
.LBB0_1031:
	ds_read_b128 v[152:155], v149
	ds_read_b128 v[156:159], v149 offset:1024
	ds_read_b128 v[160:163], v149 offset:2048
	ds_read_b128 v[164:167], v149 offset:3072
	ds_read_b128 v[168:171], v150
	ds_read_b128 v[172:175], v150 offset:1024
	ds_read_b128 v[176:179], v150 offset:2048
	ds_read_b128 v[184:187], v150 offset:3072
	s_add_u32 s56, s54, 0x100
	s_addc_u32 s57, s55, 0
	s_cmp_eq_u32 s88, 40
	s_cselect_b32 s61, s13, s57
	s_cselect_b32 s60, s12, s56
	s_cselect_b32 s59, s53, s87
	s_cselect_b32 s58, s52, s86
	v_lshl_add_u64 v[144:145], s[54:55], 0, v[136:137]
	s_add_i32 m0, s65, 0xc000
	ds_read_b128 v[188:191], v151
	ds_read_b128 v[192:195], v151 offset:1024
	ds_read_b128 v[196:199], v151 offset:2048
	ds_read_b128 v[200:203], v151 offset:3072
	ds_read_b128 v[204:207], v151 offset:4096
	ds_read_b128 v[208:211], v151 offset:5120
	ds_read_b128 v[212:215], v151 offset:6144
	ds_read_b128 v[216:219], v151 offset:7168
	global_load_lds_dwordx4 v[144:145], off
	v_lshl_add_u64 v[144:145], s[54:55], 0, v[138:139]
	s_add_i32 m0, s65, 0xe000
	s_nop 0
	global_load_lds_dwordx4 v[144:145], off
	s_waitcnt vmcnt(8)
	s_waitcnt lgkmcnt(0)
	s_barrier
	s_setprio 1
	s_waitcnt lgkmcnt(0)
	v_mfma_f32_16x16x32_bf16 v[124:127], v[152:155], v[188:191], v[124:127]
	v_mfma_f32_16x16x32_bf16 v[124:127], v[156:159], v[192:195], v[124:127]
	v_mfma_f32_16x16x32_bf16 v[120:123], v[160:163], v[188:191], v[120:123]
	v_mfma_f32_16x16x32_bf16 v[120:123], v[164:167], v[192:195], v[120:123]
	v_mfma_f32_16x16x32_bf16 v[116:119], v[152:155], v[196:199], v[116:119]
	v_mfma_f32_16x16x32_bf16 v[116:119], v[156:159], v[200:203], v[116:119]
	v_mfma_f32_16x16x32_bf16 v[108:111], v[160:163], v[196:199], v[108:111]
	v_mfma_f32_16x16x32_bf16 v[108:111], v[164:167], v[200:203], v[108:111]
	v_mfma_f32_16x16x32_bf16 v[100:103], v[152:155], v[204:207], v[100:103]
	v_mfma_f32_16x16x32_bf16 v[100:103], v[156:159], v[208:211], v[100:103]
	v_mfma_f32_16x16x32_bf16 v[92:95], v[160:163], v[204:207], v[92:95]
	v_mfma_f32_16x16x32_bf16 v[92:95], v[164:167], v[208:211], v[92:95]
	v_mfma_f32_16x16x32_bf16 v[84:87], v[152:155], v[212:215], v[84:87]
	v_mfma_f32_16x16x32_bf16 v[84:87], v[156:159], v[216:219], v[84:87]
	v_mfma_f32_16x16x32_bf16 v[76:79], v[160:163], v[212:215], v[76:79]
	v_mfma_f32_16x16x32_bf16 v[76:79], v[164:167], v[216:219], v[76:79]
	v_mfma_f32_16x16x32_bf16 v[112:115], v[168:171], v[188:191], v[112:115]
	v_mfma_f32_16x16x32_bf16 v[112:115], v[172:175], v[192:195], v[112:115]
	v_mfma_f32_16x16x32_bf16 v[104:107], v[176:179], v[188:191], v[104:107]
	v_mfma_f32_16x16x32_bf16 v[104:107], v[184:187], v[192:195], v[104:107]
	v_mfma_f32_16x16x32_bf16 v[96:99], v[168:171], v[196:199], v[96:99]
	v_mfma_f32_16x16x32_bf16 v[96:99], v[172:175], v[200:203], v[96:99]
	v_mfma_f32_16x16x32_bf16 v[88:91], v[176:179], v[196:199], v[88:91]
	v_mfma_f32_16x16x32_bf16 v[88:91], v[184:187], v[200:203], v[88:91]
	v_mfma_f32_16x16x32_bf16 v[80:83], v[168:171], v[204:207], v[80:83]
	v_mfma_f32_16x16x32_bf16 v[80:83], v[172:175], v[208:211], v[80:83]
	v_mfma_f32_16x16x32_bf16 v[72:75], v[176:179], v[204:207], v[72:75]
	v_mfma_f32_16x16x32_bf16 v[72:75], v[184:187], v[208:211], v[72:75]
	v_mfma_f32_16x16x32_bf16 v[68:71], v[168:171], v[212:215], v[68:71]
	v_mfma_f32_16x16x32_bf16 v[68:71], v[172:175], v[216:219], v[68:71]
	v_mfma_f32_16x16x32_bf16 v[64:67], v[176:179], v[212:215], v[64:67]
	v_mfma_f32_16x16x32_bf16 v[64:67], v[184:187], v[216:219], v[64:67]
	s_setprio 0
	s_barrier
	s_add_i32 s54, s72, s64
	v_lshl_add_u64 v[144:145], s[58:59], 0, v[130:131]
	s_mov_b32 m0, s54
	ds_read_b128 v[188:191], v151 offset:16384
	ds_read_b128 v[192:195], v151 offset:17408
	ds_read_b128 v[196:199], v151 offset:18432
	ds_read_b128 v[200:203], v151 offset:19456
	ds_read_b128 v[204:207], v151 offset:20480
	ds_read_b128 v[208:211], v151 offset:21504
	ds_read_b128 v[212:215], v151 offset:22528
	ds_read_b128 v[216:219], v151 offset:23552
	global_load_lds_dwordx4 v[144:145], off
	s_add_i32 m0, s54, 0x2000
	s_add_u32 s54, s58, 0xb0000
	v_lshl_add_u64 v[220:221], s[58:59], 0, v[134:135]
	s_addc_u32 s55, s59, 0
	s_add_i32 s79, s73, s64
	global_load_lds_dwordx4 v[220:221], off
	v_lshl_add_u64 v[222:223], s[54:55], 0, v[130:131]
	s_mov_b32 m0, s79
	v_lshl_add_u64 v[224:225], s[60:61], 0, v[132:133]
	global_load_lds_dwordx4 v[222:223], off
	v_lshl_add_u64 v[222:223], s[54:55], 0, v[134:135]
	s_add_i32 m0, s79, 0x2000
	s_nop 0
	global_load_lds_dwordx4 v[222:223], off
	v_lshl_add_u64 v[222:223], s[60:61], 0, v[128:129]
	s_mov_b32 m0, s65
	s_nop 0
	global_load_lds_dwordx4 v[222:223], off
	s_mov_b32 m0, s66
	s_nop 0
	global_load_lds_dwordx4 v[224:225], off
	s_waitcnt vmcnt(8)
	s_waitcnt lgkmcnt(0)
	s_barrier
	s_setprio 1
	s_waitcnt lgkmcnt(0)
	v_mfma_f32_16x16x32_bf16 v[60:63], v[152:155], v[188:191], v[60:63]
	v_mfma_f32_16x16x32_bf16 v[60:63], v[156:159], v[192:195], v[60:63]
	v_mfma_f32_16x16x32_bf16 v[56:59], v[160:163], v[188:191], v[56:59]
	v_mfma_f32_16x16x32_bf16 v[56:59], v[164:167], v[192:195], v[56:59]
	v_mfma_f32_16x16x32_bf16 v[52:55], v[152:155], v[196:199], v[52:55]
	v_mfma_f32_16x16x32_bf16 v[52:55], v[156:159], v[200:203], v[52:55]
	v_mfma_f32_16x16x32_bf16 v[44:47], v[160:163], v[196:199], v[44:47]
	v_mfma_f32_16x16x32_bf16 v[44:47], v[164:167], v[200:203], v[44:47]
	v_mfma_f32_16x16x32_bf16 v[36:39], v[152:155], v[204:207], v[36:39]
	v_mfma_f32_16x16x32_bf16 v[36:39], v[156:159], v[208:211], v[36:39]
	v_mfma_f32_16x16x32_bf16 v[28:31], v[160:163], v[204:207], v[28:31]
	v_mfma_f32_16x16x32_bf16 v[28:31], v[164:167], v[208:211], v[28:31]
	v_mfma_f32_16x16x32_bf16 v[20:23], v[152:155], v[212:215], v[20:23]
	v_mfma_f32_16x16x32_bf16 v[20:23], v[156:159], v[216:219], v[20:23]
	v_mfma_f32_16x16x32_bf16 v[12:15], v[160:163], v[212:215], v[12:15]
	v_mfma_f32_16x16x32_bf16 v[12:15], v[164:167], v[216:219], v[12:15]
	v_mfma_f32_16x16x32_bf16 v[48:51], v[168:171], v[188:191], v[48:51]
	v_mfma_f32_16x16x32_bf16 v[48:51], v[172:175], v[192:195], v[48:51]
	v_mfma_f32_16x16x32_bf16 v[40:43], v[176:179], v[188:191], v[40:43]
	v_mfma_f32_16x16x32_bf16 v[40:43], v[184:187], v[192:195], v[40:43]
	v_mfma_f32_16x16x32_bf16 v[32:35], v[168:171], v[196:199], v[32:35]
	v_mfma_f32_16x16x32_bf16 v[32:35], v[172:175], v[200:203], v[32:35]
	v_mfma_f32_16x16x32_bf16 v[24:27], v[176:179], v[196:199], v[24:27]
	v_mfma_f32_16x16x32_bf16 v[24:27], v[184:187], v[200:203], v[24:27]
	v_mfma_f32_16x16x32_bf16 v[16:19], v[168:171], v[204:207], v[16:19]
	v_mfma_f32_16x16x32_bf16 v[16:19], v[172:175], v[208:211], v[16:19]
	v_mfma_f32_16x16x32_bf16 v[8:11], v[176:179], v[204:207], v[8:11]
	v_mfma_f32_16x16x32_bf16 v[8:11], v[184:187], v[208:211], v[8:11]
	v_mfma_f32_16x16x32_bf16 v[4:7], v[168:171], v[212:215], v[4:7]
	v_mfma_f32_16x16x32_bf16 v[4:7], v[172:175], v[216:219], v[4:7]
	v_mfma_f32_16x16x32_bf16 v[0:3], v[176:179], v[212:215], v[0:3]
	v_mfma_f32_16x16x32_bf16 v[0:3], v[184:187], v[216:219], v[0:3]
	s_setprio 0
	s_barrier
.Lmid_gemm8:
	s_add_i32 s79, 0, 0x18000
	s_add_i32 s89, 0, 0x1c000
	v_add_u32_e32 v164, s79, v147
	v_add_u32_e32 v181, s89, v147
	ds_read_b128 v[152:155], v164
	ds_read_b128 v[156:159], v164 offset:1024
	ds_read_b128 v[160:163], v164 offset:2048
	ds_read_b128 v[164:167], v164 offset:3072
	ds_read_b128 v[168:171], v181
	ds_read_b128 v[172:175], v181 offset:1024
	ds_read_b128 v[176:179], v181 offset:2048
	ds_read_b128 v[184:187], v181 offset:3072
	s_add_u32 s54, s60, 0xb0000
	s_addc_u32 s55, s61, 0
	s_mov_b32 m0, s67
	v_lshl_add_u64 v[226:227], s[54:55], 0, v[128:129]
	ds_read_b128 v[188:191], v151 offset:32768
	ds_read_b128 v[192:195], v151 offset:33792
	ds_read_b128 v[196:199], v151 offset:34816
	ds_read_b128 v[200:203], v151 offset:35840
	ds_read_b128 v[204:207], v151 offset:36864
	ds_read_b128 v[208:211], v151 offset:37888
	ds_read_b128 v[212:215], v151 offset:38912
	ds_read_b128 v[216:219], v151 offset:39936
	global_load_lds_dwordx4 v[226:227], off
	v_lshl_add_u64 v[226:227], s[54:55], 0, v[132:133]
	s_mov_b32 m0, s68
	s_nop 0
	global_load_lds_dwordx4 v[226:227], off
	s_waitcnt vmcnt(8)
	s_waitcnt lgkmcnt(0)
	s_barrier
	s_setprio 1
	s_waitcnt lgkmcnt(0)
	v_mfma_f32_16x16x32_bf16 v[124:127], v[152:155], v[188:191], v[124:127]
	v_mfma_f32_16x16x32_bf16 v[124:127], v[156:159], v[192:195], v[124:127]
	v_mfma_f32_16x16x32_bf16 v[120:123], v[160:163], v[188:191], v[120:123]
	v_mfma_f32_16x16x32_bf16 v[120:123], v[164:167], v[192:195], v[120:123]
	v_mfma_f32_16x16x32_bf16 v[116:119], v[152:155], v[196:199], v[116:119]
	v_mfma_f32_16x16x32_bf16 v[116:119], v[156:159], v[200:203], v[116:119]
	v_mfma_f32_16x16x32_bf16 v[108:111], v[160:163], v[196:199], v[108:111]
	v_mfma_f32_16x16x32_bf16 v[108:111], v[164:167], v[200:203], v[108:111]
	v_mfma_f32_16x16x32_bf16 v[100:103], v[152:155], v[204:207], v[100:103]
	v_mfma_f32_16x16x32_bf16 v[100:103], v[156:159], v[208:211], v[100:103]
	v_mfma_f32_16x16x32_bf16 v[92:95], v[160:163], v[204:207], v[92:95]
	v_mfma_f32_16x16x32_bf16 v[92:95], v[164:167], v[208:211], v[92:95]
	v_mfma_f32_16x16x32_bf16 v[84:87], v[152:155], v[212:215], v[84:87]
	v_mfma_f32_16x16x32_bf16 v[84:87], v[156:159], v[216:219], v[84:87]
	v_mfma_f32_16x16x32_bf16 v[76:79], v[160:163], v[212:215], v[76:79]
	v_mfma_f32_16x16x32_bf16 v[76:79], v[164:167], v[216:219], v[76:79]
	v_mfma_f32_16x16x32_bf16 v[112:115], v[168:171], v[188:191], v[112:115]
	v_mfma_f32_16x16x32_bf16 v[112:115], v[172:175], v[192:195], v[112:115]
	v_mfma_f32_16x16x32_bf16 v[104:107], v[176:179], v[188:191], v[104:107]
	v_mfma_f32_16x16x32_bf16 v[104:107], v[184:187], v[192:195], v[104:107]
	v_mfma_f32_16x16x32_bf16 v[96:99], v[168:171], v[196:199], v[96:99]
	v_mfma_f32_16x16x32_bf16 v[96:99], v[172:175], v[200:203], v[96:99]
	v_mfma_f32_16x16x32_bf16 v[88:91], v[176:179], v[196:199], v[88:91]
	v_mfma_f32_16x16x32_bf16 v[88:91], v[184:187], v[200:203], v[88:91]
	v_mfma_f32_16x16x32_bf16 v[80:83], v[168:171], v[204:207], v[80:83]
	v_mfma_f32_16x16x32_bf16 v[80:83], v[172:175], v[208:211], v[80:83]
	v_mfma_f32_16x16x32_bf16 v[72:75], v[176:179], v[204:207], v[72:75]
	v_mfma_f32_16x16x32_bf16 v[72:75], v[184:187], v[208:211], v[72:75]
	v_mfma_f32_16x16x32_bf16 v[68:71], v[168:171], v[212:215], v[68:71]
	v_mfma_f32_16x16x32_bf16 v[68:71], v[172:175], v[216:219], v[68:71]
	v_mfma_f32_16x16x32_bf16 v[64:67], v[176:179], v[212:215], v[64:67]
	v_mfma_f32_16x16x32_bf16 v[64:67], v[184:187], v[216:219], v[64:67]
	s_setprio 0
	s_barrier
	s_add_i32 s54, s79, s64
	v_lshl_add_u64 v[144:145], v[144:145], 0, s[16:17]
	s_mov_b32 m0, s54
	ds_read_b128 v[188:191], v151 offset:49152
	ds_read_b128 v[192:195], v151 offset:50176
	ds_read_b128 v[196:199], v151 offset:51200
	ds_read_b128 v[200:203], v151 offset:52224
	ds_read_b128 v[204:207], v151 offset:53248
	ds_read_b128 v[208:211], v151 offset:54272
	ds_read_b128 v[212:215], v151 offset:55296
	ds_read_b128 v[216:219], v151 offset:56320
	global_load_lds_dwordx4 v[144:145], off
	s_add_i32 m0, s54, 0x2000
	s_add_u32 s54, s58, 0xb0080
	v_lshl_add_u64 v[144:145], v[220:221], 0, s[16:17]
	s_addc_u32 s55, s59, 0
	s_add_i32 s58, s89, s64
	global_load_lds_dwordx4 v[144:145], off
	v_lshl_add_u64 v[144:145], s[54:55], 0, v[130:131]
	s_mov_b32 m0, s58
	s_nop 0
	global_load_lds_dwordx4 v[144:145], off
	v_lshl_add_u64 v[144:145], s[54:55], 0, v[134:135]
	s_add_i32 m0, s58, 0x2000
	s_nop 0
	global_load_lds_dwordx4 v[144:145], off
	v_lshl_add_u64 v[144:145], v[222:223], 0, s[16:17]
	s_mov_b32 m0, s70
	s_nop 0
	global_load_lds_dwordx4 v[144:145], off
	v_lshl_add_u64 v[144:145], v[224:225], 0, s[16:17]
	s_mov_b32 m0, s71
	s_nop 0
	global_load_lds_dwordx4 v[144:145], off
	s_waitcnt vmcnt(8)
	s_waitcnt lgkmcnt(0)
	s_barrier
	s_setprio 1
	s_waitcnt lgkmcnt(0)
	v_mfma_f32_16x16x32_bf16 v[60:63], v[152:155], v[188:191], v[60:63]
	v_mfma_f32_16x16x32_bf16 v[60:63], v[156:159], v[192:195], v[60:63]
	v_mfma_f32_16x16x32_bf16 v[56:59], v[160:163], v[188:191], v[56:59]
	v_mfma_f32_16x16x32_bf16 v[56:59], v[164:167], v[192:195], v[56:59]
	v_mfma_f32_16x16x32_bf16 v[52:55], v[152:155], v[196:199], v[52:55]
	v_mfma_f32_16x16x32_bf16 v[52:55], v[156:159], v[200:203], v[52:55]
	v_mfma_f32_16x16x32_bf16 v[44:47], v[160:163], v[196:199], v[44:47]
	v_mfma_f32_16x16x32_bf16 v[44:47], v[164:167], v[200:203], v[44:47]
	v_mfma_f32_16x16x32_bf16 v[36:39], v[152:155], v[204:207], v[36:39]
	v_mfma_f32_16x16x32_bf16 v[36:39], v[156:159], v[208:211], v[36:39]
	v_mfma_f32_16x16x32_bf16 v[28:31], v[160:163], v[204:207], v[28:31]
	v_mfma_f32_16x16x32_bf16 v[28:31], v[164:167], v[208:211], v[28:31]
	v_mfma_f32_16x16x32_bf16 v[20:23], v[152:155], v[212:215], v[20:23]
	v_mfma_f32_16x16x32_bf16 v[20:23], v[156:159], v[216:219], v[20:23]
	v_mfma_f32_16x16x32_bf16 v[12:15], v[160:163], v[212:215], v[12:15]
	v_mfma_f32_16x16x32_bf16 v[12:15], v[164:167], v[216:219], v[12:15]
	v_mfma_f32_16x16x32_bf16 v[48:51], v[168:171], v[188:191], v[48:51]
	v_mfma_f32_16x16x32_bf16 v[48:51], v[172:175], v[192:195], v[48:51]
	v_mfma_f32_16x16x32_bf16 v[40:43], v[176:179], v[188:191], v[40:43]
	v_mfma_f32_16x16x32_bf16 v[40:43], v[184:187], v[192:195], v[40:43]
	v_mfma_f32_16x16x32_bf16 v[32:35], v[168:171], v[196:199], v[32:35]
	v_mfma_f32_16x16x32_bf16 v[32:35], v[172:175], v[200:203], v[32:35]
	v_mfma_f32_16x16x32_bf16 v[24:27], v[176:179], v[196:199], v[24:27]
	v_mfma_f32_16x16x32_bf16 v[24:27], v[184:187], v[200:203], v[24:27]
	v_mfma_f32_16x16x32_bf16 v[16:19], v[168:171], v[204:207], v[16:19]
	v_mfma_f32_16x16x32_bf16 v[16:19], v[172:175], v[208:211], v[16:19]
	v_mfma_f32_16x16x32_bf16 v[8:11], v[176:179], v[204:207], v[8:11]
	v_mfma_f32_16x16x32_bf16 v[8:11], v[184:187], v[208:211], v[8:11]
	v_mfma_f32_16x16x32_bf16 v[4:7], v[168:171], v[212:215], v[4:7]
	v_mfma_f32_16x16x32_bf16 v[4:7], v[172:175], v[216:219], v[4:7]
	v_mfma_f32_16x16x32_bf16 v[0:3], v[176:179], v[212:215], v[0:3]
	v_mfma_f32_16x16x32_bf16 v[0:3], v[184:187], v[216:219], v[0:3]
	s_setprio 0
	s_barrier
	s_add_i32 s88, s88, 2
	s_add_u32 s86, s86, 0x100
	s_addc_u32 s87, s87, 0
	s_cmp_gt_u32 s88, 41
	s_mov_b64 s[54:55], s[56:57]
	s_cbranch_scc0 .LBB0_1031
	s_and_b64 vcc, exec, s[18:19]
	s_cbranch_vccz .LBB0_1034
	s_barrier

.LBB0_1161:
	s_ashr_i32 s53, s52, 31
	s_lshl_b64 s[54:55], s[52:53], 19
	s_add_u32 s54, s80, s54
	s_addc_u32 s55, s81, s55
	s_and_b64 s[56:57], s[10:11], exec
	s_cselect_b32 s53, s55, s61
	s_cselect_b32 s83, s54, s60
	s_ashr_i32 s49, s48, 31
	s_lshl_b64 s[56:57], s[48:49], 19
	s_add_u32 s56, s66, s56
	s_addc_u32 s57, s67, s57
	s_and_b64 s[64:65], s[10:11], exec
	s_cselect_b32 s49, s57, s63
	s_cselect_b32 s84, s56, s62
	s_add_u32 s60, s60, 0x40080
	s_addc_u32 s61, s61, 0
	s_add_u32 s85, s62, 0x100
	s_addc_u32 s86, s63, 0
	s_mov_b32 s87, -2
	ds_read_b128 v[152:155], v148
	ds_read_b128 v[156:159], v148 offset:1024
	ds_read_b128 v[160:163], v148 offset:2048
	ds_read_b128 v[164:167], v148 offset:3072
	ds_read_b128 v[168:171], v149
	ds_read_b128 v[172:175], v149 offset:1024
	ds_read_b128 v[176:179], v149 offset:2048
	ds_read_b128 v[184:187], v149 offset:3072
	s_add_u32 s62, s60, 0xfffc0080
	s_addc_u32 s63, s61, -1
	s_cmp_eq_u32 s87, 12
	s_cselect_b32 s65, s53, s63
	s_cselect_b32 s64, s83, s62
	s_cselect_b32 s63, s49, s86
	s_cselect_b32 s62, s84, s85
	v_lshl_add_u64 v[220:221], s[60:61], 0, v[138:139]
	s_add_i32 m0, s69, 0xc000
	ds_read_b128 v[188:191], v150
	ds_read_b128 v[192:195], v150 offset:1024
	ds_read_b128 v[196:199], v150 offset:2048
	ds_read_b128 v[200:203], v150 offset:3072
	ds_read_b128 v[204:207], v150 offset:4096
	ds_read_b128 v[208:211], v150 offset:5120
	ds_read_b128 v[212:215], v150 offset:6144
	ds_read_b128 v[216:219], v150 offset:7168
	global_load_lds_dwordx4 v[220:221], off
	v_lshl_add_u64 v[220:221], s[60:61], 0, v[140:141]
	s_add_i32 m0, s69, 0xe000
	s_nop 0
	global_load_lds_dwordx4 v[220:221], off
	s_waitcnt vmcnt(8)
	s_waitcnt lgkmcnt(0)
	s_barrier
	s_setprio 1
	s_waitcnt lgkmcnt(0)
	v_mfma_f32_16x16x32_bf16 v[124:127], v[152:155], v[188:191], 0
	v_mfma_f32_16x16x32_bf16 v[124:127], v[156:159], v[192:195], v[124:127]
	v_mfma_f32_16x16x32_bf16 v[120:123], v[160:163], v[188:191], 0
	v_mfma_f32_16x16x32_bf16 v[120:123], v[164:167], v[192:195], v[120:123]
	v_mfma_f32_16x16x32_bf16 v[116:119], v[152:155], v[196:199], 0
	v_mfma_f32_16x16x32_bf16 v[116:119], v[156:159], v[200:203], v[116:119]
	v_mfma_f32_16x16x32_bf16 v[112:115], v[160:163], v[196:199], 0
	v_mfma_f32_16x16x32_bf16 v[112:115], v[164:167], v[200:203], v[112:115]
	v_mfma_f32_16x16x32_bf16 v[108:111], v[152:155], v[204:207], 0
	v_mfma_f32_16x16x32_bf16 v[108:111], v[156:159], v[208:211], v[108:111]
	v_mfma_f32_16x16x32_bf16 v[104:107], v[160:163], v[204:207], 0
	v_mfma_f32_16x16x32_bf16 v[104:107], v[164:167], v[208:211], v[104:107]
	v_mfma_f32_16x16x32_bf16 v[100:103], v[152:155], v[212:215], 0
	v_mfma_f32_16x16x32_bf16 v[100:103], v[156:159], v[216:219], v[100:103]
	v_mfma_f32_16x16x32_bf16 v[96:99], v[160:163], v[212:215], 0
	v_mfma_f32_16x16x32_bf16 v[96:99], v[164:167], v[216:219], v[96:99]
	v_mfma_f32_16x16x32_bf16 v[68:71], v[168:171], v[188:191], 0
	v_mfma_f32_16x16x32_bf16 v[68:71], v[172:175], v[192:195], v[68:71]
	v_mfma_f32_16x16x32_bf16 v[64:67], v[176:179], v[188:191], 0
	v_mfma_f32_16x16x32_bf16 v[64:67], v[184:187], v[192:195], v[64:67]
	v_mfma_f32_16x16x32_bf16 v[52:55], v[168:171], v[196:199], 0
	v_mfma_f32_16x16x32_bf16 v[52:55], v[172:175], v[200:203], v[52:55]
	v_mfma_f32_16x16x32_bf16 v[48:51], v[176:179], v[196:199], 0
	v_mfma_f32_16x16x32_bf16 v[48:51], v[184:187], v[200:203], v[48:51]
	v_mfma_f32_16x16x32_bf16 v[44:47], v[168:171], v[204:207], 0
	v_mfma_f32_16x16x32_bf16 v[44:47], v[172:175], v[208:211], v[44:47]
	v_mfma_f32_16x16x32_bf16 v[40:43], v[176:179], v[204:207], 0
	v_mfma_f32_16x16x32_bf16 v[40:43], v[184:187], v[208:211], v[40:43]
	v_mfma_f32_16x16x32_bf16 v[36:39], v[168:171], v[212:215], 0
	v_mfma_f32_16x16x32_bf16 v[36:39], v[172:175], v[216:219], v[36:39]
	v_mfma_f32_16x16x32_bf16 v[32:35], v[176:179], v[212:215], 0
	v_mfma_f32_16x16x32_bf16 v[32:35], v[184:187], v[216:219], v[32:35]
	s_setprio 0
	s_barrier
	s_add_i32 s79, s77, s68
	v_lshl_add_u64 v[220:221], s[62:63], 0, v[130:131]
	s_mov_b32 m0, s79
	ds_read_b128 v[188:191], v150 offset:16384
	ds_read_b128 v[192:195], v150 offset:17408
	ds_read_b128 v[196:199], v150 offset:18432
	ds_read_b128 v[200:203], v150 offset:19456
	ds_read_b128 v[204:207], v150 offset:20480
	ds_read_b128 v[208:211], v150 offset:21504
	ds_read_b128 v[212:215], v150 offset:22528
	ds_read_b128 v[216:219], v150 offset:23552
	global_load_lds_dwordx4 v[220:221], off
	s_add_i32 m0, s79, 0x2000
	s_add_u32 s88, s62, 0x40000
	v_lshl_add_u64 v[222:223], s[62:63], 0, v[134:135]
	s_addc_u32 s89, s63, 0
	s_add_i32 s79, s82, s68
	global_load_lds_dwordx4 v[222:223], off
	v_lshl_add_u64 v[224:225], s[88:89], 0, v[130:131]
	s_mov_b32 m0, s79
	v_lshl_add_u64 v[226:227], s[64:65], 0, v[132:133]
	global_load_lds_dwordx4 v[224:225], off
	v_lshl_add_u64 v[224:225], s[88:89], 0, v[134:135]
	s_add_i32 m0, s79, 0x2000
	s_nop 0
	global_load_lds_dwordx4 v[224:225], off
	v_lshl_add_u64 v[224:225], s[64:65], 0, v[128:129]
	s_mov_b32 m0, s69
	s_nop 0
	global_load_lds_dwordx4 v[224:225], off
	s_mov_b32 m0, s70
	s_nop 0
	global_load_lds_dwordx4 v[226:227], off
	s_waitcnt vmcnt(8)
	s_waitcnt lgkmcnt(0)
	s_barrier
	s_setprio 1
	s_waitcnt lgkmcnt(0)
	v_mfma_f32_16x16x32_bf16 v[92:95], v[152:155], v[188:191], 0
	v_mfma_f32_16x16x32_bf16 v[92:95], v[156:159], v[192:195], v[92:95]
	v_mfma_f32_16x16x32_bf16 v[88:91], v[160:163], v[188:191], 0
	v_mfma_f32_16x16x32_bf16 v[88:91], v[164:167], v[192:195], v[88:91]
	v_mfma_f32_16x16x32_bf16 v[84:87], v[152:155], v[196:199], 0
	v_mfma_f32_16x16x32_bf16 v[84:87], v[156:159], v[200:203], v[84:87]
	v_mfma_f32_16x16x32_bf16 v[80:83], v[160:163], v[196:199], 0
	v_mfma_f32_16x16x32_bf16 v[80:83], v[164:167], v[200:203], v[80:83]
	v_mfma_f32_16x16x32_bf16 v[76:79], v[152:155], v[204:207], 0
	v_mfma_f32_16x16x32_bf16 v[76:79], v[156:159], v[208:211], v[76:79]
	v_mfma_f32_16x16x32_bf16 v[72:75], v[160:163], v[204:207], 0
	v_mfma_f32_16x16x32_bf16 v[72:75], v[164:167], v[208:211], v[72:75]
	v_mfma_f32_16x16x32_bf16 v[60:63], v[152:155], v[212:215], 0
	v_mfma_f32_16x16x32_bf16 v[60:63], v[156:159], v[216:219], v[60:63]
	v_mfma_f32_16x16x32_bf16 v[56:59], v[160:163], v[212:215], 0
	v_mfma_f32_16x16x32_bf16 v[56:59], v[164:167], v[216:219], v[56:59]
	v_mfma_f32_16x16x32_bf16 v[28:31], v[168:171], v[188:191], 0
	v_mfma_f32_16x16x32_bf16 v[28:31], v[172:175], v[192:195], v[28:31]
	v_mfma_f32_16x16x32_bf16 v[24:27], v[176:179], v[188:191], 0
	v_mfma_f32_16x16x32_bf16 v[24:27], v[184:187], v[192:195], v[24:27]
	v_mfma_f32_16x16x32_bf16 v[20:23], v[168:171], v[196:199], 0
	v_mfma_f32_16x16x32_bf16 v[20:23], v[172:175], v[200:203], v[20:23]
	v_mfma_f32_16x16x32_bf16 v[16:19], v[176:179], v[196:199], 0
	v_mfma_f32_16x16x32_bf16 v[16:19], v[184:187], v[200:203], v[16:19]
	v_mfma_f32_16x16x32_bf16 v[12:15], v[168:171], v[204:207], 0
	v_mfma_f32_16x16x32_bf16 v[12:15], v[172:175], v[208:211], v[12:15]
	v_mfma_f32_16x16x32_bf16 v[8:11], v[176:179], v[204:207], 0
	v_mfma_f32_16x16x32_bf16 v[8:11], v[184:187], v[208:211], v[8:11]
	v_mfma_f32_16x16x32_bf16 v[4:7], v[168:171], v[212:215], 0
	v_mfma_f32_16x16x32_bf16 v[4:7], v[172:175], v[216:219], v[4:7]
	v_mfma_f32_16x16x32_bf16 v[0:3], v[176:179], v[212:215], 0
	v_mfma_f32_16x16x32_bf16 v[0:3], v[184:187], v[216:219], v[0:3]
	s_setprio 0
	s_barrier
	s_branch .Lmid_gemm9
.LBB0_1162:
	ds_read_b128 v[152:155], v148
	ds_read_b128 v[156:159], v148 offset:1024
	ds_read_b128 v[160:163], v148 offset:2048
	ds_read_b128 v[164:167], v148 offset:3072
	ds_read_b128 v[168:171], v149
	ds_read_b128 v[172:175], v149 offset:1024
	ds_read_b128 v[176:179], v149 offset:2048
	ds_read_b128 v[184:187], v149 offset:3072
	s_add_u32 s62, s60, 0xfffc0080
	s_addc_u32 s63, s61, -1
	s_cmp_eq_u32 s87, 12
	s_cselect_b32 s65, s53, s63
	s_cselect_b32 s64, s83, s62
	s_cselect_b32 s63, s49, s86
	s_cselect_b32 s62, s84, s85
	v_lshl_add_u64 v[220:221], s[60:61], 0, v[138:139]
	s_add_i32 m0, s69, 0xc000
	ds_read_b128 v[188:191], v150
	ds_read_b128 v[192:195], v150 offset:1024
	ds_read_b128 v[196:199], v150 offset:2048
	ds_read_b128 v[200:203], v150 offset:3072
	ds_read_b128 v[204:207], v150 offset:4096
	ds_read_b128 v[208:211], v150 offset:5120
	ds_read_b128 v[212:215], v150 offset:6144
	ds_read_b128 v[216:219], v150 offset:7168
	global_load_lds_dwordx4 v[220:221], off
	v_lshl_add_u64 v[220:221], s[60:61], 0, v[140:141]
	s_add_i32 m0, s69, 0xe000
	s_nop 0
	global_load_lds_dwordx4 v[220:221], off
	s_waitcnt vmcnt(8)
	s_waitcnt lgkmcnt(0)
	s_barrier
	s_setprio 1
	s_waitcnt lgkmcnt(0)
	v_mfma_f32_16x16x32_bf16 v[124:127], v[152:155], v[188:191], v[124:127]
	v_mfma_f32_16x16x32_bf16 v[124:127], v[156:159], v[192:195], v[124:127]
	v_mfma_f32_16x16x32_bf16 v[120:123], v[160:163], v[188:191], v[120:123]
	v_mfma_f32_16x16x32_bf16 v[120:123], v[164:167], v[192:195], v[120:123]
	v_mfma_f32_16x16x32_bf16 v[116:119], v[152:155], v[196:199], v[116:119]
	v_mfma_f32_16x16x32_bf16 v[116:119], v[156:159], v[200:203], v[116:119]
	v_mfma_f32_16x16x32_bf16 v[112:115], v[160:163], v[196:199], v[112:115]
	v_mfma_f32_16x16x32_bf16 v[112:115], v[164:167], v[200:203], v[112:115]
	v_mfma_f32_16x16x32_bf16 v[108:111], v[152:155], v[204:207], v[108:111]
	v_mfma_f32_16x16x32_bf16 v[108:111], v[156:159], v[208:211], v[108:111]
	v_mfma_f32_16x16x32_bf16 v[104:107], v[160:163], v[204:207], v[104:107]
	v_mfma_f32_16x16x32_bf16 v[104:107], v[164:167], v[208:211], v[104:107]
	v_mfma_f32_16x16x32_bf16 v[100:103], v[152:155], v[212:215], v[100:103]
	v_mfma_f32_16x16x32_bf16 v[100:103], v[156:159], v[216:219], v[100:103]
	v_mfma_f32_16x16x32_bf16 v[96:99], v[160:163], v[212:215], v[96:99]
	v_mfma_f32_16x16x32_bf16 v[96:99], v[164:167], v[216:219], v[96:99]
	v_mfma_f32_16x16x32_bf16 v[68:71], v[168:171], v[188:191], v[68:71]
	v_mfma_f32_16x16x32_bf16 v[68:71], v[172:175], v[192:195], v[68:71]
	v_mfma_f32_16x16x32_bf16 v[64:67], v[176:179], v[188:191], v[64:67]
	v_mfma_f32_16x16x32_bf16 v[64:67], v[184:187], v[192:195], v[64:67]
	v_mfma_f32_16x16x32_bf16 v[52:55], v[168:171], v[196:199], v[52:55]
	v_mfma_f32_16x16x32_bf16 v[52:55], v[172:175], v[200:203], v[52:55]
	v_mfma_f32_16x16x32_bf16 v[48:51], v[176:179], v[196:199], v[48:51]
	v_mfma_f32_16x16x32_bf16 v[48:51], v[184:187], v[200:203], v[48:51]
	v_mfma_f32_16x16x32_bf16 v[44:47], v[168:171], v[204:207], v[44:47]
	v_mfma_f32_16x16x32_bf16 v[44:47], v[172:175], v[208:211], v[44:47]
	v_mfma_f32_16x16x32_bf16 v[40:43], v[176:179], v[204:207], v[40:43]
	v_mfma_f32_16x16x32_bf16 v[40:43], v[184:187], v[208:211], v[40:43]
	v_mfma_f32_16x16x32_bf16 v[36:39], v[168:171], v[212:215], v[36:39]
	v_mfma_f32_16x16x32_bf16 v[36:39], v[172:175], v[216:219], v[36:39]
	v_mfma_f32_16x16x32_bf16 v[32:35], v[176:179], v[212:215], v[32:35]
	v_mfma_f32_16x16x32_bf16 v[32:35], v[184:187], v[216:219], v[32:35]
	s_setprio 0
	s_barrier
	s_add_i32 s79, s77, s68
	v_lshl_add_u64 v[220:221], s[62:63], 0, v[130:131]
	s_mov_b32 m0, s79
	ds_read_b128 v[188:191], v150 offset:16384
	ds_read_b128 v[192:195], v150 offset:17408
	ds_read_b128 v[196:199], v150 offset:18432
	ds_read_b128 v[200:203], v150 offset:19456
	ds_read_b128 v[204:207], v150 offset:20480
	ds_read_b128 v[208:211], v150 offset:21504
	ds_read_b128 v[212:215], v150 offset:22528
	ds_read_b128 v[216:219], v150 offset:23552
	global_load_lds_dwordx4 v[220:221], off
	s_add_i32 m0, s79, 0x2000
	s_add_u32 s88, s62, 0x40000
	v_lshl_add_u64 v[222:223], s[62:63], 0, v[134:135]
	s_addc_u32 s89, s63, 0
	s_add_i32 s79, s82, s68
	global_load_lds_dwordx4 v[222:223], off
	v_lshl_add_u64 v[224:225], s[88:89], 0, v[130:131]
	s_mov_b32 m0, s79
	v_lshl_add_u64 v[226:227], s[64:65], 0, v[132:133]
	global_load_lds_dwordx4 v[224:225], off
	v_lshl_add_u64 v[224:225], s[88:89], 0, v[134:135]
	s_add_i32 m0, s79, 0x2000
	s_nop 0
	global_load_lds_dwordx4 v[224:225], off
	v_lshl_add_u64 v[224:225], s[64:65], 0, v[128:129]
	s_mov_b32 m0, s69
	s_nop 0
	global_load_lds_dwordx4 v[224:225], off
	s_mov_b32 m0, s70
	s_nop 0
	global_load_lds_dwordx4 v[226:227], off
	s_waitcnt vmcnt(8)
	s_waitcnt lgkmcnt(0)
	s_barrier
	s_setprio 1
	s_waitcnt lgkmcnt(0)
	v_mfma_f32_16x16x32_bf16 v[92:95], v[152:155], v[188:191], v[92:95]
	v_mfma_f32_16x16x32_bf16 v[92:95], v[156:159], v[192:195], v[92:95]
	v_mfma_f32_16x16x32_bf16 v[88:91], v[160:163], v[188:191], v[88:91]
	v_mfma_f32_16x16x32_bf16 v[88:91], v[164:167], v[192:195], v[88:91]
	v_mfma_f32_16x16x32_bf16 v[84:87], v[152:155], v[196:199], v[84:87]
	v_mfma_f32_16x16x32_bf16 v[84:87], v[156:159], v[200:203], v[84:87]
	v_mfma_f32_16x16x32_bf16 v[80:83], v[160:163], v[196:199], v[80:83]
	v_mfma_f32_16x16x32_bf16 v[80:83], v[164:167], v[200:203], v[80:83]
	v_mfma_f32_16x16x32_bf16 v[76:79], v[152:155], v[204:207], v[76:79]
	v_mfma_f32_16x16x32_bf16 v[76:79], v[156:159], v[208:211], v[76:79]
	v_mfma_f32_16x16x32_bf16 v[72:75], v[160:163], v[204:207], v[72:75]
	v_mfma_f32_16x16x32_bf16 v[72:75], v[164:167], v[208:211], v[72:75]
	v_mfma_f32_16x16x32_bf16 v[60:63], v[152:155], v[212:215], v[60:63]
	v_mfma_f32_16x16x32_bf16 v[60:63], v[156:159], v[216:219], v[60:63]
	v_mfma_f32_16x16x32_bf16 v[56:59], v[160:163], v[212:215], v[56:59]
	v_mfma_f32_16x16x32_bf16 v[56:59], v[164:167], v[216:219], v[56:59]
	v_mfma_f32_16x16x32_bf16 v[28:31], v[168:171], v[188:191], v[28:31]
	v_mfma_f32_16x16x32_bf16 v[28:31], v[172:175], v[192:195], v[28:31]
	v_mfma_f32_16x16x32_bf16 v[24:27], v[176:179], v[188:191], v[24:27]
	v_mfma_f32_16x16x32_bf16 v[24:27], v[184:187], v[192:195], v[24:27]
	v_mfma_f32_16x16x32_bf16 v[20:23], v[168:171], v[196:199], v[20:23]
	v_mfma_f32_16x16x32_bf16 v[20:23], v[172:175], v[200:203], v[20:23]
	v_mfma_f32_16x16x32_bf16 v[16:19], v[176:179], v[196:199], v[16:19]
	v_mfma_f32_16x16x32_bf16 v[16:19], v[184:187], v[200:203], v[16:19]
	v_mfma_f32_16x16x32_bf16 v[12:15], v[168:171], v[204:207], v[12:15]
	v_mfma_f32_16x16x32_bf16 v[12:15], v[172:175], v[208:211], v[12:15]
	v_mfma_f32_16x16x32_bf16 v[8:11], v[176:179], v[204:207], v[8:11]
	v_mfma_f32_16x16x32_bf16 v[8:11], v[184:187], v[208:211], v[8:11]
	v_mfma_f32_16x16x32_bf16 v[4:7], v[168:171], v[212:215], v[4:7]
	v_mfma_f32_16x16x32_bf16 v[4:7], v[172:175], v[216:219], v[4:7]
	v_mfma_f32_16x16x32_bf16 v[0:3], v[176:179], v[212:215], v[0:3]
	v_mfma_f32_16x16x32_bf16 v[0:3], v[184:187], v[216:219], v[0:3]
	s_setprio 0
	s_barrier
.Lmid_gemm9:
	s_add_i32 s79, 0, 0x18000
	s_add_i32 s88, 0, 0x1c000
	v_add_u32_e32 v164, s79, v147
	v_add_u32_e32 v181, s88, v147
	ds_read_b128 v[152:155], v164
	ds_read_b128 v[156:159], v164 offset:1024
	ds_read_b128 v[160:163], v164 offset:2048
	ds_read_b128 v[164:167], v164 offset:3072
	ds_read_b128 v[168:171], v181
	ds_read_b128 v[172:175], v181 offset:1024
	ds_read_b128 v[176:179], v181 offset:2048
	ds_read_b128 v[184:187], v181 offset:3072
	s_add_u32 s64, s64, 0x40000
	s_addc_u32 s65, s65, 0
	s_mov_b32 m0, s71
	v_lshl_add_u64 v[228:229], s[64:65], 0, v[128:129]
	ds_read_b128 v[188:191], v150 offset:32768
	ds_read_b128 v[192:195], v150 offset:33792
	ds_read_b128 v[196:199], v150 offset:34816
	ds_read_b128 v[200:203], v150 offset:35840
	ds_read_b128 v[204:207], v150 offset:36864
	ds_read_b128 v[208:211], v150 offset:37888
	ds_read_b128 v[212:215], v150 offset:38912
	ds_read_b128 v[216:219], v150 offset:39936
	global_load_lds_dwordx4 v[228:229], off
	v_lshl_add_u64 v[228:229], s[64:65], 0, v[132:133]
	s_mov_b32 m0, s72
	s_nop 0
	global_load_lds_dwordx4 v[228:229], off
	s_waitcnt vmcnt(8)
	s_waitcnt lgkmcnt(0)
	s_barrier
	s_setprio 1
	s_waitcnt lgkmcnt(0)
	v_mfma_f32_16x16x32_bf16 v[124:127], v[152:155], v[188:191], v[124:127]
	v_mfma_f32_16x16x32_bf16 v[124:127], v[156:159], v[192:195], v[124:127]
	v_mfma_f32_16x16x32_bf16 v[120:123], v[160:163], v[188:191], v[120:123]
	v_mfma_f32_16x16x32_bf16 v[120:123], v[164:167], v[192:195], v[120:123]
	v_mfma_f32_16x16x32_bf16 v[116:119], v[152:155], v[196:199], v[116:119]
	v_mfma_f32_16x16x32_bf16 v[116:119], v[156:159], v[200:203], v[116:119]
	v_mfma_f32_16x16x32_bf16 v[112:115], v[160:163], v[196:199], v[112:115]
	v_mfma_f32_16x16x32_bf16 v[112:115], v[164:167], v[200:203], v[112:115]
	v_mfma_f32_16x16x32_bf16 v[108:111], v[152:155], v[204:207], v[108:111]
	v_mfma_f32_16x16x32_bf16 v[108:111], v[156:159], v[208:211], v[108:111]
	v_mfma_f32_16x16x32_bf16 v[104:107], v[160:163], v[204:207], v[104:107]
	v_mfma_f32_16x16x32_bf16 v[104:107], v[164:167], v[208:211], v[104:107]
	v_mfma_f32_16x16x32_bf16 v[100:103], v[152:155], v[212:215], v[100:103]
	v_mfma_f32_16x16x32_bf16 v[100:103], v[156:159], v[216:219], v[100:103]
	v_mfma_f32_16x16x32_bf16 v[96:99], v[160:163], v[212:215], v[96:99]
	v_mfma_f32_16x16x32_bf16 v[96:99], v[164:167], v[216:219], v[96:99]
	v_mfma_f32_16x16x32_bf16 v[68:71], v[168:171], v[188:191], v[68:71]
	v_mfma_f32_16x16x32_bf16 v[68:71], v[172:175], v[192:195], v[68:71]
	v_mfma_f32_16x16x32_bf16 v[64:67], v[176:179], v[188:191], v[64:67]
	v_mfma_f32_16x16x32_bf16 v[64:67], v[184:187], v[192:195], v[64:67]
	v_mfma_f32_16x16x32_bf16 v[52:55], v[168:171], v[196:199], v[52:55]
	v_mfma_f32_16x16x32_bf16 v[52:55], v[172:175], v[200:203], v[52:55]
	v_mfma_f32_16x16x32_bf16 v[48:51], v[176:179], v[196:199], v[48:51]
	v_mfma_f32_16x16x32_bf16 v[48:51], v[184:187], v[200:203], v[48:51]
	v_mfma_f32_16x16x32_bf16 v[44:47], v[168:171], v[204:207], v[44:47]
	v_mfma_f32_16x16x32_bf16 v[44:47], v[172:175], v[208:211], v[44:47]
	v_mfma_f32_16x16x32_bf16 v[40:43], v[176:179], v[204:207], v[40:43]
	v_mfma_f32_16x16x32_bf16 v[40:43], v[184:187], v[208:211], v[40:43]
	v_mfma_f32_16x16x32_bf16 v[36:39], v[168:171], v[212:215], v[36:39]
	v_mfma_f32_16x16x32_bf16 v[36:39], v[172:175], v[216:219], v[36:39]
	v_mfma_f32_16x16x32_bf16 v[32:35], v[176:179], v[212:215], v[32:35]
	v_mfma_f32_16x16x32_bf16 v[32:35], v[184:187], v[216:219], v[32:35]
	s_setprio 0
	s_barrier
	s_add_i32 s64, s79, s68
	v_lshl_add_u64 v[220:221], v[220:221], 0, s[12:13]
	s_mov_b32 m0, s64
	ds_read_b128 v[188:191], v150 offset:49152
	ds_read_b128 v[192:195], v150 offset:50176
	ds_read_b128 v[196:199], v150 offset:51200
	ds_read_b128 v[200:203], v150 offset:52224
	ds_read_b128 v[204:207], v150 offset:53248
	ds_read_b128 v[208:211], v150 offset:54272
	ds_read_b128 v[212:215], v150 offset:55296
	ds_read_b128 v[216:219], v150 offset:56320
	global_load_lds_dwordx4 v[220:221], off
	s_add_i32 m0, s64, 0x2000
	s_add_u32 s62, s62, 0x40080
	v_lshl_add_u64 v[220:221], v[222:223], 0, s[12:13]
	s_addc_u32 s63, s63, 0
	s_add_i32 s64, s88, s68
	global_load_lds_dwordx4 v[220:221], off
	v_lshl_add_u64 v[220:221], s[62:63], 0, v[130:131]
	s_mov_b32 m0, s64
	s_nop 0
	global_load_lds_dwordx4 v[220:221], off
	v_lshl_add_u64 v[220:221], s[62:63], 0, v[134:135]
	s_add_i32 m0, s64, 0x2000
	s_nop 0
	global_load_lds_dwordx4 v[220:221], off
	v_lshl_add_u64 v[220:221], v[224:225], 0, s[12:13]
	s_mov_b32 m0, s75
	s_nop 0
	global_load_lds_dwordx4 v[220:221], off
	v_lshl_add_u64 v[220:221], v[226:227], 0, s[12:13]
	s_mov_b32 m0, s76
	s_nop 0
	global_load_lds_dwordx4 v[220:221], off
	s_waitcnt vmcnt(8)
	s_waitcnt lgkmcnt(0)
	s_barrier
	s_setprio 1
	s_waitcnt lgkmcnt(0)
	v_mfma_f32_16x16x32_bf16 v[92:95], v[152:155], v[188:191], v[92:95]
	v_mfma_f32_16x16x32_bf16 v[92:95], v[156:159], v[192:195], v[92:95]
	v_mfma_f32_16x16x32_bf16 v[88:91], v[160:163], v[188:191], v[88:91]
	v_mfma_f32_16x16x32_bf16 v[88:91], v[164:167], v[192:195], v[88:91]
	v_mfma_f32_16x16x32_bf16 v[84:87], v[152:155], v[196:199], v[84:87]
	v_mfma_f32_16x16x32_bf16 v[84:87], v[156:159], v[200:203], v[84:87]
	v_mfma_f32_16x16x32_bf16 v[80:83], v[160:163], v[196:199], v[80:83]
	v_mfma_f32_16x16x32_bf16 v[80:83], v[164:167], v[200:203], v[80:83]
	v_mfma_f32_16x16x32_bf16 v[76:79], v[152:155], v[204:207], v[76:79]
	v_mfma_f32_16x16x32_bf16 v[76:79], v[156:159], v[208:211], v[76:79]
	v_mfma_f32_16x16x32_bf16 v[72:75], v[160:163], v[204:207], v[72:75]
	v_mfma_f32_16x16x32_bf16 v[72:75], v[164:167], v[208:211], v[72:75]
	v_mfma_f32_16x16x32_bf16 v[60:63], v[152:155], v[212:215], v[60:63]
	v_mfma_f32_16x16x32_bf16 v[60:63], v[156:159], v[216:219], v[60:63]
	v_mfma_f32_16x16x32_bf16 v[56:59], v[160:163], v[212:215], v[56:59]
	v_mfma_f32_16x16x32_bf16 v[56:59], v[164:167], v[216:219], v[56:59]
	v_mfma_f32_16x16x32_bf16 v[28:31], v[168:171], v[188:191], v[28:31]
	v_mfma_f32_16x16x32_bf16 v[28:31], v[172:175], v[192:195], v[28:31]
	v_mfma_f32_16x16x32_bf16 v[24:27], v[176:179], v[188:191], v[24:27]
	v_mfma_f32_16x16x32_bf16 v[24:27], v[184:187], v[192:195], v[24:27]
	v_mfma_f32_16x16x32_bf16 v[20:23], v[168:171], v[196:199], v[20:23]
	v_mfma_f32_16x16x32_bf16 v[20:23], v[172:175], v[200:203], v[20:23]
	v_mfma_f32_16x16x32_bf16 v[16:19], v[176:179], v[196:199], v[16:19]
	v_mfma_f32_16x16x32_bf16 v[16:19], v[184:187], v[200:203], v[16:19]
	v_mfma_f32_16x16x32_bf16 v[12:15], v[168:171], v[204:207], v[12:15]
	v_mfma_f32_16x16x32_bf16 v[12:15], v[172:175], v[208:211], v[12:15]
	v_mfma_f32_16x16x32_bf16 v[8:11], v[176:179], v[204:207], v[8:11]
	v_mfma_f32_16x16x32_bf16 v[8:11], v[184:187], v[208:211], v[8:11]
	v_mfma_f32_16x16x32_bf16 v[4:7], v[168:171], v[212:215], v[4:7]
	v_mfma_f32_16x16x32_bf16 v[4:7], v[172:175], v[216:219], v[4:7]
	v_mfma_f32_16x16x32_bf16 v[0:3], v[176:179], v[212:215], v[0:3]
	v_mfma_f32_16x16x32_bf16 v[0:3], v[184:187], v[216:219], v[0:3]
	s_setprio 0
	s_barrier
	s_add_i32 s87, s87, 2
	s_add_u32 s60, s60, 0x100
	s_addc_u32 s61, s61, 0
	s_add_u32 s85, s85, 0x100
	s_addc_u32 s86, s86, 0
	s_cmp_gt_u32 s87, 13
	s_cbranch_scc0 .LBB0_1162
	s_and_b64 vcc, exec, s[16:17]
	s_cbranch_vccz .LBB0_1165
	s_barrier

.LBB0_1310:
	s_ashr_i32 s49, s48, 31
	s_lshl_b64 s[50:51], s[48:49], 19
	s_add_u32 s50, s38, s50
	s_addc_u32 s51, s39, s51
	s_and_b64 s[52:53], s[10:11], exec
	s_cselect_b32 s49, s51, s57
	s_cselect_b32 s82, s50, s56
	s_ashr_i32 s47, s46, 31
	s_lshl_b64 s[52:53], s[46:47], 19
	s_add_u32 s52, s62, s52
	s_addc_u32 s53, s63, s53
	s_and_b64 s[60:61], s[10:11], exec
	s_cselect_b32 s47, s53, s59
	s_cselect_b32 s83, s52, s58
	s_add_u32 s56, s56, 0x40080
	s_addc_u32 s57, s57, 0
	s_add_u32 s84, s58, 0x100
	s_addc_u32 s85, s59, 0
	s_mov_b32 s86, -2
	ds_read_b128 v[152:155], v149
	ds_read_b128 v[156:159], v149 offset:1024
	ds_read_b128 v[160:163], v149 offset:2048
	ds_read_b128 v[164:167], v149 offset:3072
	ds_read_b128 v[168:171], v150
	ds_read_b128 v[172:175], v150 offset:1024
	ds_read_b128 v[176:179], v150 offset:2048
	ds_read_b128 v[184:187], v150 offset:3072
	s_add_u32 s58, s56, 0xfffc0080
	s_addc_u32 s59, s57, -1
	s_cmp_eq_u32 s86, 12
	s_cselect_b32 s61, s49, s59
	s_cselect_b32 s60, s82, s58
	s_cselect_b32 s59, s47, s85
	s_cselect_b32 s58, s83, s84
	v_lshl_add_u64 v[144:145], s[56:57], 0, v[136:137]
	s_add_i32 m0, s55, 0xc000
	ds_read_b128 v[188:191], v151
	ds_read_b128 v[192:195], v151 offset:1024
	ds_read_b128 v[196:199], v151 offset:2048
	ds_read_b128 v[200:203], v151 offset:3072
	ds_read_b128 v[204:207], v151 offset:4096
	ds_read_b128 v[208:211], v151 offset:5120
	ds_read_b128 v[212:215], v151 offset:6144
	ds_read_b128 v[216:219], v151 offset:7168
	global_load_lds_dwordx4 v[144:145], off
	v_lshl_add_u64 v[144:145], s[56:57], 0, v[138:139]
	s_add_i32 m0, s55, 0xe000
	s_nop 0
	global_load_lds_dwordx4 v[144:145], off
	s_waitcnt vmcnt(8)
	s_waitcnt lgkmcnt(0)
	s_barrier
	s_setprio 1
	s_waitcnt lgkmcnt(0)
	v_mfma_f32_16x16x32_bf16 v[124:127], v[152:155], v[188:191], 0
	v_mfma_f32_16x16x32_bf16 v[124:127], v[156:159], v[192:195], v[124:127]
	v_mfma_f32_16x16x32_bf16 v[120:123], v[160:163], v[188:191], 0
	v_mfma_f32_16x16x32_bf16 v[120:123], v[164:167], v[192:195], v[120:123]
	v_mfma_f32_16x16x32_bf16 v[116:119], v[152:155], v[196:199], 0
	v_mfma_f32_16x16x32_bf16 v[116:119], v[156:159], v[200:203], v[116:119]
	v_mfma_f32_16x16x32_bf16 v[108:111], v[160:163], v[196:199], 0
	v_mfma_f32_16x16x32_bf16 v[108:111], v[164:167], v[200:203], v[108:111]
	v_mfma_f32_16x16x32_bf16 v[100:103], v[152:155], v[204:207], 0
	v_mfma_f32_16x16x32_bf16 v[100:103], v[156:159], v[208:211], v[100:103]
	v_mfma_f32_16x16x32_bf16 v[92:95], v[160:163], v[204:207], 0
	v_mfma_f32_16x16x32_bf16 v[92:95], v[164:167], v[208:211], v[92:95]
	v_mfma_f32_16x16x32_bf16 v[84:87], v[152:155], v[212:215], 0
	v_mfma_f32_16x16x32_bf16 v[84:87], v[156:159], v[216:219], v[84:87]
	v_mfma_f32_16x16x32_bf16 v[76:79], v[160:163], v[212:215], 0
	v_mfma_f32_16x16x32_bf16 v[76:79], v[164:167], v[216:219], v[76:79]
	v_mfma_f32_16x16x32_bf16 v[112:115], v[168:171], v[188:191], 0
	v_mfma_f32_16x16x32_bf16 v[112:115], v[172:175], v[192:195], v[112:115]
	v_mfma_f32_16x16x32_bf16 v[104:107], v[176:179], v[188:191], 0
	v_mfma_f32_16x16x32_bf16 v[104:107], v[184:187], v[192:195], v[104:107]
	v_mfma_f32_16x16x32_bf16 v[96:99], v[168:171], v[196:199], 0
	v_mfma_f32_16x16x32_bf16 v[96:99], v[172:175], v[200:203], v[96:99]
	v_mfma_f32_16x16x32_bf16 v[88:91], v[176:179], v[196:199], 0
	v_mfma_f32_16x16x32_bf16 v[88:91], v[184:187], v[200:203], v[88:91]
	v_mfma_f32_16x16x32_bf16 v[80:83], v[168:171], v[204:207], 0
	v_mfma_f32_16x16x32_bf16 v[80:83], v[172:175], v[208:211], v[80:83]
	v_mfma_f32_16x16x32_bf16 v[72:75], v[176:179], v[204:207], 0
	v_mfma_f32_16x16x32_bf16 v[72:75], v[184:187], v[208:211], v[72:75]
	v_mfma_f32_16x16x32_bf16 v[68:71], v[168:171], v[212:215], 0
	v_mfma_f32_16x16x32_bf16 v[68:71], v[172:175], v[216:219], v[68:71]
	v_mfma_f32_16x16x32_bf16 v[64:67], v[176:179], v[212:215], 0
	v_mfma_f32_16x16x32_bf16 v[64:67], v[184:187], v[216:219], v[64:67]
	s_setprio 0
	s_barrier
	s_add_i32 s79, s71, s64
	v_lshl_add_u64 v[144:145], s[58:59], 0, v[130:131]
	s_mov_b32 m0, s79
	ds_read_b128 v[188:191], v151 offset:16384
	ds_read_b128 v[192:195], v151 offset:17408
	ds_read_b128 v[196:199], v151 offset:18432
	ds_read_b128 v[200:203], v151 offset:19456
	ds_read_b128 v[204:207], v151 offset:20480
	ds_read_b128 v[208:211], v151 offset:21504
	ds_read_b128 v[212:215], v151 offset:22528
	ds_read_b128 v[216:219], v151 offset:23552
	global_load_lds_dwordx4 v[144:145], off
	s_add_i32 m0, s79, 0x2000
	s_add_u32 s88, s58, 0x40000
	v_lshl_add_u64 v[220:221], s[58:59], 0, v[134:135]
	s_addc_u32 s89, s59, 0
	s_add_i32 s79, s72, s64
	global_load_lds_dwordx4 v[220:221], off
	v_lshl_add_u64 v[222:223], s[88:89], 0, v[130:131]
	s_mov_b32 m0, s79
	v_lshl_add_u64 v[224:225], s[60:61], 0, v[132:133]
	global_load_lds_dwordx4 v[222:223], off
	v_lshl_add_u64 v[222:223], s[88:89], 0, v[134:135]
	s_add_i32 m0, s79, 0x2000
	s_nop 0
	global_load_lds_dwordx4 v[222:223], off
	v_lshl_add_u64 v[222:223], s[60:61], 0, v[128:129]
	s_mov_b32 m0, s55
	s_nop 0
	global_load_lds_dwordx4 v[222:223], off
	s_mov_b32 m0, s65
	s_nop 0
	global_load_lds_dwordx4 v[224:225], off
	s_waitcnt vmcnt(8)
	s_waitcnt lgkmcnt(0)
	s_barrier
	s_setprio 1
	s_waitcnt lgkmcnt(0)
	v_mfma_f32_16x16x32_bf16 v[60:63], v[152:155], v[188:191], 0
	v_mfma_f32_16x16x32_bf16 v[60:63], v[156:159], v[192:195], v[60:63]
	v_mfma_f32_16x16x32_bf16 v[56:59], v[160:163], v[188:191], 0
	v_mfma_f32_16x16x32_bf16 v[56:59], v[164:167], v[192:195], v[56:59]
	v_mfma_f32_16x16x32_bf16 v[52:55], v[152:155], v[196:199], 0
	v_mfma_f32_16x16x32_bf16 v[52:55], v[156:159], v[200:203], v[52:55]
	v_mfma_f32_16x16x32_bf16 v[44:47], v[160:163], v[196:199], 0
	v_mfma_f32_16x16x32_bf16 v[44:47], v[164:167], v[200:203], v[44:47]
	v_mfma_f32_16x16x32_bf16 v[36:39], v[152:155], v[204:207], 0
	v_mfma_f32_16x16x32_bf16 v[36:39], v[156:159], v[208:211], v[36:39]
	v_mfma_f32_16x16x32_bf16 v[28:31], v[160:163], v[204:207], 0
	v_mfma_f32_16x16x32_bf16 v[28:31], v[164:167], v[208:211], v[28:31]
	v_mfma_f32_16x16x32_bf16 v[20:23], v[152:155], v[212:215], 0
	v_mfma_f32_16x16x32_bf16 v[20:23], v[156:159], v[216:219], v[20:23]
	v_mfma_f32_16x16x32_bf16 v[12:15], v[160:163], v[212:215], 0
	v_mfma_f32_16x16x32_bf16 v[12:15], v[164:167], v[216:219], v[12:15]
	v_mfma_f32_16x16x32_bf16 v[48:51], v[168:171], v[188:191], 0
	v_mfma_f32_16x16x32_bf16 v[48:51], v[172:175], v[192:195], v[48:51]
	v_mfma_f32_16x16x32_bf16 v[40:43], v[176:179], v[188:191], 0
	v_mfma_f32_16x16x32_bf16 v[40:43], v[184:187], v[192:195], v[40:43]
	v_mfma_f32_16x16x32_bf16 v[32:35], v[168:171], v[196:199], 0
	v_mfma_f32_16x16x32_bf16 v[32:35], v[172:175], v[200:203], v[32:35]
	v_mfma_f32_16x16x32_bf16 v[24:27], v[176:179], v[196:199], 0
	v_mfma_f32_16x16x32_bf16 v[24:27], v[184:187], v[200:203], v[24:27]
	v_mfma_f32_16x16x32_bf16 v[16:19], v[168:171], v[204:207], 0
	v_mfma_f32_16x16x32_bf16 v[16:19], v[172:175], v[208:211], v[16:19]
	v_mfma_f32_16x16x32_bf16 v[8:11], v[176:179], v[204:207], 0
	v_mfma_f32_16x16x32_bf16 v[8:11], v[184:187], v[208:211], v[8:11]
	v_mfma_f32_16x16x32_bf16 v[4:7], v[168:171], v[212:215], 0
	v_mfma_f32_16x16x32_bf16 v[4:7], v[172:175], v[216:219], v[4:7]
	v_mfma_f32_16x16x32_bf16 v[0:3], v[176:179], v[212:215], 0
	v_mfma_f32_16x16x32_bf16 v[0:3], v[184:187], v[216:219], v[0:3]
	s_setprio 0
	s_barrier
	s_branch .Lmid_gemm10
.LBB0_1311:
	ds_read_b128 v[152:155], v149
	ds_read_b128 v[156:159], v149 offset:1024
	ds_read_b128 v[160:163], v149 offset:2048
	ds_read_b128 v[164:167], v149 offset:3072
	ds_read_b128 v[168:171], v150
	ds_read_b128 v[172:175], v150 offset:1024
	ds_read_b128 v[176:179], v150 offset:2048
	ds_read_b128 v[184:187], v150 offset:3072
	s_add_u32 s58, s56, 0xfffc0080
	s_addc_u32 s59, s57, -1
	s_cmp_eq_u32 s86, 12
	s_cselect_b32 s61, s49, s59
	s_cselect_b32 s60, s82, s58
	s_cselect_b32 s59, s47, s85
	s_cselect_b32 s58, s83, s84
	v_lshl_add_u64 v[144:145], s[56:57], 0, v[136:137]
	s_add_i32 m0, s55, 0xc000
	ds_read_b128 v[188:191], v151
	ds_read_b128 v[192:195], v151 offset:1024
	ds_read_b128 v[196:199], v151 offset:2048
	ds_read_b128 v[200:203], v151 offset:3072
	ds_read_b128 v[204:207], v151 offset:4096
	ds_read_b128 v[208:211], v151 offset:5120
	ds_read_b128 v[212:215], v151 offset:6144
	ds_read_b128 v[216:219], v151 offset:7168
	global_load_lds_dwordx4 v[144:145], off
	v_lshl_add_u64 v[144:145], s[56:57], 0, v[138:139]
	s_add_i32 m0, s55, 0xe000
	s_nop 0
	global_load_lds_dwordx4 v[144:145], off
	s_waitcnt vmcnt(8)
	s_waitcnt lgkmcnt(0)
	s_barrier
	s_setprio 1
	s_waitcnt lgkmcnt(0)
	v_mfma_f32_16x16x32_bf16 v[124:127], v[152:155], v[188:191], v[124:127]
	v_mfma_f32_16x16x32_bf16 v[124:127], v[156:159], v[192:195], v[124:127]
	v_mfma_f32_16x16x32_bf16 v[120:123], v[160:163], v[188:191], v[120:123]
	v_mfma_f32_16x16x32_bf16 v[120:123], v[164:167], v[192:195], v[120:123]
	v_mfma_f32_16x16x32_bf16 v[116:119], v[152:155], v[196:199], v[116:119]
	v_mfma_f32_16x16x32_bf16 v[116:119], v[156:159], v[200:203], v[116:119]
	v_mfma_f32_16x16x32_bf16 v[108:111], v[160:163], v[196:199], v[108:111]
	v_mfma_f32_16x16x32_bf16 v[108:111], v[164:167], v[200:203], v[108:111]
	v_mfma_f32_16x16x32_bf16 v[100:103], v[152:155], v[204:207], v[100:103]
	v_mfma_f32_16x16x32_bf16 v[100:103], v[156:159], v[208:211], v[100:103]
	v_mfma_f32_16x16x32_bf16 v[92:95], v[160:163], v[204:207], v[92:95]
	v_mfma_f32_16x16x32_bf16 v[92:95], v[164:167], v[208:211], v[92:95]
	v_mfma_f32_16x16x32_bf16 v[84:87], v[152:155], v[212:215], v[84:87]
	v_mfma_f32_16x16x32_bf16 v[84:87], v[156:159], v[216:219], v[84:87]
	v_mfma_f32_16x16x32_bf16 v[76:79], v[160:163], v[212:215], v[76:79]
	v_mfma_f32_16x16x32_bf16 v[76:79], v[164:167], v[216:219], v[76:79]
	v_mfma_f32_16x16x32_bf16 v[112:115], v[168:171], v[188:191], v[112:115]
	v_mfma_f32_16x16x32_bf16 v[112:115], v[172:175], v[192:195], v[112:115]
	v_mfma_f32_16x16x32_bf16 v[104:107], v[176:179], v[188:191], v[104:107]
	v_mfma_f32_16x16x32_bf16 v[104:107], v[184:187], v[192:195], v[104:107]
	v_mfma_f32_16x16x32_bf16 v[96:99], v[168:171], v[196:199], v[96:99]
	v_mfma_f32_16x16x32_bf16 v[96:99], v[172:175], v[200:203], v[96:99]
	v_mfma_f32_16x16x32_bf16 v[88:91], v[176:179], v[196:199], v[88:91]
	v_mfma_f32_16x16x32_bf16 v[88:91], v[184:187], v[200:203], v[88:91]
	v_mfma_f32_16x16x32_bf16 v[80:83], v[168:171], v[204:207], v[80:83]
	v_mfma_f32_16x16x32_bf16 v[80:83], v[172:175], v[208:211], v[80:83]
	v_mfma_f32_16x16x32_bf16 v[72:75], v[176:179], v[204:207], v[72:75]
	v_mfma_f32_16x16x32_bf16 v[72:75], v[184:187], v[208:211], v[72:75]
	v_mfma_f32_16x16x32_bf16 v[68:71], v[168:171], v[212:215], v[68:71]
	v_mfma_f32_16x16x32_bf16 v[68:71], v[172:175], v[216:219], v[68:71]
	v_mfma_f32_16x16x32_bf16 v[64:67], v[176:179], v[212:215], v[64:67]
	v_mfma_f32_16x16x32_bf16 v[64:67], v[184:187], v[216:219], v[64:67]
	s_setprio 0
	s_barrier
	s_add_i32 s79, s71, s64
	v_lshl_add_u64 v[144:145], s[58:59], 0, v[130:131]
	s_mov_b32 m0, s79
	ds_read_b128 v[188:191], v151 offset:16384
	ds_read_b128 v[192:195], v151 offset:17408
	ds_read_b128 v[196:199], v151 offset:18432
	ds_read_b128 v[200:203], v151 offset:19456
	ds_read_b128 v[204:207], v151 offset:20480
	ds_read_b128 v[208:211], v151 offset:21504
	ds_read_b128 v[212:215], v151 offset:22528
	ds_read_b128 v[216:219], v151 offset:23552
	global_load_lds_dwordx4 v[144:145], off
	s_add_i32 m0, s79, 0x2000
	s_add_u32 s88, s58, 0x40000
	v_lshl_add_u64 v[220:221], s[58:59], 0, v[134:135]
	s_addc_u32 s89, s59, 0
	s_add_i32 s79, s72, s64
	global_load_lds_dwordx4 v[220:221], off
	v_lshl_add_u64 v[222:223], s[88:89], 0, v[130:131]
	s_mov_b32 m0, s79
	v_lshl_add_u64 v[224:225], s[60:61], 0, v[132:133]
	global_load_lds_dwordx4 v[222:223], off
	v_lshl_add_u64 v[222:223], s[88:89], 0, v[134:135]
	s_add_i32 m0, s79, 0x2000
	s_nop 0
	global_load_lds_dwordx4 v[222:223], off
	v_lshl_add_u64 v[222:223], s[60:61], 0, v[128:129]
	s_mov_b32 m0, s55
	s_nop 0
	global_load_lds_dwordx4 v[222:223], off
	s_mov_b32 m0, s65
	s_nop 0
	global_load_lds_dwordx4 v[224:225], off
	s_waitcnt vmcnt(8)
	s_waitcnt lgkmcnt(0)
	s_barrier
	s_setprio 1
	s_waitcnt lgkmcnt(0)
	v_mfma_f32_16x16x32_bf16 v[60:63], v[152:155], v[188:191], v[60:63]
	v_mfma_f32_16x16x32_bf16 v[60:63], v[156:159], v[192:195], v[60:63]
	v_mfma_f32_16x16x32_bf16 v[56:59], v[160:163], v[188:191], v[56:59]
	v_mfma_f32_16x16x32_bf16 v[56:59], v[164:167], v[192:195], v[56:59]
	v_mfma_f32_16x16x32_bf16 v[52:55], v[152:155], v[196:199], v[52:55]
	v_mfma_f32_16x16x32_bf16 v[52:55], v[156:159], v[200:203], v[52:55]
	v_mfma_f32_16x16x32_bf16 v[44:47], v[160:163], v[196:199], v[44:47]
	v_mfma_f32_16x16x32_bf16 v[44:47], v[164:167], v[200:203], v[44:47]
	v_mfma_f32_16x16x32_bf16 v[36:39], v[152:155], v[204:207], v[36:39]
	v_mfma_f32_16x16x32_bf16 v[36:39], v[156:159], v[208:211], v[36:39]
	v_mfma_f32_16x16x32_bf16 v[28:31], v[160:163], v[204:207], v[28:31]
	v_mfma_f32_16x16x32_bf16 v[28:31], v[164:167], v[208:211], v[28:31]
	v_mfma_f32_16x16x32_bf16 v[20:23], v[152:155], v[212:215], v[20:23]
	v_mfma_f32_16x16x32_bf16 v[20:23], v[156:159], v[216:219], v[20:23]
	v_mfma_f32_16x16x32_bf16 v[12:15], v[160:163], v[212:215], v[12:15]
	v_mfma_f32_16x16x32_bf16 v[12:15], v[164:167], v[216:219], v[12:15]
	v_mfma_f32_16x16x32_bf16 v[48:51], v[168:171], v[188:191], v[48:51]
	v_mfma_f32_16x16x32_bf16 v[48:51], v[172:175], v[192:195], v[48:51]
	v_mfma_f32_16x16x32_bf16 v[40:43], v[176:179], v[188:191], v[40:43]
	v_mfma_f32_16x16x32_bf16 v[40:43], v[184:187], v[192:195], v[40:43]
	v_mfma_f32_16x16x32_bf16 v[32:35], v[168:171], v[196:199], v[32:35]
	v_mfma_f32_16x16x32_bf16 v[32:35], v[172:175], v[200:203], v[32:35]
	v_mfma_f32_16x16x32_bf16 v[24:27], v[176:179], v[196:199], v[24:27]
	v_mfma_f32_16x16x32_bf16 v[24:27], v[184:187], v[200:203], v[24:27]
	v_mfma_f32_16x16x32_bf16 v[16:19], v[168:171], v[204:207], v[16:19]
	v_mfma_f32_16x16x32_bf16 v[16:19], v[172:175], v[208:211], v[16:19]
	v_mfma_f32_16x16x32_bf16 v[8:11], v[176:179], v[204:207], v[8:11]
	v_mfma_f32_16x16x32_bf16 v[8:11], v[184:187], v[208:211], v[8:11]
	v_mfma_f32_16x16x32_bf16 v[4:7], v[168:171], v[212:215], v[4:7]
	v_mfma_f32_16x16x32_bf16 v[4:7], v[172:175], v[216:219], v[4:7]
	v_mfma_f32_16x16x32_bf16 v[0:3], v[176:179], v[212:215], v[0:3]
	v_mfma_f32_16x16x32_bf16 v[0:3], v[184:187], v[216:219], v[0:3]
	s_setprio 0
	s_barrier
.Lmid_gemm10:
	s_add_i32 s79, 0, 0x18000
	s_add_i32 s87, 0, 0x1c000
	v_add_u32_e32 v164, s79, v147
	v_add_u32_e32 v181, s87, v147
	ds_read_b128 v[152:155], v164
	ds_read_b128 v[156:159], v164 offset:1024
	ds_read_b128 v[160:163], v164 offset:2048
	ds_read_b128 v[164:167], v164 offset:3072
	ds_read_b128 v[168:171], v181
	ds_read_b128 v[172:175], v181 offset:1024
	ds_read_b128 v[176:179], v181 offset:2048
	ds_read_b128 v[184:187], v181 offset:3072
	s_add_u32 s60, s60, 0x40000
	s_addc_u32 s61, s61, 0
	s_mov_b32 m0, s66
	v_lshl_add_u64 v[226:227], s[60:61], 0, v[128:129]
	ds_read_b128 v[188:191], v151 offset:32768
	ds_read_b128 v[192:195], v151 offset:33792
	ds_read_b128 v[196:199], v151 offset:34816
	ds_read_b128 v[200:203], v151 offset:35840
	ds_read_b128 v[204:207], v151 offset:36864
	ds_read_b128 v[208:211], v151 offset:37888
	ds_read_b128 v[212:215], v151 offset:38912
	ds_read_b128 v[216:219], v151 offset:39936
	global_load_lds_dwordx4 v[226:227], off
	v_lshl_add_u64 v[226:227], s[60:61], 0, v[132:133]
	s_mov_b32 m0, s67
	s_nop 0
	global_load_lds_dwordx4 v[226:227], off
	s_waitcnt vmcnt(8)
	s_waitcnt lgkmcnt(0)
	s_barrier
	s_setprio 1
	s_waitcnt lgkmcnt(0)
	v_mfma_f32_16x16x32_bf16 v[124:127], v[152:155], v[188:191], v[124:127]
	v_mfma_f32_16x16x32_bf16 v[124:127], v[156:159], v[192:195], v[124:127]
	v_mfma_f32_16x16x32_bf16 v[120:123], v[160:163], v[188:191], v[120:123]
	v_mfma_f32_16x16x32_bf16 v[120:123], v[164:167], v[192:195], v[120:123]
	v_mfma_f32_16x16x32_bf16 v[116:119], v[152:155], v[196:199], v[116:119]
	v_mfma_f32_16x16x32_bf16 v[116:119], v[156:159], v[200:203], v[116:119]
	v_mfma_f32_16x16x32_bf16 v[108:111], v[160:163], v[196:199], v[108:111]
	v_mfma_f32_16x16x32_bf16 v[108:111], v[164:167], v[200:203], v[108:111]
	v_mfma_f32_16x16x32_bf16 v[100:103], v[152:155], v[204:207], v[100:103]
	v_mfma_f32_16x16x32_bf16 v[100:103], v[156:159], v[208:211], v[100:103]
	v_mfma_f32_16x16x32_bf16 v[92:95], v[160:163], v[204:207], v[92:95]
	v_mfma_f32_16x16x32_bf16 v[92:95], v[164:167], v[208:211], v[92:95]
	v_mfma_f32_16x16x32_bf16 v[84:87], v[152:155], v[212:215], v[84:87]
	v_mfma_f32_16x16x32_bf16 v[84:87], v[156:159], v[216:219], v[84:87]
	v_mfma_f32_16x16x32_bf16 v[76:79], v[160:163], v[212:215], v[76:79]
	v_mfma_f32_16x16x32_bf16 v[76:79], v[164:167], v[216:219], v[76:79]
	v_mfma_f32_16x16x32_bf16 v[112:115], v[168:171], v[188:191], v[112:115]
	v_mfma_f32_16x16x32_bf16 v[112:115], v[172:175], v[192:195], v[112:115]
	v_mfma_f32_16x16x32_bf16 v[104:107], v[176:179], v[188:191], v[104:107]
	v_mfma_f32_16x16x32_bf16 v[104:107], v[184:187], v[192:195], v[104:107]
	v_mfma_f32_16x16x32_bf16 v[96:99], v[168:171], v[196:199], v[96:99]
	v_mfma_f32_16x16x32_bf16 v[96:99], v[172:175], v[200:203], v[96:99]
	v_mfma_f32_16x16x32_bf16 v[88:91], v[176:179], v[196:199], v[88:91]
	v_mfma_f32_16x16x32_bf16 v[88:91], v[184:187], v[200:203], v[88:91]
	v_mfma_f32_16x16x32_bf16 v[80:83], v[168:171], v[204:207], v[80:83]
	v_mfma_f32_16x16x32_bf16 v[80:83], v[172:175], v[208:211], v[80:83]
	v_mfma_f32_16x16x32_bf16 v[72:75], v[176:179], v[204:207], v[72:75]
	v_mfma_f32_16x16x32_bf16 v[72:75], v[184:187], v[208:211], v[72:75]
	v_mfma_f32_16x16x32_bf16 v[68:71], v[168:171], v[212:215], v[68:71]
	v_mfma_f32_16x16x32_bf16 v[68:71], v[172:175], v[216:219], v[68:71]
	v_mfma_f32_16x16x32_bf16 v[64:67], v[176:179], v[212:215], v[64:67]
	v_mfma_f32_16x16x32_bf16 v[64:67], v[184:187], v[216:219], v[64:67]
	s_setprio 0
	s_barrier
	s_add_i32 s60, s79, s64
	v_lshl_add_u64 v[144:145], v[144:145], 0, s[16:17]
	s_mov_b32 m0, s60
	ds_read_b128 v[188:191], v151 offset:49152
	ds_read_b128 v[192:195], v151 offset:50176
	ds_read_b128 v[196:199], v151 offset:51200
	ds_read_b128 v[200:203], v151 offset:52224
	ds_read_b128 v[204:207], v151 offset:53248
	ds_read_b128 v[208:211], v151 offset:54272
	ds_read_b128 v[212:215], v151 offset:55296
	ds_read_b128 v[216:219], v151 offset:56320
	global_load_lds_dwordx4 v[144:145], off
	s_add_i32 m0, s60, 0x2000
	s_add_u32 s58, s58, 0x40080
	v_lshl_add_u64 v[144:145], v[220:221], 0, s[16:17]
	s_addc_u32 s59, s59, 0
	s_add_i32 s60, s87, s64
	global_load_lds_dwordx4 v[144:145], off
	v_lshl_add_u64 v[144:145], s[58:59], 0, v[130:131]
	s_mov_b32 m0, s60
	s_nop 0
	global_load_lds_dwordx4 v[144:145], off
	v_lshl_add_u64 v[144:145], s[58:59], 0, v[134:135]
	s_add_i32 m0, s60, 0x2000
	s_nop 0
	global_load_lds_dwordx4 v[144:145], off
	v_lshl_add_u64 v[144:145], v[222:223], 0, s[16:17]
	s_mov_b32 m0, s69
	s_nop 0
	global_load_lds_dwordx4 v[144:145], off
	v_lshl_add_u64 v[144:145], v[224:225], 0, s[16:17]
	s_mov_b32 m0, s70
	s_nop 0
	global_load_lds_dwordx4 v[144:145], off
	s_waitcnt vmcnt(8)
	s_waitcnt lgkmcnt(0)
	s_barrier
	s_setprio 1
	s_waitcnt lgkmcnt(0)
	v_mfma_f32_16x16x32_bf16 v[60:63], v[152:155], v[188:191], v[60:63]
	v_mfma_f32_16x16x32_bf16 v[60:63], v[156:159], v[192:195], v[60:63]
	v_mfma_f32_16x16x32_bf16 v[56:59], v[160:163], v[188:191], v[56:59]
	v_mfma_f32_16x16x32_bf16 v[56:59], v[164:167], v[192:195], v[56:59]
	v_mfma_f32_16x16x32_bf16 v[52:55], v[152:155], v[196:199], v[52:55]
	v_mfma_f32_16x16x32_bf16 v[52:55], v[156:159], v[200:203], v[52:55]
	v_mfma_f32_16x16x32_bf16 v[44:47], v[160:163], v[196:199], v[44:47]
	v_mfma_f32_16x16x32_bf16 v[44:47], v[164:167], v[200:203], v[44:47]
	v_mfma_f32_16x16x32_bf16 v[36:39], v[152:155], v[204:207], v[36:39]
	v_mfma_f32_16x16x32_bf16 v[36:39], v[156:159], v[208:211], v[36:39]
	v_mfma_f32_16x16x32_bf16 v[28:31], v[160:163], v[204:207], v[28:31]
	v_mfma_f32_16x16x32_bf16 v[28:31], v[164:167], v[208:211], v[28:31]
	v_mfma_f32_16x16x32_bf16 v[20:23], v[152:155], v[212:215], v[20:23]
	v_mfma_f32_16x16x32_bf16 v[20:23], v[156:159], v[216:219], v[20:23]
	v_mfma_f32_16x16x32_bf16 v[12:15], v[160:163], v[212:215], v[12:15]
	v_mfma_f32_16x16x32_bf16 v[12:15], v[164:167], v[216:219], v[12:15]
	v_mfma_f32_16x16x32_bf16 v[48:51], v[168:171], v[188:191], v[48:51]
	v_mfma_f32_16x16x32_bf16 v[48:51], v[172:175], v[192:195], v[48:51]
	v_mfma_f32_16x16x32_bf16 v[40:43], v[176:179], v[188:191], v[40:43]
	v_mfma_f32_16x16x32_bf16 v[40:43], v[184:187], v[192:195], v[40:43]
	v_mfma_f32_16x16x32_bf16 v[32:35], v[168:171], v[196:199], v[32:35]
	v_mfma_f32_16x16x32_bf16 v[32:35], v[172:175], v[200:203], v[32:35]
	v_mfma_f32_16x16x32_bf16 v[24:27], v[176:179], v[196:199], v[24:27]
	v_mfma_f32_16x16x32_bf16 v[24:27], v[184:187], v[200:203], v[24:27]
	v_mfma_f32_16x16x32_bf16 v[16:19], v[168:171], v[204:207], v[16:19]
	v_mfma_f32_16x16x32_bf16 v[16:19], v[172:175], v[208:211], v[16:19]
	v_mfma_f32_16x16x32_bf16 v[8:11], v[176:179], v[204:207], v[8:11]
	v_mfma_f32_16x16x32_bf16 v[8:11], v[184:187], v[208:211], v[8:11]
	v_mfma_f32_16x16x32_bf16 v[4:7], v[168:171], v[212:215], v[4:7]
	v_mfma_f32_16x16x32_bf16 v[4:7], v[172:175], v[216:219], v[4:7]
	v_mfma_f32_16x16x32_bf16 v[0:3], v[176:179], v[212:215], v[0:3]
	v_mfma_f32_16x16x32_bf16 v[0:3], v[184:187], v[216:219], v[0:3]
	s_setprio 0
	s_barrier
	s_add_i32 s86, s86, 2
	s_add_u32 s56, s56, 0x100
	s_addc_u32 s57, s57, 0
	s_add_u32 s84, s84, 0x100
	s_addc_u32 s85, s85, 0
	s_cmp_gt_u32 s86, 13
	s_cbranch_scc0 .LBB0_1311
	s_and_b64 vcc, exec, s[18:19]
	s_cbranch_vccz .LBB0_1314
	s_barrier

.LBB0_1433:
	s_ashr_i32 s19, s18, 31
	s_lshl_b64 s[30:31], s[18:19], 19
	s_add_u32 s30, s80, s30
	s_addc_u32 s31, s81, s31
	s_and_b64 s[36:37], s[8:9], exec
	s_cselect_b32 s19, s31, s47
	s_cselect_b32 s66, s30, s46
	s_ashr_i32 s17, s16, 31
	s_lshl_b64 s[36:37], s[16:17], 19
	s_add_u32 s36, s52, s36
	s_addc_u32 s37, s53, s37
	s_and_b64 s[50:51], s[8:9], exec
	s_cselect_b32 s17, s37, s49
	s_cselect_b32 s67, s36, s48
	s_add_u32 s46, s46, 0x40080
	s_addc_u32 s47, s47, 0
	s_add_u32 s68, s48, 0x100
	s_addc_u32 s69, s49, 0
	s_mov_b32 s70, -2
	ds_read_b128 v[140:143], v147
	ds_read_b128 v[150:153], v147 offset:1024
	ds_read_b128 v[154:157], v147 offset:2048
	ds_read_b128 v[158:161], v147 offset:3072
	ds_read_b128 v[162:165], v148
	ds_read_b128 v[166:169], v148 offset:1024
	ds_read_b128 v[170:173], v148 offset:2048
	ds_read_b128 v[174:177], v148 offset:3072
	s_add_u32 s48, s46, 0xfffc0080
	s_addc_u32 s49, s47, -1
	s_cmp_eq_u32 s70, 12
	s_cselect_b32 s51, s19, s49
	s_cselect_b32 s50, s66, s48
	s_cselect_b32 s49, s17, s69
	s_cselect_b32 s48, s67, s68
	v_lshl_add_u64 v[178:179], s[46:47], 0, v[132:133]
	s_add_i32 m0, s45, 0xc000
	ds_read_b128 v[184:187], v149
	ds_read_b128 v[188:191], v149 offset:1024
	ds_read_b128 v[192:195], v149 offset:2048
	ds_read_b128 v[196:199], v149 offset:3072
	ds_read_b128 v[200:203], v149 offset:4096
	ds_read_b128 v[204:207], v149 offset:5120
	ds_read_b128 v[208:211], v149 offset:6144
	ds_read_b128 v[212:215], v149 offset:7168
	global_load_lds_dwordx4 v[178:179], off
	v_lshl_add_u64 v[178:179], s[46:47], 0, v[134:135]
	s_add_i32 m0, s45, 0xe000
	s_nop 0
	global_load_lds_dwordx4 v[178:179], off
	s_waitcnt vmcnt(8)
	s_waitcnt lgkmcnt(0)
	s_barrier
	s_setprio 1
	s_waitcnt lgkmcnt(0)
	v_mfma_f32_16x16x32_bf16 v[124:127], v[140:143], v[184:187], 0
	v_mfma_f32_16x16x32_bf16 v[124:127], v[150:153], v[188:191], v[124:127]
	v_mfma_f32_16x16x32_bf16 v[120:123], v[154:157], v[184:187], 0
	v_mfma_f32_16x16x32_bf16 v[120:123], v[158:161], v[188:191], v[120:123]
	v_mfma_f32_16x16x32_bf16 v[108:111], v[140:143], v[192:195], 0
	v_mfma_f32_16x16x32_bf16 v[108:111], v[150:153], v[196:199], v[108:111]
	v_mfma_f32_16x16x32_bf16 v[104:107], v[154:157], v[192:195], 0
	v_mfma_f32_16x16x32_bf16 v[104:107], v[158:161], v[196:199], v[104:107]
	v_mfma_f32_16x16x32_bf16 v[92:95], v[140:143], v[200:203], 0
	v_mfma_f32_16x16x32_bf16 v[92:95], v[150:153], v[204:207], v[92:95]
	v_mfma_f32_16x16x32_bf16 v[88:91], v[154:157], v[200:203], 0
	v_mfma_f32_16x16x32_bf16 v[88:91], v[158:161], v[204:207], v[88:91]
	v_mfma_f32_16x16x32_bf16 v[76:79], v[140:143], v[208:211], 0
	v_mfma_f32_16x16x32_bf16 v[76:79], v[150:153], v[212:215], v[76:79]
	v_mfma_f32_16x16x32_bf16 v[72:75], v[154:157], v[208:211], 0
	v_mfma_f32_16x16x32_bf16 v[72:75], v[158:161], v[212:215], v[72:75]
	v_mfma_f32_16x16x32_bf16 v[116:119], v[162:165], v[184:187], 0
	v_mfma_f32_16x16x32_bf16 v[116:119], v[166:169], v[188:191], v[116:119]
	v_mfma_f32_16x16x32_bf16 v[112:115], v[170:173], v[184:187], 0
	v_mfma_f32_16x16x32_bf16 v[112:115], v[174:177], v[188:191], v[112:115]
	v_mfma_f32_16x16x32_bf16 v[100:103], v[162:165], v[192:195], 0
	v_mfma_f32_16x16x32_bf16 v[100:103], v[166:169], v[196:199], v[100:103]
	v_mfma_f32_16x16x32_bf16 v[96:99], v[170:173], v[192:195], 0
	v_mfma_f32_16x16x32_bf16 v[96:99], v[174:177], v[196:199], v[96:99]
	v_mfma_f32_16x16x32_bf16 v[84:87], v[162:165], v[200:203], 0
	v_mfma_f32_16x16x32_bf16 v[84:87], v[166:169], v[204:207], v[84:87]
	v_mfma_f32_16x16x32_bf16 v[80:83], v[170:173], v[200:203], 0
	v_mfma_f32_16x16x32_bf16 v[80:83], v[174:177], v[204:207], v[80:83]
	v_mfma_f32_16x16x32_bf16 v[68:71], v[162:165], v[208:211], 0
	v_mfma_f32_16x16x32_bf16 v[68:71], v[166:169], v[212:215], v[68:71]
	v_mfma_f32_16x16x32_bf16 v[64:67], v[170:173], v[208:211], 0
	v_mfma_f32_16x16x32_bf16 v[64:67], v[174:177], v[212:215], v[64:67]
	s_setprio 0
	s_barrier
	s_add_i32 s71, s62, s54
	v_lshl_add_u64 v[178:179], s[48:49], 0, v[130:131]
	s_mov_b32 m0, s71
	ds_read_b128 v[184:187], v149 offset:16384
	ds_read_b128 v[188:191], v149 offset:17408
	ds_read_b128 v[192:195], v149 offset:18432
	ds_read_b128 v[196:199], v149 offset:19456
	ds_read_b128 v[200:203], v149 offset:20480
	ds_read_b128 v[204:207], v149 offset:21504
	ds_read_b128 v[208:211], v149 offset:22528
	ds_read_b128 v[212:215], v149 offset:23552
	global_load_lds_dwordx4 v[178:179], off
	s_add_i32 m0, s71, 0x2000
	s_add_u32 s72, s48, 0x40000
	v_lshl_add_u64 v[216:217], s[48:49], 0, v[128:129]
	s_addc_u32 s73, s49, 0
	s_add_i32 s71, s63, s54
	global_load_lds_dwordx4 v[216:217], off
	v_lshl_add_u64 v[218:219], s[72:73], 0, v[130:131]
	s_mov_b32 m0, s71
	v_lshl_add_u64 v[220:221], s[50:51], 0, v[128:129]
	global_load_lds_dwordx4 v[218:219], off
	v_lshl_add_u64 v[218:219], s[72:73], 0, v[128:129]
	s_add_i32 m0, s71, 0x2000
	s_nop 0
	global_load_lds_dwordx4 v[218:219], off
	v_lshl_add_u64 v[218:219], s[50:51], 0, v[130:131]
	s_mov_b32 m0, s45
	s_nop 0
	global_load_lds_dwordx4 v[218:219], off
	s_mov_b32 m0, s56
	s_nop 0
	global_load_lds_dwordx4 v[220:221], off
	s_waitcnt vmcnt(8)
	s_waitcnt lgkmcnt(0)
	s_barrier
	s_setprio 1
	s_waitcnt lgkmcnt(0)
	v_mfma_f32_16x16x32_bf16 v[60:63], v[140:143], v[184:187], 0
	v_mfma_f32_16x16x32_bf16 v[60:63], v[150:153], v[188:191], v[60:63]
	v_mfma_f32_16x16x32_bf16 v[56:59], v[154:157], v[184:187], 0
	v_mfma_f32_16x16x32_bf16 v[56:59], v[158:161], v[188:191], v[56:59]
	v_mfma_f32_16x16x32_bf16 v[44:47], v[140:143], v[192:195], 0
	v_mfma_f32_16x16x32_bf16 v[44:47], v[150:153], v[196:199], v[44:47]
	v_mfma_f32_16x16x32_bf16 v[40:43], v[154:157], v[192:195], 0
	v_mfma_f32_16x16x32_bf16 v[40:43], v[158:161], v[196:199], v[40:43]
	v_mfma_f32_16x16x32_bf16 v[28:31], v[140:143], v[200:203], 0
	v_mfma_f32_16x16x32_bf16 v[28:31], v[150:153], v[204:207], v[28:31]
	v_mfma_f32_16x16x32_bf16 v[24:27], v[154:157], v[200:203], 0
	v_mfma_f32_16x16x32_bf16 v[24:27], v[158:161], v[204:207], v[24:27]
	v_mfma_f32_16x16x32_bf16 v[12:15], v[140:143], v[208:211], 0
	v_mfma_f32_16x16x32_bf16 v[12:15], v[150:153], v[212:215], v[12:15]
	v_mfma_f32_16x16x32_bf16 v[8:11], v[154:157], v[208:211], 0
	v_mfma_f32_16x16x32_bf16 v[8:11], v[158:161], v[212:215], v[8:11]
	v_mfma_f32_16x16x32_bf16 v[52:55], v[162:165], v[184:187], 0
	v_mfma_f32_16x16x32_bf16 v[52:55], v[166:169], v[188:191], v[52:55]
	v_mfma_f32_16x16x32_bf16 v[48:51], v[170:173], v[184:187], 0
	v_mfma_f32_16x16x32_bf16 v[48:51], v[174:177], v[188:191], v[48:51]
	v_mfma_f32_16x16x32_bf16 v[36:39], v[162:165], v[192:195], 0
	v_mfma_f32_16x16x32_bf16 v[36:39], v[166:169], v[196:199], v[36:39]
	v_mfma_f32_16x16x32_bf16 v[32:35], v[170:173], v[192:195], 0
	v_mfma_f32_16x16x32_bf16 v[32:35], v[174:177], v[196:199], v[32:35]
	v_mfma_f32_16x16x32_bf16 v[20:23], v[162:165], v[200:203], 0
	v_mfma_f32_16x16x32_bf16 v[20:23], v[166:169], v[204:207], v[20:23]
	v_mfma_f32_16x16x32_bf16 v[16:19], v[170:173], v[200:203], 0
	v_mfma_f32_16x16x32_bf16 v[16:19], v[174:177], v[204:207], v[16:19]
	v_mfma_f32_16x16x32_bf16 v[4:7], v[162:165], v[208:211], 0
	v_mfma_f32_16x16x32_bf16 v[4:7], v[166:169], v[212:215], v[4:7]
	v_mfma_f32_16x16x32_bf16 v[0:3], v[170:173], v[208:211], 0
	v_mfma_f32_16x16x32_bf16 v[0:3], v[174:177], v[212:215], v[0:3]
	s_setprio 0
	s_barrier
	s_branch .Lmid_gemm11
.LBB0_1434:
	ds_read_b128 v[140:143], v147
	ds_read_b128 v[150:153], v147 offset:1024
	ds_read_b128 v[154:157], v147 offset:2048
	ds_read_b128 v[158:161], v147 offset:3072
	ds_read_b128 v[162:165], v148
	ds_read_b128 v[166:169], v148 offset:1024
	ds_read_b128 v[170:173], v148 offset:2048
	ds_read_b128 v[174:177], v148 offset:3072
	s_add_u32 s48, s46, 0xfffc0080
	s_addc_u32 s49, s47, -1
	s_cmp_eq_u32 s70, 12
	s_cselect_b32 s51, s19, s49
	s_cselect_b32 s50, s66, s48
	s_cselect_b32 s49, s17, s69
	s_cselect_b32 s48, s67, s68
	v_lshl_add_u64 v[178:179], s[46:47], 0, v[132:133]
	s_add_i32 m0, s45, 0xc000
	ds_read_b128 v[184:187], v149
	ds_read_b128 v[188:191], v149 offset:1024
	ds_read_b128 v[192:195], v149 offset:2048
	ds_read_b128 v[196:199], v149 offset:3072
	ds_read_b128 v[200:203], v149 offset:4096
	ds_read_b128 v[204:207], v149 offset:5120
	ds_read_b128 v[208:211], v149 offset:6144
	ds_read_b128 v[212:215], v149 offset:7168
	global_load_lds_dwordx4 v[178:179], off
	v_lshl_add_u64 v[178:179], s[46:47], 0, v[134:135]
	s_add_i32 m0, s45, 0xe000
	s_nop 0
	global_load_lds_dwordx4 v[178:179], off
	s_waitcnt vmcnt(8)
	s_waitcnt lgkmcnt(0)
	s_barrier
	s_setprio 1
	s_waitcnt lgkmcnt(0)
	v_mfma_f32_16x16x32_bf16 v[124:127], v[140:143], v[184:187], v[124:127]
	v_mfma_f32_16x16x32_bf16 v[124:127], v[150:153], v[188:191], v[124:127]
	v_mfma_f32_16x16x32_bf16 v[120:123], v[154:157], v[184:187], v[120:123]
	v_mfma_f32_16x16x32_bf16 v[120:123], v[158:161], v[188:191], v[120:123]
	v_mfma_f32_16x16x32_bf16 v[108:111], v[140:143], v[192:195], v[108:111]
	v_mfma_f32_16x16x32_bf16 v[108:111], v[150:153], v[196:199], v[108:111]
	v_mfma_f32_16x16x32_bf16 v[104:107], v[154:157], v[192:195], v[104:107]
	v_mfma_f32_16x16x32_bf16 v[104:107], v[158:161], v[196:199], v[104:107]
	v_mfma_f32_16x16x32_bf16 v[92:95], v[140:143], v[200:203], v[92:95]
	v_mfma_f32_16x16x32_bf16 v[92:95], v[150:153], v[204:207], v[92:95]
	v_mfma_f32_16x16x32_bf16 v[88:91], v[154:157], v[200:203], v[88:91]
	v_mfma_f32_16x16x32_bf16 v[88:91], v[158:161], v[204:207], v[88:91]
	v_mfma_f32_16x16x32_bf16 v[76:79], v[140:143], v[208:211], v[76:79]
	v_mfma_f32_16x16x32_bf16 v[76:79], v[150:153], v[212:215], v[76:79]
	v_mfma_f32_16x16x32_bf16 v[72:75], v[154:157], v[208:211], v[72:75]
	v_mfma_f32_16x16x32_bf16 v[72:75], v[158:161], v[212:215], v[72:75]
	v_mfma_f32_16x16x32_bf16 v[116:119], v[162:165], v[184:187], v[116:119]
	v_mfma_f32_16x16x32_bf16 v[116:119], v[166:169], v[188:191], v[116:119]
	v_mfma_f32_16x16x32_bf16 v[112:115], v[170:173], v[184:187], v[112:115]
	v_mfma_f32_16x16x32_bf16 v[112:115], v[174:177], v[188:191], v[112:115]
	v_mfma_f32_16x16x32_bf16 v[100:103], v[162:165], v[192:195], v[100:103]
	v_mfma_f32_16x16x32_bf16 v[100:103], v[166:169], v[196:199], v[100:103]
	v_mfma_f32_16x16x32_bf16 v[96:99], v[170:173], v[192:195], v[96:99]
	v_mfma_f32_16x16x32_bf16 v[96:99], v[174:177], v[196:199], v[96:99]
	v_mfma_f32_16x16x32_bf16 v[84:87], v[162:165], v[200:203], v[84:87]
	v_mfma_f32_16x16x32_bf16 v[84:87], v[166:169], v[204:207], v[84:87]
	v_mfma_f32_16x16x32_bf16 v[80:83], v[170:173], v[200:203], v[80:83]
	v_mfma_f32_16x16x32_bf16 v[80:83], v[174:177], v[204:207], v[80:83]
	v_mfma_f32_16x16x32_bf16 v[68:71], v[162:165], v[208:211], v[68:71]
	v_mfma_f32_16x16x32_bf16 v[68:71], v[166:169], v[212:215], v[68:71]
	v_mfma_f32_16x16x32_bf16 v[64:67], v[170:173], v[208:211], v[64:67]
	v_mfma_f32_16x16x32_bf16 v[64:67], v[174:177], v[212:215], v[64:67]
	s_setprio 0
	s_barrier
	s_add_i32 s71, s62, s54
	v_lshl_add_u64 v[178:179], s[48:49], 0, v[130:131]
	s_mov_b32 m0, s71
	ds_read_b128 v[184:187], v149 offset:16384
	ds_read_b128 v[188:191], v149 offset:17408
	ds_read_b128 v[192:195], v149 offset:18432
	ds_read_b128 v[196:199], v149 offset:19456
	ds_read_b128 v[200:203], v149 offset:20480
	ds_read_b128 v[204:207], v149 offset:21504
	ds_read_b128 v[208:211], v149 offset:22528
	ds_read_b128 v[212:215], v149 offset:23552
	global_load_lds_dwordx4 v[178:179], off
	s_add_i32 m0, s71, 0x2000
	s_add_u32 s72, s48, 0x40000
	v_lshl_add_u64 v[216:217], s[48:49], 0, v[128:129]
	s_addc_u32 s73, s49, 0
	s_add_i32 s71, s63, s54
	global_load_lds_dwordx4 v[216:217], off
	v_lshl_add_u64 v[218:219], s[72:73], 0, v[130:131]
	s_mov_b32 m0, s71
	v_lshl_add_u64 v[220:221], s[50:51], 0, v[128:129]
	global_load_lds_dwordx4 v[218:219], off
	v_lshl_add_u64 v[218:219], s[72:73], 0, v[128:129]
	s_add_i32 m0, s71, 0x2000
	s_nop 0
	global_load_lds_dwordx4 v[218:219], off
	v_lshl_add_u64 v[218:219], s[50:51], 0, v[130:131]
	s_mov_b32 m0, s45
	s_nop 0
	global_load_lds_dwordx4 v[218:219], off
	s_mov_b32 m0, s56
	s_nop 0
	global_load_lds_dwordx4 v[220:221], off
	s_waitcnt vmcnt(8)
	s_waitcnt lgkmcnt(0)
	s_barrier
	s_setprio 1
	s_waitcnt lgkmcnt(0)
	v_mfma_f32_16x16x32_bf16 v[60:63], v[140:143], v[184:187], v[60:63]
	v_mfma_f32_16x16x32_bf16 v[60:63], v[150:153], v[188:191], v[60:63]
	v_mfma_f32_16x16x32_bf16 v[56:59], v[154:157], v[184:187], v[56:59]
	v_mfma_f32_16x16x32_bf16 v[56:59], v[158:161], v[188:191], v[56:59]
	v_mfma_f32_16x16x32_bf16 v[44:47], v[140:143], v[192:195], v[44:47]
	v_mfma_f32_16x16x32_bf16 v[44:47], v[150:153], v[196:199], v[44:47]
	v_mfma_f32_16x16x32_bf16 v[40:43], v[154:157], v[192:195], v[40:43]
	v_mfma_f32_16x16x32_bf16 v[40:43], v[158:161], v[196:199], v[40:43]
	v_mfma_f32_16x16x32_bf16 v[28:31], v[140:143], v[200:203], v[28:31]
	v_mfma_f32_16x16x32_bf16 v[28:31], v[150:153], v[204:207], v[28:31]
	v_mfma_f32_16x16x32_bf16 v[24:27], v[154:157], v[200:203], v[24:27]
	v_mfma_f32_16x16x32_bf16 v[24:27], v[158:161], v[204:207], v[24:27]
	v_mfma_f32_16x16x32_bf16 v[12:15], v[140:143], v[208:211], v[12:15]
	v_mfma_f32_16x16x32_bf16 v[12:15], v[150:153], v[212:215], v[12:15]
	v_mfma_f32_16x16x32_bf16 v[8:11], v[154:157], v[208:211], v[8:11]
	v_mfma_f32_16x16x32_bf16 v[8:11], v[158:161], v[212:215], v[8:11]
	v_mfma_f32_16x16x32_bf16 v[52:55], v[162:165], v[184:187], v[52:55]
	v_mfma_f32_16x16x32_bf16 v[52:55], v[166:169], v[188:191], v[52:55]
	v_mfma_f32_16x16x32_bf16 v[48:51], v[170:173], v[184:187], v[48:51]
	v_mfma_f32_16x16x32_bf16 v[48:51], v[174:177], v[188:191], v[48:51]
	v_mfma_f32_16x16x32_bf16 v[36:39], v[162:165], v[192:195], v[36:39]
	v_mfma_f32_16x16x32_bf16 v[36:39], v[166:169], v[196:199], v[36:39]
	v_mfma_f32_16x16x32_bf16 v[32:35], v[170:173], v[192:195], v[32:35]
	v_mfma_f32_16x16x32_bf16 v[32:35], v[174:177], v[196:199], v[32:35]
	v_mfma_f32_16x16x32_bf16 v[20:23], v[162:165], v[200:203], v[20:23]
	v_mfma_f32_16x16x32_bf16 v[20:23], v[166:169], v[204:207], v[20:23]
	v_mfma_f32_16x16x32_bf16 v[16:19], v[170:173], v[200:203], v[16:19]
	v_mfma_f32_16x16x32_bf16 v[16:19], v[174:177], v[204:207], v[16:19]
	v_mfma_f32_16x16x32_bf16 v[4:7], v[162:165], v[208:211], v[4:7]
	v_mfma_f32_16x16x32_bf16 v[4:7], v[166:169], v[212:215], v[4:7]
	v_mfma_f32_16x16x32_bf16 v[0:3], v[170:173], v[208:211], v[0:3]
	v_mfma_f32_16x16x32_bf16 v[0:3], v[174:177], v[212:215], v[0:3]
	s_setprio 0
	s_barrier
.Lmid_gemm11:
	s_add_i32 s71, 0, 0x18000
	s_add_i32 s72, 0, 0x1c000
	v_add_u32_e32 v158, s71, v145
	v_add_u32_e32 v174, s72, v145
	ds_read_b128 v[140:143], v158
	ds_read_b128 v[150:153], v158 offset:1024
	ds_read_b128 v[154:157], v158 offset:2048
	ds_read_b128 v[158:161], v158 offset:3072
	ds_read_b128 v[162:165], v174
	ds_read_b128 v[166:169], v174 offset:1024
	ds_read_b128 v[170:173], v174 offset:2048
	ds_read_b128 v[174:177], v174 offset:3072
	s_add_u32 s50, s50, 0x40000
	s_addc_u32 s51, s51, 0
	s_mov_b32 m0, s57
	v_lshl_add_u64 v[222:223], s[50:51], 0, v[130:131]
	ds_read_b128 v[184:187], v149 offset:32768
	ds_read_b128 v[188:191], v149 offset:33792
	ds_read_b128 v[192:195], v149 offset:34816
	ds_read_b128 v[196:199], v149 offset:35840
	ds_read_b128 v[200:203], v149 offset:36864
	ds_read_b128 v[204:207], v149 offset:37888
	ds_read_b128 v[208:211], v149 offset:38912
	ds_read_b128 v[212:215], v149 offset:39936
	global_load_lds_dwordx4 v[222:223], off
	v_lshl_add_u64 v[222:223], s[50:51], 0, v[128:129]
	s_mov_b32 m0, s58
	s_nop 0
	global_load_lds_dwordx4 v[222:223], off
	s_waitcnt vmcnt(8)
	s_waitcnt lgkmcnt(0)
	s_barrier
	s_setprio 1
	s_waitcnt lgkmcnt(0)
	v_mfma_f32_16x16x32_bf16 v[124:127], v[140:143], v[184:187], v[124:127]
	v_mfma_f32_16x16x32_bf16 v[124:127], v[150:153], v[188:191], v[124:127]
	v_mfma_f32_16x16x32_bf16 v[120:123], v[154:157], v[184:187], v[120:123]
	v_mfma_f32_16x16x32_bf16 v[120:123], v[158:161], v[188:191], v[120:123]
	v_mfma_f32_16x16x32_bf16 v[108:111], v[140:143], v[192:195], v[108:111]
	v_mfma_f32_16x16x32_bf16 v[108:111], v[150:153], v[196:199], v[108:111]
	v_mfma_f32_16x16x32_bf16 v[104:107], v[154:157], v[192:195], v[104:107]
	v_mfma_f32_16x16x32_bf16 v[104:107], v[158:161], v[196:199], v[104:107]
	v_mfma_f32_16x16x32_bf16 v[92:95], v[140:143], v[200:203], v[92:95]
	v_mfma_f32_16x16x32_bf16 v[92:95], v[150:153], v[204:207], v[92:95]
	v_mfma_f32_16x16x32_bf16 v[88:91], v[154:157], v[200:203], v[88:91]
	v_mfma_f32_16x16x32_bf16 v[88:91], v[158:161], v[204:207], v[88:91]
	v_mfma_f32_16x16x32_bf16 v[76:79], v[140:143], v[208:211], v[76:79]
	v_mfma_f32_16x16x32_bf16 v[76:79], v[150:153], v[212:215], v[76:79]
	v_mfma_f32_16x16x32_bf16 v[72:75], v[154:157], v[208:211], v[72:75]
	v_mfma_f32_16x16x32_bf16 v[72:75], v[158:161], v[212:215], v[72:75]
	v_mfma_f32_16x16x32_bf16 v[116:119], v[162:165], v[184:187], v[116:119]
	v_mfma_f32_16x16x32_bf16 v[116:119], v[166:169], v[188:191], v[116:119]
	v_mfma_f32_16x16x32_bf16 v[112:115], v[170:173], v[184:187], v[112:115]
	v_mfma_f32_16x16x32_bf16 v[112:115], v[174:177], v[188:191], v[112:115]
	v_mfma_f32_16x16x32_bf16 v[100:103], v[162:165], v[192:195], v[100:103]
	v_mfma_f32_16x16x32_bf16 v[100:103], v[166:169], v[196:199], v[100:103]
	v_mfma_f32_16x16x32_bf16 v[96:99], v[170:173], v[192:195], v[96:99]
	v_mfma_f32_16x16x32_bf16 v[96:99], v[174:177], v[196:199], v[96:99]
	v_mfma_f32_16x16x32_bf16 v[84:87], v[162:165], v[200:203], v[84:87]
	v_mfma_f32_16x16x32_bf16 v[84:87], v[166:169], v[204:207], v[84:87]
	v_mfma_f32_16x16x32_bf16 v[80:83], v[170:173], v[200:203], v[80:83]
	v_mfma_f32_16x16x32_bf16 v[80:83], v[174:177], v[204:207], v[80:83]
	v_mfma_f32_16x16x32_bf16 v[68:71], v[162:165], v[208:211], v[68:71]
	v_mfma_f32_16x16x32_bf16 v[68:71], v[166:169], v[212:215], v[68:71]
	v_mfma_f32_16x16x32_bf16 v[64:67], v[170:173], v[208:211], v[64:67]
	v_mfma_f32_16x16x32_bf16 v[64:67], v[174:177], v[212:215], v[64:67]
	s_setprio 0
	s_barrier
	s_add_i32 s50, s71, s54
	v_lshl_add_u64 v[178:179], v[178:179], 0, s[10:11]
	s_mov_b32 m0, s50
	ds_read_b128 v[184:187], v149 offset:49152
	ds_read_b128 v[188:191], v149 offset:50176
	ds_read_b128 v[192:195], v149 offset:51200
	ds_read_b128 v[196:199], v149 offset:52224
	ds_read_b128 v[200:203], v149 offset:53248
	ds_read_b128 v[204:207], v149 offset:54272
	ds_read_b128 v[208:211], v149 offset:55296
	ds_read_b128 v[212:215], v149 offset:56320
	global_load_lds_dwordx4 v[178:179], off
	s_add_i32 m0, s50, 0x2000
	s_add_u32 s48, s48, 0x40080
	v_lshl_add_u64 v[178:179], v[216:217], 0, s[10:11]
	s_addc_u32 s49, s49, 0
	s_add_i32 s50, s72, s54
	global_load_lds_dwordx4 v[178:179], off
	v_lshl_add_u64 v[178:179], s[48:49], 0, v[130:131]
	s_mov_b32 m0, s50
	s_nop 0
	global_load_lds_dwordx4 v[178:179], off
	v_lshl_add_u64 v[178:179], s[48:49], 0, v[128:129]
	s_add_i32 m0, s50, 0x2000
	s_nop 0
	global_load_lds_dwordx4 v[178:179], off
	v_lshl_add_u64 v[178:179], v[218:219], 0, s[10:11]
	s_mov_b32 m0, s60
	s_nop 0
	global_load_lds_dwordx4 v[178:179], off
	v_lshl_add_u64 v[178:179], v[220:221], 0, s[10:11]
	s_mov_b32 m0, s61
	s_nop 0
	global_load_lds_dwordx4 v[178:179], off
	s_waitcnt vmcnt(8)
	s_waitcnt lgkmcnt(0)
	s_barrier
	s_setprio 1
	s_waitcnt lgkmcnt(0)
	v_mfma_f32_16x16x32_bf16 v[60:63], v[140:143], v[184:187], v[60:63]
	v_mfma_f32_16x16x32_bf16 v[60:63], v[150:153], v[188:191], v[60:63]
	v_mfma_f32_16x16x32_bf16 v[56:59], v[154:157], v[184:187], v[56:59]
	v_mfma_f32_16x16x32_bf16 v[56:59], v[158:161], v[188:191], v[56:59]
	v_mfma_f32_16x16x32_bf16 v[44:47], v[140:143], v[192:195], v[44:47]
	v_mfma_f32_16x16x32_bf16 v[44:47], v[150:153], v[196:199], v[44:47]
	v_mfma_f32_16x16x32_bf16 v[40:43], v[154:157], v[192:195], v[40:43]
	v_mfma_f32_16x16x32_bf16 v[40:43], v[158:161], v[196:199], v[40:43]
	v_mfma_f32_16x16x32_bf16 v[28:31], v[140:143], v[200:203], v[28:31]
	v_mfma_f32_16x16x32_bf16 v[28:31], v[150:153], v[204:207], v[28:31]
	v_mfma_f32_16x16x32_bf16 v[24:27], v[154:157], v[200:203], v[24:27]
	v_mfma_f32_16x16x32_bf16 v[24:27], v[158:161], v[204:207], v[24:27]
	v_mfma_f32_16x16x32_bf16 v[12:15], v[140:143], v[208:211], v[12:15]
	v_mfma_f32_16x16x32_bf16 v[12:15], v[150:153], v[212:215], v[12:15]
	v_mfma_f32_16x16x32_bf16 v[8:11], v[154:157], v[208:211], v[8:11]
	v_mfma_f32_16x16x32_bf16 v[8:11], v[158:161], v[212:215], v[8:11]
	v_mfma_f32_16x16x32_bf16 v[52:55], v[162:165], v[184:187], v[52:55]
	v_mfma_f32_16x16x32_bf16 v[52:55], v[166:169], v[188:191], v[52:55]
	v_mfma_f32_16x16x32_bf16 v[48:51], v[170:173], v[184:187], v[48:51]
	v_mfma_f32_16x16x32_bf16 v[48:51], v[174:177], v[188:191], v[48:51]
	v_mfma_f32_16x16x32_bf16 v[36:39], v[162:165], v[192:195], v[36:39]
	v_mfma_f32_16x16x32_bf16 v[36:39], v[166:169], v[196:199], v[36:39]
	v_mfma_f32_16x16x32_bf16 v[32:35], v[170:173], v[192:195], v[32:35]
	v_mfma_f32_16x16x32_bf16 v[32:35], v[174:177], v[196:199], v[32:35]
	v_mfma_f32_16x16x32_bf16 v[20:23], v[162:165], v[200:203], v[20:23]
	v_mfma_f32_16x16x32_bf16 v[20:23], v[166:169], v[204:207], v[20:23]
	v_mfma_f32_16x16x32_bf16 v[16:19], v[170:173], v[200:203], v[16:19]
	v_mfma_f32_16x16x32_bf16 v[16:19], v[174:177], v[204:207], v[16:19]
	v_mfma_f32_16x16x32_bf16 v[4:7], v[162:165], v[208:211], v[4:7]
	v_mfma_f32_16x16x32_bf16 v[4:7], v[166:169], v[212:215], v[4:7]
	v_mfma_f32_16x16x32_bf16 v[0:3], v[170:173], v[208:211], v[0:3]
	v_mfma_f32_16x16x32_bf16 v[0:3], v[174:177], v[212:215], v[0:3]
	s_setprio 0
	s_barrier
	s_add_i32 s70, s70, 2
	s_add_u32 s46, s46, 0x100
	s_addc_u32 s47, s47, 0
	s_add_u32 s68, s68, 0x100
	s_addc_u32 s69, s69, 0
	s_cmp_gt_u32 s70, 13
	s_cbranch_scc0 .LBB0_1434
	s_and_b64 vcc, exec, s[12:13]
	s_cbranch_vccz .LBB0_1437
	s_barrier

.LBB0_1513:
	s_add_u32 s74, s48, 0x100
	s_addc_u32 s75, s49, 0
	s_mov_b32 s76, -2
	ds_read_b128 v[152:155], v149
	ds_read_b128 v[156:159], v149 offset:1024
	ds_read_b128 v[160:163], v149 offset:2048
	ds_read_b128 v[164:167], v149 offset:3072
	ds_read_b128 v[168:171], v150
	ds_read_b128 v[172:175], v150 offset:1024
	ds_read_b128 v[176:179], v150 offset:2048
	ds_read_b128 v[184:187], v150 offset:3072
	s_add_u32 s48, s46, 0x100
	s_addc_u32 s49, s47, 0
	s_cmp_eq_u32 s76, 40
	s_cselect_b32 s53, s9, s49
	s_cselect_b32 s52, s8, s48
	s_cselect_b32 s51, s45, s75
	s_cselect_b32 s50, s44, s74
	v_lshl_add_u64 v[144:145], s[46:47], 0, v[136:137]
	s_add_i32 m0, s57, 0xc000
	ds_read_b128 v[188:191], v151
	ds_read_b128 v[192:195], v151 offset:1024
	ds_read_b128 v[196:199], v151 offset:2048
	ds_read_b128 v[200:203], v151 offset:3072
	ds_read_b128 v[204:207], v151 offset:4096
	ds_read_b128 v[208:211], v151 offset:5120
	ds_read_b128 v[212:215], v151 offset:6144
	ds_read_b128 v[216:219], v151 offset:7168
	global_load_lds_dwordx4 v[144:145], off
	v_lshl_add_u64 v[144:145], s[46:47], 0, v[138:139]
	s_add_i32 m0, s57, 0xe000
	s_nop 0
	global_load_lds_dwordx4 v[144:145], off
	s_waitcnt vmcnt(8)
	s_waitcnt lgkmcnt(0)
	s_barrier
	s_setprio 1
	s_waitcnt lgkmcnt(0)
	v_mfma_f32_16x16x32_bf16 v[124:127], v[152:155], v[188:191], 0
	v_mfma_f32_16x16x32_bf16 v[124:127], v[156:159], v[192:195], v[124:127]
	v_mfma_f32_16x16x32_bf16 v[120:123], v[160:163], v[188:191], 0
	v_mfma_f32_16x16x32_bf16 v[120:123], v[164:167], v[192:195], v[120:123]
	v_mfma_f32_16x16x32_bf16 v[116:119], v[152:155], v[196:199], 0
	v_mfma_f32_16x16x32_bf16 v[116:119], v[156:159], v[200:203], v[116:119]
	v_mfma_f32_16x16x32_bf16 v[108:111], v[160:163], v[196:199], 0
	v_mfma_f32_16x16x32_bf16 v[108:111], v[164:167], v[200:203], v[108:111]
	v_mfma_f32_16x16x32_bf16 v[100:103], v[152:155], v[204:207], 0
	v_mfma_f32_16x16x32_bf16 v[100:103], v[156:159], v[208:211], v[100:103]
	v_mfma_f32_16x16x32_bf16 v[92:95], v[160:163], v[204:207], 0
	v_mfma_f32_16x16x32_bf16 v[92:95], v[164:167], v[208:211], v[92:95]
	v_mfma_f32_16x16x32_bf16 v[84:87], v[152:155], v[212:215], 0
	v_mfma_f32_16x16x32_bf16 v[84:87], v[156:159], v[216:219], v[84:87]
	v_mfma_f32_16x16x32_bf16 v[76:79], v[160:163], v[212:215], 0
	v_mfma_f32_16x16x32_bf16 v[76:79], v[164:167], v[216:219], v[76:79]
	v_mfma_f32_16x16x32_bf16 v[112:115], v[168:171], v[188:191], 0
	v_mfma_f32_16x16x32_bf16 v[112:115], v[172:175], v[192:195], v[112:115]
	v_mfma_f32_16x16x32_bf16 v[104:107], v[176:179], v[188:191], 0
	v_mfma_f32_16x16x32_bf16 v[104:107], v[184:187], v[192:195], v[104:107]
	v_mfma_f32_16x16x32_bf16 v[96:99], v[168:171], v[196:199], 0
	v_mfma_f32_16x16x32_bf16 v[96:99], v[172:175], v[200:203], v[96:99]
	v_mfma_f32_16x16x32_bf16 v[88:91], v[176:179], v[196:199], 0
	v_mfma_f32_16x16x32_bf16 v[88:91], v[184:187], v[200:203], v[88:91]
	v_mfma_f32_16x16x32_bf16 v[80:83], v[168:171], v[204:207], 0
	v_mfma_f32_16x16x32_bf16 v[80:83], v[172:175], v[208:211], v[80:83]
	v_mfma_f32_16x16x32_bf16 v[72:75], v[176:179], v[204:207], 0
	v_mfma_f32_16x16x32_bf16 v[72:75], v[184:187], v[208:211], v[72:75]
	v_mfma_f32_16x16x32_bf16 v[68:71], v[168:171], v[212:215], 0
	v_mfma_f32_16x16x32_bf16 v[68:71], v[172:175], v[216:219], v[68:71]
	v_mfma_f32_16x16x32_bf16 v[64:67], v[176:179], v[212:215], 0
	v_mfma_f32_16x16x32_bf16 v[64:67], v[184:187], v[216:219], v[64:67]
	s_setprio 0
	s_barrier
	s_add_i32 s46, s64, s56
	v_lshl_add_u64 v[144:145], s[50:51], 0, v[130:131]
	s_mov_b32 m0, s46
	ds_read_b128 v[188:191], v151 offset:16384
	ds_read_b128 v[192:195], v151 offset:17408
	ds_read_b128 v[196:199], v151 offset:18432
	ds_read_b128 v[200:203], v151 offset:19456
	ds_read_b128 v[204:207], v151 offset:20480
	ds_read_b128 v[208:211], v151 offset:21504
	ds_read_b128 v[212:215], v151 offset:22528
	ds_read_b128 v[216:219], v151 offset:23552
	global_load_lds_dwordx4 v[144:145], off
	s_add_i32 m0, s46, 0x2000
	s_add_u32 s46, s50, 0xb0000
	v_lshl_add_u64 v[220:221], s[50:51], 0, v[134:135]
	s_addc_u32 s47, s51, 0
	s_add_i32 s77, s65, s56
	global_load_lds_dwordx4 v[220:221], off
	v_lshl_add_u64 v[222:223], s[46:47], 0, v[130:131]
	s_mov_b32 m0, s77
	v_lshl_add_u64 v[224:225], s[52:53], 0, v[132:133]
	global_load_lds_dwordx4 v[222:223], off
	v_lshl_add_u64 v[222:223], s[46:47], 0, v[134:135]
	s_add_i32 m0, s77, 0x2000
	s_nop 0
	global_load_lds_dwordx4 v[222:223], off
	v_lshl_add_u64 v[222:223], s[52:53], 0, v[128:129]
	s_mov_b32 m0, s57
	s_nop 0
	global_load_lds_dwordx4 v[222:223], off
	s_mov_b32 m0, s58
	s_nop 0
	global_load_lds_dwordx4 v[224:225], off
	s_waitcnt vmcnt(8)
	s_waitcnt lgkmcnt(0)
	s_barrier
	s_setprio 1
	s_waitcnt lgkmcnt(0)
	v_mfma_f32_16x16x32_bf16 v[60:63], v[152:155], v[188:191], 0
	v_mfma_f32_16x16x32_bf16 v[60:63], v[156:159], v[192:195], v[60:63]
	v_mfma_f32_16x16x32_bf16 v[56:59], v[160:163], v[188:191], 0
	v_mfma_f32_16x16x32_bf16 v[56:59], v[164:167], v[192:195], v[56:59]
	v_mfma_f32_16x16x32_bf16 v[52:55], v[152:155], v[196:199], 0
	v_mfma_f32_16x16x32_bf16 v[52:55], v[156:159], v[200:203], v[52:55]
	v_mfma_f32_16x16x32_bf16 v[44:47], v[160:163], v[196:199], 0
	v_mfma_f32_16x16x32_bf16 v[44:47], v[164:167], v[200:203], v[44:47]
	v_mfma_f32_16x16x32_bf16 v[36:39], v[152:155], v[204:207], 0
	v_mfma_f32_16x16x32_bf16 v[36:39], v[156:159], v[208:211], v[36:39]
	v_mfma_f32_16x16x32_bf16 v[28:31], v[160:163], v[204:207], 0
	v_mfma_f32_16x16x32_bf16 v[28:31], v[164:167], v[208:211], v[28:31]
	v_mfma_f32_16x16x32_bf16 v[20:23], v[152:155], v[212:215], 0
	v_mfma_f32_16x16x32_bf16 v[20:23], v[156:159], v[216:219], v[20:23]
	v_mfma_f32_16x16x32_bf16 v[12:15], v[160:163], v[212:215], 0
	v_mfma_f32_16x16x32_bf16 v[12:15], v[164:167], v[216:219], v[12:15]
	v_mfma_f32_16x16x32_bf16 v[48:51], v[168:171], v[188:191], 0
	v_mfma_f32_16x16x32_bf16 v[48:51], v[172:175], v[192:195], v[48:51]
	v_mfma_f32_16x16x32_bf16 v[40:43], v[176:179], v[188:191], 0
	v_mfma_f32_16x16x32_bf16 v[40:43], v[184:187], v[192:195], v[40:43]
	v_mfma_f32_16x16x32_bf16 v[32:35], v[168:171], v[196:199], 0
	v_mfma_f32_16x16x32_bf16 v[32:35], v[172:175], v[200:203], v[32:35]
	v_mfma_f32_16x16x32_bf16 v[24:27], v[176:179], v[196:199], 0
	v_mfma_f32_16x16x32_bf16 v[24:27], v[184:187], v[200:203], v[24:27]
	v_mfma_f32_16x16x32_bf16 v[16:19], v[168:171], v[204:207], 0
	v_mfma_f32_16x16x32_bf16 v[16:19], v[172:175], v[208:211], v[16:19]
	v_mfma_f32_16x16x32_bf16 v[8:11], v[176:179], v[204:207], 0
	v_mfma_f32_16x16x32_bf16 v[8:11], v[184:187], v[208:211], v[8:11]
	v_mfma_f32_16x16x32_bf16 v[4:7], v[168:171], v[212:215], 0
	v_mfma_f32_16x16x32_bf16 v[4:7], v[172:175], v[216:219], v[4:7]
	v_mfma_f32_16x16x32_bf16 v[0:3], v[176:179], v[212:215], 0
	v_mfma_f32_16x16x32_bf16 v[0:3], v[184:187], v[216:219], v[0:3]
	s_setprio 0
	s_barrier
	s_branch .Lmid_gemm12
.LBB0_1514:
	ds_read_b128 v[152:155], v149
	ds_read_b128 v[156:159], v149 offset:1024
	ds_read_b128 v[160:163], v149 offset:2048
	ds_read_b128 v[164:167], v149 offset:3072
	ds_read_b128 v[168:171], v150
	ds_read_b128 v[172:175], v150 offset:1024
	ds_read_b128 v[176:179], v150 offset:2048
	ds_read_b128 v[184:187], v150 offset:3072
	s_add_u32 s48, s46, 0x100
	s_addc_u32 s49, s47, 0
	s_cmp_eq_u32 s76, 40
	s_cselect_b32 s53, s9, s49
	s_cselect_b32 s52, s8, s48
	s_cselect_b32 s51, s45, s75
	s_cselect_b32 s50, s44, s74
	v_lshl_add_u64 v[144:145], s[46:47], 0, v[136:137]
	s_add_i32 m0, s57, 0xc000
	ds_read_b128 v[188:191], v151
	ds_read_b128 v[192:195], v151 offset:1024
	ds_read_b128 v[196:199], v151 offset:2048
	ds_read_b128 v[200:203], v151 offset:3072
	ds_read_b128 v[204:207], v151 offset:4096
	ds_read_b128 v[208:211], v151 offset:5120
	ds_read_b128 v[212:215], v151 offset:6144
	ds_read_b128 v[216:219], v151 offset:7168
	global_load_lds_dwordx4 v[144:145], off
	v_lshl_add_u64 v[144:145], s[46:47], 0, v[138:139]
	s_add_i32 m0, s57, 0xe000
	s_nop 0
	global_load_lds_dwordx4 v[144:145], off
	s_waitcnt vmcnt(8)
	s_waitcnt lgkmcnt(0)
	s_barrier
	s_setprio 1
	s_waitcnt lgkmcnt(0)
	v_mfma_f32_16x16x32_bf16 v[124:127], v[152:155], v[188:191], v[124:127]
	v_mfma_f32_16x16x32_bf16 v[124:127], v[156:159], v[192:195], v[124:127]
	v_mfma_f32_16x16x32_bf16 v[120:123], v[160:163], v[188:191], v[120:123]
	v_mfma_f32_16x16x32_bf16 v[120:123], v[164:167], v[192:195], v[120:123]
	v_mfma_f32_16x16x32_bf16 v[116:119], v[152:155], v[196:199], v[116:119]
	v_mfma_f32_16x16x32_bf16 v[116:119], v[156:159], v[200:203], v[116:119]
	v_mfma_f32_16x16x32_bf16 v[108:111], v[160:163], v[196:199], v[108:111]
	v_mfma_f32_16x16x32_bf16 v[108:111], v[164:167], v[200:203], v[108:111]
	v_mfma_f32_16x16x32_bf16 v[100:103], v[152:155], v[204:207], v[100:103]
	v_mfma_f32_16x16x32_bf16 v[100:103], v[156:159], v[208:211], v[100:103]
	v_mfma_f32_16x16x32_bf16 v[92:95], v[160:163], v[204:207], v[92:95]
	v_mfma_f32_16x16x32_bf16 v[92:95], v[164:167], v[208:211], v[92:95]
	v_mfma_f32_16x16x32_bf16 v[84:87], v[152:155], v[212:215], v[84:87]
	v_mfma_f32_16x16x32_bf16 v[84:87], v[156:159], v[216:219], v[84:87]
	v_mfma_f32_16x16x32_bf16 v[76:79], v[160:163], v[212:215], v[76:79]
	v_mfma_f32_16x16x32_bf16 v[76:79], v[164:167], v[216:219], v[76:79]
	v_mfma_f32_16x16x32_bf16 v[112:115], v[168:171], v[188:191], v[112:115]
	v_mfma_f32_16x16x32_bf16 v[112:115], v[172:175], v[192:195], v[112:115]
	v_mfma_f32_16x16x32_bf16 v[104:107], v[176:179], v[188:191], v[104:107]
	v_mfma_f32_16x16x32_bf16 v[104:107], v[184:187], v[192:195], v[104:107]
	v_mfma_f32_16x16x32_bf16 v[96:99], v[168:171], v[196:199], v[96:99]
	v_mfma_f32_16x16x32_bf16 v[96:99], v[172:175], v[200:203], v[96:99]
	v_mfma_f32_16x16x32_bf16 v[88:91], v[176:179], v[196:199], v[88:91]
	v_mfma_f32_16x16x32_bf16 v[88:91], v[184:187], v[200:203], v[88:91]
	v_mfma_f32_16x16x32_bf16 v[80:83], v[168:171], v[204:207], v[80:83]
	v_mfma_f32_16x16x32_bf16 v[80:83], v[172:175], v[208:211], v[80:83]
	v_mfma_f32_16x16x32_bf16 v[72:75], v[176:179], v[204:207], v[72:75]
	v_mfma_f32_16x16x32_bf16 v[72:75], v[184:187], v[208:211], v[72:75]
	v_mfma_f32_16x16x32_bf16 v[68:71], v[168:171], v[212:215], v[68:71]
	v_mfma_f32_16x16x32_bf16 v[68:71], v[172:175], v[216:219], v[68:71]
	v_mfma_f32_16x16x32_bf16 v[64:67], v[176:179], v[212:215], v[64:67]
	v_mfma_f32_16x16x32_bf16 v[64:67], v[184:187], v[216:219], v[64:67]
	s_setprio 0
	s_barrier
	s_add_i32 s46, s64, s56
	v_lshl_add_u64 v[144:145], s[50:51], 0, v[130:131]
	s_mov_b32 m0, s46
	ds_read_b128 v[188:191], v151 offset:16384
	ds_read_b128 v[192:195], v151 offset:17408
	ds_read_b128 v[196:199], v151 offset:18432
	ds_read_b128 v[200:203], v151 offset:19456
	ds_read_b128 v[204:207], v151 offset:20480
	ds_read_b128 v[208:211], v151 offset:21504
	ds_read_b128 v[212:215], v151 offset:22528
	ds_read_b128 v[216:219], v151 offset:23552
	global_load_lds_dwordx4 v[144:145], off
	s_add_i32 m0, s46, 0x2000
	s_add_u32 s46, s50, 0xb0000
	v_lshl_add_u64 v[220:221], s[50:51], 0, v[134:135]
	s_addc_u32 s47, s51, 0
	s_add_i32 s77, s65, s56
	global_load_lds_dwordx4 v[220:221], off
	v_lshl_add_u64 v[222:223], s[46:47], 0, v[130:131]
	s_mov_b32 m0, s77
	v_lshl_add_u64 v[224:225], s[52:53], 0, v[132:133]
	global_load_lds_dwordx4 v[222:223], off
	v_lshl_add_u64 v[222:223], s[46:47], 0, v[134:135]
	s_add_i32 m0, s77, 0x2000
	s_nop 0
	global_load_lds_dwordx4 v[222:223], off
	v_lshl_add_u64 v[222:223], s[52:53], 0, v[128:129]
	s_mov_b32 m0, s57
	s_nop 0
	global_load_lds_dwordx4 v[222:223], off
	s_mov_b32 m0, s58
	s_nop 0
	global_load_lds_dwordx4 v[224:225], off
	s_waitcnt vmcnt(8)
	s_waitcnt lgkmcnt(0)
	s_barrier
	s_setprio 1
	s_waitcnt lgkmcnt(0)
	v_mfma_f32_16x16x32_bf16 v[60:63], v[152:155], v[188:191], v[60:63]
	v_mfma_f32_16x16x32_bf16 v[60:63], v[156:159], v[192:195], v[60:63]
	v_mfma_f32_16x16x32_bf16 v[56:59], v[160:163], v[188:191], v[56:59]
	v_mfma_f32_16x16x32_bf16 v[56:59], v[164:167], v[192:195], v[56:59]
	v_mfma_f32_16x16x32_bf16 v[52:55], v[152:155], v[196:199], v[52:55]
	v_mfma_f32_16x16x32_bf16 v[52:55], v[156:159], v[200:203], v[52:55]
	v_mfma_f32_16x16x32_bf16 v[44:47], v[160:163], v[196:199], v[44:47]
	v_mfma_f32_16x16x32_bf16 v[44:47], v[164:167], v[200:203], v[44:47]
	v_mfma_f32_16x16x32_bf16 v[36:39], v[152:155], v[204:207], v[36:39]
	v_mfma_f32_16x16x32_bf16 v[36:39], v[156:159], v[208:211], v[36:39]
	v_mfma_f32_16x16x32_bf16 v[28:31], v[160:163], v[204:207], v[28:31]
	v_mfma_f32_16x16x32_bf16 v[28:31], v[164:167], v[208:211], v[28:31]
	v_mfma_f32_16x16x32_bf16 v[20:23], v[152:155], v[212:215], v[20:23]
	v_mfma_f32_16x16x32_bf16 v[20:23], v[156:159], v[216:219], v[20:23]
	v_mfma_f32_16x16x32_bf16 v[12:15], v[160:163], v[212:215], v[12:15]
	v_mfma_f32_16x16x32_bf16 v[12:15], v[164:167], v[216:219], v[12:15]
	v_mfma_f32_16x16x32_bf16 v[48:51], v[168:171], v[188:191], v[48:51]
	v_mfma_f32_16x16x32_bf16 v[48:51], v[172:175], v[192:195], v[48:51]
	v_mfma_f32_16x16x32_bf16 v[40:43], v[176:179], v[188:191], v[40:43]
	v_mfma_f32_16x16x32_bf16 v[40:43], v[184:187], v[192:195], v[40:43]
	v_mfma_f32_16x16x32_bf16 v[32:35], v[168:171], v[196:199], v[32:35]
	v_mfma_f32_16x16x32_bf16 v[32:35], v[172:175], v[200:203], v[32:35]
	v_mfma_f32_16x16x32_bf16 v[24:27], v[176:179], v[196:199], v[24:27]
	v_mfma_f32_16x16x32_bf16 v[24:27], v[184:187], v[200:203], v[24:27]
	v_mfma_f32_16x16x32_bf16 v[16:19], v[168:171], v[204:207], v[16:19]
	v_mfma_f32_16x16x32_bf16 v[16:19], v[172:175], v[208:211], v[16:19]
	v_mfma_f32_16x16x32_bf16 v[8:11], v[176:179], v[204:207], v[8:11]
	v_mfma_f32_16x16x32_bf16 v[8:11], v[184:187], v[208:211], v[8:11]
	v_mfma_f32_16x16x32_bf16 v[4:7], v[168:171], v[212:215], v[4:7]
	v_mfma_f32_16x16x32_bf16 v[4:7], v[172:175], v[216:219], v[4:7]
	v_mfma_f32_16x16x32_bf16 v[0:3], v[176:179], v[212:215], v[0:3]
	v_mfma_f32_16x16x32_bf16 v[0:3], v[184:187], v[216:219], v[0:3]
	s_setprio 0
	s_barrier
.Lmid_gemm12:
	s_add_i32 s77, 0, 0x18000
	s_add_i32 s79, 0, 0x1c000
	v_add_u32_e32 v164, s77, v147
	v_add_u32_e32 v181, s79, v147
	ds_read_b128 v[152:155], v164
	ds_read_b128 v[156:159], v164 offset:1024
	ds_read_b128 v[160:163], v164 offset:2048
	ds_read_b128 v[164:167], v164 offset:3072
	ds_read_b128 v[168:171], v181
	ds_read_b128 v[172:175], v181 offset:1024
	ds_read_b128 v[176:179], v181 offset:2048
	ds_read_b128 v[184:187], v181 offset:3072
	s_add_u32 s46, s52, 0xb0000
	s_addc_u32 s47, s53, 0
	s_mov_b32 m0, s59
	v_lshl_add_u64 v[226:227], s[46:47], 0, v[128:129]
	ds_read_b128 v[188:191], v151 offset:32768
	ds_read_b128 v[192:195], v151 offset:33792
	ds_read_b128 v[196:199], v151 offset:34816
	ds_read_b128 v[200:203], v151 offset:35840
	ds_read_b128 v[204:207], v151 offset:36864
	ds_read_b128 v[208:211], v151 offset:37888
	ds_read_b128 v[212:215], v151 offset:38912
	ds_read_b128 v[216:219], v151 offset:39936
	global_load_lds_dwordx4 v[226:227], off
	v_lshl_add_u64 v[226:227], s[46:47], 0, v[132:133]
	s_mov_b32 m0, s60
	s_nop 0
	global_load_lds_dwordx4 v[226:227], off
	s_waitcnt vmcnt(8)
	s_waitcnt lgkmcnt(0)
	s_barrier
	s_setprio 1
	s_waitcnt lgkmcnt(0)
	v_mfma_f32_16x16x32_bf16 v[124:127], v[152:155], v[188:191], v[124:127]
	v_mfma_f32_16x16x32_bf16 v[124:127], v[156:159], v[192:195], v[124:127]
	v_mfma_f32_16x16x32_bf16 v[120:123], v[160:163], v[188:191], v[120:123]
	v_mfma_f32_16x16x32_bf16 v[120:123], v[164:167], v[192:195], v[120:123]
	v_mfma_f32_16x16x32_bf16 v[116:119], v[152:155], v[196:199], v[116:119]
	v_mfma_f32_16x16x32_bf16 v[116:119], v[156:159], v[200:203], v[116:119]
	v_mfma_f32_16x16x32_bf16 v[108:111], v[160:163], v[196:199], v[108:111]
	v_mfma_f32_16x16x32_bf16 v[108:111], v[164:167], v[200:203], v[108:111]
	v_mfma_f32_16x16x32_bf16 v[100:103], v[152:155], v[204:207], v[100:103]
	v_mfma_f32_16x16x32_bf16 v[100:103], v[156:159], v[208:211], v[100:103]
	v_mfma_f32_16x16x32_bf16 v[92:95], v[160:163], v[204:207], v[92:95]
	v_mfma_f32_16x16x32_bf16 v[92:95], v[164:167], v[208:211], v[92:95]
	v_mfma_f32_16x16x32_bf16 v[84:87], v[152:155], v[212:215], v[84:87]
	v_mfma_f32_16x16x32_bf16 v[84:87], v[156:159], v[216:219], v[84:87]
	v_mfma_f32_16x16x32_bf16 v[76:79], v[160:163], v[212:215], v[76:79]
	v_mfma_f32_16x16x32_bf16 v[76:79], v[164:167], v[216:219], v[76:79]
	v_mfma_f32_16x16x32_bf16 v[112:115], v[168:171], v[188:191], v[112:115]
	v_mfma_f32_16x16x32_bf16 v[112:115], v[172:175], v[192:195], v[112:115]
	v_mfma_f32_16x16x32_bf16 v[104:107], v[176:179], v[188:191], v[104:107]
	v_mfma_f32_16x16x32_bf16 v[104:107], v[184:187], v[192:195], v[104:107]
	v_mfma_f32_16x16x32_bf16 v[96:99], v[168:171], v[196:199], v[96:99]
	v_mfma_f32_16x16x32_bf16 v[96:99], v[172:175], v[200:203], v[96:99]
	v_mfma_f32_16x16x32_bf16 v[88:91], v[176:179], v[196:199], v[88:91]
	v_mfma_f32_16x16x32_bf16 v[88:91], v[184:187], v[200:203], v[88:91]
	v_mfma_f32_16x16x32_bf16 v[80:83], v[168:171], v[204:207], v[80:83]
	v_mfma_f32_16x16x32_bf16 v[80:83], v[172:175], v[208:211], v[80:83]
	v_mfma_f32_16x16x32_bf16 v[72:75], v[176:179], v[204:207], v[72:75]
	v_mfma_f32_16x16x32_bf16 v[72:75], v[184:187], v[208:211], v[72:75]
	v_mfma_f32_16x16x32_bf16 v[68:71], v[168:171], v[212:215], v[68:71]
	v_mfma_f32_16x16x32_bf16 v[68:71], v[172:175], v[216:219], v[68:71]
	v_mfma_f32_16x16x32_bf16 v[64:67], v[176:179], v[212:215], v[64:67]
	v_mfma_f32_16x16x32_bf16 v[64:67], v[184:187], v[216:219], v[64:67]
	s_setprio 0
	s_barrier
	s_add_i32 s46, s77, s56
	v_lshl_add_u64 v[144:145], v[144:145], 0, s[10:11]
	s_mov_b32 m0, s46
	ds_read_b128 v[188:191], v151 offset:49152
	ds_read_b128 v[192:195], v151 offset:50176
	ds_read_b128 v[196:199], v151 offset:51200
	ds_read_b128 v[200:203], v151 offset:52224
	ds_read_b128 v[204:207], v151 offset:53248
	ds_read_b128 v[208:211], v151 offset:54272
	ds_read_b128 v[212:215], v151 offset:55296
	ds_read_b128 v[216:219], v151 offset:56320
	global_load_lds_dwordx4 v[144:145], off
	s_add_i32 m0, s46, 0x2000
	s_add_u32 s46, s50, 0xb0080
	v_lshl_add_u64 v[144:145], v[220:221], 0, s[10:11]
	s_addc_u32 s47, s51, 0
	s_add_i32 s50, s79, s56
	global_load_lds_dwordx4 v[144:145], off
	v_lshl_add_u64 v[144:145], s[46:47], 0, v[130:131]
	s_mov_b32 m0, s50
	s_nop 0
	global_load_lds_dwordx4 v[144:145], off
	v_lshl_add_u64 v[144:145], s[46:47], 0, v[134:135]
	s_add_i32 m0, s50, 0x2000
	s_nop 0
	global_load_lds_dwordx4 v[144:145], off
	v_lshl_add_u64 v[144:145], v[222:223], 0, s[10:11]
	s_mov_b32 m0, s62
	s_nop 0
	global_load_lds_dwordx4 v[144:145], off
	v_lshl_add_u64 v[144:145], v[224:225], 0, s[10:11]
	s_mov_b32 m0, s63
	s_nop 0
	global_load_lds_dwordx4 v[144:145], off
	s_waitcnt vmcnt(8)
	s_waitcnt lgkmcnt(0)
	s_barrier
	s_setprio 1
	s_waitcnt lgkmcnt(0)
	v_mfma_f32_16x16x32_bf16 v[60:63], v[152:155], v[188:191], v[60:63]
	v_mfma_f32_16x16x32_bf16 v[60:63], v[156:159], v[192:195], v[60:63]
	v_mfma_f32_16x16x32_bf16 v[56:59], v[160:163], v[188:191], v[56:59]
	v_mfma_f32_16x16x32_bf16 v[56:59], v[164:167], v[192:195], v[56:59]
	v_mfma_f32_16x16x32_bf16 v[52:55], v[152:155], v[196:199], v[52:55]
	v_mfma_f32_16x16x32_bf16 v[52:55], v[156:159], v[200:203], v[52:55]
	v_mfma_f32_16x16x32_bf16 v[44:47], v[160:163], v[196:199], v[44:47]
	v_mfma_f32_16x16x32_bf16 v[44:47], v[164:167], v[200:203], v[44:47]
	v_mfma_f32_16x16x32_bf16 v[36:39], v[152:155], v[204:207], v[36:39]
	v_mfma_f32_16x16x32_bf16 v[36:39], v[156:159], v[208:211], v[36:39]
	v_mfma_f32_16x16x32_bf16 v[28:31], v[160:163], v[204:207], v[28:31]
	v_mfma_f32_16x16x32_bf16 v[28:31], v[164:167], v[208:211], v[28:31]
	v_mfma_f32_16x16x32_bf16 v[20:23], v[152:155], v[212:215], v[20:23]
	v_mfma_f32_16x16x32_bf16 v[20:23], v[156:159], v[216:219], v[20:23]
	v_mfma_f32_16x16x32_bf16 v[12:15], v[160:163], v[212:215], v[12:15]
	v_mfma_f32_16x16x32_bf16 v[12:15], v[164:167], v[216:219], v[12:15]
	v_mfma_f32_16x16x32_bf16 v[48:51], v[168:171], v[188:191], v[48:51]
	v_mfma_f32_16x16x32_bf16 v[48:51], v[172:175], v[192:195], v[48:51]
	v_mfma_f32_16x16x32_bf16 v[40:43], v[176:179], v[188:191], v[40:43]
	v_mfma_f32_16x16x32_bf16 v[40:43], v[184:187], v[192:195], v[40:43]
	v_mfma_f32_16x16x32_bf16 v[32:35], v[168:171], v[196:199], v[32:35]
	v_mfma_f32_16x16x32_bf16 v[32:35], v[172:175], v[200:203], v[32:35]
	v_mfma_f32_16x16x32_bf16 v[24:27], v[176:179], v[196:199], v[24:27]
	v_mfma_f32_16x16x32_bf16 v[24:27], v[184:187], v[200:203], v[24:27]
	v_mfma_f32_16x16x32_bf16 v[16:19], v[168:171], v[204:207], v[16:19]
	v_mfma_f32_16x16x32_bf16 v[16:19], v[172:175], v[208:211], v[16:19]
	v_mfma_f32_16x16x32_bf16 v[8:11], v[176:179], v[204:207], v[8:11]
	v_mfma_f32_16x16x32_bf16 v[8:11], v[184:187], v[208:211], v[8:11]
	v_mfma_f32_16x16x32_bf16 v[4:7], v[168:171], v[212:215], v[4:7]
	v_mfma_f32_16x16x32_bf16 v[4:7], v[172:175], v[216:219], v[4:7]
	v_mfma_f32_16x16x32_bf16 v[0:3], v[176:179], v[212:215], v[0:3]
	v_mfma_f32_16x16x32_bf16 v[0:3], v[184:187], v[216:219], v[0:3]
	s_setprio 0
	s_barrier
	s_add_i32 s76, s76, 2
	s_add_u32 s74, s74, 0x100
	s_addc_u32 s75, s75, 0
	s_cmp_gt_u32 s76, 41
	s_mov_b64 s[46:47], s[48:49]
	s_cbranch_scc0 .LBB0_1514
	s_and_b64 vcc, exec, s[12:13]
	s_cbranch_vccz .LBB0_1517
	s_barrier
